# MFMA issue order within each group of 8: snake over the two B fragments so srcA changes every second instruction instead of every instruction (bit-identical)
# baseline (speedup 1.0000x reference)
.LBB0_110:
	s_ashr_i32 s35, s34, 31
	s_lshl_b64 s[12:13], s[34:35], 19
	s_add_u32 s38, s82, s12
	s_addc_u32 s39, s83, s13
	s_and_b64 s[12:13], s[4:5], exec
	s_cselect_b32 s12, s39, s41
	s_cselect_b32 s13, s38, s40
	s_ashr_i32 s37, s36, 31
	s_lshl_b64 s[14:15], s[36:37], 19
	s_add_u32 s86, s42, s14
	s_addc_u32 s87, s43, s15
	s_and_b64 s[14:15], s[4:5], exec
	s_cselect_b32 s14, s87, s81
	s_cselect_b32 s15, s86, s80
	s_add_u32 s40, s40, 0x40080
	s_addc_u32 s41, s41, 0
	s_add_u32 s16, s80, 0x100
	s_addc_u32 s17, s81, 0
	s_mov_b32 s18, -2
	ds_read_b128 v[162:165], v155
	ds_read_b128 v[166:169], v155 offset:1024
	ds_read_b128 v[170:173], v155 offset:2048
	ds_read_b128 v[174:177], v155 offset:3072
	ds_read_b128 v[178:181], v157
	ds_read_b128 v[186:189], v157 offset:1024
	ds_read_b128 v[190:193], v157 offset:2048
	ds_read_b128 v[194:197], v157 offset:3072
	s_add_u32 s19, s40, 0xfffc0080
	s_addc_u32 s20, s41, -1
	s_cmp_eq_u32 s18, 12
	s_cselect_b32 s89, s12, s20
	s_cselect_b32 s88, s13, s19
	s_cselect_b32 s81, s14, s17
	s_cselect_b32 s80, s15, s16
	s_add_i32 m0, s62, 0xc000
	ds_read_b128 v[198:201], v159
	ds_read_b128 v[202:205], v159 offset:1024
	ds_read_b128 v[206:209], v159 offset:2048
	ds_read_b128 v[210:213], v159 offset:3072
	ds_read_b128 v[214:217], v159 offset:4096
	ds_read_b128 v[218:221], v159 offset:5120
	ds_read_b128 v[222:225], v159 offset:6144
	ds_read_b128 v[226:229], v159 offset:7168
	global_load_lds_dwordx4 v136, s[40:41]
	s_add_i32 m0, s62, 0xe000
	s_nop 0
	global_load_lds_dwordx4 v138, s[40:41]
	s_waitcnt vmcnt(8)
	s_waitcnt lgkmcnt(0)
	s_barrier
	s_waitcnt lgkmcnt(0)
	v_mfma_f32_16x16x32_bf16 v[124:127], v[162:165], v[198:201], 0
	v_mfma_f32_16x16x32_bf16 v[120:123], v[170:173], v[198:201], 0
	v_mfma_f32_16x16x32_bf16 v[100:103], v[170:173], v[206:209], 0
	v_mfma_f32_16x16x32_bf16 v[108:111], v[162:165], v[206:209], 0
	v_mfma_f32_16x16x32_bf16 v[92:95], v[162:165], v[214:217], 0
	v_mfma_f32_16x16x32_bf16 v[84:87], v[170:173], v[214:217], 0
	v_mfma_f32_16x16x32_bf16 v[68:71], v[170:173], v[222:225], 0
	v_mfma_f32_16x16x32_bf16 v[76:79], v[162:165], v[222:225], 0
	v_mfma_f32_16x16x32_bf16 v[124:127], v[166:169], v[202:205], v[124:127]
	v_mfma_f32_16x16x32_bf16 v[120:123], v[174:177], v[202:205], v[120:123]
	v_mfma_f32_16x16x32_bf16 v[100:103], v[174:177], v[210:213], v[100:103]
	v_mfma_f32_16x16x32_bf16 v[108:111], v[166:169], v[210:213], v[108:111]
	v_mfma_f32_16x16x32_bf16 v[92:95], v[166:169], v[218:221], v[92:95]
	v_mfma_f32_16x16x32_bf16 v[84:87], v[174:177], v[218:221], v[84:87]
	v_mfma_f32_16x16x32_bf16 v[68:71], v[174:177], v[226:229], v[68:71]
	v_mfma_f32_16x16x32_bf16 v[76:79], v[166:169], v[226:229], v[76:79]
	v_mfma_f32_16x16x32_bf16 v[116:119], v[178:181], v[198:201], 0
	v_mfma_f32_16x16x32_bf16 v[112:115], v[190:193], v[198:201], 0
	v_mfma_f32_16x16x32_bf16 v[96:99], v[190:193], v[206:209], 0
	v_mfma_f32_16x16x32_bf16 v[104:107], v[178:181], v[206:209], 0
	v_mfma_f32_16x16x32_bf16 v[88:91], v[178:181], v[214:217], 0
	v_mfma_f32_16x16x32_bf16 v[80:83], v[190:193], v[214:217], 0
	v_mfma_f32_16x16x32_bf16 v[64:67], v[190:193], v[222:225], 0
	v_mfma_f32_16x16x32_bf16 v[72:75], v[178:181], v[222:225], 0
	v_mfma_f32_16x16x32_bf16 v[116:119], v[186:189], v[202:205], v[116:119]
	v_mfma_f32_16x16x32_bf16 v[112:115], v[194:197], v[202:205], v[112:115]
	v_mfma_f32_16x16x32_bf16 v[96:99], v[194:197], v[210:213], v[96:99]
	v_mfma_f32_16x16x32_bf16 v[104:107], v[186:189], v[210:213], v[104:107]
	v_mfma_f32_16x16x32_bf16 v[88:91], v[186:189], v[218:221], v[88:91]
	v_mfma_f32_16x16x32_bf16 v[80:83], v[194:197], v[218:221], v[80:83]
	v_mfma_f32_16x16x32_bf16 v[64:67], v[194:197], v[226:229], v[64:67]
	v_mfma_f32_16x16x32_bf16 v[72:75], v[186:189], v[226:229], v[72:75]
	s_barrier
	s_add_i32 s19, s73, s3
	s_mov_b32 m0, s19
	ds_read_b128 v[198:201], v159 offset:16384
	ds_read_b128 v[202:205], v159 offset:17408
	ds_read_b128 v[206:209], v159 offset:18432
	ds_read_b128 v[210:213], v159 offset:19456
	ds_read_b128 v[214:217], v159 offset:20480
	ds_read_b128 v[218:221], v159 offset:21504
	ds_read_b128 v[222:225], v159 offset:22528
	ds_read_b128 v[226:229], v159 offset:23552
	global_load_lds_dwordx4 v132, s[80:81]
	s_add_i32 m0, s19, 0x2000
	s_add_u32 s20, s80, 0x40000
	s_addc_u32 s21, s81, 0
	s_add_i32 s19, s74, s3
	global_load_lds_dwordx4 v128, s[80:81]
	s_mov_b32 m0, s19
	global_load_lds_dwordx4 v132, s[20:21]
	s_add_i32 m0, s19, 0x2000
	s_nop 0
	global_load_lds_dwordx4 v128, s[20:21]
	s_mov_b32 m0, s62
	s_nop 0
	global_load_lds_dwordx4 v134, s[88:89]
	s_mov_b32 m0, s63
	s_nop 0
	global_load_lds_dwordx4 v130, s[88:89]
	s_add_u32 s98, s80, s28
	s_addc_u32 s99, s81, s29
	s_add_u32 s100, s88, s28
	s_addc_u32 s101, s89, s29
	s_waitcnt vmcnt(8)
	s_waitcnt lgkmcnt(0)
	s_barrier
	s_waitcnt lgkmcnt(0)
	v_mfma_f32_16x16x32_bf16 v[60:63], v[162:165], v[198:201], 0
	v_mfma_f32_16x16x32_bf16 v[52:55], v[170:173], v[198:201], 0
	v_mfma_f32_16x16x32_bf16 v[36:39], v[170:173], v[206:209], 0
	v_mfma_f32_16x16x32_bf16 v[44:47], v[162:165], v[206:209], 0
	v_mfma_f32_16x16x32_bf16 v[28:31], v[162:165], v[214:217], 0
	v_mfma_f32_16x16x32_bf16 v[20:23], v[170:173], v[214:217], 0
	v_mfma_f32_16x16x32_bf16 v[4:7], v[170:173], v[222:225], 0
	v_mfma_f32_16x16x32_bf16 v[12:15], v[162:165], v[222:225], 0
	v_mfma_f32_16x16x32_bf16 v[60:63], v[166:169], v[202:205], v[60:63]
	v_mfma_f32_16x16x32_bf16 v[52:55], v[174:177], v[202:205], v[52:55]
	v_mfma_f32_16x16x32_bf16 v[36:39], v[174:177], v[210:213], v[36:39]
	v_mfma_f32_16x16x32_bf16 v[44:47], v[166:169], v[210:213], v[44:47]
	v_mfma_f32_16x16x32_bf16 v[28:31], v[166:169], v[218:221], v[28:31]
	v_mfma_f32_16x16x32_bf16 v[20:23], v[174:177], v[218:221], v[20:23]
	v_mfma_f32_16x16x32_bf16 v[4:7], v[174:177], v[226:229], v[4:7]
	v_mfma_f32_16x16x32_bf16 v[12:15], v[166:169], v[226:229], v[12:15]
	v_mfma_f32_16x16x32_bf16 v[56:59], v[178:181], v[198:201], 0
	v_mfma_f32_16x16x32_bf16 v[48:51], v[190:193], v[198:201], 0
	v_mfma_f32_16x16x32_bf16 v[32:35], v[190:193], v[206:209], 0
	v_mfma_f32_16x16x32_bf16 v[40:43], v[178:181], v[206:209], 0
	v_mfma_f32_16x16x32_bf16 v[24:27], v[178:181], v[214:217], 0
	v_mfma_f32_16x16x32_bf16 v[16:19], v[190:193], v[214:217], 0
	v_mfma_f32_16x16x32_bf16 v[0:3], v[190:193], v[222:225], 0
	v_mfma_f32_16x16x32_bf16 v[8:11], v[178:181], v[222:225], 0
	v_mfma_f32_16x16x32_bf16 v[56:59], v[186:189], v[202:205], v[56:59]
	v_mfma_f32_16x16x32_bf16 v[48:51], v[194:197], v[202:205], v[48:51]
	v_mfma_f32_16x16x32_bf16 v[32:35], v[194:197], v[210:213], v[32:35]
	v_mfma_f32_16x16x32_bf16 v[40:43], v[186:189], v[210:213], v[40:43]
	v_mfma_f32_16x16x32_bf16 v[24:27], v[186:189], v[218:221], v[24:27]
	v_mfma_f32_16x16x32_bf16 v[16:19], v[194:197], v[218:221], v[16:19]
	v_mfma_f32_16x16x32_bf16 v[0:3], v[194:197], v[226:229], v[0:3]
	v_mfma_f32_16x16x32_bf16 v[8:11], v[186:189], v[226:229], v[8:11]
	s_barrier
	s_add_i32 s19, 0, 0x18000
	v_add_u32_e32 v146, s19, v151
	s_add_i32 s22, 0, 0x1c000
	ds_read_b128 v[162:165], v146
	ds_read_b128 v[166:169], v146 offset:1024
	ds_read_b128 v[170:173], v146 offset:2048
	ds_read_b128 v[174:177], v146 offset:3072
	v_add_u32_e32 v146, s22, v151
	ds_read_b128 v[178:181], v146
	ds_read_b128 v[186:189], v146 offset:1024
	ds_read_b128 v[190:193], v146 offset:2048
	ds_read_b128 v[194:197], v146 offset:3072
	s_add_u32 s20, s88, 0x40000
	s_addc_u32 s21, s89, 0
	s_mov_b32 m0, s64
	ds_read_b128 v[198:201], v159 offset:32768
	ds_read_b128 v[202:205], v159 offset:33792
	ds_read_b128 v[206:209], v159 offset:34816
	ds_read_b128 v[210:213], v159 offset:35840
	ds_read_b128 v[214:217], v159 offset:36864
	ds_read_b128 v[218:221], v159 offset:37888
	ds_read_b128 v[222:225], v159 offset:38912
	ds_read_b128 v[226:229], v159 offset:39936
	global_load_lds_dwordx4 v134, s[20:21]
	s_mov_b32 m0, s65
	s_nop 0
	global_load_lds_dwordx4 v130, s[20:21]
	s_waitcnt vmcnt(8)
	s_waitcnt lgkmcnt(0)
	s_barrier
	s_waitcnt lgkmcnt(0)
	v_mfma_f32_16x16x32_bf16 v[124:127], v[162:165], v[198:201], v[124:127]
	v_mfma_f32_16x16x32_bf16 v[120:123], v[170:173], v[198:201], v[120:123]
	v_mfma_f32_16x16x32_bf16 v[100:103], v[170:173], v[206:209], v[100:103]
	v_mfma_f32_16x16x32_bf16 v[108:111], v[162:165], v[206:209], v[108:111]
	v_mfma_f32_16x16x32_bf16 v[92:95], v[162:165], v[214:217], v[92:95]
	v_mfma_f32_16x16x32_bf16 v[84:87], v[170:173], v[214:217], v[84:87]
	v_mfma_f32_16x16x32_bf16 v[68:71], v[170:173], v[222:225], v[68:71]
	v_mfma_f32_16x16x32_bf16 v[76:79], v[162:165], v[222:225], v[76:79]
	v_mfma_f32_16x16x32_bf16 v[124:127], v[166:169], v[202:205], v[124:127]
	v_mfma_f32_16x16x32_bf16 v[120:123], v[174:177], v[202:205], v[120:123]
	v_mfma_f32_16x16x32_bf16 v[100:103], v[174:177], v[210:213], v[100:103]
	v_mfma_f32_16x16x32_bf16 v[108:111], v[166:169], v[210:213], v[108:111]
	v_mfma_f32_16x16x32_bf16 v[92:95], v[166:169], v[218:221], v[92:95]
	v_mfma_f32_16x16x32_bf16 v[84:87], v[174:177], v[218:221], v[84:87]
	v_mfma_f32_16x16x32_bf16 v[68:71], v[174:177], v[226:229], v[68:71]
	v_mfma_f32_16x16x32_bf16 v[76:79], v[166:169], v[226:229], v[76:79]
	v_mfma_f32_16x16x32_bf16 v[116:119], v[178:181], v[198:201], v[116:119]
	v_mfma_f32_16x16x32_bf16 v[112:115], v[190:193], v[198:201], v[112:115]
	v_mfma_f32_16x16x32_bf16 v[96:99], v[190:193], v[206:209], v[96:99]
	v_mfma_f32_16x16x32_bf16 v[104:107], v[178:181], v[206:209], v[104:107]
	v_mfma_f32_16x16x32_bf16 v[88:91], v[178:181], v[214:217], v[88:91]
	v_mfma_f32_16x16x32_bf16 v[80:83], v[190:193], v[214:217], v[80:83]
	v_mfma_f32_16x16x32_bf16 v[64:67], v[190:193], v[222:225], v[64:67]
	v_mfma_f32_16x16x32_bf16 v[72:75], v[178:181], v[222:225], v[72:75]
	v_mfma_f32_16x16x32_bf16 v[116:119], v[186:189], v[202:205], v[116:119]
	v_mfma_f32_16x16x32_bf16 v[112:115], v[194:197], v[202:205], v[112:115]
	v_mfma_f32_16x16x32_bf16 v[96:99], v[194:197], v[210:213], v[96:99]
	v_mfma_f32_16x16x32_bf16 v[104:107], v[186:189], v[210:213], v[104:107]
	v_mfma_f32_16x16x32_bf16 v[88:91], v[186:189], v[218:221], v[88:91]
	v_mfma_f32_16x16x32_bf16 v[80:83], v[194:197], v[218:221], v[80:83]
	v_mfma_f32_16x16x32_bf16 v[64:67], v[194:197], v[226:229], v[64:67]
	v_mfma_f32_16x16x32_bf16 v[72:75], v[186:189], v[226:229], v[72:75]
	s_barrier
	s_add_i32 s19, s19, s3
	s_mov_b32 m0, s19
	ds_read_b128 v[198:201], v159 offset:49152
	ds_read_b128 v[202:205], v159 offset:50176
	ds_read_b128 v[206:209], v159 offset:51200
	ds_read_b128 v[210:213], v159 offset:52224
	ds_read_b128 v[214:217], v159 offset:53248
	ds_read_b128 v[218:221], v159 offset:54272
	ds_read_b128 v[222:225], v159 offset:55296
	ds_read_b128 v[226:229], v159 offset:56320
	global_load_lds_dwordx4 v132, s[98:99]
	s_add_i32 m0, s19, 0x2000
	s_add_u32 s20, s80, 0x40080
	s_addc_u32 s21, s81, 0
	s_add_i32 s19, s22, s3
	global_load_lds_dwordx4 v128, s[98:99]
	s_mov_b32 m0, s19
	s_nop 0
	global_load_lds_dwordx4 v132, s[20:21]
	s_add_i32 m0, s19, 0x2000
	s_nop 0
	global_load_lds_dwordx4 v128, s[20:21]
	s_mov_b32 m0, s67
	s_nop 0
	global_load_lds_dwordx4 v134, s[100:101]
	s_mov_b32 m0, s70
	s_nop 0
	global_load_lds_dwordx4 v130, s[100:101]
	s_waitcnt vmcnt(8)
	s_waitcnt lgkmcnt(0)
	s_barrier
	s_waitcnt lgkmcnt(0)
	v_mfma_f32_16x16x32_bf16 v[60:63], v[162:165], v[198:201], v[60:63]
	v_mfma_f32_16x16x32_bf16 v[52:55], v[170:173], v[198:201], v[52:55]
	v_mfma_f32_16x16x32_bf16 v[36:39], v[170:173], v[206:209], v[36:39]
	v_mfma_f32_16x16x32_bf16 v[44:47], v[162:165], v[206:209], v[44:47]
	v_mfma_f32_16x16x32_bf16 v[28:31], v[162:165], v[214:217], v[28:31]
	v_mfma_f32_16x16x32_bf16 v[20:23], v[170:173], v[214:217], v[20:23]
	v_mfma_f32_16x16x32_bf16 v[4:7], v[170:173], v[222:225], v[4:7]
	v_mfma_f32_16x16x32_bf16 v[12:15], v[162:165], v[222:225], v[12:15]
	v_mfma_f32_16x16x32_bf16 v[60:63], v[166:169], v[202:205], v[60:63]
	v_mfma_f32_16x16x32_bf16 v[52:55], v[174:177], v[202:205], v[52:55]
	v_mfma_f32_16x16x32_bf16 v[36:39], v[174:177], v[210:213], v[36:39]
	v_mfma_f32_16x16x32_bf16 v[44:47], v[166:169], v[210:213], v[44:47]
	v_mfma_f32_16x16x32_bf16 v[28:31], v[166:169], v[218:221], v[28:31]
	v_mfma_f32_16x16x32_bf16 v[20:23], v[174:177], v[218:221], v[20:23]
	v_mfma_f32_16x16x32_bf16 v[4:7], v[174:177], v[226:229], v[4:7]
	v_mfma_f32_16x16x32_bf16 v[12:15], v[166:169], v[226:229], v[12:15]
	v_mfma_f32_16x16x32_bf16 v[56:59], v[178:181], v[198:201], v[56:59]
	v_mfma_f32_16x16x32_bf16 v[48:51], v[190:193], v[198:201], v[48:51]
	v_mfma_f32_16x16x32_bf16 v[32:35], v[190:193], v[206:209], v[32:35]
	v_mfma_f32_16x16x32_bf16 v[40:43], v[178:181], v[206:209], v[40:43]
	v_mfma_f32_16x16x32_bf16 v[24:27], v[178:181], v[214:217], v[24:27]
	v_mfma_f32_16x16x32_bf16 v[16:19], v[190:193], v[214:217], v[16:19]
	v_mfma_f32_16x16x32_bf16 v[0:3], v[190:193], v[222:225], v[0:3]
	v_mfma_f32_16x16x32_bf16 v[8:11], v[178:181], v[222:225], v[8:11]
	v_mfma_f32_16x16x32_bf16 v[56:59], v[186:189], v[202:205], v[56:59]
	v_mfma_f32_16x16x32_bf16 v[48:51], v[194:197], v[202:205], v[48:51]
	v_mfma_f32_16x16x32_bf16 v[32:35], v[194:197], v[210:213], v[32:35]
	v_mfma_f32_16x16x32_bf16 v[40:43], v[186:189], v[210:213], v[40:43]
	v_mfma_f32_16x16x32_bf16 v[24:27], v[186:189], v[218:221], v[24:27]
	v_mfma_f32_16x16x32_bf16 v[16:19], v[194:197], v[218:221], v[16:19]
	v_mfma_f32_16x16x32_bf16 v[0:3], v[194:197], v[226:229], v[0:3]
	v_mfma_f32_16x16x32_bf16 v[8:11], v[186:189], v[226:229], v[8:11]
	s_barrier
	s_add_i32 s18, s18, 2
	s_add_u32 s40, s40, 0x100
	s_addc_u32 s41, s41, 0
	s_add_u32 s16, s16, 0x100
	s_addc_u32 s17, s17, 0
	s_cmp_gt_u32 s18, 13
	s_cbranch_scc1 .Lpeel_exit_111
.LBB0_111:
	ds_read_b128 v[162:165], v155
	ds_read_b128 v[166:169], v155 offset:1024
	ds_read_b128 v[170:173], v155 offset:2048
	ds_read_b128 v[174:177], v155 offset:3072
	ds_read_b128 v[178:181], v157
	ds_read_b128 v[186:189], v157 offset:1024
	ds_read_b128 v[190:193], v157 offset:2048
	ds_read_b128 v[194:197], v157 offset:3072
	s_add_u32 s19, s40, 0xfffc0080
	s_addc_u32 s20, s41, -1
	s_cmp_eq_u32 s18, 12
	s_cselect_b32 s89, s12, s20
	s_cselect_b32 s88, s13, s19
	s_cselect_b32 s81, s14, s17
	s_cselect_b32 s80, s15, s16
	s_add_i32 m0, s62, 0xc000
	ds_read_b128 v[198:201], v159
	ds_read_b128 v[202:205], v159 offset:1024
	ds_read_b128 v[206:209], v159 offset:2048
	ds_read_b128 v[210:213], v159 offset:3072
	ds_read_b128 v[214:217], v159 offset:4096
	ds_read_b128 v[218:221], v159 offset:5120
	ds_read_b128 v[222:225], v159 offset:6144
	ds_read_b128 v[226:229], v159 offset:7168
	global_load_lds_dwordx4 v136, s[40:41]
	s_add_i32 m0, s62, 0xe000
	s_nop 0
	global_load_lds_dwordx4 v138, s[40:41]
	s_waitcnt vmcnt(8)
	s_waitcnt lgkmcnt(0)
	s_barrier
	s_waitcnt lgkmcnt(0)
	v_mfma_f32_16x16x32_bf16 v[124:127], v[162:165], v[198:201], v[124:127]
	v_mfma_f32_16x16x32_bf16 v[120:123], v[170:173], v[198:201], v[120:123]
	v_mfma_f32_16x16x32_bf16 v[100:103], v[170:173], v[206:209], v[100:103]
	v_mfma_f32_16x16x32_bf16 v[108:111], v[162:165], v[206:209], v[108:111]
	v_mfma_f32_16x16x32_bf16 v[92:95], v[162:165], v[214:217], v[92:95]
	v_mfma_f32_16x16x32_bf16 v[84:87], v[170:173], v[214:217], v[84:87]
	v_mfma_f32_16x16x32_bf16 v[68:71], v[170:173], v[222:225], v[68:71]
	v_mfma_f32_16x16x32_bf16 v[76:79], v[162:165], v[222:225], v[76:79]
	v_mfma_f32_16x16x32_bf16 v[124:127], v[166:169], v[202:205], v[124:127]
	v_mfma_f32_16x16x32_bf16 v[120:123], v[174:177], v[202:205], v[120:123]
	v_mfma_f32_16x16x32_bf16 v[100:103], v[174:177], v[210:213], v[100:103]
	v_mfma_f32_16x16x32_bf16 v[108:111], v[166:169], v[210:213], v[108:111]
	v_mfma_f32_16x16x32_bf16 v[92:95], v[166:169], v[218:221], v[92:95]
	v_mfma_f32_16x16x32_bf16 v[84:87], v[174:177], v[218:221], v[84:87]
	v_mfma_f32_16x16x32_bf16 v[68:71], v[174:177], v[226:229], v[68:71]
	v_mfma_f32_16x16x32_bf16 v[76:79], v[166:169], v[226:229], v[76:79]
	v_mfma_f32_16x16x32_bf16 v[116:119], v[178:181], v[198:201], v[116:119]
	v_mfma_f32_16x16x32_bf16 v[112:115], v[190:193], v[198:201], v[112:115]
	v_mfma_f32_16x16x32_bf16 v[96:99], v[190:193], v[206:209], v[96:99]
	v_mfma_f32_16x16x32_bf16 v[104:107], v[178:181], v[206:209], v[104:107]
	v_mfma_f32_16x16x32_bf16 v[88:91], v[178:181], v[214:217], v[88:91]
	v_mfma_f32_16x16x32_bf16 v[80:83], v[190:193], v[214:217], v[80:83]
	v_mfma_f32_16x16x32_bf16 v[64:67], v[190:193], v[222:225], v[64:67]
	v_mfma_f32_16x16x32_bf16 v[72:75], v[178:181], v[222:225], v[72:75]
	v_mfma_f32_16x16x32_bf16 v[116:119], v[186:189], v[202:205], v[116:119]
	v_mfma_f32_16x16x32_bf16 v[112:115], v[194:197], v[202:205], v[112:115]
	v_mfma_f32_16x16x32_bf16 v[96:99], v[194:197], v[210:213], v[96:99]
	v_mfma_f32_16x16x32_bf16 v[104:107], v[186:189], v[210:213], v[104:107]
	v_mfma_f32_16x16x32_bf16 v[88:91], v[186:189], v[218:221], v[88:91]
	v_mfma_f32_16x16x32_bf16 v[80:83], v[194:197], v[218:221], v[80:83]
	v_mfma_f32_16x16x32_bf16 v[64:67], v[194:197], v[226:229], v[64:67]
	v_mfma_f32_16x16x32_bf16 v[72:75], v[186:189], v[226:229], v[72:75]
	s_barrier
	s_add_i32 s19, s73, s3
	s_mov_b32 m0, s19
	ds_read_b128 v[198:201], v159 offset:16384
	ds_read_b128 v[202:205], v159 offset:17408
	ds_read_b128 v[206:209], v159 offset:18432
	ds_read_b128 v[210:213], v159 offset:19456
	ds_read_b128 v[214:217], v159 offset:20480
	ds_read_b128 v[218:221], v159 offset:21504
	ds_read_b128 v[222:225], v159 offset:22528
	ds_read_b128 v[226:229], v159 offset:23552
	global_load_lds_dwordx4 v132, s[80:81]
	s_add_i32 m0, s19, 0x2000
	s_add_u32 s20, s80, 0x40000
	s_addc_u32 s21, s81, 0
	s_add_i32 s19, s74, s3
	global_load_lds_dwordx4 v128, s[80:81]
	s_mov_b32 m0, s19
	global_load_lds_dwordx4 v132, s[20:21]
	s_add_i32 m0, s19, 0x2000
	s_nop 0
	global_load_lds_dwordx4 v128, s[20:21]
	s_mov_b32 m0, s62
	s_nop 0
	global_load_lds_dwordx4 v134, s[88:89]
	s_mov_b32 m0, s63
	s_nop 0
	global_load_lds_dwordx4 v130, s[88:89]
	s_add_u32 s98, s80, s28
	s_addc_u32 s99, s81, s29
	s_add_u32 s100, s88, s28
	s_addc_u32 s101, s89, s29
	s_waitcnt vmcnt(8)
	s_waitcnt lgkmcnt(0)
	s_barrier
	s_waitcnt lgkmcnt(0)
	v_mfma_f32_16x16x32_bf16 v[60:63], v[162:165], v[198:201], v[60:63]
	v_mfma_f32_16x16x32_bf16 v[52:55], v[170:173], v[198:201], v[52:55]
	v_mfma_f32_16x16x32_bf16 v[36:39], v[170:173], v[206:209], v[36:39]
	v_mfma_f32_16x16x32_bf16 v[44:47], v[162:165], v[206:209], v[44:47]
	v_mfma_f32_16x16x32_bf16 v[28:31], v[162:165], v[214:217], v[28:31]
	v_mfma_f32_16x16x32_bf16 v[20:23], v[170:173], v[214:217], v[20:23]
	v_mfma_f32_16x16x32_bf16 v[4:7], v[170:173], v[222:225], v[4:7]
	v_mfma_f32_16x16x32_bf16 v[12:15], v[162:165], v[222:225], v[12:15]
	v_mfma_f32_16x16x32_bf16 v[60:63], v[166:169], v[202:205], v[60:63]
	v_mfma_f32_16x16x32_bf16 v[52:55], v[174:177], v[202:205], v[52:55]
	v_mfma_f32_16x16x32_bf16 v[36:39], v[174:177], v[210:213], v[36:39]
	v_mfma_f32_16x16x32_bf16 v[44:47], v[166:169], v[210:213], v[44:47]
	v_mfma_f32_16x16x32_bf16 v[28:31], v[166:169], v[218:221], v[28:31]
	v_mfma_f32_16x16x32_bf16 v[20:23], v[174:177], v[218:221], v[20:23]
	v_mfma_f32_16x16x32_bf16 v[4:7], v[174:177], v[226:229], v[4:7]
	v_mfma_f32_16x16x32_bf16 v[12:15], v[166:169], v[226:229], v[12:15]
	v_mfma_f32_16x16x32_bf16 v[56:59], v[178:181], v[198:201], v[56:59]
	v_mfma_f32_16x16x32_bf16 v[48:51], v[190:193], v[198:201], v[48:51]
	v_mfma_f32_16x16x32_bf16 v[32:35], v[190:193], v[206:209], v[32:35]
	v_mfma_f32_16x16x32_bf16 v[40:43], v[178:181], v[206:209], v[40:43]
	v_mfma_f32_16x16x32_bf16 v[24:27], v[178:181], v[214:217], v[24:27]
	v_mfma_f32_16x16x32_bf16 v[16:19], v[190:193], v[214:217], v[16:19]
	v_mfma_f32_16x16x32_bf16 v[0:3], v[190:193], v[222:225], v[0:3]
	v_mfma_f32_16x16x32_bf16 v[8:11], v[178:181], v[222:225], v[8:11]
	v_mfma_f32_16x16x32_bf16 v[56:59], v[186:189], v[202:205], v[56:59]
	v_mfma_f32_16x16x32_bf16 v[48:51], v[194:197], v[202:205], v[48:51]
	v_mfma_f32_16x16x32_bf16 v[32:35], v[194:197], v[210:213], v[32:35]
	v_mfma_f32_16x16x32_bf16 v[40:43], v[186:189], v[210:213], v[40:43]
	v_mfma_f32_16x16x32_bf16 v[24:27], v[186:189], v[218:221], v[24:27]
	v_mfma_f32_16x16x32_bf16 v[16:19], v[194:197], v[218:221], v[16:19]
	v_mfma_f32_16x16x32_bf16 v[0:3], v[194:197], v[226:229], v[0:3]
	v_mfma_f32_16x16x32_bf16 v[8:11], v[186:189], v[226:229], v[8:11]
	s_barrier
	s_add_i32 s19, 0, 0x18000
	v_add_u32_e32 v146, s19, v151
	s_add_i32 s22, 0, 0x1c000
	ds_read_b128 v[162:165], v146
	ds_read_b128 v[166:169], v146 offset:1024
	ds_read_b128 v[170:173], v146 offset:2048
	ds_read_b128 v[174:177], v146 offset:3072
	v_add_u32_e32 v146, s22, v151
	ds_read_b128 v[178:181], v146
	ds_read_b128 v[186:189], v146 offset:1024
	ds_read_b128 v[190:193], v146 offset:2048
	ds_read_b128 v[194:197], v146 offset:3072
	s_add_u32 s20, s88, 0x40000
	s_addc_u32 s21, s89, 0
	s_mov_b32 m0, s64
	ds_read_b128 v[198:201], v159 offset:32768
	ds_read_b128 v[202:205], v159 offset:33792
	ds_read_b128 v[206:209], v159 offset:34816
	ds_read_b128 v[210:213], v159 offset:35840
	ds_read_b128 v[214:217], v159 offset:36864
	ds_read_b128 v[218:221], v159 offset:37888
	ds_read_b128 v[222:225], v159 offset:38912
	ds_read_b128 v[226:229], v159 offset:39936
	global_load_lds_dwordx4 v134, s[20:21]
	s_mov_b32 m0, s65
	s_nop 0
	global_load_lds_dwordx4 v130, s[20:21]
	s_waitcnt vmcnt(8)
	s_waitcnt lgkmcnt(0)
	s_barrier
	s_waitcnt lgkmcnt(0)
	v_mfma_f32_16x16x32_bf16 v[124:127], v[162:165], v[198:201], v[124:127]
	v_mfma_f32_16x16x32_bf16 v[120:123], v[170:173], v[198:201], v[120:123]
	v_mfma_f32_16x16x32_bf16 v[100:103], v[170:173], v[206:209], v[100:103]
	v_mfma_f32_16x16x32_bf16 v[108:111], v[162:165], v[206:209], v[108:111]
	v_mfma_f32_16x16x32_bf16 v[92:95], v[162:165], v[214:217], v[92:95]
	v_mfma_f32_16x16x32_bf16 v[84:87], v[170:173], v[214:217], v[84:87]
	v_mfma_f32_16x16x32_bf16 v[68:71], v[170:173], v[222:225], v[68:71]
	v_mfma_f32_16x16x32_bf16 v[76:79], v[162:165], v[222:225], v[76:79]
	v_mfma_f32_16x16x32_bf16 v[124:127], v[166:169], v[202:205], v[124:127]
	v_mfma_f32_16x16x32_bf16 v[120:123], v[174:177], v[202:205], v[120:123]
	v_mfma_f32_16x16x32_bf16 v[100:103], v[174:177], v[210:213], v[100:103]
	v_mfma_f32_16x16x32_bf16 v[108:111], v[166:169], v[210:213], v[108:111]
	v_mfma_f32_16x16x32_bf16 v[92:95], v[166:169], v[218:221], v[92:95]
	v_mfma_f32_16x16x32_bf16 v[84:87], v[174:177], v[218:221], v[84:87]
	v_mfma_f32_16x16x32_bf16 v[68:71], v[174:177], v[226:229], v[68:71]
	v_mfma_f32_16x16x32_bf16 v[76:79], v[166:169], v[226:229], v[76:79]
	v_mfma_f32_16x16x32_bf16 v[116:119], v[178:181], v[198:201], v[116:119]
	v_mfma_f32_16x16x32_bf16 v[112:115], v[190:193], v[198:201], v[112:115]
	v_mfma_f32_16x16x32_bf16 v[96:99], v[190:193], v[206:209], v[96:99]
	v_mfma_f32_16x16x32_bf16 v[104:107], v[178:181], v[206:209], v[104:107]
	v_mfma_f32_16x16x32_bf16 v[88:91], v[178:181], v[214:217], v[88:91]
	v_mfma_f32_16x16x32_bf16 v[80:83], v[190:193], v[214:217], v[80:83]
	v_mfma_f32_16x16x32_bf16 v[64:67], v[190:193], v[222:225], v[64:67]
	v_mfma_f32_16x16x32_bf16 v[72:75], v[178:181], v[222:225], v[72:75]
	v_mfma_f32_16x16x32_bf16 v[116:119], v[186:189], v[202:205], v[116:119]
	v_mfma_f32_16x16x32_bf16 v[112:115], v[194:197], v[202:205], v[112:115]
	v_mfma_f32_16x16x32_bf16 v[96:99], v[194:197], v[210:213], v[96:99]
	v_mfma_f32_16x16x32_bf16 v[104:107], v[186:189], v[210:213], v[104:107]
	v_mfma_f32_16x16x32_bf16 v[88:91], v[186:189], v[218:221], v[88:91]
	v_mfma_f32_16x16x32_bf16 v[80:83], v[194:197], v[218:221], v[80:83]
	v_mfma_f32_16x16x32_bf16 v[64:67], v[194:197], v[226:229], v[64:67]
	v_mfma_f32_16x16x32_bf16 v[72:75], v[186:189], v[226:229], v[72:75]
	s_barrier
	s_add_i32 s19, s19, s3
	s_mov_b32 m0, s19
	ds_read_b128 v[198:201], v159 offset:49152
	ds_read_b128 v[202:205], v159 offset:50176
	ds_read_b128 v[206:209], v159 offset:51200
	ds_read_b128 v[210:213], v159 offset:52224
	ds_read_b128 v[214:217], v159 offset:53248
	ds_read_b128 v[218:221], v159 offset:54272
	ds_read_b128 v[222:225], v159 offset:55296
	ds_read_b128 v[226:229], v159 offset:56320
	global_load_lds_dwordx4 v132, s[98:99]
	s_add_i32 m0, s19, 0x2000
	s_add_u32 s20, s80, 0x40080
	s_addc_u32 s21, s81, 0
	s_add_i32 s19, s22, s3
	global_load_lds_dwordx4 v128, s[98:99]
	s_mov_b32 m0, s19
	s_nop 0
	global_load_lds_dwordx4 v132, s[20:21]
	s_add_i32 m0, s19, 0x2000
	s_nop 0
	global_load_lds_dwordx4 v128, s[20:21]
	s_mov_b32 m0, s67
	s_nop 0
	global_load_lds_dwordx4 v134, s[100:101]
	s_mov_b32 m0, s70
	s_nop 0
	global_load_lds_dwordx4 v130, s[100:101]
	s_waitcnt vmcnt(8)
	s_waitcnt lgkmcnt(0)
	s_barrier
	s_waitcnt lgkmcnt(0)
	v_mfma_f32_16x16x32_bf16 v[60:63], v[162:165], v[198:201], v[60:63]
	v_mfma_f32_16x16x32_bf16 v[52:55], v[170:173], v[198:201], v[52:55]
	v_mfma_f32_16x16x32_bf16 v[36:39], v[170:173], v[206:209], v[36:39]
	v_mfma_f32_16x16x32_bf16 v[44:47], v[162:165], v[206:209], v[44:47]
	v_mfma_f32_16x16x32_bf16 v[28:31], v[162:165], v[214:217], v[28:31]
	v_mfma_f32_16x16x32_bf16 v[20:23], v[170:173], v[214:217], v[20:23]
	v_mfma_f32_16x16x32_bf16 v[4:7], v[170:173], v[222:225], v[4:7]
	v_mfma_f32_16x16x32_bf16 v[12:15], v[162:165], v[222:225], v[12:15]
	v_mfma_f32_16x16x32_bf16 v[60:63], v[166:169], v[202:205], v[60:63]
	v_mfma_f32_16x16x32_bf16 v[52:55], v[174:177], v[202:205], v[52:55]
	v_mfma_f32_16x16x32_bf16 v[36:39], v[174:177], v[210:213], v[36:39]
	v_mfma_f32_16x16x32_bf16 v[44:47], v[166:169], v[210:213], v[44:47]
	v_mfma_f32_16x16x32_bf16 v[28:31], v[166:169], v[218:221], v[28:31]
	v_mfma_f32_16x16x32_bf16 v[20:23], v[174:177], v[218:221], v[20:23]
	v_mfma_f32_16x16x32_bf16 v[4:7], v[174:177], v[226:229], v[4:7]
	v_mfma_f32_16x16x32_bf16 v[12:15], v[166:169], v[226:229], v[12:15]
	v_mfma_f32_16x16x32_bf16 v[56:59], v[178:181], v[198:201], v[56:59]
	v_mfma_f32_16x16x32_bf16 v[48:51], v[190:193], v[198:201], v[48:51]
	v_mfma_f32_16x16x32_bf16 v[32:35], v[190:193], v[206:209], v[32:35]
	v_mfma_f32_16x16x32_bf16 v[40:43], v[178:181], v[206:209], v[40:43]
	v_mfma_f32_16x16x32_bf16 v[24:27], v[178:181], v[214:217], v[24:27]
	v_mfma_f32_16x16x32_bf16 v[16:19], v[190:193], v[214:217], v[16:19]
	v_mfma_f32_16x16x32_bf16 v[0:3], v[190:193], v[222:225], v[0:3]
	v_mfma_f32_16x16x32_bf16 v[8:11], v[178:181], v[222:225], v[8:11]
	v_mfma_f32_16x16x32_bf16 v[56:59], v[186:189], v[202:205], v[56:59]
	v_mfma_f32_16x16x32_bf16 v[48:51], v[194:197], v[202:205], v[48:51]
	v_mfma_f32_16x16x32_bf16 v[32:35], v[194:197], v[210:213], v[32:35]
	v_mfma_f32_16x16x32_bf16 v[40:43], v[186:189], v[210:213], v[40:43]
	v_mfma_f32_16x16x32_bf16 v[24:27], v[186:189], v[218:221], v[24:27]
	v_mfma_f32_16x16x32_bf16 v[16:19], v[194:197], v[218:221], v[16:19]
	v_mfma_f32_16x16x32_bf16 v[0:3], v[194:197], v[226:229], v[0:3]
	v_mfma_f32_16x16x32_bf16 v[8:11], v[186:189], v[226:229], v[8:11]
	s_barrier
	s_add_i32 s18, s18, 2
	s_add_u32 s40, s40, 0x100
	s_addc_u32 s41, s41, 0
	s_add_u32 s16, s16, 0x100
	s_addc_u32 s17, s17, 0
	s_cmp_gt_u32 s18, 13
	s_cbranch_scc0 .LBB0_111

.LBB0_444:
	s_add_u32 s40, s40, 0xb0080
	s_addc_u32 s41, s41, 0
	s_add_u32 s39, s42, 0x100
	s_addc_u32 s61, s43, 0
	s_mov_b32 s62, -2
	s_waitcnt lgkmcnt(0)
	ds_read_b128 v[128:131], v213
	ds_read_b128 v[132:135], v213 offset:1024
	ds_read_b128 v[136:139], v213 offset:2048
	ds_read_b128 v[140:143], v213 offset:3072
	ds_read_b128 v[144:147], v214
	ds_read_b128 v[148:151], v214 offset:1024
	ds_read_b128 v[152:155], v214 offset:2048
	ds_read_b128 v[156:159], v214 offset:3072
	s_add_u32 s42, s40, 0xfff50080
	s_addc_u32 s43, s41, -1
	s_cmp_eq_u32 s62, 40
	s_cselect_b32 s81, s1, s43
	s_cselect_b32 s80, s0, s42
	s_cselect_b32 s43, s37, s61
	s_cselect_b32 s42, s36, s39
	s_add_i32 m0, s14, 0xc000
	ds_read_b128 v[160:163], v215
	ds_read_b128 v[164:167], v215 offset:1024
	ds_read_b128 v[168:171], v215 offset:2048
	ds_read_b128 v[172:175], v215 offset:3072
	ds_read_b128 v[198:201], v215 offset:4096
	ds_read_b128 v[202:205], v215 offset:5120
	ds_read_b128 v[206:209], v215 offset:6144
	ds_read_b128 v[218:221], v215 offset:7168
	global_load_lds_dwordx4 v190, s[40:41]
	s_add_i32 m0, s14, 0xe000
	s_nop 0
	global_load_lds_dwordx4 v192, s[40:41]
	s_waitcnt vmcnt(8)
	s_waitcnt lgkmcnt(0)
	s_barrier
	s_waitcnt lgkmcnt(0)
	v_mfma_f32_16x16x32_bf16 v[124:127], v[128:131], v[160:163], 0
	v_mfma_f32_16x16x32_bf16 v[120:123], v[136:139], v[160:163], 0
	v_mfma_f32_16x16x32_bf16 v[104:107], v[136:139], v[168:171], 0
	v_mfma_f32_16x16x32_bf16 v[108:111], v[128:131], v[168:171], 0
	v_mfma_f32_16x16x32_bf16 v[92:95], v[128:131], v[198:201], 0
	v_mfma_f32_16x16x32_bf16 v[88:91], v[136:139], v[198:201], 0
	v_mfma_f32_16x16x32_bf16 v[72:75], v[136:139], v[206:209], 0
	v_mfma_f32_16x16x32_bf16 v[76:79], v[128:131], v[206:209], 0
	v_mfma_f32_16x16x32_bf16 v[124:127], v[132:135], v[164:167], v[124:127]
	v_mfma_f32_16x16x32_bf16 v[120:123], v[140:143], v[164:167], v[120:123]
	v_mfma_f32_16x16x32_bf16 v[104:107], v[140:143], v[172:175], v[104:107]
	v_mfma_f32_16x16x32_bf16 v[108:111], v[132:135], v[172:175], v[108:111]
	v_mfma_f32_16x16x32_bf16 v[92:95], v[132:135], v[202:205], v[92:95]
	v_mfma_f32_16x16x32_bf16 v[88:91], v[140:143], v[202:205], v[88:91]
	v_mfma_f32_16x16x32_bf16 v[72:75], v[140:143], v[218:221], v[72:75]
	v_mfma_f32_16x16x32_bf16 v[76:79], v[132:135], v[218:221], v[76:79]
	v_mfma_f32_16x16x32_bf16 v[116:119], v[144:147], v[160:163], 0
	v_mfma_f32_16x16x32_bf16 v[112:115], v[152:155], v[160:163], 0
	v_mfma_f32_16x16x32_bf16 v[96:99], v[152:155], v[168:171], 0
	v_mfma_f32_16x16x32_bf16 v[100:103], v[144:147], v[168:171], 0
	v_mfma_f32_16x16x32_bf16 v[84:87], v[144:147], v[198:201], 0
	v_mfma_f32_16x16x32_bf16 v[80:83], v[152:155], v[198:201], 0
	v_mfma_f32_16x16x32_bf16 v[64:67], v[152:155], v[206:209], 0
	v_mfma_f32_16x16x32_bf16 v[68:71], v[144:147], v[206:209], 0
	v_mfma_f32_16x16x32_bf16 v[116:119], v[148:151], v[164:167], v[116:119]
	v_mfma_f32_16x16x32_bf16 v[112:115], v[156:159], v[164:167], v[112:115]
	v_mfma_f32_16x16x32_bf16 v[96:99], v[156:159], v[172:175], v[96:99]
	v_mfma_f32_16x16x32_bf16 v[100:103], v[148:151], v[172:175], v[100:103]
	v_mfma_f32_16x16x32_bf16 v[84:87], v[148:151], v[202:205], v[84:87]
	v_mfma_f32_16x16x32_bf16 v[80:83], v[156:159], v[202:205], v[80:83]
	v_mfma_f32_16x16x32_bf16 v[64:67], v[156:159], v[218:221], v[64:67]
	v_mfma_f32_16x16x32_bf16 v[68:71], v[148:151], v[218:221], v[68:71]
	s_barrier
	s_add_i32 s63, s24, s13
	s_mov_b32 m0, s63
	ds_read_b128 v[160:163], v215 offset:16384
	ds_read_b128 v[164:167], v215 offset:17408
	ds_read_b128 v[168:171], v215 offset:18432
	ds_read_b128 v[172:175], v215 offset:19456
	ds_read_b128 v[198:201], v215 offset:20480
	ds_read_b128 v[202:205], v215 offset:21504
	ds_read_b128 v[206:209], v215 offset:22528
	ds_read_b128 v[218:221], v215 offset:23552
	global_load_lds_dwordx4 v178, s[42:43]
	s_add_i32 m0, s63, 0x2000
	s_add_u32 s64, s42, 0xb0000
	s_addc_u32 s65, s43, 0
	s_add_i32 s63, s25, s13
	global_load_lds_dwordx4 v182, s[42:43]
	s_mov_b32 m0, s63
	global_load_lds_dwordx4 v178, s[64:65]
	s_add_i32 m0, s63, 0x2000
	s_nop 0
	global_load_lds_dwordx4 v182, s[64:65]
	s_mov_b32 m0, s14
	s_nop 0
	global_load_lds_dwordx4 v176, s[80:81]
	s_mov_b32 m0, s15
	s_nop 0
	global_load_lds_dwordx4 v180, s[80:81]
	s_add_u32 s98, s42, s30
	s_addc_u32 s99, s43, s31
	s_add_u32 s100, s80, s30
	s_addc_u32 s101, s81, s31
	s_waitcnt vmcnt(8)
	s_waitcnt lgkmcnt(0)
	s_barrier
	s_waitcnt lgkmcnt(0)
	v_mfma_f32_16x16x32_bf16 v[60:63], v[128:131], v[160:163], 0
	v_mfma_f32_16x16x32_bf16 v[56:59], v[136:139], v[160:163], 0
	v_mfma_f32_16x16x32_bf16 v[40:43], v[136:139], v[168:171], 0
	v_mfma_f32_16x16x32_bf16 v[44:47], v[128:131], v[168:171], 0
	v_mfma_f32_16x16x32_bf16 v[28:31], v[128:131], v[198:201], 0
	v_mfma_f32_16x16x32_bf16 v[24:27], v[136:139], v[198:201], 0
	v_mfma_f32_16x16x32_bf16 v[8:11], v[136:139], v[206:209], 0
	v_mfma_f32_16x16x32_bf16 v[12:15], v[128:131], v[206:209], 0
	v_mfma_f32_16x16x32_bf16 v[60:63], v[132:135], v[164:167], v[60:63]
	v_mfma_f32_16x16x32_bf16 v[56:59], v[140:143], v[164:167], v[56:59]
	v_mfma_f32_16x16x32_bf16 v[40:43], v[140:143], v[172:175], v[40:43]
	v_mfma_f32_16x16x32_bf16 v[44:47], v[132:135], v[172:175], v[44:47]
	v_mfma_f32_16x16x32_bf16 v[28:31], v[132:135], v[202:205], v[28:31]
	v_mfma_f32_16x16x32_bf16 v[24:27], v[140:143], v[202:205], v[24:27]
	v_mfma_f32_16x16x32_bf16 v[8:11], v[140:143], v[218:221], v[8:11]
	v_mfma_f32_16x16x32_bf16 v[12:15], v[132:135], v[218:221], v[12:15]
	v_mfma_f32_16x16x32_bf16 v[52:55], v[144:147], v[160:163], 0
	v_mfma_f32_16x16x32_bf16 v[48:51], v[152:155], v[160:163], 0
	v_mfma_f32_16x16x32_bf16 v[32:35], v[152:155], v[168:171], 0
	v_mfma_f32_16x16x32_bf16 v[36:39], v[144:147], v[168:171], 0
	v_mfma_f32_16x16x32_bf16 v[20:23], v[144:147], v[198:201], 0
	v_mfma_f32_16x16x32_bf16 v[16:19], v[152:155], v[198:201], 0
	v_mfma_f32_16x16x32_bf16 v[0:3], v[152:155], v[206:209], 0
	v_mfma_f32_16x16x32_bf16 v[4:7], v[144:147], v[206:209], 0
	v_mfma_f32_16x16x32_bf16 v[52:55], v[148:151], v[164:167], v[52:55]
	v_mfma_f32_16x16x32_bf16 v[48:51], v[156:159], v[164:167], v[48:51]
	v_mfma_f32_16x16x32_bf16 v[32:35], v[156:159], v[172:175], v[32:35]
	v_mfma_f32_16x16x32_bf16 v[36:39], v[148:151], v[172:175], v[36:39]
	v_mfma_f32_16x16x32_bf16 v[20:23], v[148:151], v[202:205], v[20:23]
	v_mfma_f32_16x16x32_bf16 v[16:19], v[156:159], v[202:205], v[16:19]
	v_mfma_f32_16x16x32_bf16 v[0:3], v[156:159], v[218:221], v[0:3]
	v_mfma_f32_16x16x32_bf16 v[4:7], v[148:151], v[218:221], v[4:7]
	s_barrier
	s_add_i32 s63, 0, 0x18000
	s_add_i32 s66, 0, 0x1c000
	v_add_u32_e32 v140, s63, v210
	v_add_u32_e32 v156, s66, v210
	ds_read_b128 v[128:131], v140
	ds_read_b128 v[132:135], v140 offset:1024
	ds_read_b128 v[136:139], v140 offset:2048
	ds_read_b128 v[140:143], v140 offset:3072
	ds_read_b128 v[144:147], v156
	ds_read_b128 v[148:151], v156 offset:1024
	ds_read_b128 v[152:155], v156 offset:2048
	ds_read_b128 v[156:159], v156 offset:3072
	s_add_u32 s64, s80, 0xb0000
	s_addc_u32 s65, s81, 0
	s_mov_b32 m0, s16
	ds_read_b128 v[160:163], v215 offset:32768
	ds_read_b128 v[164:167], v215 offset:33792
	ds_read_b128 v[168:171], v215 offset:34816
	ds_read_b128 v[172:175], v215 offset:35840
	ds_read_b128 v[198:201], v215 offset:36864
	ds_read_b128 v[202:205], v215 offset:37888
	ds_read_b128 v[206:209], v215 offset:38912
	ds_read_b128 v[218:221], v215 offset:39936
	global_load_lds_dwordx4 v176, s[64:65]
	s_mov_b32 m0, s17
	s_nop 0
	global_load_lds_dwordx4 v180, s[64:65]
	s_waitcnt vmcnt(8)
	s_waitcnt lgkmcnt(0)
	s_barrier
	s_waitcnt lgkmcnt(0)
	v_mfma_f32_16x16x32_bf16 v[124:127], v[128:131], v[160:163], v[124:127]
	v_mfma_f32_16x16x32_bf16 v[120:123], v[136:139], v[160:163], v[120:123]
	v_mfma_f32_16x16x32_bf16 v[104:107], v[136:139], v[168:171], v[104:107]
	v_mfma_f32_16x16x32_bf16 v[108:111], v[128:131], v[168:171], v[108:111]
	v_mfma_f32_16x16x32_bf16 v[92:95], v[128:131], v[198:201], v[92:95]
	v_mfma_f32_16x16x32_bf16 v[88:91], v[136:139], v[198:201], v[88:91]
	v_mfma_f32_16x16x32_bf16 v[72:75], v[136:139], v[206:209], v[72:75]
	v_mfma_f32_16x16x32_bf16 v[76:79], v[128:131], v[206:209], v[76:79]
	v_mfma_f32_16x16x32_bf16 v[124:127], v[132:135], v[164:167], v[124:127]
	v_mfma_f32_16x16x32_bf16 v[120:123], v[140:143], v[164:167], v[120:123]
	v_mfma_f32_16x16x32_bf16 v[104:107], v[140:143], v[172:175], v[104:107]
	v_mfma_f32_16x16x32_bf16 v[108:111], v[132:135], v[172:175], v[108:111]
	v_mfma_f32_16x16x32_bf16 v[92:95], v[132:135], v[202:205], v[92:95]
	v_mfma_f32_16x16x32_bf16 v[88:91], v[140:143], v[202:205], v[88:91]
	v_mfma_f32_16x16x32_bf16 v[72:75], v[140:143], v[218:221], v[72:75]
	v_mfma_f32_16x16x32_bf16 v[76:79], v[132:135], v[218:221], v[76:79]
	v_mfma_f32_16x16x32_bf16 v[116:119], v[144:147], v[160:163], v[116:119]
	v_mfma_f32_16x16x32_bf16 v[112:115], v[152:155], v[160:163], v[112:115]
	v_mfma_f32_16x16x32_bf16 v[96:99], v[152:155], v[168:171], v[96:99]
	v_mfma_f32_16x16x32_bf16 v[100:103], v[144:147], v[168:171], v[100:103]
	v_mfma_f32_16x16x32_bf16 v[84:87], v[144:147], v[198:201], v[84:87]
	v_mfma_f32_16x16x32_bf16 v[80:83], v[152:155], v[198:201], v[80:83]
	v_mfma_f32_16x16x32_bf16 v[64:67], v[152:155], v[206:209], v[64:67]
	v_mfma_f32_16x16x32_bf16 v[68:71], v[144:147], v[206:209], v[68:71]
	v_mfma_f32_16x16x32_bf16 v[116:119], v[148:151], v[164:167], v[116:119]
	v_mfma_f32_16x16x32_bf16 v[112:115], v[156:159], v[164:167], v[112:115]
	v_mfma_f32_16x16x32_bf16 v[96:99], v[156:159], v[172:175], v[96:99]
	v_mfma_f32_16x16x32_bf16 v[100:103], v[148:151], v[172:175], v[100:103]
	v_mfma_f32_16x16x32_bf16 v[84:87], v[148:151], v[202:205], v[84:87]
	v_mfma_f32_16x16x32_bf16 v[80:83], v[156:159], v[202:205], v[80:83]
	v_mfma_f32_16x16x32_bf16 v[64:67], v[156:159], v[218:221], v[64:67]
	v_mfma_f32_16x16x32_bf16 v[68:71], v[148:151], v[218:221], v[68:71]
	s_barrier
	s_add_i32 s63, s63, s13
	s_mov_b32 m0, s63
	ds_read_b128 v[160:163], v215 offset:49152
	ds_read_b128 v[164:167], v215 offset:50176
	ds_read_b128 v[168:171], v215 offset:51200
	ds_read_b128 v[172:175], v215 offset:52224
	ds_read_b128 v[198:201], v215 offset:53248
	ds_read_b128 v[202:205], v215 offset:54272
	ds_read_b128 v[206:209], v215 offset:55296
	ds_read_b128 v[218:221], v215 offset:56320
	global_load_lds_dwordx4 v178, s[98:99]
	s_add_i32 m0, s63, 0x2000
	s_add_u32 s42, s42, 0xb0080
	s_addc_u32 s43, s43, 0
	s_add_i32 s63, s66, s13
	global_load_lds_dwordx4 v182, s[98:99]
	s_mov_b32 m0, s63
	s_nop 0
	global_load_lds_dwordx4 v178, s[42:43]
	s_add_i32 m0, s63, 0x2000
	s_nop 0
	global_load_lds_dwordx4 v182, s[42:43]
	s_mov_b32 m0, s19
	s_nop 0
	global_load_lds_dwordx4 v176, s[100:101]
	s_mov_b32 m0, s20
	s_nop 0
	global_load_lds_dwordx4 v180, s[100:101]
	s_waitcnt vmcnt(8)
	s_waitcnt lgkmcnt(0)
	s_barrier
	s_waitcnt lgkmcnt(0)
	v_mfma_f32_16x16x32_bf16 v[60:63], v[128:131], v[160:163], v[60:63]
	v_mfma_f32_16x16x32_bf16 v[56:59], v[136:139], v[160:163], v[56:59]
	v_mfma_f32_16x16x32_bf16 v[40:43], v[136:139], v[168:171], v[40:43]
	v_mfma_f32_16x16x32_bf16 v[44:47], v[128:131], v[168:171], v[44:47]
	v_mfma_f32_16x16x32_bf16 v[28:31], v[128:131], v[198:201], v[28:31]
	v_mfma_f32_16x16x32_bf16 v[24:27], v[136:139], v[198:201], v[24:27]
	v_mfma_f32_16x16x32_bf16 v[8:11], v[136:139], v[206:209], v[8:11]
	v_mfma_f32_16x16x32_bf16 v[12:15], v[128:131], v[206:209], v[12:15]
	v_mfma_f32_16x16x32_bf16 v[60:63], v[132:135], v[164:167], v[60:63]
	v_mfma_f32_16x16x32_bf16 v[56:59], v[140:143], v[164:167], v[56:59]
	v_mfma_f32_16x16x32_bf16 v[40:43], v[140:143], v[172:175], v[40:43]
	v_mfma_f32_16x16x32_bf16 v[44:47], v[132:135], v[172:175], v[44:47]
	v_mfma_f32_16x16x32_bf16 v[28:31], v[132:135], v[202:205], v[28:31]
	v_mfma_f32_16x16x32_bf16 v[24:27], v[140:143], v[202:205], v[24:27]
	v_mfma_f32_16x16x32_bf16 v[8:11], v[140:143], v[218:221], v[8:11]
	v_mfma_f32_16x16x32_bf16 v[12:15], v[132:135], v[218:221], v[12:15]
	v_mfma_f32_16x16x32_bf16 v[52:55], v[144:147], v[160:163], v[52:55]
	v_mfma_f32_16x16x32_bf16 v[48:51], v[152:155], v[160:163], v[48:51]
	v_mfma_f32_16x16x32_bf16 v[32:35], v[152:155], v[168:171], v[32:35]
	v_mfma_f32_16x16x32_bf16 v[36:39], v[144:147], v[168:171], v[36:39]
	v_mfma_f32_16x16x32_bf16 v[20:23], v[144:147], v[198:201], v[20:23]
	v_mfma_f32_16x16x32_bf16 v[16:19], v[152:155], v[198:201], v[16:19]
	v_mfma_f32_16x16x32_bf16 v[0:3], v[152:155], v[206:209], v[0:3]
	v_mfma_f32_16x16x32_bf16 v[4:7], v[144:147], v[206:209], v[4:7]
	v_mfma_f32_16x16x32_bf16 v[52:55], v[148:151], v[164:167], v[52:55]
	v_mfma_f32_16x16x32_bf16 v[48:51], v[156:159], v[164:167], v[48:51]
	v_mfma_f32_16x16x32_bf16 v[32:35], v[156:159], v[172:175], v[32:35]
	v_mfma_f32_16x16x32_bf16 v[36:39], v[148:151], v[172:175], v[36:39]
	v_mfma_f32_16x16x32_bf16 v[20:23], v[148:151], v[202:205], v[20:23]
	v_mfma_f32_16x16x32_bf16 v[16:19], v[156:159], v[202:205], v[16:19]
	v_mfma_f32_16x16x32_bf16 v[0:3], v[156:159], v[218:221], v[0:3]
	v_mfma_f32_16x16x32_bf16 v[4:7], v[148:151], v[218:221], v[4:7]
	s_barrier
	s_add_i32 s62, s62, 2
	s_add_u32 s40, s40, 0x100
	s_addc_u32 s41, s41, 0
	s_add_u32 s39, s39, 0x100
	s_addc_u32 s61, s61, 0
	s_cmp_gt_u32 s62, 41
	s_cbranch_scc1 .Lpeel_exit_445
.LBB0_445:
	ds_read_b128 v[128:131], v213
	ds_read_b128 v[132:135], v213 offset:1024
	ds_read_b128 v[136:139], v213 offset:2048
	ds_read_b128 v[140:143], v213 offset:3072
	ds_read_b128 v[144:147], v214
	ds_read_b128 v[148:151], v214 offset:1024
	ds_read_b128 v[152:155], v214 offset:2048
	ds_read_b128 v[156:159], v214 offset:3072
	s_add_u32 s42, s40, 0xfff50080
	s_addc_u32 s43, s41, -1
	s_cmp_eq_u32 s62, 40
	s_cselect_b32 s81, s1, s43
	s_cselect_b32 s80, s0, s42
	s_cselect_b32 s43, s37, s61
	s_cselect_b32 s42, s36, s39
	s_add_i32 m0, s14, 0xc000
	ds_read_b128 v[160:163], v215
	ds_read_b128 v[164:167], v215 offset:1024
	ds_read_b128 v[168:171], v215 offset:2048
	ds_read_b128 v[172:175], v215 offset:3072
	ds_read_b128 v[198:201], v215 offset:4096
	ds_read_b128 v[202:205], v215 offset:5120
	ds_read_b128 v[206:209], v215 offset:6144
	ds_read_b128 v[218:221], v215 offset:7168
	global_load_lds_dwordx4 v190, s[40:41]
	s_add_i32 m0, s14, 0xe000
	s_nop 0
	global_load_lds_dwordx4 v192, s[40:41]
	s_waitcnt vmcnt(8)
	s_waitcnt lgkmcnt(0)
	s_barrier
	s_waitcnt lgkmcnt(0)
	v_mfma_f32_16x16x32_bf16 v[124:127], v[128:131], v[160:163], v[124:127]
	v_mfma_f32_16x16x32_bf16 v[120:123], v[136:139], v[160:163], v[120:123]
	v_mfma_f32_16x16x32_bf16 v[104:107], v[136:139], v[168:171], v[104:107]
	v_mfma_f32_16x16x32_bf16 v[108:111], v[128:131], v[168:171], v[108:111]
	v_mfma_f32_16x16x32_bf16 v[92:95], v[128:131], v[198:201], v[92:95]
	v_mfma_f32_16x16x32_bf16 v[88:91], v[136:139], v[198:201], v[88:91]
	v_mfma_f32_16x16x32_bf16 v[72:75], v[136:139], v[206:209], v[72:75]
	v_mfma_f32_16x16x32_bf16 v[76:79], v[128:131], v[206:209], v[76:79]
	v_mfma_f32_16x16x32_bf16 v[124:127], v[132:135], v[164:167], v[124:127]
	v_mfma_f32_16x16x32_bf16 v[120:123], v[140:143], v[164:167], v[120:123]
	v_mfma_f32_16x16x32_bf16 v[104:107], v[140:143], v[172:175], v[104:107]
	v_mfma_f32_16x16x32_bf16 v[108:111], v[132:135], v[172:175], v[108:111]
	v_mfma_f32_16x16x32_bf16 v[92:95], v[132:135], v[202:205], v[92:95]
	v_mfma_f32_16x16x32_bf16 v[88:91], v[140:143], v[202:205], v[88:91]
	v_mfma_f32_16x16x32_bf16 v[72:75], v[140:143], v[218:221], v[72:75]
	v_mfma_f32_16x16x32_bf16 v[76:79], v[132:135], v[218:221], v[76:79]
	v_mfma_f32_16x16x32_bf16 v[116:119], v[144:147], v[160:163], v[116:119]
	v_mfma_f32_16x16x32_bf16 v[112:115], v[152:155], v[160:163], v[112:115]
	v_mfma_f32_16x16x32_bf16 v[96:99], v[152:155], v[168:171], v[96:99]
	v_mfma_f32_16x16x32_bf16 v[100:103], v[144:147], v[168:171], v[100:103]
	v_mfma_f32_16x16x32_bf16 v[84:87], v[144:147], v[198:201], v[84:87]
	v_mfma_f32_16x16x32_bf16 v[80:83], v[152:155], v[198:201], v[80:83]
	v_mfma_f32_16x16x32_bf16 v[64:67], v[152:155], v[206:209], v[64:67]
	v_mfma_f32_16x16x32_bf16 v[68:71], v[144:147], v[206:209], v[68:71]
	v_mfma_f32_16x16x32_bf16 v[116:119], v[148:151], v[164:167], v[116:119]
	v_mfma_f32_16x16x32_bf16 v[112:115], v[156:159], v[164:167], v[112:115]
	v_mfma_f32_16x16x32_bf16 v[96:99], v[156:159], v[172:175], v[96:99]
	v_mfma_f32_16x16x32_bf16 v[100:103], v[148:151], v[172:175], v[100:103]
	v_mfma_f32_16x16x32_bf16 v[84:87], v[148:151], v[202:205], v[84:87]
	v_mfma_f32_16x16x32_bf16 v[80:83], v[156:159], v[202:205], v[80:83]
	v_mfma_f32_16x16x32_bf16 v[64:67], v[156:159], v[218:221], v[64:67]
	v_mfma_f32_16x16x32_bf16 v[68:71], v[148:151], v[218:221], v[68:71]
	s_barrier
	s_add_i32 s63, s24, s13
	s_mov_b32 m0, s63
	ds_read_b128 v[160:163], v215 offset:16384
	ds_read_b128 v[164:167], v215 offset:17408
	ds_read_b128 v[168:171], v215 offset:18432
	ds_read_b128 v[172:175], v215 offset:19456
	ds_read_b128 v[198:201], v215 offset:20480
	ds_read_b128 v[202:205], v215 offset:21504
	ds_read_b128 v[206:209], v215 offset:22528
	ds_read_b128 v[218:221], v215 offset:23552
	global_load_lds_dwordx4 v178, s[42:43]
	s_add_i32 m0, s63, 0x2000
	s_add_u32 s64, s42, 0xb0000
	s_addc_u32 s65, s43, 0
	s_add_i32 s63, s25, s13
	global_load_lds_dwordx4 v182, s[42:43]
	s_mov_b32 m0, s63
	global_load_lds_dwordx4 v178, s[64:65]
	s_add_i32 m0, s63, 0x2000
	s_nop 0
	global_load_lds_dwordx4 v182, s[64:65]
	s_mov_b32 m0, s14
	s_nop 0
	global_load_lds_dwordx4 v176, s[80:81]
	s_mov_b32 m0, s15
	s_nop 0
	global_load_lds_dwordx4 v180, s[80:81]
	s_add_u32 s98, s42, s30
	s_addc_u32 s99, s43, s31
	s_add_u32 s100, s80, s30
	s_addc_u32 s101, s81, s31
	s_waitcnt vmcnt(8)
	s_waitcnt lgkmcnt(0)
	s_barrier
	s_waitcnt lgkmcnt(0)
	v_mfma_f32_16x16x32_bf16 v[60:63], v[128:131], v[160:163], v[60:63]
	v_mfma_f32_16x16x32_bf16 v[56:59], v[136:139], v[160:163], v[56:59]
	v_mfma_f32_16x16x32_bf16 v[40:43], v[136:139], v[168:171], v[40:43]
	v_mfma_f32_16x16x32_bf16 v[44:47], v[128:131], v[168:171], v[44:47]
	v_mfma_f32_16x16x32_bf16 v[28:31], v[128:131], v[198:201], v[28:31]
	v_mfma_f32_16x16x32_bf16 v[24:27], v[136:139], v[198:201], v[24:27]
	v_mfma_f32_16x16x32_bf16 v[8:11], v[136:139], v[206:209], v[8:11]
	v_mfma_f32_16x16x32_bf16 v[12:15], v[128:131], v[206:209], v[12:15]
	v_mfma_f32_16x16x32_bf16 v[60:63], v[132:135], v[164:167], v[60:63]
	v_mfma_f32_16x16x32_bf16 v[56:59], v[140:143], v[164:167], v[56:59]
	v_mfma_f32_16x16x32_bf16 v[40:43], v[140:143], v[172:175], v[40:43]
	v_mfma_f32_16x16x32_bf16 v[44:47], v[132:135], v[172:175], v[44:47]
	v_mfma_f32_16x16x32_bf16 v[28:31], v[132:135], v[202:205], v[28:31]
	v_mfma_f32_16x16x32_bf16 v[24:27], v[140:143], v[202:205], v[24:27]
	v_mfma_f32_16x16x32_bf16 v[8:11], v[140:143], v[218:221], v[8:11]
	v_mfma_f32_16x16x32_bf16 v[12:15], v[132:135], v[218:221], v[12:15]
	v_mfma_f32_16x16x32_bf16 v[52:55], v[144:147], v[160:163], v[52:55]
	v_mfma_f32_16x16x32_bf16 v[48:51], v[152:155], v[160:163], v[48:51]
	v_mfma_f32_16x16x32_bf16 v[32:35], v[152:155], v[168:171], v[32:35]
	v_mfma_f32_16x16x32_bf16 v[36:39], v[144:147], v[168:171], v[36:39]
	v_mfma_f32_16x16x32_bf16 v[20:23], v[144:147], v[198:201], v[20:23]
	v_mfma_f32_16x16x32_bf16 v[16:19], v[152:155], v[198:201], v[16:19]
	v_mfma_f32_16x16x32_bf16 v[0:3], v[152:155], v[206:209], v[0:3]
	v_mfma_f32_16x16x32_bf16 v[4:7], v[144:147], v[206:209], v[4:7]
	v_mfma_f32_16x16x32_bf16 v[52:55], v[148:151], v[164:167], v[52:55]
	v_mfma_f32_16x16x32_bf16 v[48:51], v[156:159], v[164:167], v[48:51]
	v_mfma_f32_16x16x32_bf16 v[32:35], v[156:159], v[172:175], v[32:35]
	v_mfma_f32_16x16x32_bf16 v[36:39], v[148:151], v[172:175], v[36:39]
	v_mfma_f32_16x16x32_bf16 v[20:23], v[148:151], v[202:205], v[20:23]
	v_mfma_f32_16x16x32_bf16 v[16:19], v[156:159], v[202:205], v[16:19]
	v_mfma_f32_16x16x32_bf16 v[0:3], v[156:159], v[218:221], v[0:3]
	v_mfma_f32_16x16x32_bf16 v[4:7], v[148:151], v[218:221], v[4:7]
	s_barrier
	s_add_i32 s63, 0, 0x18000
	s_add_i32 s66, 0, 0x1c000
	v_add_u32_e32 v140, s63, v210
	v_add_u32_e32 v156, s66, v210
	ds_read_b128 v[128:131], v140
	ds_read_b128 v[132:135], v140 offset:1024
	ds_read_b128 v[136:139], v140 offset:2048
	ds_read_b128 v[140:143], v140 offset:3072
	ds_read_b128 v[144:147], v156
	ds_read_b128 v[148:151], v156 offset:1024
	ds_read_b128 v[152:155], v156 offset:2048
	ds_read_b128 v[156:159], v156 offset:3072
	s_add_u32 s64, s80, 0xb0000
	s_addc_u32 s65, s81, 0
	s_mov_b32 m0, s16
	ds_read_b128 v[160:163], v215 offset:32768
	ds_read_b128 v[164:167], v215 offset:33792
	ds_read_b128 v[168:171], v215 offset:34816
	ds_read_b128 v[172:175], v215 offset:35840
	ds_read_b128 v[198:201], v215 offset:36864
	ds_read_b128 v[202:205], v215 offset:37888
	ds_read_b128 v[206:209], v215 offset:38912
	ds_read_b128 v[218:221], v215 offset:39936
	global_load_lds_dwordx4 v176, s[64:65]
	s_mov_b32 m0, s17
	s_nop 0
	global_load_lds_dwordx4 v180, s[64:65]
	s_waitcnt vmcnt(8)
	s_waitcnt lgkmcnt(0)
	s_barrier
	s_waitcnt lgkmcnt(0)
	v_mfma_f32_16x16x32_bf16 v[124:127], v[128:131], v[160:163], v[124:127]
	v_mfma_f32_16x16x32_bf16 v[120:123], v[136:139], v[160:163], v[120:123]
	v_mfma_f32_16x16x32_bf16 v[104:107], v[136:139], v[168:171], v[104:107]
	v_mfma_f32_16x16x32_bf16 v[108:111], v[128:131], v[168:171], v[108:111]
	v_mfma_f32_16x16x32_bf16 v[92:95], v[128:131], v[198:201], v[92:95]
	v_mfma_f32_16x16x32_bf16 v[88:91], v[136:139], v[198:201], v[88:91]
	v_mfma_f32_16x16x32_bf16 v[72:75], v[136:139], v[206:209], v[72:75]
	v_mfma_f32_16x16x32_bf16 v[76:79], v[128:131], v[206:209], v[76:79]
	v_mfma_f32_16x16x32_bf16 v[124:127], v[132:135], v[164:167], v[124:127]
	v_mfma_f32_16x16x32_bf16 v[120:123], v[140:143], v[164:167], v[120:123]
	v_mfma_f32_16x16x32_bf16 v[104:107], v[140:143], v[172:175], v[104:107]
	v_mfma_f32_16x16x32_bf16 v[108:111], v[132:135], v[172:175], v[108:111]
	v_mfma_f32_16x16x32_bf16 v[92:95], v[132:135], v[202:205], v[92:95]
	v_mfma_f32_16x16x32_bf16 v[88:91], v[140:143], v[202:205], v[88:91]
	v_mfma_f32_16x16x32_bf16 v[72:75], v[140:143], v[218:221], v[72:75]
	v_mfma_f32_16x16x32_bf16 v[76:79], v[132:135], v[218:221], v[76:79]
	v_mfma_f32_16x16x32_bf16 v[116:119], v[144:147], v[160:163], v[116:119]
	v_mfma_f32_16x16x32_bf16 v[112:115], v[152:155], v[160:163], v[112:115]
	v_mfma_f32_16x16x32_bf16 v[96:99], v[152:155], v[168:171], v[96:99]
	v_mfma_f32_16x16x32_bf16 v[100:103], v[144:147], v[168:171], v[100:103]
	v_mfma_f32_16x16x32_bf16 v[84:87], v[144:147], v[198:201], v[84:87]
	v_mfma_f32_16x16x32_bf16 v[80:83], v[152:155], v[198:201], v[80:83]
	v_mfma_f32_16x16x32_bf16 v[64:67], v[152:155], v[206:209], v[64:67]
	v_mfma_f32_16x16x32_bf16 v[68:71], v[144:147], v[206:209], v[68:71]
	v_mfma_f32_16x16x32_bf16 v[116:119], v[148:151], v[164:167], v[116:119]
	v_mfma_f32_16x16x32_bf16 v[112:115], v[156:159], v[164:167], v[112:115]
	v_mfma_f32_16x16x32_bf16 v[96:99], v[156:159], v[172:175], v[96:99]
	v_mfma_f32_16x16x32_bf16 v[100:103], v[148:151], v[172:175], v[100:103]
	v_mfma_f32_16x16x32_bf16 v[84:87], v[148:151], v[202:205], v[84:87]
	v_mfma_f32_16x16x32_bf16 v[80:83], v[156:159], v[202:205], v[80:83]
	v_mfma_f32_16x16x32_bf16 v[64:67], v[156:159], v[218:221], v[64:67]
	v_mfma_f32_16x16x32_bf16 v[68:71], v[148:151], v[218:221], v[68:71]
	s_barrier
	s_add_i32 s63, s63, s13
	s_mov_b32 m0, s63
	ds_read_b128 v[160:163], v215 offset:49152
	ds_read_b128 v[164:167], v215 offset:50176
	ds_read_b128 v[168:171], v215 offset:51200
	ds_read_b128 v[172:175], v215 offset:52224
	ds_read_b128 v[198:201], v215 offset:53248
	ds_read_b128 v[202:205], v215 offset:54272
	ds_read_b128 v[206:209], v215 offset:55296
	ds_read_b128 v[218:221], v215 offset:56320
	global_load_lds_dwordx4 v178, s[98:99]
	s_add_i32 m0, s63, 0x2000
	s_add_u32 s42, s42, 0xb0080
	s_addc_u32 s43, s43, 0
	s_add_i32 s63, s66, s13
	global_load_lds_dwordx4 v182, s[98:99]
	s_mov_b32 m0, s63
	s_nop 0
	global_load_lds_dwordx4 v178, s[42:43]
	s_add_i32 m0, s63, 0x2000
	s_nop 0
	global_load_lds_dwordx4 v182, s[42:43]
	s_mov_b32 m0, s19
	s_nop 0
	global_load_lds_dwordx4 v176, s[100:101]
	s_mov_b32 m0, s20
	s_nop 0
	global_load_lds_dwordx4 v180, s[100:101]
	s_waitcnt vmcnt(8)
	s_waitcnt lgkmcnt(0)
	s_barrier
	s_waitcnt lgkmcnt(0)
	v_mfma_f32_16x16x32_bf16 v[60:63], v[128:131], v[160:163], v[60:63]
	v_mfma_f32_16x16x32_bf16 v[56:59], v[136:139], v[160:163], v[56:59]
	v_mfma_f32_16x16x32_bf16 v[40:43], v[136:139], v[168:171], v[40:43]
	v_mfma_f32_16x16x32_bf16 v[44:47], v[128:131], v[168:171], v[44:47]
	v_mfma_f32_16x16x32_bf16 v[28:31], v[128:131], v[198:201], v[28:31]
	v_mfma_f32_16x16x32_bf16 v[24:27], v[136:139], v[198:201], v[24:27]
	v_mfma_f32_16x16x32_bf16 v[8:11], v[136:139], v[206:209], v[8:11]
	v_mfma_f32_16x16x32_bf16 v[12:15], v[128:131], v[206:209], v[12:15]
	v_mfma_f32_16x16x32_bf16 v[60:63], v[132:135], v[164:167], v[60:63]
	v_mfma_f32_16x16x32_bf16 v[56:59], v[140:143], v[164:167], v[56:59]
	v_mfma_f32_16x16x32_bf16 v[40:43], v[140:143], v[172:175], v[40:43]
	v_mfma_f32_16x16x32_bf16 v[44:47], v[132:135], v[172:175], v[44:47]
	v_mfma_f32_16x16x32_bf16 v[28:31], v[132:135], v[202:205], v[28:31]
	v_mfma_f32_16x16x32_bf16 v[24:27], v[140:143], v[202:205], v[24:27]
	v_mfma_f32_16x16x32_bf16 v[8:11], v[140:143], v[218:221], v[8:11]
	v_mfma_f32_16x16x32_bf16 v[12:15], v[132:135], v[218:221], v[12:15]
	v_mfma_f32_16x16x32_bf16 v[52:55], v[144:147], v[160:163], v[52:55]
	v_mfma_f32_16x16x32_bf16 v[48:51], v[152:155], v[160:163], v[48:51]
	v_mfma_f32_16x16x32_bf16 v[32:35], v[152:155], v[168:171], v[32:35]
	v_mfma_f32_16x16x32_bf16 v[36:39], v[144:147], v[168:171], v[36:39]
	v_mfma_f32_16x16x32_bf16 v[20:23], v[144:147], v[198:201], v[20:23]
	v_mfma_f32_16x16x32_bf16 v[16:19], v[152:155], v[198:201], v[16:19]
	v_mfma_f32_16x16x32_bf16 v[0:3], v[152:155], v[206:209], v[0:3]
	v_mfma_f32_16x16x32_bf16 v[4:7], v[144:147], v[206:209], v[4:7]
	v_mfma_f32_16x16x32_bf16 v[52:55], v[148:151], v[164:167], v[52:55]
	v_mfma_f32_16x16x32_bf16 v[48:51], v[156:159], v[164:167], v[48:51]
	v_mfma_f32_16x16x32_bf16 v[32:35], v[156:159], v[172:175], v[32:35]
	v_mfma_f32_16x16x32_bf16 v[36:39], v[148:151], v[172:175], v[36:39]
	v_mfma_f32_16x16x32_bf16 v[20:23], v[148:151], v[202:205], v[20:23]
	v_mfma_f32_16x16x32_bf16 v[16:19], v[156:159], v[202:205], v[16:19]
	v_mfma_f32_16x16x32_bf16 v[0:3], v[156:159], v[218:221], v[0:3]
	v_mfma_f32_16x16x32_bf16 v[4:7], v[148:151], v[218:221], v[4:7]
	s_barrier
	s_add_i32 s62, s62, 2
	s_add_u32 s40, s40, 0x100
	s_addc_u32 s41, s41, 0
	s_add_u32 s39, s39, 0x100
	s_addc_u32 s61, s61, 0
	s_cmp_gt_u32 s62, 41
	s_cbranch_scc0 .LBB0_445

.LBB0_545:
	s_ashr_i32 s35, s34, 31
	s_lshl_b64 s[8:9], s[34:35], 19
	s_add_u32 s38, s82, s8
	s_addc_u32 s39, s83, s9
	s_and_b64 s[8:9], s[4:5], exec
	s_cselect_b32 s8, s39, s7
	s_cselect_b32 s9, s38, s6
	s_ashr_i32 s37, s36, 31
	s_lshl_b64 s[14:15], s[36:37], 19
	s_add_u32 s86, s60, s14
	s_addc_u32 s87, s61, s15
	s_and_b64 s[14:15], s[4:5], exec
	s_cselect_b32 s14, s87, s43
	s_cselect_b32 s15, s86, s42
	s_add_u32 s6, s6, 0x40080
	s_addc_u32 s7, s7, 0
	s_add_u32 s16, s42, 0x100
	s_addc_u32 s17, s43, 0
	s_mov_b32 s18, -2
	ds_read_b128 v[144:147], v155
	ds_read_b128 v[148:151], v155 offset:1024
	ds_read_b128 v[160:163], v155 offset:2048
	ds_read_b128 v[164:167], v155 offset:3072
	ds_read_b128 v[168:171], v156
	ds_read_b128 v[172:175], v156 offset:1024
	ds_read_b128 v[176:179], v156 offset:2048
	ds_read_b128 v[180:183], v156 offset:3072
	s_add_u32 s19, s6, 0xfffc0080
	s_addc_u32 s20, s7, -1
	s_cmp_eq_u32 s18, 12
	s_cselect_b32 s89, s8, s20
	s_cselect_b32 s88, s9, s19
	s_cselect_b32 s43, s14, s17
	s_cselect_b32 s42, s15, s16
	s_add_i32 m0, s63, 0xc000
	ds_read_b128 v[186:189], v157
	ds_read_b128 v[190:193], v157 offset:1024
	ds_read_b128 v[194:197], v157 offset:2048
	ds_read_b128 v[198:201], v157 offset:3072
	ds_read_b128 v[202:205], v157 offset:4096
	ds_read_b128 v[206:209], v157 offset:5120
	ds_read_b128 v[210:213], v157 offset:6144
	ds_read_b128 v[214:217], v157 offset:7168
	global_load_lds_dwordx4 v136, s[6:7]
	s_add_i32 m0, s63, 0xe000
	s_nop 0
	global_load_lds_dwordx4 v138, s[6:7]
	s_waitcnt vmcnt(8)
	s_waitcnt lgkmcnt(0)
	s_barrier
	s_waitcnt lgkmcnt(0)
	v_mfma_f32_16x16x32_bf16 v[124:127], v[144:147], v[186:189], 0
	v_mfma_f32_16x16x32_bf16 v[120:123], v[160:163], v[186:189], 0
	v_mfma_f32_16x16x32_bf16 v[104:107], v[160:163], v[194:197], 0
	v_mfma_f32_16x16x32_bf16 v[108:111], v[144:147], v[194:197], 0
	v_mfma_f32_16x16x32_bf16 v[92:95], v[144:147], v[202:205], 0
	v_mfma_f32_16x16x32_bf16 v[88:91], v[160:163], v[202:205], 0
	v_mfma_f32_16x16x32_bf16 v[72:75], v[160:163], v[210:213], 0
	v_mfma_f32_16x16x32_bf16 v[76:79], v[144:147], v[210:213], 0
	v_mfma_f32_16x16x32_bf16 v[124:127], v[148:151], v[190:193], v[124:127]
	v_mfma_f32_16x16x32_bf16 v[120:123], v[164:167], v[190:193], v[120:123]
	v_mfma_f32_16x16x32_bf16 v[104:107], v[164:167], v[198:201], v[104:107]
	v_mfma_f32_16x16x32_bf16 v[108:111], v[148:151], v[198:201], v[108:111]
	v_mfma_f32_16x16x32_bf16 v[92:95], v[148:151], v[206:209], v[92:95]
	v_mfma_f32_16x16x32_bf16 v[88:91], v[164:167], v[206:209], v[88:91]
	v_mfma_f32_16x16x32_bf16 v[72:75], v[164:167], v[214:217], v[72:75]
	v_mfma_f32_16x16x32_bf16 v[76:79], v[148:151], v[214:217], v[76:79]
	v_mfma_f32_16x16x32_bf16 v[116:119], v[168:171], v[186:189], 0
	v_mfma_f32_16x16x32_bf16 v[112:115], v[176:179], v[186:189], 0
	v_mfma_f32_16x16x32_bf16 v[96:99], v[176:179], v[194:197], 0
	v_mfma_f32_16x16x32_bf16 v[100:103], v[168:171], v[194:197], 0
	v_mfma_f32_16x16x32_bf16 v[84:87], v[168:171], v[202:205], 0
	v_mfma_f32_16x16x32_bf16 v[80:83], v[176:179], v[202:205], 0
	v_mfma_f32_16x16x32_bf16 v[64:67], v[176:179], v[210:213], 0
	v_mfma_f32_16x16x32_bf16 v[68:71], v[168:171], v[210:213], 0
	v_mfma_f32_16x16x32_bf16 v[116:119], v[172:175], v[190:193], v[116:119]
	v_mfma_f32_16x16x32_bf16 v[112:115], v[180:183], v[190:193], v[112:115]
	v_mfma_f32_16x16x32_bf16 v[96:99], v[180:183], v[198:201], v[96:99]
	v_mfma_f32_16x16x32_bf16 v[100:103], v[172:175], v[198:201], v[100:103]
	v_mfma_f32_16x16x32_bf16 v[84:87], v[172:175], v[206:209], v[84:87]
	v_mfma_f32_16x16x32_bf16 v[80:83], v[180:183], v[206:209], v[80:83]
	v_mfma_f32_16x16x32_bf16 v[64:67], v[180:183], v[214:217], v[64:67]
	v_mfma_f32_16x16x32_bf16 v[68:71], v[172:175], v[214:217], v[68:71]
	s_barrier
	s_add_i32 s19, s72, s62
	s_mov_b32 m0, s19
	ds_read_b128 v[186:189], v157 offset:16384
	ds_read_b128 v[190:193], v157 offset:17408
	ds_read_b128 v[194:197], v157 offset:18432
	ds_read_b128 v[198:201], v157 offset:19456
	ds_read_b128 v[202:205], v157 offset:20480
	ds_read_b128 v[206:209], v157 offset:21504
	ds_read_b128 v[210:213], v157 offset:22528
	ds_read_b128 v[214:217], v157 offset:23552
	global_load_lds_dwordx4 v130, s[42:43]
	s_add_i32 m0, s19, 0x2000
	s_add_u32 s20, s42, 0x40000
	s_addc_u32 s21, s43, 0
	s_add_i32 s19, s73, s62
	global_load_lds_dwordx4 v134, s[42:43]
	s_mov_b32 m0, s19
	global_load_lds_dwordx4 v130, s[20:21]
	s_add_i32 m0, s19, 0x2000
	s_nop 0
	global_load_lds_dwordx4 v134, s[20:21]
	s_mov_b32 m0, s63
	s_nop 0
	global_load_lds_dwordx4 v128, s[88:89]
	s_mov_b32 m0, s64
	s_nop 0
	global_load_lds_dwordx4 v132, s[88:89]
	s_add_u32 s98, s42, s28
	s_addc_u32 s99, s43, s29
	s_add_u32 s100, s88, s28
	s_addc_u32 s101, s89, s29
	s_waitcnt vmcnt(8)
	s_waitcnt lgkmcnt(0)
	s_barrier
	s_waitcnt lgkmcnt(0)
	v_mfma_f32_16x16x32_bf16 v[60:63], v[144:147], v[186:189], 0
	v_mfma_f32_16x16x32_bf16 v[56:59], v[160:163], v[186:189], 0
	v_mfma_f32_16x16x32_bf16 v[40:43], v[160:163], v[194:197], 0
	v_mfma_f32_16x16x32_bf16 v[44:47], v[144:147], v[194:197], 0
	v_mfma_f32_16x16x32_bf16 v[28:31], v[144:147], v[202:205], 0
	v_mfma_f32_16x16x32_bf16 v[24:27], v[160:163], v[202:205], 0
	v_mfma_f32_16x16x32_bf16 v[8:11], v[160:163], v[210:213], 0
	v_mfma_f32_16x16x32_bf16 v[12:15], v[144:147], v[210:213], 0
	v_mfma_f32_16x16x32_bf16 v[60:63], v[148:151], v[190:193], v[60:63]
	v_mfma_f32_16x16x32_bf16 v[56:59], v[164:167], v[190:193], v[56:59]
	v_mfma_f32_16x16x32_bf16 v[40:43], v[164:167], v[198:201], v[40:43]
	v_mfma_f32_16x16x32_bf16 v[44:47], v[148:151], v[198:201], v[44:47]
	v_mfma_f32_16x16x32_bf16 v[28:31], v[148:151], v[206:209], v[28:31]
	v_mfma_f32_16x16x32_bf16 v[24:27], v[164:167], v[206:209], v[24:27]
	v_mfma_f32_16x16x32_bf16 v[8:11], v[164:167], v[214:217], v[8:11]
	v_mfma_f32_16x16x32_bf16 v[12:15], v[148:151], v[214:217], v[12:15]
	v_mfma_f32_16x16x32_bf16 v[52:55], v[168:171], v[186:189], 0
	v_mfma_f32_16x16x32_bf16 v[48:51], v[176:179], v[186:189], 0
	v_mfma_f32_16x16x32_bf16 v[32:35], v[176:179], v[194:197], 0
	v_mfma_f32_16x16x32_bf16 v[36:39], v[168:171], v[194:197], 0
	v_mfma_f32_16x16x32_bf16 v[20:23], v[168:171], v[202:205], 0
	v_mfma_f32_16x16x32_bf16 v[16:19], v[176:179], v[202:205], 0
	v_mfma_f32_16x16x32_bf16 v[0:3], v[176:179], v[210:213], 0
	v_mfma_f32_16x16x32_bf16 v[4:7], v[168:171], v[210:213], 0
	v_mfma_f32_16x16x32_bf16 v[52:55], v[172:175], v[190:193], v[52:55]
	v_mfma_f32_16x16x32_bf16 v[48:51], v[180:183], v[190:193], v[48:51]
	v_mfma_f32_16x16x32_bf16 v[32:35], v[180:183], v[198:201], v[32:35]
	v_mfma_f32_16x16x32_bf16 v[36:39], v[172:175], v[198:201], v[36:39]
	v_mfma_f32_16x16x32_bf16 v[20:23], v[172:175], v[206:209], v[20:23]
	v_mfma_f32_16x16x32_bf16 v[16:19], v[180:183], v[206:209], v[16:19]
	v_mfma_f32_16x16x32_bf16 v[0:3], v[180:183], v[214:217], v[0:3]
	v_mfma_f32_16x16x32_bf16 v[4:7], v[172:175], v[214:217], v[4:7]
	s_barrier
	s_add_i32 s19, 0, 0x18000
	v_add_u32_e32 v159, s19, v153
	s_add_i32 s22, 0, 0x1c000
	ds_read_b128 v[144:147], v159
	ds_read_b128 v[148:151], v159 offset:1024
	ds_read_b128 v[160:163], v159 offset:2048
	ds_read_b128 v[164:167], v159 offset:3072
	v_add_u32_e32 v159, s22, v153
	ds_read_b128 v[168:171], v159
	ds_read_b128 v[172:175], v159 offset:1024
	ds_read_b128 v[176:179], v159 offset:2048
	ds_read_b128 v[180:183], v159 offset:3072
	s_add_u32 s20, s88, 0x40000
	s_addc_u32 s21, s89, 0
	s_mov_b32 m0, s65
	ds_read_b128 v[186:189], v157 offset:32768
	ds_read_b128 v[190:193], v157 offset:33792
	ds_read_b128 v[194:197], v157 offset:34816
	ds_read_b128 v[198:201], v157 offset:35840
	ds_read_b128 v[202:205], v157 offset:36864
	ds_read_b128 v[206:209], v157 offset:37888
	ds_read_b128 v[210:213], v157 offset:38912
	ds_read_b128 v[214:217], v157 offset:39936
	global_load_lds_dwordx4 v128, s[20:21]
	s_mov_b32 m0, s66
	s_nop 0
	global_load_lds_dwordx4 v132, s[20:21]
	s_waitcnt vmcnt(8)
	s_waitcnt lgkmcnt(0)
	s_barrier
	s_waitcnt lgkmcnt(0)
	v_mfma_f32_16x16x32_bf16 v[124:127], v[144:147], v[186:189], v[124:127]
	v_mfma_f32_16x16x32_bf16 v[120:123], v[160:163], v[186:189], v[120:123]
	v_mfma_f32_16x16x32_bf16 v[104:107], v[160:163], v[194:197], v[104:107]
	v_mfma_f32_16x16x32_bf16 v[108:111], v[144:147], v[194:197], v[108:111]
	v_mfma_f32_16x16x32_bf16 v[92:95], v[144:147], v[202:205], v[92:95]
	v_mfma_f32_16x16x32_bf16 v[88:91], v[160:163], v[202:205], v[88:91]
	v_mfma_f32_16x16x32_bf16 v[72:75], v[160:163], v[210:213], v[72:75]
	v_mfma_f32_16x16x32_bf16 v[76:79], v[144:147], v[210:213], v[76:79]
	v_mfma_f32_16x16x32_bf16 v[124:127], v[148:151], v[190:193], v[124:127]
	v_mfma_f32_16x16x32_bf16 v[120:123], v[164:167], v[190:193], v[120:123]
	v_mfma_f32_16x16x32_bf16 v[104:107], v[164:167], v[198:201], v[104:107]
	v_mfma_f32_16x16x32_bf16 v[108:111], v[148:151], v[198:201], v[108:111]
	v_mfma_f32_16x16x32_bf16 v[92:95], v[148:151], v[206:209], v[92:95]
	v_mfma_f32_16x16x32_bf16 v[88:91], v[164:167], v[206:209], v[88:91]
	v_mfma_f32_16x16x32_bf16 v[72:75], v[164:167], v[214:217], v[72:75]
	v_mfma_f32_16x16x32_bf16 v[76:79], v[148:151], v[214:217], v[76:79]
	v_mfma_f32_16x16x32_bf16 v[116:119], v[168:171], v[186:189], v[116:119]
	v_mfma_f32_16x16x32_bf16 v[112:115], v[176:179], v[186:189], v[112:115]
	v_mfma_f32_16x16x32_bf16 v[96:99], v[176:179], v[194:197], v[96:99]
	v_mfma_f32_16x16x32_bf16 v[100:103], v[168:171], v[194:197], v[100:103]
	v_mfma_f32_16x16x32_bf16 v[84:87], v[168:171], v[202:205], v[84:87]
	v_mfma_f32_16x16x32_bf16 v[80:83], v[176:179], v[202:205], v[80:83]
	v_mfma_f32_16x16x32_bf16 v[64:67], v[176:179], v[210:213], v[64:67]
	v_mfma_f32_16x16x32_bf16 v[68:71], v[168:171], v[210:213], v[68:71]
	v_mfma_f32_16x16x32_bf16 v[116:119], v[172:175], v[190:193], v[116:119]
	v_mfma_f32_16x16x32_bf16 v[112:115], v[180:183], v[190:193], v[112:115]
	v_mfma_f32_16x16x32_bf16 v[96:99], v[180:183], v[198:201], v[96:99]
	v_mfma_f32_16x16x32_bf16 v[100:103], v[172:175], v[198:201], v[100:103]
	v_mfma_f32_16x16x32_bf16 v[84:87], v[172:175], v[206:209], v[84:87]
	v_mfma_f32_16x16x32_bf16 v[80:83], v[180:183], v[206:209], v[80:83]
	v_mfma_f32_16x16x32_bf16 v[64:67], v[180:183], v[214:217], v[64:67]
	v_mfma_f32_16x16x32_bf16 v[68:71], v[172:175], v[214:217], v[68:71]
	s_barrier
	s_add_i32 s19, s19, s62
	s_mov_b32 m0, s19
	ds_read_b128 v[186:189], v157 offset:49152
	ds_read_b128 v[190:193], v157 offset:50176
	ds_read_b128 v[194:197], v157 offset:51200
	ds_read_b128 v[198:201], v157 offset:52224
	ds_read_b128 v[202:205], v157 offset:53248
	ds_read_b128 v[206:209], v157 offset:54272
	ds_read_b128 v[210:213], v157 offset:55296
	ds_read_b128 v[214:217], v157 offset:56320
	global_load_lds_dwordx4 v130, s[98:99]
	s_add_i32 m0, s19, 0x2000
	s_add_u32 s20, s42, 0x40080
	s_addc_u32 s21, s43, 0
	s_add_i32 s19, s22, s62
	global_load_lds_dwordx4 v134, s[98:99]
	s_mov_b32 m0, s19
	s_nop 0
	global_load_lds_dwordx4 v130, s[20:21]
	s_add_i32 m0, s19, 0x2000
	s_nop 0
	global_load_lds_dwordx4 v134, s[20:21]
	s_mov_b32 m0, s70
	s_nop 0
	global_load_lds_dwordx4 v128, s[100:101]
	s_mov_b32 m0, s71
	s_nop 0
	global_load_lds_dwordx4 v132, s[100:101]
	s_waitcnt vmcnt(8)
	s_waitcnt lgkmcnt(0)
	s_barrier
	s_waitcnt lgkmcnt(0)
	v_mfma_f32_16x16x32_bf16 v[60:63], v[144:147], v[186:189], v[60:63]
	v_mfma_f32_16x16x32_bf16 v[56:59], v[160:163], v[186:189], v[56:59]
	v_mfma_f32_16x16x32_bf16 v[40:43], v[160:163], v[194:197], v[40:43]
	v_mfma_f32_16x16x32_bf16 v[44:47], v[144:147], v[194:197], v[44:47]
	v_mfma_f32_16x16x32_bf16 v[28:31], v[144:147], v[202:205], v[28:31]
	v_mfma_f32_16x16x32_bf16 v[24:27], v[160:163], v[202:205], v[24:27]
	v_mfma_f32_16x16x32_bf16 v[8:11], v[160:163], v[210:213], v[8:11]
	v_mfma_f32_16x16x32_bf16 v[12:15], v[144:147], v[210:213], v[12:15]
	v_mfma_f32_16x16x32_bf16 v[60:63], v[148:151], v[190:193], v[60:63]
	v_mfma_f32_16x16x32_bf16 v[56:59], v[164:167], v[190:193], v[56:59]
	v_mfma_f32_16x16x32_bf16 v[40:43], v[164:167], v[198:201], v[40:43]
	v_mfma_f32_16x16x32_bf16 v[44:47], v[148:151], v[198:201], v[44:47]
	v_mfma_f32_16x16x32_bf16 v[28:31], v[148:151], v[206:209], v[28:31]
	v_mfma_f32_16x16x32_bf16 v[24:27], v[164:167], v[206:209], v[24:27]
	v_mfma_f32_16x16x32_bf16 v[8:11], v[164:167], v[214:217], v[8:11]
	v_mfma_f32_16x16x32_bf16 v[12:15], v[148:151], v[214:217], v[12:15]
	v_mfma_f32_16x16x32_bf16 v[52:55], v[168:171], v[186:189], v[52:55]
	v_mfma_f32_16x16x32_bf16 v[48:51], v[176:179], v[186:189], v[48:51]
	v_mfma_f32_16x16x32_bf16 v[32:35], v[176:179], v[194:197], v[32:35]
	v_mfma_f32_16x16x32_bf16 v[36:39], v[168:171], v[194:197], v[36:39]
	v_mfma_f32_16x16x32_bf16 v[20:23], v[168:171], v[202:205], v[20:23]
	v_mfma_f32_16x16x32_bf16 v[16:19], v[176:179], v[202:205], v[16:19]
	v_mfma_f32_16x16x32_bf16 v[0:3], v[176:179], v[210:213], v[0:3]
	v_mfma_f32_16x16x32_bf16 v[4:7], v[168:171], v[210:213], v[4:7]
	v_mfma_f32_16x16x32_bf16 v[52:55], v[172:175], v[190:193], v[52:55]
	v_mfma_f32_16x16x32_bf16 v[48:51], v[180:183], v[190:193], v[48:51]
	v_mfma_f32_16x16x32_bf16 v[32:35], v[180:183], v[198:201], v[32:35]
	v_mfma_f32_16x16x32_bf16 v[36:39], v[172:175], v[198:201], v[36:39]
	v_mfma_f32_16x16x32_bf16 v[20:23], v[172:175], v[206:209], v[20:23]
	v_mfma_f32_16x16x32_bf16 v[16:19], v[180:183], v[206:209], v[16:19]
	v_mfma_f32_16x16x32_bf16 v[0:3], v[180:183], v[214:217], v[0:3]
	v_mfma_f32_16x16x32_bf16 v[4:7], v[172:175], v[214:217], v[4:7]
	s_barrier
	s_add_i32 s18, s18, 2
	s_add_u32 s6, s6, 0x100
	s_addc_u32 s7, s7, 0
	s_add_u32 s16, s16, 0x100
	s_addc_u32 s17, s17, 0
	s_cmp_gt_u32 s18, 13
	s_cbranch_scc1 .Lpeel_exit_546
.LBB0_546:
	ds_read_b128 v[144:147], v155
	ds_read_b128 v[148:151], v155 offset:1024
	ds_read_b128 v[160:163], v155 offset:2048
	ds_read_b128 v[164:167], v155 offset:3072
	ds_read_b128 v[168:171], v156
	ds_read_b128 v[172:175], v156 offset:1024
	ds_read_b128 v[176:179], v156 offset:2048
	ds_read_b128 v[180:183], v156 offset:3072
	s_add_u32 s19, s6, 0xfffc0080
	s_addc_u32 s20, s7, -1
	s_cmp_eq_u32 s18, 12
	s_cselect_b32 s89, s8, s20
	s_cselect_b32 s88, s9, s19
	s_cselect_b32 s43, s14, s17
	s_cselect_b32 s42, s15, s16
	s_add_i32 m0, s63, 0xc000
	ds_read_b128 v[186:189], v157
	ds_read_b128 v[190:193], v157 offset:1024
	ds_read_b128 v[194:197], v157 offset:2048
	ds_read_b128 v[198:201], v157 offset:3072
	ds_read_b128 v[202:205], v157 offset:4096
	ds_read_b128 v[206:209], v157 offset:5120
	ds_read_b128 v[210:213], v157 offset:6144
	ds_read_b128 v[214:217], v157 offset:7168
	global_load_lds_dwordx4 v136, s[6:7]
	s_add_i32 m0, s63, 0xe000
	s_nop 0
	global_load_lds_dwordx4 v138, s[6:7]
	s_waitcnt vmcnt(8)
	s_waitcnt lgkmcnt(0)
	s_barrier
	s_waitcnt lgkmcnt(0)
	v_mfma_f32_16x16x32_bf16 v[124:127], v[144:147], v[186:189], v[124:127]
	v_mfma_f32_16x16x32_bf16 v[120:123], v[160:163], v[186:189], v[120:123]
	v_mfma_f32_16x16x32_bf16 v[104:107], v[160:163], v[194:197], v[104:107]
	v_mfma_f32_16x16x32_bf16 v[108:111], v[144:147], v[194:197], v[108:111]
	v_mfma_f32_16x16x32_bf16 v[92:95], v[144:147], v[202:205], v[92:95]
	v_mfma_f32_16x16x32_bf16 v[88:91], v[160:163], v[202:205], v[88:91]
	v_mfma_f32_16x16x32_bf16 v[72:75], v[160:163], v[210:213], v[72:75]
	v_mfma_f32_16x16x32_bf16 v[76:79], v[144:147], v[210:213], v[76:79]
	v_mfma_f32_16x16x32_bf16 v[124:127], v[148:151], v[190:193], v[124:127]
	v_mfma_f32_16x16x32_bf16 v[120:123], v[164:167], v[190:193], v[120:123]
	v_mfma_f32_16x16x32_bf16 v[104:107], v[164:167], v[198:201], v[104:107]
	v_mfma_f32_16x16x32_bf16 v[108:111], v[148:151], v[198:201], v[108:111]
	v_mfma_f32_16x16x32_bf16 v[92:95], v[148:151], v[206:209], v[92:95]
	v_mfma_f32_16x16x32_bf16 v[88:91], v[164:167], v[206:209], v[88:91]
	v_mfma_f32_16x16x32_bf16 v[72:75], v[164:167], v[214:217], v[72:75]
	v_mfma_f32_16x16x32_bf16 v[76:79], v[148:151], v[214:217], v[76:79]
	v_mfma_f32_16x16x32_bf16 v[116:119], v[168:171], v[186:189], v[116:119]
	v_mfma_f32_16x16x32_bf16 v[112:115], v[176:179], v[186:189], v[112:115]
	v_mfma_f32_16x16x32_bf16 v[96:99], v[176:179], v[194:197], v[96:99]
	v_mfma_f32_16x16x32_bf16 v[100:103], v[168:171], v[194:197], v[100:103]
	v_mfma_f32_16x16x32_bf16 v[84:87], v[168:171], v[202:205], v[84:87]
	v_mfma_f32_16x16x32_bf16 v[80:83], v[176:179], v[202:205], v[80:83]
	v_mfma_f32_16x16x32_bf16 v[64:67], v[176:179], v[210:213], v[64:67]
	v_mfma_f32_16x16x32_bf16 v[68:71], v[168:171], v[210:213], v[68:71]
	v_mfma_f32_16x16x32_bf16 v[116:119], v[172:175], v[190:193], v[116:119]
	v_mfma_f32_16x16x32_bf16 v[112:115], v[180:183], v[190:193], v[112:115]
	v_mfma_f32_16x16x32_bf16 v[96:99], v[180:183], v[198:201], v[96:99]
	v_mfma_f32_16x16x32_bf16 v[100:103], v[172:175], v[198:201], v[100:103]
	v_mfma_f32_16x16x32_bf16 v[84:87], v[172:175], v[206:209], v[84:87]
	v_mfma_f32_16x16x32_bf16 v[80:83], v[180:183], v[206:209], v[80:83]
	v_mfma_f32_16x16x32_bf16 v[64:67], v[180:183], v[214:217], v[64:67]
	v_mfma_f32_16x16x32_bf16 v[68:71], v[172:175], v[214:217], v[68:71]
	s_barrier
	s_add_i32 s19, s72, s62
	s_mov_b32 m0, s19
	ds_read_b128 v[186:189], v157 offset:16384
	ds_read_b128 v[190:193], v157 offset:17408
	ds_read_b128 v[194:197], v157 offset:18432
	ds_read_b128 v[198:201], v157 offset:19456
	ds_read_b128 v[202:205], v157 offset:20480
	ds_read_b128 v[206:209], v157 offset:21504
	ds_read_b128 v[210:213], v157 offset:22528
	ds_read_b128 v[214:217], v157 offset:23552
	global_load_lds_dwordx4 v130, s[42:43]
	s_add_i32 m0, s19, 0x2000
	s_add_u32 s20, s42, 0x40000
	s_addc_u32 s21, s43, 0
	s_add_i32 s19, s73, s62
	global_load_lds_dwordx4 v134, s[42:43]
	s_mov_b32 m0, s19
	global_load_lds_dwordx4 v130, s[20:21]
	s_add_i32 m0, s19, 0x2000
	s_nop 0
	global_load_lds_dwordx4 v134, s[20:21]
	s_mov_b32 m0, s63
	s_nop 0
	global_load_lds_dwordx4 v128, s[88:89]
	s_mov_b32 m0, s64
	s_nop 0
	global_load_lds_dwordx4 v132, s[88:89]
	s_add_u32 s98, s42, s28
	s_addc_u32 s99, s43, s29
	s_add_u32 s100, s88, s28
	s_addc_u32 s101, s89, s29
	s_waitcnt vmcnt(8)
	s_waitcnt lgkmcnt(0)
	s_barrier
	s_waitcnt lgkmcnt(0)
	v_mfma_f32_16x16x32_bf16 v[60:63], v[144:147], v[186:189], v[60:63]
	v_mfma_f32_16x16x32_bf16 v[56:59], v[160:163], v[186:189], v[56:59]
	v_mfma_f32_16x16x32_bf16 v[40:43], v[160:163], v[194:197], v[40:43]
	v_mfma_f32_16x16x32_bf16 v[44:47], v[144:147], v[194:197], v[44:47]
	v_mfma_f32_16x16x32_bf16 v[28:31], v[144:147], v[202:205], v[28:31]
	v_mfma_f32_16x16x32_bf16 v[24:27], v[160:163], v[202:205], v[24:27]
	v_mfma_f32_16x16x32_bf16 v[8:11], v[160:163], v[210:213], v[8:11]
	v_mfma_f32_16x16x32_bf16 v[12:15], v[144:147], v[210:213], v[12:15]
	v_mfma_f32_16x16x32_bf16 v[60:63], v[148:151], v[190:193], v[60:63]
	v_mfma_f32_16x16x32_bf16 v[56:59], v[164:167], v[190:193], v[56:59]
	v_mfma_f32_16x16x32_bf16 v[40:43], v[164:167], v[198:201], v[40:43]
	v_mfma_f32_16x16x32_bf16 v[44:47], v[148:151], v[198:201], v[44:47]
	v_mfma_f32_16x16x32_bf16 v[28:31], v[148:151], v[206:209], v[28:31]
	v_mfma_f32_16x16x32_bf16 v[24:27], v[164:167], v[206:209], v[24:27]
	v_mfma_f32_16x16x32_bf16 v[8:11], v[164:167], v[214:217], v[8:11]
	v_mfma_f32_16x16x32_bf16 v[12:15], v[148:151], v[214:217], v[12:15]
	v_mfma_f32_16x16x32_bf16 v[52:55], v[168:171], v[186:189], v[52:55]
	v_mfma_f32_16x16x32_bf16 v[48:51], v[176:179], v[186:189], v[48:51]
	v_mfma_f32_16x16x32_bf16 v[32:35], v[176:179], v[194:197], v[32:35]
	v_mfma_f32_16x16x32_bf16 v[36:39], v[168:171], v[194:197], v[36:39]
	v_mfma_f32_16x16x32_bf16 v[20:23], v[168:171], v[202:205], v[20:23]
	v_mfma_f32_16x16x32_bf16 v[16:19], v[176:179], v[202:205], v[16:19]
	v_mfma_f32_16x16x32_bf16 v[0:3], v[176:179], v[210:213], v[0:3]
	v_mfma_f32_16x16x32_bf16 v[4:7], v[168:171], v[210:213], v[4:7]
	v_mfma_f32_16x16x32_bf16 v[52:55], v[172:175], v[190:193], v[52:55]
	v_mfma_f32_16x16x32_bf16 v[48:51], v[180:183], v[190:193], v[48:51]
	v_mfma_f32_16x16x32_bf16 v[32:35], v[180:183], v[198:201], v[32:35]
	v_mfma_f32_16x16x32_bf16 v[36:39], v[172:175], v[198:201], v[36:39]
	v_mfma_f32_16x16x32_bf16 v[20:23], v[172:175], v[206:209], v[20:23]
	v_mfma_f32_16x16x32_bf16 v[16:19], v[180:183], v[206:209], v[16:19]
	v_mfma_f32_16x16x32_bf16 v[0:3], v[180:183], v[214:217], v[0:3]
	v_mfma_f32_16x16x32_bf16 v[4:7], v[172:175], v[214:217], v[4:7]
	s_barrier
	s_add_i32 s19, 0, 0x18000
	v_add_u32_e32 v159, s19, v153
	s_add_i32 s22, 0, 0x1c000
	ds_read_b128 v[144:147], v159
	ds_read_b128 v[148:151], v159 offset:1024
	ds_read_b128 v[160:163], v159 offset:2048
	ds_read_b128 v[164:167], v159 offset:3072
	v_add_u32_e32 v159, s22, v153
	ds_read_b128 v[168:171], v159
	ds_read_b128 v[172:175], v159 offset:1024
	ds_read_b128 v[176:179], v159 offset:2048
	ds_read_b128 v[180:183], v159 offset:3072
	s_add_u32 s20, s88, 0x40000
	s_addc_u32 s21, s89, 0
	s_mov_b32 m0, s65
	ds_read_b128 v[186:189], v157 offset:32768
	ds_read_b128 v[190:193], v157 offset:33792
	ds_read_b128 v[194:197], v157 offset:34816
	ds_read_b128 v[198:201], v157 offset:35840
	ds_read_b128 v[202:205], v157 offset:36864
	ds_read_b128 v[206:209], v157 offset:37888
	ds_read_b128 v[210:213], v157 offset:38912
	ds_read_b128 v[214:217], v157 offset:39936
	global_load_lds_dwordx4 v128, s[20:21]
	s_mov_b32 m0, s66
	s_nop 0
	global_load_lds_dwordx4 v132, s[20:21]
	s_waitcnt vmcnt(8)
	s_waitcnt lgkmcnt(0)
	s_barrier
	s_waitcnt lgkmcnt(0)
	v_mfma_f32_16x16x32_bf16 v[124:127], v[144:147], v[186:189], v[124:127]
	v_mfma_f32_16x16x32_bf16 v[120:123], v[160:163], v[186:189], v[120:123]
	v_mfma_f32_16x16x32_bf16 v[104:107], v[160:163], v[194:197], v[104:107]
	v_mfma_f32_16x16x32_bf16 v[108:111], v[144:147], v[194:197], v[108:111]
	v_mfma_f32_16x16x32_bf16 v[92:95], v[144:147], v[202:205], v[92:95]
	v_mfma_f32_16x16x32_bf16 v[88:91], v[160:163], v[202:205], v[88:91]
	v_mfma_f32_16x16x32_bf16 v[72:75], v[160:163], v[210:213], v[72:75]
	v_mfma_f32_16x16x32_bf16 v[76:79], v[144:147], v[210:213], v[76:79]
	v_mfma_f32_16x16x32_bf16 v[124:127], v[148:151], v[190:193], v[124:127]
	v_mfma_f32_16x16x32_bf16 v[120:123], v[164:167], v[190:193], v[120:123]
	v_mfma_f32_16x16x32_bf16 v[104:107], v[164:167], v[198:201], v[104:107]
	v_mfma_f32_16x16x32_bf16 v[108:111], v[148:151], v[198:201], v[108:111]
	v_mfma_f32_16x16x32_bf16 v[92:95], v[148:151], v[206:209], v[92:95]
	v_mfma_f32_16x16x32_bf16 v[88:91], v[164:167], v[206:209], v[88:91]
	v_mfma_f32_16x16x32_bf16 v[72:75], v[164:167], v[214:217], v[72:75]
	v_mfma_f32_16x16x32_bf16 v[76:79], v[148:151], v[214:217], v[76:79]
	v_mfma_f32_16x16x32_bf16 v[116:119], v[168:171], v[186:189], v[116:119]
	v_mfma_f32_16x16x32_bf16 v[112:115], v[176:179], v[186:189], v[112:115]
	v_mfma_f32_16x16x32_bf16 v[96:99], v[176:179], v[194:197], v[96:99]
	v_mfma_f32_16x16x32_bf16 v[100:103], v[168:171], v[194:197], v[100:103]
	v_mfma_f32_16x16x32_bf16 v[84:87], v[168:171], v[202:205], v[84:87]
	v_mfma_f32_16x16x32_bf16 v[80:83], v[176:179], v[202:205], v[80:83]
	v_mfma_f32_16x16x32_bf16 v[64:67], v[176:179], v[210:213], v[64:67]
	v_mfma_f32_16x16x32_bf16 v[68:71], v[168:171], v[210:213], v[68:71]
	v_mfma_f32_16x16x32_bf16 v[116:119], v[172:175], v[190:193], v[116:119]
	v_mfma_f32_16x16x32_bf16 v[112:115], v[180:183], v[190:193], v[112:115]
	v_mfma_f32_16x16x32_bf16 v[96:99], v[180:183], v[198:201], v[96:99]
	v_mfma_f32_16x16x32_bf16 v[100:103], v[172:175], v[198:201], v[100:103]
	v_mfma_f32_16x16x32_bf16 v[84:87], v[172:175], v[206:209], v[84:87]
	v_mfma_f32_16x16x32_bf16 v[80:83], v[180:183], v[206:209], v[80:83]
	v_mfma_f32_16x16x32_bf16 v[64:67], v[180:183], v[214:217], v[64:67]
	v_mfma_f32_16x16x32_bf16 v[68:71], v[172:175], v[214:217], v[68:71]
	s_barrier
	s_add_i32 s19, s19, s62
	s_mov_b32 m0, s19
	ds_read_b128 v[186:189], v157 offset:49152
	ds_read_b128 v[190:193], v157 offset:50176
	ds_read_b128 v[194:197], v157 offset:51200
	ds_read_b128 v[198:201], v157 offset:52224
	ds_read_b128 v[202:205], v157 offset:53248
	ds_read_b128 v[206:209], v157 offset:54272
	ds_read_b128 v[210:213], v157 offset:55296
	ds_read_b128 v[214:217], v157 offset:56320
	global_load_lds_dwordx4 v130, s[98:99]
	s_add_i32 m0, s19, 0x2000
	s_add_u32 s20, s42, 0x40080
	s_addc_u32 s21, s43, 0
	s_add_i32 s19, s22, s62
	global_load_lds_dwordx4 v134, s[98:99]
	s_mov_b32 m0, s19
	s_nop 0
	global_load_lds_dwordx4 v130, s[20:21]
	s_add_i32 m0, s19, 0x2000
	s_nop 0
	global_load_lds_dwordx4 v134, s[20:21]
	s_mov_b32 m0, s70
	s_nop 0
	global_load_lds_dwordx4 v128, s[100:101]
	s_mov_b32 m0, s71
	s_nop 0
	global_load_lds_dwordx4 v132, s[100:101]
	s_waitcnt vmcnt(8)
	s_waitcnt lgkmcnt(0)
	s_barrier
	s_waitcnt lgkmcnt(0)
	v_mfma_f32_16x16x32_bf16 v[60:63], v[144:147], v[186:189], v[60:63]
	v_mfma_f32_16x16x32_bf16 v[56:59], v[160:163], v[186:189], v[56:59]
	v_mfma_f32_16x16x32_bf16 v[40:43], v[160:163], v[194:197], v[40:43]
	v_mfma_f32_16x16x32_bf16 v[44:47], v[144:147], v[194:197], v[44:47]
	v_mfma_f32_16x16x32_bf16 v[28:31], v[144:147], v[202:205], v[28:31]
	v_mfma_f32_16x16x32_bf16 v[24:27], v[160:163], v[202:205], v[24:27]
	v_mfma_f32_16x16x32_bf16 v[8:11], v[160:163], v[210:213], v[8:11]
	v_mfma_f32_16x16x32_bf16 v[12:15], v[144:147], v[210:213], v[12:15]
	v_mfma_f32_16x16x32_bf16 v[60:63], v[148:151], v[190:193], v[60:63]
	v_mfma_f32_16x16x32_bf16 v[56:59], v[164:167], v[190:193], v[56:59]
	v_mfma_f32_16x16x32_bf16 v[40:43], v[164:167], v[198:201], v[40:43]
	v_mfma_f32_16x16x32_bf16 v[44:47], v[148:151], v[198:201], v[44:47]
	v_mfma_f32_16x16x32_bf16 v[28:31], v[148:151], v[206:209], v[28:31]
	v_mfma_f32_16x16x32_bf16 v[24:27], v[164:167], v[206:209], v[24:27]
	v_mfma_f32_16x16x32_bf16 v[8:11], v[164:167], v[214:217], v[8:11]
	v_mfma_f32_16x16x32_bf16 v[12:15], v[148:151], v[214:217], v[12:15]
	v_mfma_f32_16x16x32_bf16 v[52:55], v[168:171], v[186:189], v[52:55]
	v_mfma_f32_16x16x32_bf16 v[48:51], v[176:179], v[186:189], v[48:51]
	v_mfma_f32_16x16x32_bf16 v[32:35], v[176:179], v[194:197], v[32:35]
	v_mfma_f32_16x16x32_bf16 v[36:39], v[168:171], v[194:197], v[36:39]
	v_mfma_f32_16x16x32_bf16 v[20:23], v[168:171], v[202:205], v[20:23]
	v_mfma_f32_16x16x32_bf16 v[16:19], v[176:179], v[202:205], v[16:19]
	v_mfma_f32_16x16x32_bf16 v[0:3], v[176:179], v[210:213], v[0:3]
	v_mfma_f32_16x16x32_bf16 v[4:7], v[168:171], v[210:213], v[4:7]
	v_mfma_f32_16x16x32_bf16 v[52:55], v[172:175], v[190:193], v[52:55]
	v_mfma_f32_16x16x32_bf16 v[48:51], v[180:183], v[190:193], v[48:51]
	v_mfma_f32_16x16x32_bf16 v[32:35], v[180:183], v[198:201], v[32:35]
	v_mfma_f32_16x16x32_bf16 v[36:39], v[172:175], v[198:201], v[36:39]
	v_mfma_f32_16x16x32_bf16 v[20:23], v[172:175], v[206:209], v[20:23]
	v_mfma_f32_16x16x32_bf16 v[16:19], v[180:183], v[206:209], v[16:19]
	v_mfma_f32_16x16x32_bf16 v[0:3], v[180:183], v[214:217], v[0:3]
	v_mfma_f32_16x16x32_bf16 v[4:7], v[172:175], v[214:217], v[4:7]
	s_barrier
	s_add_i32 s18, s18, 2
	s_add_u32 s6, s6, 0x100
	s_addc_u32 s7, s7, 0
	s_add_u32 s16, s16, 0x100
	s_addc_u32 s17, s17, 0
	s_cmp_gt_u32 s18, 13
	s_cbranch_scc0 .LBB0_546

.LBB0_860:
	s_add_u32 s17, s88, s90
	s_addc_u32 s20, s89, s91
	s_add_u32 s21, s17, 0x100
	s_addc_u32 s22, s20, 0
	s_and_b64 s[18:19], s[42:43], exec
	s_cselect_b32 s93, s39, s22
	s_cselect_b32 s92, s38, s21
	s_add_u32 s18, s80, s90
	s_addc_u32 s19, s81, s91
	s_add_u32 s21, s18, 0x100
	s_addc_u32 s22, s19, 0
	s_and_b64 s[18:19], s[42:43], exec
	s_cselect_b32 s95, s15, s22
	s_cselect_b32 s94, s16, s21
	s_add_u32 vcc_lo, s17, 0x40080
	ds_read_b128 v[36:39], v219
	ds_read_b128 v[40:43], v219 offset:1024
	ds_read_b128 v[44:47], v219 offset:2048
	ds_read_b128 v[52:55], v219 offset:3072
	ds_read_b128 v[60:63], v220
	ds_read_b128 v[64:67], v220 offset:1024
	ds_read_b128 v[68:71], v220 offset:2048
	ds_read_b128 v[84:87], v220 offset:3072
	s_addc_u32 vcc_hi, s20, 0
	s_add_i32 s74, s72, s63
	s_add_i32 m0, s41, 0xc000
	s_add_i32 s75, s41, 0xe000
	s_add_i32 s23, s74, 0x2000
	s_add_u32 s96, s94, 0x10000
	s_addc_u32 s97, s95, 0
	s_add_i32 s37, s73, s63
	s_add_i32 s35, s37, 0x2000
	s_add_i32 s22, 0, 0x18000
	s_add_i32 s21, 0, 0x1c000
	s_add_u32 s90, s92, 0x40000
	s_addc_u32 s91, s93, 0
	s_add_i32 s20, s22, s63
	s_add_i32 s18, s20, 0x2000
	s_add_u32 s42, s94, 0x10080
	s_addc_u32 s43, s95, 0
	s_add_i32 s19, s21, s63
	s_add_i32 s17, s19, 0x2000
	v_lshl_add_u64 v[206:207], vcc, 0, v[186:187]
	ds_read_b128 v[100:103], v221
	ds_read_b128 v[120:123], v221 offset:1024
	ds_read_b128 v[136:139], v221 offset:2048
	ds_read_b128 v[156:159], v221 offset:3072
	ds_read_b128 v[176:179], v221 offset:4096
	ds_read_b128 v[180:183], v221 offset:5120
	ds_read_b128 v[198:201], v221 offset:6144
	ds_read_b128 v[202:205], v221 offset:7168
	global_load_lds_dwordx4 v[206:207], off
	v_lshl_add_u64 v[206:207], vcc, 0, v[190:191]
	s_mov_b32 m0, s75
	s_nop 0
	global_load_lds_dwordx4 v[206:207], off
	s_waitcnt vmcnt(8)
	s_waitcnt lgkmcnt(0)
	s_barrier
	s_waitcnt lgkmcnt(0)
	v_mfma_f32_16x16x32_bf16 v[172:175], v[36:39], v[100:103], v[172:175]
	v_mfma_f32_16x16x32_bf16 v[164:167], v[44:47], v[100:103], v[164:167]
	v_mfma_f32_16x16x32_bf16 v[144:147], v[44:47], v[136:139], v[144:147]
	v_mfma_f32_16x16x32_bf16 v[152:155], v[36:39], v[136:139], v[152:155]
	v_mfma_f32_16x16x32_bf16 v[132:135], v[36:39], v[176:179], v[132:135]
	v_mfma_f32_16x16x32_bf16 v[124:127], v[44:47], v[176:179], v[124:127]
	v_mfma_f32_16x16x32_bf16 v[104:107], v[44:47], v[198:201], v[104:107]
	v_mfma_f32_16x16x32_bf16 v[112:115], v[36:39], v[198:201], v[112:115]
	v_mfma_f32_16x16x32_bf16 v[172:175], v[40:43], v[120:123], v[172:175]
	v_mfma_f32_16x16x32_bf16 v[164:167], v[52:55], v[120:123], v[164:167]
	v_mfma_f32_16x16x32_bf16 v[144:147], v[52:55], v[156:159], v[144:147]
	v_mfma_f32_16x16x32_bf16 v[152:155], v[40:43], v[156:159], v[152:155]
	v_mfma_f32_16x16x32_bf16 v[132:135], v[40:43], v[180:183], v[132:135]
	v_mfma_f32_16x16x32_bf16 v[124:127], v[52:55], v[180:183], v[124:127]
	v_mfma_f32_16x16x32_bf16 v[104:107], v[52:55], v[202:205], v[104:107]
	v_mfma_f32_16x16x32_bf16 v[112:115], v[40:43], v[202:205], v[112:115]
	v_mfma_f32_16x16x32_bf16 v[168:171], v[60:63], v[100:103], v[168:171]
	v_mfma_f32_16x16x32_bf16 v[100:103], v[68:71], v[100:103], v[160:163]
	v_mfma_f32_16x16x32_bf16 v[128:131], v[60:63], v[176:179], v[128:131]
	v_mfma_f32_16x16x32_bf16 v[116:119], v[68:71], v[176:179], v[116:119]
	v_mfma_f32_16x16x32_bf16 v[108:111], v[60:63], v[198:201], v[108:111]
	v_mfma_f32_16x16x32_bf16 v[96:99], v[68:71], v[198:201], v[96:99]
	v_mfma_f32_16x16x32_bf16 v[168:171], v[64:67], v[120:123], v[168:171]
	v_mfma_f32_16x16x32_bf16 v[100:103], v[84:87], v[120:123], v[100:103]
	v_mfma_f32_16x16x32_bf16 v[120:123], v[60:63], v[136:139], v[148:151]
	v_mfma_f32_16x16x32_bf16 v[136:139], v[68:71], v[136:139], v[140:143]
	v_mfma_f32_16x16x32_bf16 v[128:131], v[64:67], v[180:183], v[128:131]
	v_mfma_f32_16x16x32_bf16 v[116:119], v[84:87], v[180:183], v[116:119]
	v_mfma_f32_16x16x32_bf16 v[108:111], v[64:67], v[202:205], v[108:111]
	v_mfma_f32_16x16x32_bf16 v[96:99], v[84:87], v[202:205], v[96:99]
	v_mfma_f32_16x16x32_bf16 v[120:123], v[64:67], v[156:159], v[120:123]
	v_mfma_f32_16x16x32_bf16 v[136:139], v[84:87], v[156:159], v[136:139]
	s_barrier
	s_mov_b32 m0, s74
	ds_read_b128 v[140:143], v221 offset:16384
	ds_read_b128 v[148:151], v221 offset:17408
	ds_read_b128 v[156:159], v221 offset:18432
	ds_read_b128 v[160:163], v221 offset:19456
	ds_read_b128 v[176:179], v221 offset:20480
	ds_read_b128 v[180:183], v221 offset:21504
	ds_read_b128 v[198:201], v221 offset:22528
	ds_read_b128 v[202:205], v221 offset:23552
	global_load_lds_dwordx4 v188, s[94:95]
	s_mov_b32 m0, s23
	global_load_lds_dwordx4 v192, s[94:95]
	s_mov_b32 m0, s37
	global_load_lds_dwordx4 v188, s[96:97]
	s_mov_b32 m0, s35
	v_lshl_add_u64 v[226:227], s[92:93], 0, v[190:191]
	global_load_lds_dwordx4 v192, s[96:97]
	s_mov_b32 m0, s41
	s_nop 0
	global_load_lds_dwordx4 v186, s[92:93]
	s_mov_b32 m0, s64
	s_nop 0
	global_load_lds_dwordx4 v190, s[92:93]
	s_add_u32 s98, s94, s28
	s_addc_u32 s99, s95, s29
	s_add_u32 s100, s92, s28
	s_addc_u32 s101, s93, s29
	s_waitcnt vmcnt(8)
	s_waitcnt lgkmcnt(0)
	s_barrier
	s_waitcnt lgkmcnt(0)
	v_mfma_f32_16x16x32_bf16 v[92:95], v[36:39], v[140:143], v[92:95]
	v_mfma_f32_16x16x32_bf16 v[80:83], v[44:47], v[140:143], v[80:83]
	v_mfma_f32_16x16x32_bf16 v[48:51], v[44:47], v[156:159], v[48:51]
	v_mfma_f32_16x16x32_bf16 v[72:75], v[36:39], v[156:159], v[72:75]
	v_mfma_f32_16x16x32_bf16 v[28:31], v[36:39], v[176:179], v[28:31]
	v_mfma_f32_16x16x32_bf16 v[20:23], v[44:47], v[176:179], v[20:23]
	v_mfma_f32_16x16x32_bf16 v[4:7], v[44:47], v[198:201], v[4:7]
	v_mfma_f32_16x16x32_bf16 v[12:15], v[36:39], v[198:201], v[12:15]
	v_mfma_f32_16x16x32_bf16 v[92:95], v[40:43], v[148:151], v[92:95]
	v_mfma_f32_16x16x32_bf16 v[80:83], v[52:55], v[148:151], v[80:83]
	v_mfma_f32_16x16x32_bf16 v[48:51], v[52:55], v[160:163], v[48:51]
	v_mfma_f32_16x16x32_bf16 v[72:75], v[40:43], v[160:163], v[72:75]
	v_mfma_f32_16x16x32_bf16 v[28:31], v[40:43], v[180:183], v[28:31]
	v_mfma_f32_16x16x32_bf16 v[20:23], v[52:55], v[180:183], v[20:23]
	v_mfma_f32_16x16x32_bf16 v[4:7], v[52:55], v[202:205], v[4:7]
	v_mfma_f32_16x16x32_bf16 v[12:15], v[40:43], v[202:205], v[12:15]
	v_mfma_f32_16x16x32_bf16 v[32:35], v[68:71], v[156:159], v[32:35]
	v_mfma_f32_16x16x32_bf16 v[24:27], v[60:63], v[176:179], v[24:27]
	v_mfma_f32_16x16x32_bf16 v[16:19], v[68:71], v[176:179], v[16:19]
	v_mfma_f32_16x16x32_bf16 v[8:11], v[60:63], v[198:201], v[8:11]
	v_mfma_f32_16x16x32_bf16 v[0:3], v[68:71], v[198:201], v[0:3]
	v_mfma_f32_16x16x32_bf16 v[36:39], v[60:63], v[140:143], v[88:91]
	v_mfma_f32_16x16x32_bf16 v[40:43], v[68:71], v[140:143], v[76:79]
	v_mfma_f32_16x16x32_bf16 v[44:47], v[60:63], v[156:159], v[56:59]
	v_mfma_f32_16x16x32_bf16 v[32:35], v[84:87], v[160:163], v[32:35]
	v_mfma_f32_16x16x32_bf16 v[24:27], v[64:67], v[180:183], v[24:27]
	v_mfma_f32_16x16x32_bf16 v[16:19], v[84:87], v[180:183], v[16:19]
	v_mfma_f32_16x16x32_bf16 v[8:11], v[64:67], v[202:205], v[8:11]
	v_mfma_f32_16x16x32_bf16 v[0:3], v[84:87], v[202:205], v[0:3]
	v_mfma_f32_16x16x32_bf16 v[36:39], v[64:67], v[148:151], v[36:39]
	v_mfma_f32_16x16x32_bf16 v[40:43], v[84:87], v[148:151], v[40:43]
	v_mfma_f32_16x16x32_bf16 v[44:47], v[64:67], v[160:163], v[44:47]
	s_barrier
	v_add_u32_e32 v64, s22, v217
	v_add_u32_e32 v76, s21, v217
	ds_read_b128 v[52:55], v64
	ds_read_b128 v[56:59], v64 offset:1024
	ds_read_b128 v[60:63], v64 offset:2048
	ds_read_b128 v[64:67], v64 offset:3072
	ds_read_b128 v[68:71], v76
	ds_read_b128 v[84:87], v76 offset:1024
	ds_read_b128 v[156:159], v76 offset:2048
	ds_read_b128 v[176:179], v76 offset:3072
	s_mov_b32 m0, s65
	ds_read_b128 v[76:79], v221 offset:32768
	ds_read_b128 v[88:91], v221 offset:33792
	ds_read_b128 v[140:143], v221 offset:34816
	ds_read_b128 v[180:183], v221 offset:35840
	ds_read_b128 v[198:201], v221 offset:36864
	ds_read_b128 v[202:205], v221 offset:37888
	ds_read_b128 v[206:209], v221 offset:38912
	ds_read_b128 v[210:213], v221 offset:39936
	global_load_lds_dwordx4 v186, s[90:91]
	v_lshl_add_u64 v[148:149], s[90:91], 0, v[190:191]
	s_mov_b32 m0, s66
	s_nop 0
	global_load_lds_dwordx4 v190, s[90:91]
	s_waitcnt vmcnt(8)
	s_waitcnt lgkmcnt(0)
	s_barrier
	s_waitcnt lgkmcnt(0)
	v_mfma_f32_16x16x32_bf16 v[148:151], v[52:55], v[76:79], v[172:175]
	v_mfma_f32_16x16x32_bf16 v[172:175], v[56:59], v[88:91], v[148:151]
	v_mfma_f32_16x16x32_bf16 v[148:151], v[60:63], v[76:79], v[164:167]
	v_mfma_f32_16x16x32_bf16 v[164:167], v[64:67], v[88:91], v[148:151]
	v_mfma_f32_16x16x32_bf16 v[148:151], v[52:55], v[140:143], v[152:155]
	v_mfma_f32_16x16x32_bf16 v[144:147], v[60:63], v[140:143], v[144:147]
	v_mfma_f32_16x16x32_bf16 v[132:135], v[52:55], v[198:201], v[132:135]
	v_mfma_f32_16x16x32_bf16 v[124:127], v[60:63], v[198:201], v[124:127]
	v_mfma_f32_16x16x32_bf16 v[112:115], v[52:55], v[206:209], v[112:115]
	v_mfma_f32_16x16x32_bf16 v[104:107], v[60:63], v[206:209], v[104:107]
	v_mfma_f32_16x16x32_bf16 v[152:155], v[56:59], v[180:183], v[148:151]
	v_mfma_f32_16x16x32_bf16 v[144:147], v[64:67], v[180:183], v[144:147]
	v_mfma_f32_16x16x32_bf16 v[132:135], v[56:59], v[202:205], v[132:135]
	v_mfma_f32_16x16x32_bf16 v[124:127], v[64:67], v[202:205], v[124:127]
	v_mfma_f32_16x16x32_bf16 v[112:115], v[56:59], v[210:213], v[112:115]
	v_mfma_f32_16x16x32_bf16 v[104:107], v[64:67], v[210:213], v[104:107]
	v_mfma_f32_16x16x32_bf16 v[148:151], v[68:71], v[76:79], v[168:171]
	v_mfma_f32_16x16x32_bf16 v[76:79], v[156:159], v[76:79], v[100:103]
	v_mfma_f32_16x16x32_bf16 v[160:163], v[176:179], v[88:91], v[76:79]
	v_mfma_f32_16x16x32_bf16 v[76:79], v[68:71], v[140:143], v[120:123]
	v_mfma_f32_16x16x32_bf16 v[168:171], v[84:87], v[88:91], v[148:151]
	v_mfma_f32_16x16x32_bf16 v[148:151], v[84:87], v[180:183], v[76:79]
	v_mfma_f32_16x16x32_bf16 v[76:79], v[156:159], v[140:143], v[136:139]
	v_mfma_f32_16x16x32_bf16 v[140:143], v[176:179], v[180:183], v[76:79]
	v_mfma_f32_16x16x32_bf16 v[76:79], v[68:71], v[198:201], v[128:131]
	v_mfma_f32_16x16x32_bf16 v[128:131], v[84:87], v[202:205], v[76:79]
	v_mfma_f32_16x16x32_bf16 v[76:79], v[156:159], v[198:201], v[116:119]
	v_mfma_f32_16x16x32_bf16 v[116:119], v[176:179], v[202:205], v[76:79]
	v_mfma_f32_16x16x32_bf16 v[76:79], v[68:71], v[206:209], v[108:111]
	v_mfma_f32_16x16x32_bf16 v[108:111], v[84:87], v[210:213], v[76:79]
	v_mfma_f32_16x16x32_bf16 v[76:79], v[156:159], v[206:209], v[96:99]
	v_mfma_f32_16x16x32_bf16 v[96:99], v[176:179], v[210:213], v[76:79]
	s_barrier
	s_mov_b32 m0, s20
	s_nop 2
	ds_read_b128 v[76:79], v221 offset:49152
	ds_read_b128 v[100:103], v221 offset:50176
	ds_read_b128 v[120:123], v221 offset:51200
	ds_read_b128 v[136:139], v221 offset:52224
	ds_read_b128 v[180:183], v221 offset:53248
	ds_read_b128 v[198:201], v221 offset:54272
	ds_read_b128 v[202:205], v221 offset:55296
	ds_read_b128 v[206:209], v221 offset:56320
	global_load_lds_dwordx4 v188, s[98:99]
	s_mov_b32 m0, s18
	s_nop 0
	global_load_lds_dwordx4 v192, s[98:99]
	s_mov_b32 m0, s19
	s_nop 0
	global_load_lds_dwordx4 v188, s[42:43]
	s_mov_b32 m0, s17
	s_nop 0
	global_load_lds_dwordx4 v192, s[42:43]
	s_mov_b32 m0, s70
	s_nop 0
	global_load_lds_dwordx4 v186, s[100:101]
	v_lshl_add_u64 v[88:89], v[226:227], 0, s[28:29]
	s_mov_b32 m0, s71
	s_nop 0
	global_load_lds_dwordx4 v190, s[100:101]
	s_waitcnt vmcnt(8)
	s_waitcnt lgkmcnt(0)
	s_barrier
	s_waitcnt lgkmcnt(0)
	v_mfma_f32_16x16x32_bf16 v[88:91], v[52:55], v[76:79], v[92:95]
	v_mfma_f32_16x16x32_bf16 v[80:83], v[60:63], v[76:79], v[80:83]
	v_mfma_f32_16x16x32_bf16 v[72:75], v[52:55], v[120:123], v[72:75]
	v_mfma_f32_16x16x32_bf16 v[48:51], v[60:63], v[120:123], v[48:51]
	v_mfma_f32_16x16x32_bf16 v[28:31], v[52:55], v[180:183], v[28:31]
	v_mfma_f32_16x16x32_bf16 v[20:23], v[60:63], v[180:183], v[20:23]
	v_mfma_f32_16x16x32_bf16 v[12:15], v[52:55], v[202:205], v[12:15]
	v_mfma_f32_16x16x32_bf16 v[4:7], v[60:63], v[202:205], v[4:7]
	v_mfma_f32_16x16x32_bf16 v[92:95], v[56:59], v[100:103], v[88:91]
	v_mfma_f32_16x16x32_bf16 v[80:83], v[64:67], v[100:103], v[80:83]
	v_mfma_f32_16x16x32_bf16 v[72:75], v[56:59], v[136:139], v[72:75]
	v_mfma_f32_16x16x32_bf16 v[48:51], v[64:67], v[136:139], v[48:51]
	v_mfma_f32_16x16x32_bf16 v[28:31], v[56:59], v[198:201], v[28:31]
	v_mfma_f32_16x16x32_bf16 v[20:23], v[64:67], v[198:201], v[20:23]
	v_mfma_f32_16x16x32_bf16 v[12:15], v[56:59], v[206:209], v[12:15]
	v_mfma_f32_16x16x32_bf16 v[4:7], v[64:67], v[206:209], v[4:7]
	v_mfma_f32_16x16x32_bf16 v[36:39], v[68:71], v[76:79], v[36:39]
	v_mfma_f32_16x16x32_bf16 v[88:91], v[84:87], v[100:103], v[36:39]
	v_mfma_f32_16x16x32_bf16 v[36:39], v[156:159], v[76:79], v[40:43]
	v_mfma_f32_16x16x32_bf16 v[76:79], v[176:179], v[100:103], v[36:39]
	v_mfma_f32_16x16x32_bf16 v[36:39], v[68:71], v[120:123], v[44:47]
	v_mfma_f32_16x16x32_bf16 v[32:35], v[156:159], v[120:123], v[32:35]
	v_mfma_f32_16x16x32_bf16 v[24:27], v[68:71], v[180:183], v[24:27]
	v_mfma_f32_16x16x32_bf16 v[16:19], v[156:159], v[180:183], v[16:19]
	v_mfma_f32_16x16x32_bf16 v[8:11], v[68:71], v[202:205], v[8:11]
	v_mfma_f32_16x16x32_bf16 v[0:3], v[156:159], v[202:205], v[0:3]
	v_mfma_f32_16x16x32_bf16 v[56:59], v[84:87], v[136:139], v[36:39]
	v_mfma_f32_16x16x32_bf16 v[32:35], v[176:179], v[136:139], v[32:35]
	v_mfma_f32_16x16x32_bf16 v[24:27], v[84:87], v[198:201], v[24:27]
	v_mfma_f32_16x16x32_bf16 v[16:19], v[176:179], v[198:201], v[16:19]
	v_mfma_f32_16x16x32_bf16 v[8:11], v[84:87], v[206:209], v[8:11]
	v_mfma_f32_16x16x32_bf16 v[0:3], v[176:179], v[206:209], v[0:3]
	s_barrier
	s_andn2_b64 vcc, exec, s[0:1]
	s_mov_b64 s[42:43], -1
	s_mov_b64 s[0:1], 0
	s_mov_b64 s[90:91], 0x100
	s_cbranch_vccz .LBB0_860
	s_and_b64 vcc, exec, s[30:31]
	s_cbranch_vccz .LBB0_863
	s_barrier

.LBB0_1025:
	s_ashr_i32 s27, s26, 31
	s_lshl_b64 s[30:31], s[26:27], 19
	s_add_u32 s30, s3, s30
	s_addc_u32 s31, s14, s31
	s_and_b64 s[34:35], s[8:9], exec
	s_cselect_b32 s27, s31, s41
	s_cselect_b32 s37, s30, s40
	s_ashr_i32 s29, s28, 31
	s_lshl_b64 s[34:35], s[28:29], 19
	s_add_u32 s34, s15, s34
	s_addc_u32 s35, s16, s35
	s_and_b64 s[62:63], s[8:9], exec
	s_cselect_b32 s29, s35, s43
	s_cselect_b32 s39, s34, s42
	s_add_u32 s40, s40, 0x40080
	s_addc_u32 s41, s41, 0
	s_add_u32 s70, s42, 0x100
	s_addc_u32 s71, s43, 0
	s_mov_b32 s72, -2
	s_waitcnt lgkmcnt(0)
	ds_read_b128 v[128:131], v189
	ds_read_b128 v[132:135], v189 offset:1024
	ds_read_b128 v[136:139], v189 offset:2048
	ds_read_b128 v[140:143], v189 offset:3072
	ds_read_b128 v[144:147], v190
	ds_read_b128 v[148:151], v190 offset:1024
	ds_read_b128 v[172:175], v190 offset:2048
	ds_read_b128 v[176:179], v190 offset:3072
	s_add_u32 s42, s40, 0xfffc0080
	s_addc_u32 s43, s41, -1
	s_cmp_eq_u32 s72, 12
	s_cselect_b32 s63, s27, s43
	s_cselect_b32 s62, s37, s42
	s_cselect_b32 s43, s29, s71
	s_cselect_b32 s42, s39, s70
	s_add_i32 m0, s18, 0xc000
	ds_read_b128 v[180:183], v191
	ds_read_b128 v[194:197], v191 offset:1024
	ds_read_b128 v[198:201], v191 offset:2048
	ds_read_b128 v[202:205], v191 offset:3072
	ds_read_b128 v[206:209], v191 offset:4096
	ds_read_b128 v[210:213], v191 offset:5120
	ds_read_b128 v[214:217], v191 offset:6144
	ds_read_b128 v[218:221], v191 offset:7168
	global_load_lds_dwordx4 v164, s[40:41]
	s_add_i32 m0, s18, 0xe000
	s_nop 0
	global_load_lds_dwordx4 v166, s[40:41]
	s_waitcnt vmcnt(8)
	s_waitcnt lgkmcnt(0)
	s_barrier
	s_waitcnt lgkmcnt(0)
	v_mfma_f32_16x16x32_bf16 v[124:127], v[128:131], v[180:183], 0
	v_mfma_f32_16x16x32_bf16 v[120:123], v[136:139], v[180:183], 0
	v_mfma_f32_16x16x32_bf16 v[104:107], v[136:139], v[198:201], 0
	v_mfma_f32_16x16x32_bf16 v[108:111], v[128:131], v[198:201], 0
	v_mfma_f32_16x16x32_bf16 v[92:95], v[128:131], v[206:209], 0
	v_mfma_f32_16x16x32_bf16 v[88:91], v[136:139], v[206:209], 0
	v_mfma_f32_16x16x32_bf16 v[72:75], v[136:139], v[214:217], 0
	v_mfma_f32_16x16x32_bf16 v[76:79], v[128:131], v[214:217], 0
	v_mfma_f32_16x16x32_bf16 v[124:127], v[132:135], v[194:197], v[124:127]
	v_mfma_f32_16x16x32_bf16 v[120:123], v[140:143], v[194:197], v[120:123]
	v_mfma_f32_16x16x32_bf16 v[104:107], v[140:143], v[202:205], v[104:107]
	v_mfma_f32_16x16x32_bf16 v[108:111], v[132:135], v[202:205], v[108:111]
	v_mfma_f32_16x16x32_bf16 v[92:95], v[132:135], v[210:213], v[92:95]
	v_mfma_f32_16x16x32_bf16 v[88:91], v[140:143], v[210:213], v[88:91]
	v_mfma_f32_16x16x32_bf16 v[72:75], v[140:143], v[218:221], v[72:75]
	v_mfma_f32_16x16x32_bf16 v[76:79], v[132:135], v[218:221], v[76:79]
	v_mfma_f32_16x16x32_bf16 v[116:119], v[144:147], v[180:183], 0
	v_mfma_f32_16x16x32_bf16 v[112:115], v[172:175], v[180:183], 0
	v_mfma_f32_16x16x32_bf16 v[96:99], v[172:175], v[198:201], 0
	v_mfma_f32_16x16x32_bf16 v[100:103], v[144:147], v[198:201], 0
	v_mfma_f32_16x16x32_bf16 v[84:87], v[144:147], v[206:209], 0
	v_mfma_f32_16x16x32_bf16 v[80:83], v[172:175], v[206:209], 0
	v_mfma_f32_16x16x32_bf16 v[64:67], v[172:175], v[214:217], 0
	v_mfma_f32_16x16x32_bf16 v[68:71], v[144:147], v[214:217], 0
	v_mfma_f32_16x16x32_bf16 v[116:119], v[148:151], v[194:197], v[116:119]
	v_mfma_f32_16x16x32_bf16 v[112:115], v[176:179], v[194:197], v[112:115]
	v_mfma_f32_16x16x32_bf16 v[96:99], v[176:179], v[202:205], v[96:99]
	v_mfma_f32_16x16x32_bf16 v[100:103], v[148:151], v[202:205], v[100:103]
	v_mfma_f32_16x16x32_bf16 v[84:87], v[148:151], v[210:213], v[84:87]
	v_mfma_f32_16x16x32_bf16 v[80:83], v[176:179], v[210:213], v[80:83]
	v_mfma_f32_16x16x32_bf16 v[64:67], v[176:179], v[218:221], v[64:67]
	v_mfma_f32_16x16x32_bf16 v[68:71], v[148:151], v[218:221], v[68:71]
	s_barrier
	s_add_i32 s73, s66, s17
	s_mov_b32 m0, s73
	ds_read_b128 v[180:183], v191 offset:16384
	ds_read_b128 v[194:197], v191 offset:17408
	ds_read_b128 v[198:201], v191 offset:18432
	ds_read_b128 v[202:205], v191 offset:19456
	ds_read_b128 v[206:209], v191 offset:20480
	ds_read_b128 v[210:213], v191 offset:21504
	ds_read_b128 v[214:217], v191 offset:22528
	ds_read_b128 v[218:221], v191 offset:23552
	global_load_lds_dwordx4 v154, s[42:43]
	s_add_i32 m0, s73, 0x2000
	s_add_u32 s74, s42, 0x40000
	s_addc_u32 s75, s43, 0
	s_add_i32 s73, s67, s17
	global_load_lds_dwordx4 v158, s[42:43]
	s_mov_b32 m0, s73
	global_load_lds_dwordx4 v154, s[74:75]
	s_add_i32 m0, s73, 0x2000
	s_nop 0
	global_load_lds_dwordx4 v158, s[74:75]
	s_mov_b32 m0, s18
	s_nop 0
	global_load_lds_dwordx4 v152, s[62:63]
	s_mov_b32 m0, s19
	s_nop 0
	global_load_lds_dwordx4 v156, s[62:63]
	s_add_u32 s98, s42, s12
	s_addc_u32 s99, s43, s13
	s_add_u32 s100, s62, s12
	s_addc_u32 s101, s63, s13
	s_waitcnt vmcnt(8)
	s_waitcnt lgkmcnt(0)
	s_barrier
	s_waitcnt lgkmcnt(0)
	v_mfma_f32_16x16x32_bf16 v[60:63], v[128:131], v[180:183], 0
	v_mfma_f32_16x16x32_bf16 v[56:59], v[136:139], v[180:183], 0
	v_mfma_f32_16x16x32_bf16 v[40:43], v[136:139], v[198:201], 0
	v_mfma_f32_16x16x32_bf16 v[44:47], v[128:131], v[198:201], 0
	v_mfma_f32_16x16x32_bf16 v[28:31], v[128:131], v[206:209], 0
	v_mfma_f32_16x16x32_bf16 v[24:27], v[136:139], v[206:209], 0
	v_mfma_f32_16x16x32_bf16 v[8:11], v[136:139], v[214:217], 0
	v_mfma_f32_16x16x32_bf16 v[12:15], v[128:131], v[214:217], 0
	v_mfma_f32_16x16x32_bf16 v[60:63], v[132:135], v[194:197], v[60:63]
	v_mfma_f32_16x16x32_bf16 v[56:59], v[140:143], v[194:197], v[56:59]
	v_mfma_f32_16x16x32_bf16 v[40:43], v[140:143], v[202:205], v[40:43]
	v_mfma_f32_16x16x32_bf16 v[44:47], v[132:135], v[202:205], v[44:47]
	v_mfma_f32_16x16x32_bf16 v[28:31], v[132:135], v[210:213], v[28:31]
	v_mfma_f32_16x16x32_bf16 v[24:27], v[140:143], v[210:213], v[24:27]
	v_mfma_f32_16x16x32_bf16 v[8:11], v[140:143], v[218:221], v[8:11]
	v_mfma_f32_16x16x32_bf16 v[12:15], v[132:135], v[218:221], v[12:15]
	v_mfma_f32_16x16x32_bf16 v[52:55], v[144:147], v[180:183], 0
	v_mfma_f32_16x16x32_bf16 v[48:51], v[172:175], v[180:183], 0
	v_mfma_f32_16x16x32_bf16 v[32:35], v[172:175], v[198:201], 0
	v_mfma_f32_16x16x32_bf16 v[36:39], v[144:147], v[198:201], 0
	v_mfma_f32_16x16x32_bf16 v[20:23], v[144:147], v[206:209], 0
	v_mfma_f32_16x16x32_bf16 v[16:19], v[172:175], v[206:209], 0
	v_mfma_f32_16x16x32_bf16 v[0:3], v[172:175], v[214:217], 0
	v_mfma_f32_16x16x32_bf16 v[4:7], v[144:147], v[214:217], 0
	v_mfma_f32_16x16x32_bf16 v[52:55], v[148:151], v[194:197], v[52:55]
	v_mfma_f32_16x16x32_bf16 v[48:51], v[176:179], v[194:197], v[48:51]
	v_mfma_f32_16x16x32_bf16 v[32:35], v[176:179], v[202:205], v[32:35]
	v_mfma_f32_16x16x32_bf16 v[36:39], v[148:151], v[202:205], v[36:39]
	v_mfma_f32_16x16x32_bf16 v[20:23], v[148:151], v[210:213], v[20:23]
	v_mfma_f32_16x16x32_bf16 v[16:19], v[176:179], v[210:213], v[16:19]
	v_mfma_f32_16x16x32_bf16 v[0:3], v[176:179], v[218:221], v[0:3]
	v_mfma_f32_16x16x32_bf16 v[4:7], v[148:151], v[218:221], v[4:7]
	s_barrier
	s_add_i32 s73, 0, 0x18000
	s_add_i32 s74, 0, 0x1c000
	v_add_u32_e32 v140, s73, v186
	v_add_u32_e32 v176, s74, v186
	ds_read_b128 v[128:131], v140
	ds_read_b128 v[132:135], v140 offset:1024
	ds_read_b128 v[136:139], v140 offset:2048
	ds_read_b128 v[140:143], v140 offset:3072
	ds_read_b128 v[144:147], v176
	ds_read_b128 v[148:151], v176 offset:1024
	ds_read_b128 v[172:175], v176 offset:2048
	ds_read_b128 v[176:179], v176 offset:3072
	s_add_u32 s62, s62, 0x40000
	s_addc_u32 s63, s63, 0
	s_mov_b32 m0, s20
	ds_read_b128 v[180:183], v191 offset:32768
	ds_read_b128 v[194:197], v191 offset:33792
	ds_read_b128 v[198:201], v191 offset:34816
	ds_read_b128 v[202:205], v191 offset:35840
	ds_read_b128 v[206:209], v191 offset:36864
	ds_read_b128 v[210:213], v191 offset:37888
	ds_read_b128 v[214:217], v191 offset:38912
	ds_read_b128 v[218:221], v191 offset:39936
	global_load_lds_dwordx4 v152, s[62:63]
	s_mov_b32 m0, s21
	s_nop 0
	global_load_lds_dwordx4 v156, s[62:63]
	s_waitcnt vmcnt(8)
	s_waitcnt lgkmcnt(0)
	s_barrier
	s_waitcnt lgkmcnt(0)
	v_mfma_f32_16x16x32_bf16 v[124:127], v[128:131], v[180:183], v[124:127]
	v_mfma_f32_16x16x32_bf16 v[120:123], v[136:139], v[180:183], v[120:123]
	v_mfma_f32_16x16x32_bf16 v[104:107], v[136:139], v[198:201], v[104:107]
	v_mfma_f32_16x16x32_bf16 v[108:111], v[128:131], v[198:201], v[108:111]
	v_mfma_f32_16x16x32_bf16 v[92:95], v[128:131], v[206:209], v[92:95]
	v_mfma_f32_16x16x32_bf16 v[88:91], v[136:139], v[206:209], v[88:91]
	v_mfma_f32_16x16x32_bf16 v[72:75], v[136:139], v[214:217], v[72:75]
	v_mfma_f32_16x16x32_bf16 v[76:79], v[128:131], v[214:217], v[76:79]
	v_mfma_f32_16x16x32_bf16 v[124:127], v[132:135], v[194:197], v[124:127]
	v_mfma_f32_16x16x32_bf16 v[120:123], v[140:143], v[194:197], v[120:123]
	v_mfma_f32_16x16x32_bf16 v[104:107], v[140:143], v[202:205], v[104:107]
	v_mfma_f32_16x16x32_bf16 v[108:111], v[132:135], v[202:205], v[108:111]
	v_mfma_f32_16x16x32_bf16 v[92:95], v[132:135], v[210:213], v[92:95]
	v_mfma_f32_16x16x32_bf16 v[88:91], v[140:143], v[210:213], v[88:91]
	v_mfma_f32_16x16x32_bf16 v[72:75], v[140:143], v[218:221], v[72:75]
	v_mfma_f32_16x16x32_bf16 v[76:79], v[132:135], v[218:221], v[76:79]
	v_mfma_f32_16x16x32_bf16 v[116:119], v[144:147], v[180:183], v[116:119]
	v_mfma_f32_16x16x32_bf16 v[112:115], v[172:175], v[180:183], v[112:115]
	v_mfma_f32_16x16x32_bf16 v[96:99], v[172:175], v[198:201], v[96:99]
	v_mfma_f32_16x16x32_bf16 v[100:103], v[144:147], v[198:201], v[100:103]
	v_mfma_f32_16x16x32_bf16 v[84:87], v[144:147], v[206:209], v[84:87]
	v_mfma_f32_16x16x32_bf16 v[80:83], v[172:175], v[206:209], v[80:83]
	v_mfma_f32_16x16x32_bf16 v[64:67], v[172:175], v[214:217], v[64:67]
	v_mfma_f32_16x16x32_bf16 v[68:71], v[144:147], v[214:217], v[68:71]
	v_mfma_f32_16x16x32_bf16 v[116:119], v[148:151], v[194:197], v[116:119]
	v_mfma_f32_16x16x32_bf16 v[112:115], v[176:179], v[194:197], v[112:115]
	v_mfma_f32_16x16x32_bf16 v[96:99], v[176:179], v[202:205], v[96:99]
	v_mfma_f32_16x16x32_bf16 v[100:103], v[148:151], v[202:205], v[100:103]
	v_mfma_f32_16x16x32_bf16 v[84:87], v[148:151], v[210:213], v[84:87]
	v_mfma_f32_16x16x32_bf16 v[80:83], v[176:179], v[210:213], v[80:83]
	v_mfma_f32_16x16x32_bf16 v[64:67], v[176:179], v[218:221], v[64:67]
	v_mfma_f32_16x16x32_bf16 v[68:71], v[148:151], v[218:221], v[68:71]
	s_barrier
	s_add_i32 s62, s73, s17
	s_mov_b32 m0, s62
	ds_read_b128 v[180:183], v191 offset:49152
	ds_read_b128 v[194:197], v191 offset:50176
	ds_read_b128 v[198:201], v191 offset:51200
	ds_read_b128 v[202:205], v191 offset:52224
	ds_read_b128 v[206:209], v191 offset:53248
	ds_read_b128 v[210:213], v191 offset:54272
	ds_read_b128 v[214:217], v191 offset:55296
	ds_read_b128 v[218:221], v191 offset:56320
	global_load_lds_dwordx4 v154, s[98:99]
	s_add_i32 m0, s62, 0x2000
	s_add_u32 s42, s42, 0x40080
	s_addc_u32 s43, s43, 0
	s_add_i32 s62, s74, s17
	global_load_lds_dwordx4 v158, s[98:99]
	s_mov_b32 m0, s62
	s_nop 0
	global_load_lds_dwordx4 v154, s[42:43]
	s_add_i32 m0, s62, 0x2000
	s_nop 0
	global_load_lds_dwordx4 v158, s[42:43]
	s_mov_b32 m0, s23
	s_nop 0
	global_load_lds_dwordx4 v152, s[100:101]
	s_mov_b32 m0, s60
	s_nop 0
	global_load_lds_dwordx4 v156, s[100:101]
	s_waitcnt vmcnt(8)
	s_waitcnt lgkmcnt(0)
	s_barrier
	s_waitcnt lgkmcnt(0)
	v_mfma_f32_16x16x32_bf16 v[60:63], v[128:131], v[180:183], v[60:63]
	v_mfma_f32_16x16x32_bf16 v[56:59], v[136:139], v[180:183], v[56:59]
	v_mfma_f32_16x16x32_bf16 v[40:43], v[136:139], v[198:201], v[40:43]
	v_mfma_f32_16x16x32_bf16 v[44:47], v[128:131], v[198:201], v[44:47]
	v_mfma_f32_16x16x32_bf16 v[28:31], v[128:131], v[206:209], v[28:31]
	v_mfma_f32_16x16x32_bf16 v[24:27], v[136:139], v[206:209], v[24:27]
	v_mfma_f32_16x16x32_bf16 v[8:11], v[136:139], v[214:217], v[8:11]
	v_mfma_f32_16x16x32_bf16 v[12:15], v[128:131], v[214:217], v[12:15]
	v_mfma_f32_16x16x32_bf16 v[60:63], v[132:135], v[194:197], v[60:63]
	v_mfma_f32_16x16x32_bf16 v[56:59], v[140:143], v[194:197], v[56:59]
	v_mfma_f32_16x16x32_bf16 v[40:43], v[140:143], v[202:205], v[40:43]
	v_mfma_f32_16x16x32_bf16 v[44:47], v[132:135], v[202:205], v[44:47]
	v_mfma_f32_16x16x32_bf16 v[28:31], v[132:135], v[210:213], v[28:31]
	v_mfma_f32_16x16x32_bf16 v[24:27], v[140:143], v[210:213], v[24:27]
	v_mfma_f32_16x16x32_bf16 v[8:11], v[140:143], v[218:221], v[8:11]
	v_mfma_f32_16x16x32_bf16 v[12:15], v[132:135], v[218:221], v[12:15]
	v_mfma_f32_16x16x32_bf16 v[52:55], v[144:147], v[180:183], v[52:55]
	v_mfma_f32_16x16x32_bf16 v[48:51], v[172:175], v[180:183], v[48:51]
	v_mfma_f32_16x16x32_bf16 v[32:35], v[172:175], v[198:201], v[32:35]
	v_mfma_f32_16x16x32_bf16 v[36:39], v[144:147], v[198:201], v[36:39]
	v_mfma_f32_16x16x32_bf16 v[20:23], v[144:147], v[206:209], v[20:23]
	v_mfma_f32_16x16x32_bf16 v[16:19], v[172:175], v[206:209], v[16:19]
	v_mfma_f32_16x16x32_bf16 v[0:3], v[172:175], v[214:217], v[0:3]
	v_mfma_f32_16x16x32_bf16 v[4:7], v[144:147], v[214:217], v[4:7]
	v_mfma_f32_16x16x32_bf16 v[52:55], v[148:151], v[194:197], v[52:55]
	v_mfma_f32_16x16x32_bf16 v[48:51], v[176:179], v[194:197], v[48:51]
	v_mfma_f32_16x16x32_bf16 v[32:35], v[176:179], v[202:205], v[32:35]
	v_mfma_f32_16x16x32_bf16 v[36:39], v[148:151], v[202:205], v[36:39]
	v_mfma_f32_16x16x32_bf16 v[20:23], v[148:151], v[210:213], v[20:23]
	v_mfma_f32_16x16x32_bf16 v[16:19], v[176:179], v[210:213], v[16:19]
	v_mfma_f32_16x16x32_bf16 v[0:3], v[176:179], v[218:221], v[0:3]
	v_mfma_f32_16x16x32_bf16 v[4:7], v[148:151], v[218:221], v[4:7]
	s_barrier
	s_add_i32 s72, s72, 2
	s_add_u32 s40, s40, 0x100
	s_addc_u32 s41, s41, 0
	s_add_u32 s70, s70, 0x100
	s_addc_u32 s71, s71, 0
	s_cmp_gt_u32 s72, 13
	s_cbranch_scc1 .Lpeel_exit_1026
.LBB0_1026:
	ds_read_b128 v[128:131], v189
	ds_read_b128 v[132:135], v189 offset:1024
	ds_read_b128 v[136:139], v189 offset:2048
	ds_read_b128 v[140:143], v189 offset:3072
	ds_read_b128 v[144:147], v190
	ds_read_b128 v[148:151], v190 offset:1024
	ds_read_b128 v[172:175], v190 offset:2048
	ds_read_b128 v[176:179], v190 offset:3072
	s_add_u32 s42, s40, 0xfffc0080
	s_addc_u32 s43, s41, -1
	s_cmp_eq_u32 s72, 12
	s_cselect_b32 s63, s27, s43
	s_cselect_b32 s62, s37, s42
	s_cselect_b32 s43, s29, s71
	s_cselect_b32 s42, s39, s70
	s_add_i32 m0, s18, 0xc000
	ds_read_b128 v[180:183], v191
	ds_read_b128 v[194:197], v191 offset:1024
	ds_read_b128 v[198:201], v191 offset:2048
	ds_read_b128 v[202:205], v191 offset:3072
	ds_read_b128 v[206:209], v191 offset:4096
	ds_read_b128 v[210:213], v191 offset:5120
	ds_read_b128 v[214:217], v191 offset:6144
	ds_read_b128 v[218:221], v191 offset:7168
	global_load_lds_dwordx4 v164, s[40:41]
	s_add_i32 m0, s18, 0xe000
	s_nop 0
	global_load_lds_dwordx4 v166, s[40:41]
	s_waitcnt vmcnt(8)
	s_waitcnt lgkmcnt(0)
	s_barrier
	s_waitcnt lgkmcnt(0)
	v_mfma_f32_16x16x32_bf16 v[124:127], v[128:131], v[180:183], v[124:127]
	v_mfma_f32_16x16x32_bf16 v[120:123], v[136:139], v[180:183], v[120:123]
	v_mfma_f32_16x16x32_bf16 v[104:107], v[136:139], v[198:201], v[104:107]
	v_mfma_f32_16x16x32_bf16 v[108:111], v[128:131], v[198:201], v[108:111]
	v_mfma_f32_16x16x32_bf16 v[92:95], v[128:131], v[206:209], v[92:95]
	v_mfma_f32_16x16x32_bf16 v[88:91], v[136:139], v[206:209], v[88:91]
	v_mfma_f32_16x16x32_bf16 v[72:75], v[136:139], v[214:217], v[72:75]
	v_mfma_f32_16x16x32_bf16 v[76:79], v[128:131], v[214:217], v[76:79]
	v_mfma_f32_16x16x32_bf16 v[124:127], v[132:135], v[194:197], v[124:127]
	v_mfma_f32_16x16x32_bf16 v[120:123], v[140:143], v[194:197], v[120:123]
	v_mfma_f32_16x16x32_bf16 v[104:107], v[140:143], v[202:205], v[104:107]
	v_mfma_f32_16x16x32_bf16 v[108:111], v[132:135], v[202:205], v[108:111]
	v_mfma_f32_16x16x32_bf16 v[92:95], v[132:135], v[210:213], v[92:95]
	v_mfma_f32_16x16x32_bf16 v[88:91], v[140:143], v[210:213], v[88:91]
	v_mfma_f32_16x16x32_bf16 v[72:75], v[140:143], v[218:221], v[72:75]
	v_mfma_f32_16x16x32_bf16 v[76:79], v[132:135], v[218:221], v[76:79]
	v_mfma_f32_16x16x32_bf16 v[116:119], v[144:147], v[180:183], v[116:119]
	v_mfma_f32_16x16x32_bf16 v[112:115], v[172:175], v[180:183], v[112:115]
	v_mfma_f32_16x16x32_bf16 v[96:99], v[172:175], v[198:201], v[96:99]
	v_mfma_f32_16x16x32_bf16 v[100:103], v[144:147], v[198:201], v[100:103]
	v_mfma_f32_16x16x32_bf16 v[84:87], v[144:147], v[206:209], v[84:87]
	v_mfma_f32_16x16x32_bf16 v[80:83], v[172:175], v[206:209], v[80:83]
	v_mfma_f32_16x16x32_bf16 v[64:67], v[172:175], v[214:217], v[64:67]
	v_mfma_f32_16x16x32_bf16 v[68:71], v[144:147], v[214:217], v[68:71]
	v_mfma_f32_16x16x32_bf16 v[116:119], v[148:151], v[194:197], v[116:119]
	v_mfma_f32_16x16x32_bf16 v[112:115], v[176:179], v[194:197], v[112:115]
	v_mfma_f32_16x16x32_bf16 v[96:99], v[176:179], v[202:205], v[96:99]
	v_mfma_f32_16x16x32_bf16 v[100:103], v[148:151], v[202:205], v[100:103]
	v_mfma_f32_16x16x32_bf16 v[84:87], v[148:151], v[210:213], v[84:87]
	v_mfma_f32_16x16x32_bf16 v[80:83], v[176:179], v[210:213], v[80:83]
	v_mfma_f32_16x16x32_bf16 v[64:67], v[176:179], v[218:221], v[64:67]
	v_mfma_f32_16x16x32_bf16 v[68:71], v[148:151], v[218:221], v[68:71]
	s_barrier
	s_add_i32 s73, s66, s17
	s_mov_b32 m0, s73
	ds_read_b128 v[180:183], v191 offset:16384
	ds_read_b128 v[194:197], v191 offset:17408
	ds_read_b128 v[198:201], v191 offset:18432
	ds_read_b128 v[202:205], v191 offset:19456
	ds_read_b128 v[206:209], v191 offset:20480
	ds_read_b128 v[210:213], v191 offset:21504
	ds_read_b128 v[214:217], v191 offset:22528
	ds_read_b128 v[218:221], v191 offset:23552
	global_load_lds_dwordx4 v154, s[42:43]
	s_add_i32 m0, s73, 0x2000
	s_add_u32 s74, s42, 0x40000
	s_addc_u32 s75, s43, 0
	s_add_i32 s73, s67, s17
	global_load_lds_dwordx4 v158, s[42:43]
	s_mov_b32 m0, s73
	global_load_lds_dwordx4 v154, s[74:75]
	s_add_i32 m0, s73, 0x2000
	s_nop 0
	global_load_lds_dwordx4 v158, s[74:75]
	s_mov_b32 m0, s18
	s_nop 0
	global_load_lds_dwordx4 v152, s[62:63]
	s_mov_b32 m0, s19
	s_nop 0
	global_load_lds_dwordx4 v156, s[62:63]
	s_add_u32 s98, s42, s12
	s_addc_u32 s99, s43, s13
	s_add_u32 s100, s62, s12
	s_addc_u32 s101, s63, s13
	s_waitcnt vmcnt(8)
	s_waitcnt lgkmcnt(0)
	s_barrier
	s_waitcnt lgkmcnt(0)
	v_mfma_f32_16x16x32_bf16 v[60:63], v[128:131], v[180:183], v[60:63]
	v_mfma_f32_16x16x32_bf16 v[56:59], v[136:139], v[180:183], v[56:59]
	v_mfma_f32_16x16x32_bf16 v[40:43], v[136:139], v[198:201], v[40:43]
	v_mfma_f32_16x16x32_bf16 v[44:47], v[128:131], v[198:201], v[44:47]
	v_mfma_f32_16x16x32_bf16 v[28:31], v[128:131], v[206:209], v[28:31]
	v_mfma_f32_16x16x32_bf16 v[24:27], v[136:139], v[206:209], v[24:27]
	v_mfma_f32_16x16x32_bf16 v[8:11], v[136:139], v[214:217], v[8:11]
	v_mfma_f32_16x16x32_bf16 v[12:15], v[128:131], v[214:217], v[12:15]
	v_mfma_f32_16x16x32_bf16 v[60:63], v[132:135], v[194:197], v[60:63]
	v_mfma_f32_16x16x32_bf16 v[56:59], v[140:143], v[194:197], v[56:59]
	v_mfma_f32_16x16x32_bf16 v[40:43], v[140:143], v[202:205], v[40:43]
	v_mfma_f32_16x16x32_bf16 v[44:47], v[132:135], v[202:205], v[44:47]
	v_mfma_f32_16x16x32_bf16 v[28:31], v[132:135], v[210:213], v[28:31]
	v_mfma_f32_16x16x32_bf16 v[24:27], v[140:143], v[210:213], v[24:27]
	v_mfma_f32_16x16x32_bf16 v[8:11], v[140:143], v[218:221], v[8:11]
	v_mfma_f32_16x16x32_bf16 v[12:15], v[132:135], v[218:221], v[12:15]
	v_mfma_f32_16x16x32_bf16 v[52:55], v[144:147], v[180:183], v[52:55]
	v_mfma_f32_16x16x32_bf16 v[48:51], v[172:175], v[180:183], v[48:51]
	v_mfma_f32_16x16x32_bf16 v[32:35], v[172:175], v[198:201], v[32:35]
	v_mfma_f32_16x16x32_bf16 v[36:39], v[144:147], v[198:201], v[36:39]
	v_mfma_f32_16x16x32_bf16 v[20:23], v[144:147], v[206:209], v[20:23]
	v_mfma_f32_16x16x32_bf16 v[16:19], v[172:175], v[206:209], v[16:19]
	v_mfma_f32_16x16x32_bf16 v[0:3], v[172:175], v[214:217], v[0:3]
	v_mfma_f32_16x16x32_bf16 v[4:7], v[144:147], v[214:217], v[4:7]
	v_mfma_f32_16x16x32_bf16 v[52:55], v[148:151], v[194:197], v[52:55]
	v_mfma_f32_16x16x32_bf16 v[48:51], v[176:179], v[194:197], v[48:51]
	v_mfma_f32_16x16x32_bf16 v[32:35], v[176:179], v[202:205], v[32:35]
	v_mfma_f32_16x16x32_bf16 v[36:39], v[148:151], v[202:205], v[36:39]
	v_mfma_f32_16x16x32_bf16 v[20:23], v[148:151], v[210:213], v[20:23]
	v_mfma_f32_16x16x32_bf16 v[16:19], v[176:179], v[210:213], v[16:19]
	v_mfma_f32_16x16x32_bf16 v[0:3], v[176:179], v[218:221], v[0:3]
	v_mfma_f32_16x16x32_bf16 v[4:7], v[148:151], v[218:221], v[4:7]
	s_barrier
	s_add_i32 s73, 0, 0x18000
	s_add_i32 s74, 0, 0x1c000
	v_add_u32_e32 v140, s73, v186
	v_add_u32_e32 v176, s74, v186
	ds_read_b128 v[128:131], v140
	ds_read_b128 v[132:135], v140 offset:1024
	ds_read_b128 v[136:139], v140 offset:2048
	ds_read_b128 v[140:143], v140 offset:3072
	ds_read_b128 v[144:147], v176
	ds_read_b128 v[148:151], v176 offset:1024
	ds_read_b128 v[172:175], v176 offset:2048
	ds_read_b128 v[176:179], v176 offset:3072
	s_add_u32 s62, s62, 0x40000
	s_addc_u32 s63, s63, 0
	s_mov_b32 m0, s20
	ds_read_b128 v[180:183], v191 offset:32768
	ds_read_b128 v[194:197], v191 offset:33792
	ds_read_b128 v[198:201], v191 offset:34816
	ds_read_b128 v[202:205], v191 offset:35840
	ds_read_b128 v[206:209], v191 offset:36864
	ds_read_b128 v[210:213], v191 offset:37888
	ds_read_b128 v[214:217], v191 offset:38912
	ds_read_b128 v[218:221], v191 offset:39936
	global_load_lds_dwordx4 v152, s[62:63]
	s_mov_b32 m0, s21
	s_nop 0
	global_load_lds_dwordx4 v156, s[62:63]
	s_waitcnt vmcnt(8)
	s_waitcnt lgkmcnt(0)
	s_barrier
	s_waitcnt lgkmcnt(0)
	v_mfma_f32_16x16x32_bf16 v[124:127], v[128:131], v[180:183], v[124:127]
	v_mfma_f32_16x16x32_bf16 v[120:123], v[136:139], v[180:183], v[120:123]
	v_mfma_f32_16x16x32_bf16 v[104:107], v[136:139], v[198:201], v[104:107]
	v_mfma_f32_16x16x32_bf16 v[108:111], v[128:131], v[198:201], v[108:111]
	v_mfma_f32_16x16x32_bf16 v[92:95], v[128:131], v[206:209], v[92:95]
	v_mfma_f32_16x16x32_bf16 v[88:91], v[136:139], v[206:209], v[88:91]
	v_mfma_f32_16x16x32_bf16 v[72:75], v[136:139], v[214:217], v[72:75]
	v_mfma_f32_16x16x32_bf16 v[76:79], v[128:131], v[214:217], v[76:79]
	v_mfma_f32_16x16x32_bf16 v[124:127], v[132:135], v[194:197], v[124:127]
	v_mfma_f32_16x16x32_bf16 v[120:123], v[140:143], v[194:197], v[120:123]
	v_mfma_f32_16x16x32_bf16 v[104:107], v[140:143], v[202:205], v[104:107]
	v_mfma_f32_16x16x32_bf16 v[108:111], v[132:135], v[202:205], v[108:111]
	v_mfma_f32_16x16x32_bf16 v[92:95], v[132:135], v[210:213], v[92:95]
	v_mfma_f32_16x16x32_bf16 v[88:91], v[140:143], v[210:213], v[88:91]
	v_mfma_f32_16x16x32_bf16 v[72:75], v[140:143], v[218:221], v[72:75]
	v_mfma_f32_16x16x32_bf16 v[76:79], v[132:135], v[218:221], v[76:79]
	v_mfma_f32_16x16x32_bf16 v[116:119], v[144:147], v[180:183], v[116:119]
	v_mfma_f32_16x16x32_bf16 v[112:115], v[172:175], v[180:183], v[112:115]
	v_mfma_f32_16x16x32_bf16 v[96:99], v[172:175], v[198:201], v[96:99]
	v_mfma_f32_16x16x32_bf16 v[100:103], v[144:147], v[198:201], v[100:103]
	v_mfma_f32_16x16x32_bf16 v[84:87], v[144:147], v[206:209], v[84:87]
	v_mfma_f32_16x16x32_bf16 v[80:83], v[172:175], v[206:209], v[80:83]
	v_mfma_f32_16x16x32_bf16 v[64:67], v[172:175], v[214:217], v[64:67]
	v_mfma_f32_16x16x32_bf16 v[68:71], v[144:147], v[214:217], v[68:71]
	v_mfma_f32_16x16x32_bf16 v[116:119], v[148:151], v[194:197], v[116:119]
	v_mfma_f32_16x16x32_bf16 v[112:115], v[176:179], v[194:197], v[112:115]
	v_mfma_f32_16x16x32_bf16 v[96:99], v[176:179], v[202:205], v[96:99]
	v_mfma_f32_16x16x32_bf16 v[100:103], v[148:151], v[202:205], v[100:103]
	v_mfma_f32_16x16x32_bf16 v[84:87], v[148:151], v[210:213], v[84:87]
	v_mfma_f32_16x16x32_bf16 v[80:83], v[176:179], v[210:213], v[80:83]
	v_mfma_f32_16x16x32_bf16 v[64:67], v[176:179], v[218:221], v[64:67]
	v_mfma_f32_16x16x32_bf16 v[68:71], v[148:151], v[218:221], v[68:71]
	s_barrier
	s_add_i32 s62, s73, s17
	s_mov_b32 m0, s62
	ds_read_b128 v[180:183], v191 offset:49152
	ds_read_b128 v[194:197], v191 offset:50176
	ds_read_b128 v[198:201], v191 offset:51200
	ds_read_b128 v[202:205], v191 offset:52224
	ds_read_b128 v[206:209], v191 offset:53248
	ds_read_b128 v[210:213], v191 offset:54272
	ds_read_b128 v[214:217], v191 offset:55296
	ds_read_b128 v[218:221], v191 offset:56320
	global_load_lds_dwordx4 v154, s[98:99]
	s_add_i32 m0, s62, 0x2000
	s_add_u32 s42, s42, 0x40080
	s_addc_u32 s43, s43, 0
	s_add_i32 s62, s74, s17
	global_load_lds_dwordx4 v158, s[98:99]
	s_mov_b32 m0, s62
	s_nop 0
	global_load_lds_dwordx4 v154, s[42:43]
	s_add_i32 m0, s62, 0x2000
	s_nop 0
	global_load_lds_dwordx4 v158, s[42:43]
	s_mov_b32 m0, s23
	s_nop 0
	global_load_lds_dwordx4 v152, s[100:101]
	s_mov_b32 m0, s60
	s_nop 0
	global_load_lds_dwordx4 v156, s[100:101]
	s_waitcnt vmcnt(8)
	s_waitcnt lgkmcnt(0)
	s_barrier
	s_waitcnt lgkmcnt(0)
	v_mfma_f32_16x16x32_bf16 v[60:63], v[128:131], v[180:183], v[60:63]
	v_mfma_f32_16x16x32_bf16 v[56:59], v[136:139], v[180:183], v[56:59]
	v_mfma_f32_16x16x32_bf16 v[40:43], v[136:139], v[198:201], v[40:43]
	v_mfma_f32_16x16x32_bf16 v[44:47], v[128:131], v[198:201], v[44:47]
	v_mfma_f32_16x16x32_bf16 v[28:31], v[128:131], v[206:209], v[28:31]
	v_mfma_f32_16x16x32_bf16 v[24:27], v[136:139], v[206:209], v[24:27]
	v_mfma_f32_16x16x32_bf16 v[8:11], v[136:139], v[214:217], v[8:11]
	v_mfma_f32_16x16x32_bf16 v[12:15], v[128:131], v[214:217], v[12:15]
	v_mfma_f32_16x16x32_bf16 v[60:63], v[132:135], v[194:197], v[60:63]
	v_mfma_f32_16x16x32_bf16 v[56:59], v[140:143], v[194:197], v[56:59]
	v_mfma_f32_16x16x32_bf16 v[40:43], v[140:143], v[202:205], v[40:43]
	v_mfma_f32_16x16x32_bf16 v[44:47], v[132:135], v[202:205], v[44:47]
	v_mfma_f32_16x16x32_bf16 v[28:31], v[132:135], v[210:213], v[28:31]
	v_mfma_f32_16x16x32_bf16 v[24:27], v[140:143], v[210:213], v[24:27]
	v_mfma_f32_16x16x32_bf16 v[8:11], v[140:143], v[218:221], v[8:11]
	v_mfma_f32_16x16x32_bf16 v[12:15], v[132:135], v[218:221], v[12:15]
	v_mfma_f32_16x16x32_bf16 v[52:55], v[144:147], v[180:183], v[52:55]
	v_mfma_f32_16x16x32_bf16 v[48:51], v[172:175], v[180:183], v[48:51]
	v_mfma_f32_16x16x32_bf16 v[32:35], v[172:175], v[198:201], v[32:35]
	v_mfma_f32_16x16x32_bf16 v[36:39], v[144:147], v[198:201], v[36:39]
	v_mfma_f32_16x16x32_bf16 v[20:23], v[144:147], v[206:209], v[20:23]
	v_mfma_f32_16x16x32_bf16 v[16:19], v[172:175], v[206:209], v[16:19]
	v_mfma_f32_16x16x32_bf16 v[0:3], v[172:175], v[214:217], v[0:3]
	v_mfma_f32_16x16x32_bf16 v[4:7], v[144:147], v[214:217], v[4:7]
	v_mfma_f32_16x16x32_bf16 v[52:55], v[148:151], v[194:197], v[52:55]
	v_mfma_f32_16x16x32_bf16 v[48:51], v[176:179], v[194:197], v[48:51]
	v_mfma_f32_16x16x32_bf16 v[32:35], v[176:179], v[202:205], v[32:35]
	v_mfma_f32_16x16x32_bf16 v[36:39], v[148:151], v[202:205], v[36:39]
	v_mfma_f32_16x16x32_bf16 v[20:23], v[148:151], v[210:213], v[20:23]
	v_mfma_f32_16x16x32_bf16 v[16:19], v[176:179], v[210:213], v[16:19]
	v_mfma_f32_16x16x32_bf16 v[0:3], v[176:179], v[218:221], v[0:3]
	v_mfma_f32_16x16x32_bf16 v[4:7], v[148:151], v[218:221], v[4:7]
	s_barrier
	s_add_i32 s72, s72, 2
	s_add_u32 s40, s40, 0x100
	s_addc_u32 s41, s41, 0
	s_add_u32 s70, s70, 0x100
	s_addc_u32 s71, s71, 0
	s_cmp_gt_u32 s72, 13
	s_cbranch_scc0 .LBB0_1026

.LBB0_1114:
	s_ashr_i32 s27, s26, 31
	s_lshl_b64 s[30:31], s[26:27], 19
	s_add_u32 s30, s82, s30
	s_addc_u32 s31, s83, s31
	s_and_b64 s[34:35], s[4:5], exec
	s_cselect_b32 s27, s31, s39
	s_cselect_b32 s64, s30, s38
	s_ashr_i32 s29, s28, 31
	s_lshl_b64 s[34:35], s[28:29], 19
	s_add_u32 s34, s6, s34
	s_addc_u32 s35, s7, s35
	s_and_b64 s[42:43], s[4:5], exec
	s_cselect_b32 s29, s35, s41
	s_cselect_b32 s65, s34, s40
	s_add_u32 s38, s38, 0x40080
	s_addc_u32 s39, s39, 0
	s_add_u32 s66, s40, 0x100
	s_addc_u32 s67, s41, 0
	s_mov_b32 s70, -2
	ds_read_b128 v[144:147], v155
	ds_read_b128 v[160:163], v155 offset:1024
	ds_read_b128 v[164:167], v155 offset:2048
	ds_read_b128 v[168:171], v155 offset:3072
	ds_read_b128 v[172:175], v157
	ds_read_b128 v[176:179], v157 offset:1024
	ds_read_b128 v[180:183], v157 offset:2048
	ds_read_b128 v[186:189], v157 offset:3072
	s_add_u32 s40, s38, 0xfffc0080
	s_addc_u32 s41, s39, -1
	s_cmp_eq_u32 s70, 12
	s_cselect_b32 s43, s27, s41
	s_cselect_b32 s42, s64, s40
	s_cselect_b32 s41, s29, s67
	s_cselect_b32 s40, s65, s66
	s_add_i32 m0, s16, 0xc000
	ds_read_b128 v[190:193], v158
	ds_read_b128 v[194:197], v158 offset:1024
	ds_read_b128 v[198:201], v158 offset:2048
	ds_read_b128 v[202:205], v158 offset:3072
	ds_read_b128 v[206:209], v158 offset:4096
	ds_read_b128 v[210:213], v158 offset:5120
	ds_read_b128 v[214:217], v158 offset:6144
	ds_read_b128 v[218:221], v158 offset:7168
	global_load_lds_dwordx4 v136, s[38:39]
	s_add_i32 m0, s16, 0xe000
	s_nop 0
	global_load_lds_dwordx4 v138, s[38:39]
	s_waitcnt vmcnt(8)
	s_waitcnt lgkmcnt(0)
	s_barrier
	s_waitcnt lgkmcnt(0)
	v_mfma_f32_16x16x32_bf16 v[124:127], v[144:147], v[190:193], 0
	v_mfma_f32_16x16x32_bf16 v[120:123], v[164:167], v[190:193], 0
	v_mfma_f32_16x16x32_bf16 v[104:107], v[164:167], v[198:201], 0
	v_mfma_f32_16x16x32_bf16 v[116:119], v[144:147], v[198:201], 0
	v_mfma_f32_16x16x32_bf16 v[92:95], v[144:147], v[206:209], 0
	v_mfma_f32_16x16x32_bf16 v[88:91], v[164:167], v[206:209], 0
	v_mfma_f32_16x16x32_bf16 v[72:75], v[164:167], v[214:217], 0
	v_mfma_f32_16x16x32_bf16 v[76:79], v[144:147], v[214:217], 0
	v_mfma_f32_16x16x32_bf16 v[124:127], v[160:163], v[194:197], v[124:127]
	v_mfma_f32_16x16x32_bf16 v[120:123], v[168:171], v[194:197], v[120:123]
	v_mfma_f32_16x16x32_bf16 v[104:107], v[168:171], v[202:205], v[104:107]
	v_mfma_f32_16x16x32_bf16 v[116:119], v[160:163], v[202:205], v[116:119]
	v_mfma_f32_16x16x32_bf16 v[92:95], v[160:163], v[210:213], v[92:95]
	v_mfma_f32_16x16x32_bf16 v[88:91], v[168:171], v[210:213], v[88:91]
	v_mfma_f32_16x16x32_bf16 v[72:75], v[168:171], v[218:221], v[72:75]
	v_mfma_f32_16x16x32_bf16 v[76:79], v[160:163], v[218:221], v[76:79]
	v_mfma_f32_16x16x32_bf16 v[112:115], v[172:175], v[190:193], 0
	v_mfma_f32_16x16x32_bf16 v[108:111], v[180:183], v[190:193], 0
	v_mfma_f32_16x16x32_bf16 v[96:99], v[180:183], v[198:201], 0
	v_mfma_f32_16x16x32_bf16 v[100:103], v[172:175], v[198:201], 0
	v_mfma_f32_16x16x32_bf16 v[84:87], v[172:175], v[206:209], 0
	v_mfma_f32_16x16x32_bf16 v[80:83], v[180:183], v[206:209], 0
	v_mfma_f32_16x16x32_bf16 v[64:67], v[180:183], v[214:217], 0
	v_mfma_f32_16x16x32_bf16 v[68:71], v[172:175], v[214:217], 0
	v_mfma_f32_16x16x32_bf16 v[112:115], v[176:179], v[194:197], v[112:115]
	v_mfma_f32_16x16x32_bf16 v[108:111], v[186:189], v[194:197], v[108:111]
	v_mfma_f32_16x16x32_bf16 v[96:99], v[186:189], v[202:205], v[96:99]
	v_mfma_f32_16x16x32_bf16 v[100:103], v[176:179], v[202:205], v[100:103]
	v_mfma_f32_16x16x32_bf16 v[84:87], v[176:179], v[210:213], v[84:87]
	v_mfma_f32_16x16x32_bf16 v[80:83], v[186:189], v[210:213], v[80:83]
	v_mfma_f32_16x16x32_bf16 v[64:67], v[186:189], v[218:221], v[64:67]
	v_mfma_f32_16x16x32_bf16 v[68:71], v[176:179], v[218:221], v[68:71]
	s_barrier
	s_add_i32 s71, s60, s3
	s_mov_b32 m0, s71
	ds_read_b128 v[190:193], v158 offset:16384
	ds_read_b128 v[194:197], v158 offset:17408
	ds_read_b128 v[198:201], v158 offset:18432
	ds_read_b128 v[202:205], v158 offset:19456
	ds_read_b128 v[206:209], v158 offset:20480
	ds_read_b128 v[210:213], v158 offset:21504
	ds_read_b128 v[214:217], v158 offset:22528
	ds_read_b128 v[218:221], v158 offset:23552
	global_load_lds_dwordx4 v132, s[40:41]
	s_add_i32 m0, s71, 0x2000
	s_add_u32 s72, s40, 0x40000
	s_addc_u32 s73, s41, 0
	s_add_i32 s71, s61, s3
	global_load_lds_dwordx4 v128, s[40:41]
	s_mov_b32 m0, s71
	global_load_lds_dwordx4 v132, s[72:73]
	s_add_i32 m0, s71, 0x2000
	s_nop 0
	global_load_lds_dwordx4 v128, s[72:73]
	s_mov_b32 m0, s16
	s_nop 0
	global_load_lds_dwordx4 v134, s[42:43]
	s_mov_b32 m0, s17
	s_nop 0
	global_load_lds_dwordx4 v130, s[42:43]
	s_add_u32 s98, s40, s12
	s_addc_u32 s99, s41, s13
	s_add_u32 s100, s42, s12
	s_addc_u32 s101, s43, s13
	s_waitcnt vmcnt(8)
	s_waitcnt lgkmcnt(0)
	s_barrier
	s_waitcnt lgkmcnt(0)
	v_mfma_f32_16x16x32_bf16 v[60:63], v[144:147], v[190:193], 0
	v_mfma_f32_16x16x32_bf16 v[56:59], v[164:167], v[190:193], 0
	v_mfma_f32_16x16x32_bf16 v[40:43], v[164:167], v[198:201], 0
	v_mfma_f32_16x16x32_bf16 v[44:47], v[144:147], v[198:201], 0
	v_mfma_f32_16x16x32_bf16 v[28:31], v[144:147], v[206:209], 0
	v_mfma_f32_16x16x32_bf16 v[24:27], v[164:167], v[206:209], 0
	v_mfma_f32_16x16x32_bf16 v[8:11], v[164:167], v[214:217], 0
	v_mfma_f32_16x16x32_bf16 v[12:15], v[144:147], v[214:217], 0
	v_mfma_f32_16x16x32_bf16 v[60:63], v[160:163], v[194:197], v[60:63]
	v_mfma_f32_16x16x32_bf16 v[56:59], v[168:171], v[194:197], v[56:59]
	v_mfma_f32_16x16x32_bf16 v[40:43], v[168:171], v[202:205], v[40:43]
	v_mfma_f32_16x16x32_bf16 v[44:47], v[160:163], v[202:205], v[44:47]
	v_mfma_f32_16x16x32_bf16 v[28:31], v[160:163], v[210:213], v[28:31]
	v_mfma_f32_16x16x32_bf16 v[24:27], v[168:171], v[210:213], v[24:27]
	v_mfma_f32_16x16x32_bf16 v[8:11], v[168:171], v[218:221], v[8:11]
	v_mfma_f32_16x16x32_bf16 v[12:15], v[160:163], v[218:221], v[12:15]
	v_mfma_f32_16x16x32_bf16 v[52:55], v[172:175], v[190:193], 0
	v_mfma_f32_16x16x32_bf16 v[48:51], v[180:183], v[190:193], 0
	v_mfma_f32_16x16x32_bf16 v[32:35], v[180:183], v[198:201], 0
	v_mfma_f32_16x16x32_bf16 v[36:39], v[172:175], v[198:201], 0
	v_mfma_f32_16x16x32_bf16 v[20:23], v[172:175], v[206:209], 0
	v_mfma_f32_16x16x32_bf16 v[16:19], v[180:183], v[206:209], 0
	v_mfma_f32_16x16x32_bf16 v[0:3], v[180:183], v[214:217], 0
	v_mfma_f32_16x16x32_bf16 v[4:7], v[172:175], v[214:217], 0
	v_mfma_f32_16x16x32_bf16 v[52:55], v[176:179], v[194:197], v[52:55]
	v_mfma_f32_16x16x32_bf16 v[48:51], v[186:189], v[194:197], v[48:51]
	v_mfma_f32_16x16x32_bf16 v[32:35], v[186:189], v[202:205], v[32:35]
	v_mfma_f32_16x16x32_bf16 v[36:39], v[176:179], v[202:205], v[36:39]
	v_mfma_f32_16x16x32_bf16 v[20:23], v[176:179], v[210:213], v[20:23]
	v_mfma_f32_16x16x32_bf16 v[16:19], v[186:189], v[210:213], v[16:19]
	v_mfma_f32_16x16x32_bf16 v[0:3], v[186:189], v[218:221], v[0:3]
	v_mfma_f32_16x16x32_bf16 v[4:7], v[176:179], v[218:221], v[4:7]
	s_barrier
	s_add_i32 s71, 0, 0x18000
	v_add_u32_e32 v148, s71, v151
	s_add_i32 s72, 0, 0x1c000
	ds_read_b128 v[144:147], v148
	ds_read_b128 v[160:163], v148 offset:1024
	ds_read_b128 v[164:167], v148 offset:2048
	ds_read_b128 v[168:171], v148 offset:3072
	v_add_u32_e32 v148, s72, v151
	ds_read_b128 v[172:175], v148
	ds_read_b128 v[176:179], v148 offset:1024
	ds_read_b128 v[180:183], v148 offset:2048
	ds_read_b128 v[186:189], v148 offset:3072
	s_add_u32 s42, s42, 0x40000
	s_addc_u32 s43, s43, 0
	s_mov_b32 m0, s18
	ds_read_b128 v[190:193], v158 offset:32768
	ds_read_b128 v[194:197], v158 offset:33792
	ds_read_b128 v[198:201], v158 offset:34816
	ds_read_b128 v[202:205], v158 offset:35840
	ds_read_b128 v[206:209], v158 offset:36864
	ds_read_b128 v[210:213], v158 offset:37888
	ds_read_b128 v[214:217], v158 offset:38912
	ds_read_b128 v[218:221], v158 offset:39936
	global_load_lds_dwordx4 v134, s[42:43]
	s_mov_b32 m0, s19
	s_nop 0
	global_load_lds_dwordx4 v130, s[42:43]
	s_waitcnt vmcnt(8)
	s_waitcnt lgkmcnt(0)
	s_barrier
	s_waitcnt lgkmcnt(0)
	v_mfma_f32_16x16x32_bf16 v[124:127], v[144:147], v[190:193], v[124:127]
	v_mfma_f32_16x16x32_bf16 v[120:123], v[164:167], v[190:193], v[120:123]
	v_mfma_f32_16x16x32_bf16 v[104:107], v[164:167], v[198:201], v[104:107]
	v_mfma_f32_16x16x32_bf16 v[116:119], v[144:147], v[198:201], v[116:119]
	v_mfma_f32_16x16x32_bf16 v[92:95], v[144:147], v[206:209], v[92:95]
	v_mfma_f32_16x16x32_bf16 v[88:91], v[164:167], v[206:209], v[88:91]
	v_mfma_f32_16x16x32_bf16 v[72:75], v[164:167], v[214:217], v[72:75]
	v_mfma_f32_16x16x32_bf16 v[76:79], v[144:147], v[214:217], v[76:79]
	v_mfma_f32_16x16x32_bf16 v[124:127], v[160:163], v[194:197], v[124:127]
	v_mfma_f32_16x16x32_bf16 v[120:123], v[168:171], v[194:197], v[120:123]
	v_mfma_f32_16x16x32_bf16 v[104:107], v[168:171], v[202:205], v[104:107]
	v_mfma_f32_16x16x32_bf16 v[116:119], v[160:163], v[202:205], v[116:119]
	v_mfma_f32_16x16x32_bf16 v[92:95], v[160:163], v[210:213], v[92:95]
	v_mfma_f32_16x16x32_bf16 v[88:91], v[168:171], v[210:213], v[88:91]
	v_mfma_f32_16x16x32_bf16 v[72:75], v[168:171], v[218:221], v[72:75]
	v_mfma_f32_16x16x32_bf16 v[76:79], v[160:163], v[218:221], v[76:79]
	v_mfma_f32_16x16x32_bf16 v[112:115], v[172:175], v[190:193], v[112:115]
	v_mfma_f32_16x16x32_bf16 v[108:111], v[180:183], v[190:193], v[108:111]
	v_mfma_f32_16x16x32_bf16 v[96:99], v[180:183], v[198:201], v[96:99]
	v_mfma_f32_16x16x32_bf16 v[100:103], v[172:175], v[198:201], v[100:103]
	v_mfma_f32_16x16x32_bf16 v[84:87], v[172:175], v[206:209], v[84:87]
	v_mfma_f32_16x16x32_bf16 v[80:83], v[180:183], v[206:209], v[80:83]
	v_mfma_f32_16x16x32_bf16 v[64:67], v[180:183], v[214:217], v[64:67]
	v_mfma_f32_16x16x32_bf16 v[68:71], v[172:175], v[214:217], v[68:71]
	v_mfma_f32_16x16x32_bf16 v[112:115], v[176:179], v[194:197], v[112:115]
	v_mfma_f32_16x16x32_bf16 v[108:111], v[186:189], v[194:197], v[108:111]
	v_mfma_f32_16x16x32_bf16 v[96:99], v[186:189], v[202:205], v[96:99]
	v_mfma_f32_16x16x32_bf16 v[100:103], v[176:179], v[202:205], v[100:103]
	v_mfma_f32_16x16x32_bf16 v[84:87], v[176:179], v[210:213], v[84:87]
	v_mfma_f32_16x16x32_bf16 v[80:83], v[186:189], v[210:213], v[80:83]
	v_mfma_f32_16x16x32_bf16 v[64:67], v[186:189], v[218:221], v[64:67]
	v_mfma_f32_16x16x32_bf16 v[68:71], v[176:179], v[218:221], v[68:71]
	s_barrier
	s_add_i32 s42, s71, s3
	s_mov_b32 m0, s42
	ds_read_b128 v[190:193], v158 offset:49152
	ds_read_b128 v[194:197], v158 offset:50176
	ds_read_b128 v[198:201], v158 offset:51200
	ds_read_b128 v[202:205], v158 offset:52224
	ds_read_b128 v[206:209], v158 offset:53248
	ds_read_b128 v[210:213], v158 offset:54272
	ds_read_b128 v[214:217], v158 offset:55296
	ds_read_b128 v[218:221], v158 offset:56320
	global_load_lds_dwordx4 v132, s[98:99]
	s_add_i32 m0, s42, 0x2000
	s_add_u32 s40, s40, 0x40080
	s_addc_u32 s41, s41, 0
	s_add_i32 s42, s72, s3
	global_load_lds_dwordx4 v128, s[98:99]
	s_mov_b32 m0, s42
	s_nop 0
	global_load_lds_dwordx4 v132, s[40:41]
	s_add_i32 m0, s42, 0x2000
	s_nop 0
	global_load_lds_dwordx4 v128, s[40:41]
	s_mov_b32 m0, s21
	s_nop 0
	global_load_lds_dwordx4 v134, s[100:101]
	s_mov_b32 m0, s22
	s_nop 0
	global_load_lds_dwordx4 v130, s[100:101]
	s_waitcnt vmcnt(8)
	s_waitcnt lgkmcnt(0)
	s_barrier
	s_waitcnt lgkmcnt(0)
	v_mfma_f32_16x16x32_bf16 v[60:63], v[144:147], v[190:193], v[60:63]
	v_mfma_f32_16x16x32_bf16 v[56:59], v[164:167], v[190:193], v[56:59]
	v_mfma_f32_16x16x32_bf16 v[40:43], v[164:167], v[198:201], v[40:43]
	v_mfma_f32_16x16x32_bf16 v[44:47], v[144:147], v[198:201], v[44:47]
	v_mfma_f32_16x16x32_bf16 v[28:31], v[144:147], v[206:209], v[28:31]
	v_mfma_f32_16x16x32_bf16 v[24:27], v[164:167], v[206:209], v[24:27]
	v_mfma_f32_16x16x32_bf16 v[8:11], v[164:167], v[214:217], v[8:11]
	v_mfma_f32_16x16x32_bf16 v[12:15], v[144:147], v[214:217], v[12:15]
	v_mfma_f32_16x16x32_bf16 v[60:63], v[160:163], v[194:197], v[60:63]
	v_mfma_f32_16x16x32_bf16 v[56:59], v[168:171], v[194:197], v[56:59]
	v_mfma_f32_16x16x32_bf16 v[40:43], v[168:171], v[202:205], v[40:43]
	v_mfma_f32_16x16x32_bf16 v[44:47], v[160:163], v[202:205], v[44:47]
	v_mfma_f32_16x16x32_bf16 v[28:31], v[160:163], v[210:213], v[28:31]
	v_mfma_f32_16x16x32_bf16 v[24:27], v[168:171], v[210:213], v[24:27]
	v_mfma_f32_16x16x32_bf16 v[8:11], v[168:171], v[218:221], v[8:11]
	v_mfma_f32_16x16x32_bf16 v[12:15], v[160:163], v[218:221], v[12:15]
	v_mfma_f32_16x16x32_bf16 v[52:55], v[172:175], v[190:193], v[52:55]
	v_mfma_f32_16x16x32_bf16 v[48:51], v[180:183], v[190:193], v[48:51]
	v_mfma_f32_16x16x32_bf16 v[32:35], v[180:183], v[198:201], v[32:35]
	v_mfma_f32_16x16x32_bf16 v[36:39], v[172:175], v[198:201], v[36:39]
	v_mfma_f32_16x16x32_bf16 v[20:23], v[172:175], v[206:209], v[20:23]
	v_mfma_f32_16x16x32_bf16 v[16:19], v[180:183], v[206:209], v[16:19]
	v_mfma_f32_16x16x32_bf16 v[0:3], v[180:183], v[214:217], v[0:3]
	v_mfma_f32_16x16x32_bf16 v[4:7], v[172:175], v[214:217], v[4:7]
	v_mfma_f32_16x16x32_bf16 v[52:55], v[176:179], v[194:197], v[52:55]
	v_mfma_f32_16x16x32_bf16 v[48:51], v[186:189], v[194:197], v[48:51]
	v_mfma_f32_16x16x32_bf16 v[32:35], v[186:189], v[202:205], v[32:35]
	v_mfma_f32_16x16x32_bf16 v[36:39], v[176:179], v[202:205], v[36:39]
	v_mfma_f32_16x16x32_bf16 v[20:23], v[176:179], v[210:213], v[20:23]
	v_mfma_f32_16x16x32_bf16 v[16:19], v[186:189], v[210:213], v[16:19]
	v_mfma_f32_16x16x32_bf16 v[0:3], v[186:189], v[218:221], v[0:3]
	v_mfma_f32_16x16x32_bf16 v[4:7], v[176:179], v[218:221], v[4:7]
	s_barrier
	s_add_i32 s70, s70, 2
	s_add_u32 s38, s38, 0x100
	s_addc_u32 s39, s39, 0
	s_add_u32 s66, s66, 0x100
	s_addc_u32 s67, s67, 0
	s_cmp_gt_u32 s70, 13
	s_cbranch_scc1 .Lpeel_exit_1115
.LBB0_1115:
	ds_read_b128 v[144:147], v155
	ds_read_b128 v[160:163], v155 offset:1024
	ds_read_b128 v[164:167], v155 offset:2048
	ds_read_b128 v[168:171], v155 offset:3072
	ds_read_b128 v[172:175], v157
	ds_read_b128 v[176:179], v157 offset:1024
	ds_read_b128 v[180:183], v157 offset:2048
	ds_read_b128 v[186:189], v157 offset:3072
	s_add_u32 s40, s38, 0xfffc0080
	s_addc_u32 s41, s39, -1
	s_cmp_eq_u32 s70, 12
	s_cselect_b32 s43, s27, s41
	s_cselect_b32 s42, s64, s40
	s_cselect_b32 s41, s29, s67
	s_cselect_b32 s40, s65, s66
	s_add_i32 m0, s16, 0xc000
	ds_read_b128 v[190:193], v158
	ds_read_b128 v[194:197], v158 offset:1024
	ds_read_b128 v[198:201], v158 offset:2048
	ds_read_b128 v[202:205], v158 offset:3072
	ds_read_b128 v[206:209], v158 offset:4096
	ds_read_b128 v[210:213], v158 offset:5120
	ds_read_b128 v[214:217], v158 offset:6144
	ds_read_b128 v[218:221], v158 offset:7168
	global_load_lds_dwordx4 v136, s[38:39]
	s_add_i32 m0, s16, 0xe000
	s_nop 0
	global_load_lds_dwordx4 v138, s[38:39]
	s_waitcnt vmcnt(8)
	s_waitcnt lgkmcnt(0)
	s_barrier
	s_waitcnt lgkmcnt(0)
	v_mfma_f32_16x16x32_bf16 v[124:127], v[144:147], v[190:193], v[124:127]
	v_mfma_f32_16x16x32_bf16 v[120:123], v[164:167], v[190:193], v[120:123]
	v_mfma_f32_16x16x32_bf16 v[104:107], v[164:167], v[198:201], v[104:107]
	v_mfma_f32_16x16x32_bf16 v[116:119], v[144:147], v[198:201], v[116:119]
	v_mfma_f32_16x16x32_bf16 v[92:95], v[144:147], v[206:209], v[92:95]
	v_mfma_f32_16x16x32_bf16 v[88:91], v[164:167], v[206:209], v[88:91]
	v_mfma_f32_16x16x32_bf16 v[72:75], v[164:167], v[214:217], v[72:75]
	v_mfma_f32_16x16x32_bf16 v[76:79], v[144:147], v[214:217], v[76:79]
	v_mfma_f32_16x16x32_bf16 v[124:127], v[160:163], v[194:197], v[124:127]
	v_mfma_f32_16x16x32_bf16 v[120:123], v[168:171], v[194:197], v[120:123]
	v_mfma_f32_16x16x32_bf16 v[104:107], v[168:171], v[202:205], v[104:107]
	v_mfma_f32_16x16x32_bf16 v[116:119], v[160:163], v[202:205], v[116:119]
	v_mfma_f32_16x16x32_bf16 v[92:95], v[160:163], v[210:213], v[92:95]
	v_mfma_f32_16x16x32_bf16 v[88:91], v[168:171], v[210:213], v[88:91]
	v_mfma_f32_16x16x32_bf16 v[72:75], v[168:171], v[218:221], v[72:75]
	v_mfma_f32_16x16x32_bf16 v[76:79], v[160:163], v[218:221], v[76:79]
	v_mfma_f32_16x16x32_bf16 v[112:115], v[172:175], v[190:193], v[112:115]
	v_mfma_f32_16x16x32_bf16 v[108:111], v[180:183], v[190:193], v[108:111]
	v_mfma_f32_16x16x32_bf16 v[96:99], v[180:183], v[198:201], v[96:99]
	v_mfma_f32_16x16x32_bf16 v[100:103], v[172:175], v[198:201], v[100:103]
	v_mfma_f32_16x16x32_bf16 v[84:87], v[172:175], v[206:209], v[84:87]
	v_mfma_f32_16x16x32_bf16 v[80:83], v[180:183], v[206:209], v[80:83]
	v_mfma_f32_16x16x32_bf16 v[64:67], v[180:183], v[214:217], v[64:67]
	v_mfma_f32_16x16x32_bf16 v[68:71], v[172:175], v[214:217], v[68:71]
	v_mfma_f32_16x16x32_bf16 v[112:115], v[176:179], v[194:197], v[112:115]
	v_mfma_f32_16x16x32_bf16 v[108:111], v[186:189], v[194:197], v[108:111]
	v_mfma_f32_16x16x32_bf16 v[96:99], v[186:189], v[202:205], v[96:99]
	v_mfma_f32_16x16x32_bf16 v[100:103], v[176:179], v[202:205], v[100:103]
	v_mfma_f32_16x16x32_bf16 v[84:87], v[176:179], v[210:213], v[84:87]
	v_mfma_f32_16x16x32_bf16 v[80:83], v[186:189], v[210:213], v[80:83]
	v_mfma_f32_16x16x32_bf16 v[64:67], v[186:189], v[218:221], v[64:67]
	v_mfma_f32_16x16x32_bf16 v[68:71], v[176:179], v[218:221], v[68:71]
	s_barrier
	s_add_i32 s71, s60, s3
	s_mov_b32 m0, s71
	ds_read_b128 v[190:193], v158 offset:16384
	ds_read_b128 v[194:197], v158 offset:17408
	ds_read_b128 v[198:201], v158 offset:18432
	ds_read_b128 v[202:205], v158 offset:19456
	ds_read_b128 v[206:209], v158 offset:20480
	ds_read_b128 v[210:213], v158 offset:21504
	ds_read_b128 v[214:217], v158 offset:22528
	ds_read_b128 v[218:221], v158 offset:23552
	global_load_lds_dwordx4 v132, s[40:41]
	s_add_i32 m0, s71, 0x2000
	s_add_u32 s72, s40, 0x40000
	s_addc_u32 s73, s41, 0
	s_add_i32 s71, s61, s3
	global_load_lds_dwordx4 v128, s[40:41]
	s_mov_b32 m0, s71
	global_load_lds_dwordx4 v132, s[72:73]
	s_add_i32 m0, s71, 0x2000
	s_nop 0
	global_load_lds_dwordx4 v128, s[72:73]
	s_mov_b32 m0, s16
	s_nop 0
	global_load_lds_dwordx4 v134, s[42:43]
	s_mov_b32 m0, s17
	s_nop 0
	global_load_lds_dwordx4 v130, s[42:43]
	s_add_u32 s98, s40, s12
	s_addc_u32 s99, s41, s13
	s_add_u32 s100, s42, s12
	s_addc_u32 s101, s43, s13
	s_waitcnt vmcnt(8)
	s_waitcnt lgkmcnt(0)
	s_barrier
	s_waitcnt lgkmcnt(0)
	v_mfma_f32_16x16x32_bf16 v[60:63], v[144:147], v[190:193], v[60:63]
	v_mfma_f32_16x16x32_bf16 v[56:59], v[164:167], v[190:193], v[56:59]
	v_mfma_f32_16x16x32_bf16 v[40:43], v[164:167], v[198:201], v[40:43]
	v_mfma_f32_16x16x32_bf16 v[44:47], v[144:147], v[198:201], v[44:47]
	v_mfma_f32_16x16x32_bf16 v[28:31], v[144:147], v[206:209], v[28:31]
	v_mfma_f32_16x16x32_bf16 v[24:27], v[164:167], v[206:209], v[24:27]
	v_mfma_f32_16x16x32_bf16 v[8:11], v[164:167], v[214:217], v[8:11]
	v_mfma_f32_16x16x32_bf16 v[12:15], v[144:147], v[214:217], v[12:15]
	v_mfma_f32_16x16x32_bf16 v[60:63], v[160:163], v[194:197], v[60:63]
	v_mfma_f32_16x16x32_bf16 v[56:59], v[168:171], v[194:197], v[56:59]
	v_mfma_f32_16x16x32_bf16 v[40:43], v[168:171], v[202:205], v[40:43]
	v_mfma_f32_16x16x32_bf16 v[44:47], v[160:163], v[202:205], v[44:47]
	v_mfma_f32_16x16x32_bf16 v[28:31], v[160:163], v[210:213], v[28:31]
	v_mfma_f32_16x16x32_bf16 v[24:27], v[168:171], v[210:213], v[24:27]
	v_mfma_f32_16x16x32_bf16 v[8:11], v[168:171], v[218:221], v[8:11]
	v_mfma_f32_16x16x32_bf16 v[12:15], v[160:163], v[218:221], v[12:15]
	v_mfma_f32_16x16x32_bf16 v[52:55], v[172:175], v[190:193], v[52:55]
	v_mfma_f32_16x16x32_bf16 v[48:51], v[180:183], v[190:193], v[48:51]
	v_mfma_f32_16x16x32_bf16 v[32:35], v[180:183], v[198:201], v[32:35]
	v_mfma_f32_16x16x32_bf16 v[36:39], v[172:175], v[198:201], v[36:39]
	v_mfma_f32_16x16x32_bf16 v[20:23], v[172:175], v[206:209], v[20:23]
	v_mfma_f32_16x16x32_bf16 v[16:19], v[180:183], v[206:209], v[16:19]
	v_mfma_f32_16x16x32_bf16 v[0:3], v[180:183], v[214:217], v[0:3]
	v_mfma_f32_16x16x32_bf16 v[4:7], v[172:175], v[214:217], v[4:7]
	v_mfma_f32_16x16x32_bf16 v[52:55], v[176:179], v[194:197], v[52:55]
	v_mfma_f32_16x16x32_bf16 v[48:51], v[186:189], v[194:197], v[48:51]
	v_mfma_f32_16x16x32_bf16 v[32:35], v[186:189], v[202:205], v[32:35]
	v_mfma_f32_16x16x32_bf16 v[36:39], v[176:179], v[202:205], v[36:39]
	v_mfma_f32_16x16x32_bf16 v[20:23], v[176:179], v[210:213], v[20:23]
	v_mfma_f32_16x16x32_bf16 v[16:19], v[186:189], v[210:213], v[16:19]
	v_mfma_f32_16x16x32_bf16 v[0:3], v[186:189], v[218:221], v[0:3]
	v_mfma_f32_16x16x32_bf16 v[4:7], v[176:179], v[218:221], v[4:7]
	s_barrier
	s_add_i32 s71, 0, 0x18000
	v_add_u32_e32 v148, s71, v151
	s_add_i32 s72, 0, 0x1c000
	ds_read_b128 v[144:147], v148
	ds_read_b128 v[160:163], v148 offset:1024
	ds_read_b128 v[164:167], v148 offset:2048
	ds_read_b128 v[168:171], v148 offset:3072
	v_add_u32_e32 v148, s72, v151
	ds_read_b128 v[172:175], v148
	ds_read_b128 v[176:179], v148 offset:1024
	ds_read_b128 v[180:183], v148 offset:2048
	ds_read_b128 v[186:189], v148 offset:3072
	s_add_u32 s42, s42, 0x40000
	s_addc_u32 s43, s43, 0
	s_mov_b32 m0, s18
	ds_read_b128 v[190:193], v158 offset:32768
	ds_read_b128 v[194:197], v158 offset:33792
	ds_read_b128 v[198:201], v158 offset:34816
	ds_read_b128 v[202:205], v158 offset:35840
	ds_read_b128 v[206:209], v158 offset:36864
	ds_read_b128 v[210:213], v158 offset:37888
	ds_read_b128 v[214:217], v158 offset:38912
	ds_read_b128 v[218:221], v158 offset:39936
	global_load_lds_dwordx4 v134, s[42:43]
	s_mov_b32 m0, s19
	s_nop 0
	global_load_lds_dwordx4 v130, s[42:43]
	s_waitcnt vmcnt(8)
	s_waitcnt lgkmcnt(0)
	s_barrier
	s_waitcnt lgkmcnt(0)
	v_mfma_f32_16x16x32_bf16 v[124:127], v[144:147], v[190:193], v[124:127]
	v_mfma_f32_16x16x32_bf16 v[120:123], v[164:167], v[190:193], v[120:123]
	v_mfma_f32_16x16x32_bf16 v[104:107], v[164:167], v[198:201], v[104:107]
	v_mfma_f32_16x16x32_bf16 v[116:119], v[144:147], v[198:201], v[116:119]
	v_mfma_f32_16x16x32_bf16 v[92:95], v[144:147], v[206:209], v[92:95]
	v_mfma_f32_16x16x32_bf16 v[88:91], v[164:167], v[206:209], v[88:91]
	v_mfma_f32_16x16x32_bf16 v[72:75], v[164:167], v[214:217], v[72:75]
	v_mfma_f32_16x16x32_bf16 v[76:79], v[144:147], v[214:217], v[76:79]
	v_mfma_f32_16x16x32_bf16 v[124:127], v[160:163], v[194:197], v[124:127]
	v_mfma_f32_16x16x32_bf16 v[120:123], v[168:171], v[194:197], v[120:123]
	v_mfma_f32_16x16x32_bf16 v[104:107], v[168:171], v[202:205], v[104:107]
	v_mfma_f32_16x16x32_bf16 v[116:119], v[160:163], v[202:205], v[116:119]
	v_mfma_f32_16x16x32_bf16 v[92:95], v[160:163], v[210:213], v[92:95]
	v_mfma_f32_16x16x32_bf16 v[88:91], v[168:171], v[210:213], v[88:91]
	v_mfma_f32_16x16x32_bf16 v[72:75], v[168:171], v[218:221], v[72:75]
	v_mfma_f32_16x16x32_bf16 v[76:79], v[160:163], v[218:221], v[76:79]
	v_mfma_f32_16x16x32_bf16 v[112:115], v[172:175], v[190:193], v[112:115]
	v_mfma_f32_16x16x32_bf16 v[108:111], v[180:183], v[190:193], v[108:111]
	v_mfma_f32_16x16x32_bf16 v[96:99], v[180:183], v[198:201], v[96:99]
	v_mfma_f32_16x16x32_bf16 v[100:103], v[172:175], v[198:201], v[100:103]
	v_mfma_f32_16x16x32_bf16 v[84:87], v[172:175], v[206:209], v[84:87]
	v_mfma_f32_16x16x32_bf16 v[80:83], v[180:183], v[206:209], v[80:83]
	v_mfma_f32_16x16x32_bf16 v[64:67], v[180:183], v[214:217], v[64:67]
	v_mfma_f32_16x16x32_bf16 v[68:71], v[172:175], v[214:217], v[68:71]
	v_mfma_f32_16x16x32_bf16 v[112:115], v[176:179], v[194:197], v[112:115]
	v_mfma_f32_16x16x32_bf16 v[108:111], v[186:189], v[194:197], v[108:111]
	v_mfma_f32_16x16x32_bf16 v[96:99], v[186:189], v[202:205], v[96:99]
	v_mfma_f32_16x16x32_bf16 v[100:103], v[176:179], v[202:205], v[100:103]
	v_mfma_f32_16x16x32_bf16 v[84:87], v[176:179], v[210:213], v[84:87]
	v_mfma_f32_16x16x32_bf16 v[80:83], v[186:189], v[210:213], v[80:83]
	v_mfma_f32_16x16x32_bf16 v[64:67], v[186:189], v[218:221], v[64:67]
	v_mfma_f32_16x16x32_bf16 v[68:71], v[176:179], v[218:221], v[68:71]
	s_barrier
	s_add_i32 s42, s71, s3
	s_mov_b32 m0, s42
	ds_read_b128 v[190:193], v158 offset:49152
	ds_read_b128 v[194:197], v158 offset:50176
	ds_read_b128 v[198:201], v158 offset:51200
	ds_read_b128 v[202:205], v158 offset:52224
	ds_read_b128 v[206:209], v158 offset:53248
	ds_read_b128 v[210:213], v158 offset:54272
	ds_read_b128 v[214:217], v158 offset:55296
	ds_read_b128 v[218:221], v158 offset:56320
	global_load_lds_dwordx4 v132, s[98:99]
	s_add_i32 m0, s42, 0x2000
	s_add_u32 s40, s40, 0x40080
	s_addc_u32 s41, s41, 0
	s_add_i32 s42, s72, s3
	global_load_lds_dwordx4 v128, s[98:99]
	s_mov_b32 m0, s42
	s_nop 0
	global_load_lds_dwordx4 v132, s[40:41]
	s_add_i32 m0, s42, 0x2000
	s_nop 0
	global_load_lds_dwordx4 v128, s[40:41]
	s_mov_b32 m0, s21
	s_nop 0
	global_load_lds_dwordx4 v134, s[100:101]
	s_mov_b32 m0, s22
	s_nop 0
	global_load_lds_dwordx4 v130, s[100:101]
	s_waitcnt vmcnt(8)
	s_waitcnt lgkmcnt(0)
	s_barrier
	s_waitcnt lgkmcnt(0)
	v_mfma_f32_16x16x32_bf16 v[60:63], v[144:147], v[190:193], v[60:63]
	v_mfma_f32_16x16x32_bf16 v[56:59], v[164:167], v[190:193], v[56:59]
	v_mfma_f32_16x16x32_bf16 v[40:43], v[164:167], v[198:201], v[40:43]
	v_mfma_f32_16x16x32_bf16 v[44:47], v[144:147], v[198:201], v[44:47]
	v_mfma_f32_16x16x32_bf16 v[28:31], v[144:147], v[206:209], v[28:31]
	v_mfma_f32_16x16x32_bf16 v[24:27], v[164:167], v[206:209], v[24:27]
	v_mfma_f32_16x16x32_bf16 v[8:11], v[164:167], v[214:217], v[8:11]
	v_mfma_f32_16x16x32_bf16 v[12:15], v[144:147], v[214:217], v[12:15]
	v_mfma_f32_16x16x32_bf16 v[60:63], v[160:163], v[194:197], v[60:63]
	v_mfma_f32_16x16x32_bf16 v[56:59], v[168:171], v[194:197], v[56:59]
	v_mfma_f32_16x16x32_bf16 v[40:43], v[168:171], v[202:205], v[40:43]
	v_mfma_f32_16x16x32_bf16 v[44:47], v[160:163], v[202:205], v[44:47]
	v_mfma_f32_16x16x32_bf16 v[28:31], v[160:163], v[210:213], v[28:31]
	v_mfma_f32_16x16x32_bf16 v[24:27], v[168:171], v[210:213], v[24:27]
	v_mfma_f32_16x16x32_bf16 v[8:11], v[168:171], v[218:221], v[8:11]
	v_mfma_f32_16x16x32_bf16 v[12:15], v[160:163], v[218:221], v[12:15]
	v_mfma_f32_16x16x32_bf16 v[52:55], v[172:175], v[190:193], v[52:55]
	v_mfma_f32_16x16x32_bf16 v[48:51], v[180:183], v[190:193], v[48:51]
	v_mfma_f32_16x16x32_bf16 v[32:35], v[180:183], v[198:201], v[32:35]
	v_mfma_f32_16x16x32_bf16 v[36:39], v[172:175], v[198:201], v[36:39]
	v_mfma_f32_16x16x32_bf16 v[20:23], v[172:175], v[206:209], v[20:23]
	v_mfma_f32_16x16x32_bf16 v[16:19], v[180:183], v[206:209], v[16:19]
	v_mfma_f32_16x16x32_bf16 v[0:3], v[180:183], v[214:217], v[0:3]
	v_mfma_f32_16x16x32_bf16 v[4:7], v[172:175], v[214:217], v[4:7]
	v_mfma_f32_16x16x32_bf16 v[52:55], v[176:179], v[194:197], v[52:55]
	v_mfma_f32_16x16x32_bf16 v[48:51], v[186:189], v[194:197], v[48:51]
	v_mfma_f32_16x16x32_bf16 v[32:35], v[186:189], v[202:205], v[32:35]
	v_mfma_f32_16x16x32_bf16 v[36:39], v[176:179], v[202:205], v[36:39]
	v_mfma_f32_16x16x32_bf16 v[20:23], v[176:179], v[210:213], v[20:23]
	v_mfma_f32_16x16x32_bf16 v[16:19], v[186:189], v[210:213], v[16:19]
	v_mfma_f32_16x16x32_bf16 v[0:3], v[186:189], v[218:221], v[0:3]
	v_mfma_f32_16x16x32_bf16 v[4:7], v[176:179], v[218:221], v[4:7]
	s_barrier
	s_add_i32 s70, s70, 2
	s_add_u32 s38, s38, 0x100
	s_addc_u32 s39, s39, 0
	s_add_u32 s66, s66, 0x100
	s_addc_u32 s67, s67, 0
	s_cmp_gt_u32 s70, 13
	s_cbranch_scc0 .LBB0_1115

.LBB0_1323:
	s_add_u32 s34, s34, 0xb0080
	s_addc_u32 s35, s35, 0
	s_add_u32 s31, s36, 0x100
	s_addc_u32 s63, s37, 0
	s_mov_b32 s64, -2
	s_waitcnt lgkmcnt(0)
	ds_read_b128 v[128:131], v189
	ds_read_b128 v[132:135], v189 offset:1024
	ds_read_b128 v[136:139], v189 offset:2048
	ds_read_b128 v[140:143], v189 offset:3072
	ds_read_b128 v[144:147], v190
	ds_read_b128 v[148:151], v190 offset:1024
	ds_read_b128 v[172:175], v190 offset:2048
	ds_read_b128 v[176:179], v190 offset:3072
	s_add_u32 s36, s34, 0xfff50080
	s_addc_u32 s37, s35, -1
	s_cmp_eq_u32 s64, 40
	s_cselect_b32 s39, s1, s37
	s_cselect_b32 s38, s0, s36
	s_cselect_b32 s37, s29, s63
	s_cselect_b32 s36, s28, s31
	s_add_i32 m0, s16, 0xc000
	ds_read_b128 v[180:183], v191
	ds_read_b128 v[194:197], v191 offset:1024
	ds_read_b128 v[198:201], v191 offset:2048
	ds_read_b128 v[202:205], v191 offset:3072
	ds_read_b128 v[206:209], v191 offset:4096
	ds_read_b128 v[210:213], v191 offset:5120
	ds_read_b128 v[214:217], v191 offset:6144
	ds_read_b128 v[218:221], v191 offset:7168
	global_load_lds_dwordx4 v164, s[34:35]
	s_add_i32 m0, s16, 0xe000
	s_nop 0
	global_load_lds_dwordx4 v166, s[34:35]
	s_waitcnt vmcnt(8)
	s_waitcnt lgkmcnt(0)
	s_barrier
	s_waitcnt lgkmcnt(0)
	v_mfma_f32_16x16x32_bf16 v[124:127], v[128:131], v[180:183], 0
	v_mfma_f32_16x16x32_bf16 v[120:123], v[136:139], v[180:183], 0
	v_mfma_f32_16x16x32_bf16 v[104:107], v[136:139], v[198:201], 0
	v_mfma_f32_16x16x32_bf16 v[108:111], v[128:131], v[198:201], 0
	v_mfma_f32_16x16x32_bf16 v[92:95], v[128:131], v[206:209], 0
	v_mfma_f32_16x16x32_bf16 v[88:91], v[136:139], v[206:209], 0
	v_mfma_f32_16x16x32_bf16 v[72:75], v[136:139], v[214:217], 0
	v_mfma_f32_16x16x32_bf16 v[76:79], v[128:131], v[214:217], 0
	v_mfma_f32_16x16x32_bf16 v[124:127], v[132:135], v[194:197], v[124:127]
	v_mfma_f32_16x16x32_bf16 v[120:123], v[140:143], v[194:197], v[120:123]
	v_mfma_f32_16x16x32_bf16 v[104:107], v[140:143], v[202:205], v[104:107]
	v_mfma_f32_16x16x32_bf16 v[108:111], v[132:135], v[202:205], v[108:111]
	v_mfma_f32_16x16x32_bf16 v[92:95], v[132:135], v[210:213], v[92:95]
	v_mfma_f32_16x16x32_bf16 v[88:91], v[140:143], v[210:213], v[88:91]
	v_mfma_f32_16x16x32_bf16 v[72:75], v[140:143], v[218:221], v[72:75]
	v_mfma_f32_16x16x32_bf16 v[76:79], v[132:135], v[218:221], v[76:79]
	v_mfma_f32_16x16x32_bf16 v[116:119], v[144:147], v[180:183], 0
	v_mfma_f32_16x16x32_bf16 v[112:115], v[172:175], v[180:183], 0
	v_mfma_f32_16x16x32_bf16 v[96:99], v[172:175], v[198:201], 0
	v_mfma_f32_16x16x32_bf16 v[100:103], v[144:147], v[198:201], 0
	v_mfma_f32_16x16x32_bf16 v[84:87], v[144:147], v[206:209], 0
	v_mfma_f32_16x16x32_bf16 v[80:83], v[172:175], v[206:209], 0
	v_mfma_f32_16x16x32_bf16 v[64:67], v[172:175], v[214:217], 0
	v_mfma_f32_16x16x32_bf16 v[68:71], v[144:147], v[214:217], 0
	v_mfma_f32_16x16x32_bf16 v[116:119], v[148:151], v[194:197], v[116:119]
	v_mfma_f32_16x16x32_bf16 v[112:115], v[176:179], v[194:197], v[112:115]
	v_mfma_f32_16x16x32_bf16 v[96:99], v[176:179], v[202:205], v[96:99]
	v_mfma_f32_16x16x32_bf16 v[100:103], v[148:151], v[202:205], v[100:103]
	v_mfma_f32_16x16x32_bf16 v[84:87], v[148:151], v[210:213], v[84:87]
	v_mfma_f32_16x16x32_bf16 v[80:83], v[176:179], v[210:213], v[80:83]
	v_mfma_f32_16x16x32_bf16 v[64:67], v[176:179], v[218:221], v[64:67]
	v_mfma_f32_16x16x32_bf16 v[68:71], v[148:151], v[218:221], v[68:71]
	s_barrier
	s_add_i32 s65, s42, s15
	s_mov_b32 m0, s65
	ds_read_b128 v[180:183], v191 offset:16384
	ds_read_b128 v[194:197], v191 offset:17408
	ds_read_b128 v[198:201], v191 offset:18432
	ds_read_b128 v[202:205], v191 offset:19456
	ds_read_b128 v[206:209], v191 offset:20480
	ds_read_b128 v[210:213], v191 offset:21504
	ds_read_b128 v[214:217], v191 offset:22528
	ds_read_b128 v[218:221], v191 offset:23552
	global_load_lds_dwordx4 v154, s[36:37]
	s_add_i32 m0, s65, 0x2000
	s_add_u32 s66, s36, 0xb0000
	s_addc_u32 s67, s37, 0
	s_add_i32 s65, s43, s15
	global_load_lds_dwordx4 v158, s[36:37]
	s_mov_b32 m0, s65
	global_load_lds_dwordx4 v154, s[66:67]
	s_add_i32 m0, s65, 0x2000
	s_nop 0
	global_load_lds_dwordx4 v158, s[66:67]
	s_mov_b32 m0, s16
	s_nop 0
	global_load_lds_dwordx4 v152, s[38:39]
	s_mov_b32 m0, s17
	s_nop 0
	global_load_lds_dwordx4 v156, s[38:39]
	s_add_u32 s98, s36, s24
	s_addc_u32 s99, s37, s25
	s_add_u32 s100, s38, s24
	s_addc_u32 s101, s39, s25
	s_waitcnt vmcnt(8)
	s_waitcnt lgkmcnt(0)
	s_barrier
	s_waitcnt lgkmcnt(0)
	v_mfma_f32_16x16x32_bf16 v[60:63], v[128:131], v[180:183], 0
	v_mfma_f32_16x16x32_bf16 v[56:59], v[136:139], v[180:183], 0
	v_mfma_f32_16x16x32_bf16 v[40:43], v[136:139], v[198:201], 0
	v_mfma_f32_16x16x32_bf16 v[44:47], v[128:131], v[198:201], 0
	v_mfma_f32_16x16x32_bf16 v[28:31], v[128:131], v[206:209], 0
	v_mfma_f32_16x16x32_bf16 v[24:27], v[136:139], v[206:209], 0
	v_mfma_f32_16x16x32_bf16 v[8:11], v[136:139], v[214:217], 0
	v_mfma_f32_16x16x32_bf16 v[12:15], v[128:131], v[214:217], 0
	v_mfma_f32_16x16x32_bf16 v[60:63], v[132:135], v[194:197], v[60:63]
	v_mfma_f32_16x16x32_bf16 v[56:59], v[140:143], v[194:197], v[56:59]
	v_mfma_f32_16x16x32_bf16 v[40:43], v[140:143], v[202:205], v[40:43]
	v_mfma_f32_16x16x32_bf16 v[44:47], v[132:135], v[202:205], v[44:47]
	v_mfma_f32_16x16x32_bf16 v[28:31], v[132:135], v[210:213], v[28:31]
	v_mfma_f32_16x16x32_bf16 v[24:27], v[140:143], v[210:213], v[24:27]
	v_mfma_f32_16x16x32_bf16 v[8:11], v[140:143], v[218:221], v[8:11]
	v_mfma_f32_16x16x32_bf16 v[12:15], v[132:135], v[218:221], v[12:15]
	v_mfma_f32_16x16x32_bf16 v[52:55], v[144:147], v[180:183], 0
	v_mfma_f32_16x16x32_bf16 v[48:51], v[172:175], v[180:183], 0
	v_mfma_f32_16x16x32_bf16 v[32:35], v[172:175], v[198:201], 0
	v_mfma_f32_16x16x32_bf16 v[36:39], v[144:147], v[198:201], 0
	v_mfma_f32_16x16x32_bf16 v[20:23], v[144:147], v[206:209], 0
	v_mfma_f32_16x16x32_bf16 v[16:19], v[172:175], v[206:209], 0
	v_mfma_f32_16x16x32_bf16 v[0:3], v[172:175], v[214:217], 0
	v_mfma_f32_16x16x32_bf16 v[4:7], v[144:147], v[214:217], 0
	v_mfma_f32_16x16x32_bf16 v[52:55], v[148:151], v[194:197], v[52:55]
	v_mfma_f32_16x16x32_bf16 v[48:51], v[176:179], v[194:197], v[48:51]
	v_mfma_f32_16x16x32_bf16 v[32:35], v[176:179], v[202:205], v[32:35]
	v_mfma_f32_16x16x32_bf16 v[36:39], v[148:151], v[202:205], v[36:39]
	v_mfma_f32_16x16x32_bf16 v[20:23], v[148:151], v[210:213], v[20:23]
	v_mfma_f32_16x16x32_bf16 v[16:19], v[176:179], v[210:213], v[16:19]
	v_mfma_f32_16x16x32_bf16 v[0:3], v[176:179], v[218:221], v[0:3]
	v_mfma_f32_16x16x32_bf16 v[4:7], v[148:151], v[218:221], v[4:7]
	s_barrier
	s_add_i32 s65, 0, 0x18000
	s_add_i32 s66, 0, 0x1c000
	v_add_u32_e32 v140, s65, v186
	v_add_u32_e32 v176, s66, v186
	ds_read_b128 v[128:131], v140
	ds_read_b128 v[132:135], v140 offset:1024
	ds_read_b128 v[136:139], v140 offset:2048
	ds_read_b128 v[140:143], v140 offset:3072
	ds_read_b128 v[144:147], v176
	ds_read_b128 v[148:151], v176 offset:1024
	ds_read_b128 v[172:175], v176 offset:2048
	ds_read_b128 v[176:179], v176 offset:3072
	s_add_u32 s38, s38, 0xb0000
	s_addc_u32 s39, s39, 0
	s_mov_b32 m0, s18
	ds_read_b128 v[180:183], v191 offset:32768
	ds_read_b128 v[194:197], v191 offset:33792
	ds_read_b128 v[198:201], v191 offset:34816
	ds_read_b128 v[202:205], v191 offset:35840
	ds_read_b128 v[206:209], v191 offset:36864
	ds_read_b128 v[210:213], v191 offset:37888
	ds_read_b128 v[214:217], v191 offset:38912
	ds_read_b128 v[218:221], v191 offset:39936
	global_load_lds_dwordx4 v152, s[38:39]
	s_mov_b32 m0, s19
	s_nop 0
	global_load_lds_dwordx4 v156, s[38:39]
	s_waitcnt vmcnt(8)
	s_waitcnt lgkmcnt(0)
	s_barrier
	s_waitcnt lgkmcnt(0)
	v_mfma_f32_16x16x32_bf16 v[124:127], v[128:131], v[180:183], v[124:127]
	v_mfma_f32_16x16x32_bf16 v[120:123], v[136:139], v[180:183], v[120:123]
	v_mfma_f32_16x16x32_bf16 v[104:107], v[136:139], v[198:201], v[104:107]
	v_mfma_f32_16x16x32_bf16 v[108:111], v[128:131], v[198:201], v[108:111]
	v_mfma_f32_16x16x32_bf16 v[92:95], v[128:131], v[206:209], v[92:95]
	v_mfma_f32_16x16x32_bf16 v[88:91], v[136:139], v[206:209], v[88:91]
	v_mfma_f32_16x16x32_bf16 v[72:75], v[136:139], v[214:217], v[72:75]
	v_mfma_f32_16x16x32_bf16 v[76:79], v[128:131], v[214:217], v[76:79]
	v_mfma_f32_16x16x32_bf16 v[124:127], v[132:135], v[194:197], v[124:127]
	v_mfma_f32_16x16x32_bf16 v[120:123], v[140:143], v[194:197], v[120:123]
	v_mfma_f32_16x16x32_bf16 v[104:107], v[140:143], v[202:205], v[104:107]
	v_mfma_f32_16x16x32_bf16 v[108:111], v[132:135], v[202:205], v[108:111]
	v_mfma_f32_16x16x32_bf16 v[92:95], v[132:135], v[210:213], v[92:95]
	v_mfma_f32_16x16x32_bf16 v[88:91], v[140:143], v[210:213], v[88:91]
	v_mfma_f32_16x16x32_bf16 v[72:75], v[140:143], v[218:221], v[72:75]
	v_mfma_f32_16x16x32_bf16 v[76:79], v[132:135], v[218:221], v[76:79]
	v_mfma_f32_16x16x32_bf16 v[116:119], v[144:147], v[180:183], v[116:119]
	v_mfma_f32_16x16x32_bf16 v[112:115], v[172:175], v[180:183], v[112:115]
	v_mfma_f32_16x16x32_bf16 v[96:99], v[172:175], v[198:201], v[96:99]
	v_mfma_f32_16x16x32_bf16 v[100:103], v[144:147], v[198:201], v[100:103]
	v_mfma_f32_16x16x32_bf16 v[84:87], v[144:147], v[206:209], v[84:87]
	v_mfma_f32_16x16x32_bf16 v[80:83], v[172:175], v[206:209], v[80:83]
	v_mfma_f32_16x16x32_bf16 v[64:67], v[172:175], v[214:217], v[64:67]
	v_mfma_f32_16x16x32_bf16 v[68:71], v[144:147], v[214:217], v[68:71]
	v_mfma_f32_16x16x32_bf16 v[116:119], v[148:151], v[194:197], v[116:119]
	v_mfma_f32_16x16x32_bf16 v[112:115], v[176:179], v[194:197], v[112:115]
	v_mfma_f32_16x16x32_bf16 v[96:99], v[176:179], v[202:205], v[96:99]
	v_mfma_f32_16x16x32_bf16 v[100:103], v[148:151], v[202:205], v[100:103]
	v_mfma_f32_16x16x32_bf16 v[84:87], v[148:151], v[210:213], v[84:87]
	v_mfma_f32_16x16x32_bf16 v[80:83], v[176:179], v[210:213], v[80:83]
	v_mfma_f32_16x16x32_bf16 v[64:67], v[176:179], v[218:221], v[64:67]
	v_mfma_f32_16x16x32_bf16 v[68:71], v[148:151], v[218:221], v[68:71]
	s_barrier
	s_add_i32 s38, s65, s15
	s_mov_b32 m0, s38
	ds_read_b128 v[180:183], v191 offset:49152
	ds_read_b128 v[194:197], v191 offset:50176
	ds_read_b128 v[198:201], v191 offset:51200
	ds_read_b128 v[202:205], v191 offset:52224
	ds_read_b128 v[206:209], v191 offset:53248
	ds_read_b128 v[210:213], v191 offset:54272
	ds_read_b128 v[214:217], v191 offset:55296
	ds_read_b128 v[218:221], v191 offset:56320
	global_load_lds_dwordx4 v154, s[98:99]
	s_add_i32 m0, s38, 0x2000
	s_add_u32 s36, s36, 0xb0080
	s_addc_u32 s37, s37, 0
	s_add_i32 s38, s66, s15
	global_load_lds_dwordx4 v158, s[98:99]
	s_mov_b32 m0, s38
	s_nop 0
	global_load_lds_dwordx4 v154, s[36:37]
	s_add_i32 m0, s38, 0x2000
	s_nop 0
	global_load_lds_dwordx4 v158, s[36:37]
	s_mov_b32 m0, s21
	s_nop 0
	global_load_lds_dwordx4 v152, s[100:101]
	s_mov_b32 m0, s22
	s_nop 0
	global_load_lds_dwordx4 v156, s[100:101]
	s_waitcnt vmcnt(8)
	s_waitcnt lgkmcnt(0)
	s_barrier
	s_waitcnt lgkmcnt(0)
	v_mfma_f32_16x16x32_bf16 v[60:63], v[128:131], v[180:183], v[60:63]
	v_mfma_f32_16x16x32_bf16 v[56:59], v[136:139], v[180:183], v[56:59]
	v_mfma_f32_16x16x32_bf16 v[40:43], v[136:139], v[198:201], v[40:43]
	v_mfma_f32_16x16x32_bf16 v[44:47], v[128:131], v[198:201], v[44:47]
	v_mfma_f32_16x16x32_bf16 v[28:31], v[128:131], v[206:209], v[28:31]
	v_mfma_f32_16x16x32_bf16 v[24:27], v[136:139], v[206:209], v[24:27]
	v_mfma_f32_16x16x32_bf16 v[8:11], v[136:139], v[214:217], v[8:11]
	v_mfma_f32_16x16x32_bf16 v[12:15], v[128:131], v[214:217], v[12:15]
	v_mfma_f32_16x16x32_bf16 v[60:63], v[132:135], v[194:197], v[60:63]
	v_mfma_f32_16x16x32_bf16 v[56:59], v[140:143], v[194:197], v[56:59]
	v_mfma_f32_16x16x32_bf16 v[40:43], v[140:143], v[202:205], v[40:43]
	v_mfma_f32_16x16x32_bf16 v[44:47], v[132:135], v[202:205], v[44:47]
	v_mfma_f32_16x16x32_bf16 v[28:31], v[132:135], v[210:213], v[28:31]
	v_mfma_f32_16x16x32_bf16 v[24:27], v[140:143], v[210:213], v[24:27]
	v_mfma_f32_16x16x32_bf16 v[8:11], v[140:143], v[218:221], v[8:11]
	v_mfma_f32_16x16x32_bf16 v[12:15], v[132:135], v[218:221], v[12:15]
	v_mfma_f32_16x16x32_bf16 v[52:55], v[144:147], v[180:183], v[52:55]
	v_mfma_f32_16x16x32_bf16 v[48:51], v[172:175], v[180:183], v[48:51]
	v_mfma_f32_16x16x32_bf16 v[32:35], v[172:175], v[198:201], v[32:35]
	v_mfma_f32_16x16x32_bf16 v[36:39], v[144:147], v[198:201], v[36:39]
	v_mfma_f32_16x16x32_bf16 v[20:23], v[144:147], v[206:209], v[20:23]
	v_mfma_f32_16x16x32_bf16 v[16:19], v[172:175], v[206:209], v[16:19]
	v_mfma_f32_16x16x32_bf16 v[0:3], v[172:175], v[214:217], v[0:3]
	v_mfma_f32_16x16x32_bf16 v[4:7], v[144:147], v[214:217], v[4:7]
	v_mfma_f32_16x16x32_bf16 v[52:55], v[148:151], v[194:197], v[52:55]
	v_mfma_f32_16x16x32_bf16 v[48:51], v[176:179], v[194:197], v[48:51]
	v_mfma_f32_16x16x32_bf16 v[32:35], v[176:179], v[202:205], v[32:35]
	v_mfma_f32_16x16x32_bf16 v[36:39], v[148:151], v[202:205], v[36:39]
	v_mfma_f32_16x16x32_bf16 v[20:23], v[148:151], v[210:213], v[20:23]
	v_mfma_f32_16x16x32_bf16 v[16:19], v[176:179], v[210:213], v[16:19]
	v_mfma_f32_16x16x32_bf16 v[0:3], v[176:179], v[218:221], v[0:3]
	v_mfma_f32_16x16x32_bf16 v[4:7], v[148:151], v[218:221], v[4:7]
	s_barrier
	s_add_i32 s64, s64, 2
	s_add_u32 s34, s34, 0x100
	s_addc_u32 s35, s35, 0
	s_add_u32 s31, s31, 0x100
	s_addc_u32 s63, s63, 0
	s_cmp_gt_u32 s64, 41
	s_cbranch_scc1 .Lpeel_exit_1324
.LBB0_1324:
	ds_read_b128 v[128:131], v189
	ds_read_b128 v[132:135], v189 offset:1024
	ds_read_b128 v[136:139], v189 offset:2048
	ds_read_b128 v[140:143], v189 offset:3072
	ds_read_b128 v[144:147], v190
	ds_read_b128 v[148:151], v190 offset:1024
	ds_read_b128 v[172:175], v190 offset:2048
	ds_read_b128 v[176:179], v190 offset:3072
	s_add_u32 s36, s34, 0xfff50080
	s_addc_u32 s37, s35, -1
	s_cmp_eq_u32 s64, 40
	s_cselect_b32 s39, s1, s37
	s_cselect_b32 s38, s0, s36
	s_cselect_b32 s37, s29, s63
	s_cselect_b32 s36, s28, s31
	s_add_i32 m0, s16, 0xc000
	ds_read_b128 v[180:183], v191
	ds_read_b128 v[194:197], v191 offset:1024
	ds_read_b128 v[198:201], v191 offset:2048
	ds_read_b128 v[202:205], v191 offset:3072
	ds_read_b128 v[206:209], v191 offset:4096
	ds_read_b128 v[210:213], v191 offset:5120
	ds_read_b128 v[214:217], v191 offset:6144
	ds_read_b128 v[218:221], v191 offset:7168
	global_load_lds_dwordx4 v164, s[34:35]
	s_add_i32 m0, s16, 0xe000
	s_nop 0
	global_load_lds_dwordx4 v166, s[34:35]
	s_waitcnt vmcnt(8)
	s_waitcnt lgkmcnt(0)
	s_barrier
	s_waitcnt lgkmcnt(0)
	v_mfma_f32_16x16x32_bf16 v[124:127], v[128:131], v[180:183], v[124:127]
	v_mfma_f32_16x16x32_bf16 v[120:123], v[136:139], v[180:183], v[120:123]
	v_mfma_f32_16x16x32_bf16 v[104:107], v[136:139], v[198:201], v[104:107]
	v_mfma_f32_16x16x32_bf16 v[108:111], v[128:131], v[198:201], v[108:111]
	v_mfma_f32_16x16x32_bf16 v[92:95], v[128:131], v[206:209], v[92:95]
	v_mfma_f32_16x16x32_bf16 v[88:91], v[136:139], v[206:209], v[88:91]
	v_mfma_f32_16x16x32_bf16 v[72:75], v[136:139], v[214:217], v[72:75]
	v_mfma_f32_16x16x32_bf16 v[76:79], v[128:131], v[214:217], v[76:79]
	v_mfma_f32_16x16x32_bf16 v[124:127], v[132:135], v[194:197], v[124:127]
	v_mfma_f32_16x16x32_bf16 v[120:123], v[140:143], v[194:197], v[120:123]
	v_mfma_f32_16x16x32_bf16 v[104:107], v[140:143], v[202:205], v[104:107]
	v_mfma_f32_16x16x32_bf16 v[108:111], v[132:135], v[202:205], v[108:111]
	v_mfma_f32_16x16x32_bf16 v[92:95], v[132:135], v[210:213], v[92:95]
	v_mfma_f32_16x16x32_bf16 v[88:91], v[140:143], v[210:213], v[88:91]
	v_mfma_f32_16x16x32_bf16 v[72:75], v[140:143], v[218:221], v[72:75]
	v_mfma_f32_16x16x32_bf16 v[76:79], v[132:135], v[218:221], v[76:79]
	v_mfma_f32_16x16x32_bf16 v[116:119], v[144:147], v[180:183], v[116:119]
	v_mfma_f32_16x16x32_bf16 v[112:115], v[172:175], v[180:183], v[112:115]
	v_mfma_f32_16x16x32_bf16 v[96:99], v[172:175], v[198:201], v[96:99]
	v_mfma_f32_16x16x32_bf16 v[100:103], v[144:147], v[198:201], v[100:103]
	v_mfma_f32_16x16x32_bf16 v[84:87], v[144:147], v[206:209], v[84:87]
	v_mfma_f32_16x16x32_bf16 v[80:83], v[172:175], v[206:209], v[80:83]
	v_mfma_f32_16x16x32_bf16 v[64:67], v[172:175], v[214:217], v[64:67]
	v_mfma_f32_16x16x32_bf16 v[68:71], v[144:147], v[214:217], v[68:71]
	v_mfma_f32_16x16x32_bf16 v[116:119], v[148:151], v[194:197], v[116:119]
	v_mfma_f32_16x16x32_bf16 v[112:115], v[176:179], v[194:197], v[112:115]
	v_mfma_f32_16x16x32_bf16 v[96:99], v[176:179], v[202:205], v[96:99]
	v_mfma_f32_16x16x32_bf16 v[100:103], v[148:151], v[202:205], v[100:103]
	v_mfma_f32_16x16x32_bf16 v[84:87], v[148:151], v[210:213], v[84:87]
	v_mfma_f32_16x16x32_bf16 v[80:83], v[176:179], v[210:213], v[80:83]
	v_mfma_f32_16x16x32_bf16 v[64:67], v[176:179], v[218:221], v[64:67]
	v_mfma_f32_16x16x32_bf16 v[68:71], v[148:151], v[218:221], v[68:71]
	s_barrier
	s_add_i32 s65, s42, s15
	s_mov_b32 m0, s65
	ds_read_b128 v[180:183], v191 offset:16384
	ds_read_b128 v[194:197], v191 offset:17408
	ds_read_b128 v[198:201], v191 offset:18432
	ds_read_b128 v[202:205], v191 offset:19456
	ds_read_b128 v[206:209], v191 offset:20480
	ds_read_b128 v[210:213], v191 offset:21504
	ds_read_b128 v[214:217], v191 offset:22528
	ds_read_b128 v[218:221], v191 offset:23552
	global_load_lds_dwordx4 v154, s[36:37]
	s_add_i32 m0, s65, 0x2000
	s_add_u32 s66, s36, 0xb0000
	s_addc_u32 s67, s37, 0
	s_add_i32 s65, s43, s15
	global_load_lds_dwordx4 v158, s[36:37]
	s_mov_b32 m0, s65
	global_load_lds_dwordx4 v154, s[66:67]
	s_add_i32 m0, s65, 0x2000
	s_nop 0
	global_load_lds_dwordx4 v158, s[66:67]
	s_mov_b32 m0, s16
	s_nop 0
	global_load_lds_dwordx4 v152, s[38:39]
	s_mov_b32 m0, s17
	s_nop 0
	global_load_lds_dwordx4 v156, s[38:39]
	s_add_u32 s98, s36, s24
	s_addc_u32 s99, s37, s25
	s_add_u32 s100, s38, s24
	s_addc_u32 s101, s39, s25
	s_waitcnt vmcnt(8)
	s_waitcnt lgkmcnt(0)
	s_barrier
	s_waitcnt lgkmcnt(0)
	v_mfma_f32_16x16x32_bf16 v[60:63], v[128:131], v[180:183], v[60:63]
	v_mfma_f32_16x16x32_bf16 v[56:59], v[136:139], v[180:183], v[56:59]
	v_mfma_f32_16x16x32_bf16 v[40:43], v[136:139], v[198:201], v[40:43]
	v_mfma_f32_16x16x32_bf16 v[44:47], v[128:131], v[198:201], v[44:47]
	v_mfma_f32_16x16x32_bf16 v[28:31], v[128:131], v[206:209], v[28:31]
	v_mfma_f32_16x16x32_bf16 v[24:27], v[136:139], v[206:209], v[24:27]
	v_mfma_f32_16x16x32_bf16 v[8:11], v[136:139], v[214:217], v[8:11]
	v_mfma_f32_16x16x32_bf16 v[12:15], v[128:131], v[214:217], v[12:15]
	v_mfma_f32_16x16x32_bf16 v[60:63], v[132:135], v[194:197], v[60:63]
	v_mfma_f32_16x16x32_bf16 v[56:59], v[140:143], v[194:197], v[56:59]
	v_mfma_f32_16x16x32_bf16 v[40:43], v[140:143], v[202:205], v[40:43]
	v_mfma_f32_16x16x32_bf16 v[44:47], v[132:135], v[202:205], v[44:47]
	v_mfma_f32_16x16x32_bf16 v[28:31], v[132:135], v[210:213], v[28:31]
	v_mfma_f32_16x16x32_bf16 v[24:27], v[140:143], v[210:213], v[24:27]
	v_mfma_f32_16x16x32_bf16 v[8:11], v[140:143], v[218:221], v[8:11]
	v_mfma_f32_16x16x32_bf16 v[12:15], v[132:135], v[218:221], v[12:15]
	v_mfma_f32_16x16x32_bf16 v[52:55], v[144:147], v[180:183], v[52:55]
	v_mfma_f32_16x16x32_bf16 v[48:51], v[172:175], v[180:183], v[48:51]
	v_mfma_f32_16x16x32_bf16 v[32:35], v[172:175], v[198:201], v[32:35]
	v_mfma_f32_16x16x32_bf16 v[36:39], v[144:147], v[198:201], v[36:39]
	v_mfma_f32_16x16x32_bf16 v[20:23], v[144:147], v[206:209], v[20:23]
	v_mfma_f32_16x16x32_bf16 v[16:19], v[172:175], v[206:209], v[16:19]
	v_mfma_f32_16x16x32_bf16 v[0:3], v[172:175], v[214:217], v[0:3]
	v_mfma_f32_16x16x32_bf16 v[4:7], v[144:147], v[214:217], v[4:7]
	v_mfma_f32_16x16x32_bf16 v[52:55], v[148:151], v[194:197], v[52:55]
	v_mfma_f32_16x16x32_bf16 v[48:51], v[176:179], v[194:197], v[48:51]
	v_mfma_f32_16x16x32_bf16 v[32:35], v[176:179], v[202:205], v[32:35]
	v_mfma_f32_16x16x32_bf16 v[36:39], v[148:151], v[202:205], v[36:39]
	v_mfma_f32_16x16x32_bf16 v[20:23], v[148:151], v[210:213], v[20:23]
	v_mfma_f32_16x16x32_bf16 v[16:19], v[176:179], v[210:213], v[16:19]
	v_mfma_f32_16x16x32_bf16 v[0:3], v[176:179], v[218:221], v[0:3]
	v_mfma_f32_16x16x32_bf16 v[4:7], v[148:151], v[218:221], v[4:7]
	s_barrier
	s_add_i32 s65, 0, 0x18000
	s_add_i32 s66, 0, 0x1c000
	v_add_u32_e32 v140, s65, v186
	v_add_u32_e32 v176, s66, v186
	ds_read_b128 v[128:131], v140
	ds_read_b128 v[132:135], v140 offset:1024
	ds_read_b128 v[136:139], v140 offset:2048
	ds_read_b128 v[140:143], v140 offset:3072
	ds_read_b128 v[144:147], v176
	ds_read_b128 v[148:151], v176 offset:1024
	ds_read_b128 v[172:175], v176 offset:2048
	ds_read_b128 v[176:179], v176 offset:3072
	s_add_u32 s38, s38, 0xb0000
	s_addc_u32 s39, s39, 0
	s_mov_b32 m0, s18
	ds_read_b128 v[180:183], v191 offset:32768
	ds_read_b128 v[194:197], v191 offset:33792
	ds_read_b128 v[198:201], v191 offset:34816
	ds_read_b128 v[202:205], v191 offset:35840
	ds_read_b128 v[206:209], v191 offset:36864
	ds_read_b128 v[210:213], v191 offset:37888
	ds_read_b128 v[214:217], v191 offset:38912
	ds_read_b128 v[218:221], v191 offset:39936
	global_load_lds_dwordx4 v152, s[38:39]
	s_mov_b32 m0, s19
	s_nop 0
	global_load_lds_dwordx4 v156, s[38:39]
	s_waitcnt vmcnt(8)
	s_waitcnt lgkmcnt(0)
	s_barrier
	s_waitcnt lgkmcnt(0)
	v_mfma_f32_16x16x32_bf16 v[124:127], v[128:131], v[180:183], v[124:127]
	v_mfma_f32_16x16x32_bf16 v[120:123], v[136:139], v[180:183], v[120:123]
	v_mfma_f32_16x16x32_bf16 v[104:107], v[136:139], v[198:201], v[104:107]
	v_mfma_f32_16x16x32_bf16 v[108:111], v[128:131], v[198:201], v[108:111]
	v_mfma_f32_16x16x32_bf16 v[92:95], v[128:131], v[206:209], v[92:95]
	v_mfma_f32_16x16x32_bf16 v[88:91], v[136:139], v[206:209], v[88:91]
	v_mfma_f32_16x16x32_bf16 v[72:75], v[136:139], v[214:217], v[72:75]
	v_mfma_f32_16x16x32_bf16 v[76:79], v[128:131], v[214:217], v[76:79]
	v_mfma_f32_16x16x32_bf16 v[124:127], v[132:135], v[194:197], v[124:127]
	v_mfma_f32_16x16x32_bf16 v[120:123], v[140:143], v[194:197], v[120:123]
	v_mfma_f32_16x16x32_bf16 v[104:107], v[140:143], v[202:205], v[104:107]
	v_mfma_f32_16x16x32_bf16 v[108:111], v[132:135], v[202:205], v[108:111]
	v_mfma_f32_16x16x32_bf16 v[92:95], v[132:135], v[210:213], v[92:95]
	v_mfma_f32_16x16x32_bf16 v[88:91], v[140:143], v[210:213], v[88:91]
	v_mfma_f32_16x16x32_bf16 v[72:75], v[140:143], v[218:221], v[72:75]
	v_mfma_f32_16x16x32_bf16 v[76:79], v[132:135], v[218:221], v[76:79]
	v_mfma_f32_16x16x32_bf16 v[116:119], v[144:147], v[180:183], v[116:119]
	v_mfma_f32_16x16x32_bf16 v[112:115], v[172:175], v[180:183], v[112:115]
	v_mfma_f32_16x16x32_bf16 v[96:99], v[172:175], v[198:201], v[96:99]
	v_mfma_f32_16x16x32_bf16 v[100:103], v[144:147], v[198:201], v[100:103]
	v_mfma_f32_16x16x32_bf16 v[84:87], v[144:147], v[206:209], v[84:87]
	v_mfma_f32_16x16x32_bf16 v[80:83], v[172:175], v[206:209], v[80:83]
	v_mfma_f32_16x16x32_bf16 v[64:67], v[172:175], v[214:217], v[64:67]
	v_mfma_f32_16x16x32_bf16 v[68:71], v[144:147], v[214:217], v[68:71]
	v_mfma_f32_16x16x32_bf16 v[116:119], v[148:151], v[194:197], v[116:119]
	v_mfma_f32_16x16x32_bf16 v[112:115], v[176:179], v[194:197], v[112:115]
	v_mfma_f32_16x16x32_bf16 v[96:99], v[176:179], v[202:205], v[96:99]
	v_mfma_f32_16x16x32_bf16 v[100:103], v[148:151], v[202:205], v[100:103]
	v_mfma_f32_16x16x32_bf16 v[84:87], v[148:151], v[210:213], v[84:87]
	v_mfma_f32_16x16x32_bf16 v[80:83], v[176:179], v[210:213], v[80:83]
	v_mfma_f32_16x16x32_bf16 v[64:67], v[176:179], v[218:221], v[64:67]
	v_mfma_f32_16x16x32_bf16 v[68:71], v[148:151], v[218:221], v[68:71]
	s_barrier
	s_add_i32 s38, s65, s15
	s_mov_b32 m0, s38
	ds_read_b128 v[180:183], v191 offset:49152
	ds_read_b128 v[194:197], v191 offset:50176
	ds_read_b128 v[198:201], v191 offset:51200
	ds_read_b128 v[202:205], v191 offset:52224
	ds_read_b128 v[206:209], v191 offset:53248
	ds_read_b128 v[210:213], v191 offset:54272
	ds_read_b128 v[214:217], v191 offset:55296
	ds_read_b128 v[218:221], v191 offset:56320
	global_load_lds_dwordx4 v154, s[98:99]
	s_add_i32 m0, s38, 0x2000
	s_add_u32 s36, s36, 0xb0080
	s_addc_u32 s37, s37, 0
	s_add_i32 s38, s66, s15
	global_load_lds_dwordx4 v158, s[98:99]
	s_mov_b32 m0, s38
	s_nop 0
	global_load_lds_dwordx4 v154, s[36:37]
	s_add_i32 m0, s38, 0x2000
	s_nop 0
	global_load_lds_dwordx4 v158, s[36:37]
	s_mov_b32 m0, s21
	s_nop 0
	global_load_lds_dwordx4 v152, s[100:101]
	s_mov_b32 m0, s22
	s_nop 0
	global_load_lds_dwordx4 v156, s[100:101]
	s_waitcnt vmcnt(8)
	s_waitcnt lgkmcnt(0)
	s_barrier
	s_waitcnt lgkmcnt(0)
	v_mfma_f32_16x16x32_bf16 v[60:63], v[128:131], v[180:183], v[60:63]
	v_mfma_f32_16x16x32_bf16 v[56:59], v[136:139], v[180:183], v[56:59]
	v_mfma_f32_16x16x32_bf16 v[40:43], v[136:139], v[198:201], v[40:43]
	v_mfma_f32_16x16x32_bf16 v[44:47], v[128:131], v[198:201], v[44:47]
	v_mfma_f32_16x16x32_bf16 v[28:31], v[128:131], v[206:209], v[28:31]
	v_mfma_f32_16x16x32_bf16 v[24:27], v[136:139], v[206:209], v[24:27]
	v_mfma_f32_16x16x32_bf16 v[8:11], v[136:139], v[214:217], v[8:11]
	v_mfma_f32_16x16x32_bf16 v[12:15], v[128:131], v[214:217], v[12:15]
	v_mfma_f32_16x16x32_bf16 v[60:63], v[132:135], v[194:197], v[60:63]
	v_mfma_f32_16x16x32_bf16 v[56:59], v[140:143], v[194:197], v[56:59]
	v_mfma_f32_16x16x32_bf16 v[40:43], v[140:143], v[202:205], v[40:43]
	v_mfma_f32_16x16x32_bf16 v[44:47], v[132:135], v[202:205], v[44:47]
	v_mfma_f32_16x16x32_bf16 v[28:31], v[132:135], v[210:213], v[28:31]
	v_mfma_f32_16x16x32_bf16 v[24:27], v[140:143], v[210:213], v[24:27]
	v_mfma_f32_16x16x32_bf16 v[8:11], v[140:143], v[218:221], v[8:11]
	v_mfma_f32_16x16x32_bf16 v[12:15], v[132:135], v[218:221], v[12:15]
	v_mfma_f32_16x16x32_bf16 v[52:55], v[144:147], v[180:183], v[52:55]
	v_mfma_f32_16x16x32_bf16 v[48:51], v[172:175], v[180:183], v[48:51]
	v_mfma_f32_16x16x32_bf16 v[32:35], v[172:175], v[198:201], v[32:35]
	v_mfma_f32_16x16x32_bf16 v[36:39], v[144:147], v[198:201], v[36:39]
	v_mfma_f32_16x16x32_bf16 v[20:23], v[144:147], v[206:209], v[20:23]
	v_mfma_f32_16x16x32_bf16 v[16:19], v[172:175], v[206:209], v[16:19]
	v_mfma_f32_16x16x32_bf16 v[0:3], v[172:175], v[214:217], v[0:3]
	v_mfma_f32_16x16x32_bf16 v[4:7], v[144:147], v[214:217], v[4:7]
	v_mfma_f32_16x16x32_bf16 v[52:55], v[148:151], v[194:197], v[52:55]
	v_mfma_f32_16x16x32_bf16 v[48:51], v[176:179], v[194:197], v[48:51]
	v_mfma_f32_16x16x32_bf16 v[32:35], v[176:179], v[202:205], v[32:35]
	v_mfma_f32_16x16x32_bf16 v[36:39], v[148:151], v[202:205], v[36:39]
	v_mfma_f32_16x16x32_bf16 v[20:23], v[148:151], v[210:213], v[20:23]
	v_mfma_f32_16x16x32_bf16 v[16:19], v[176:179], v[210:213], v[16:19]
	v_mfma_f32_16x16x32_bf16 v[0:3], v[176:179], v[218:221], v[0:3]
	v_mfma_f32_16x16x32_bf16 v[4:7], v[148:151], v[218:221], v[4:7]
	s_barrier
	s_add_i32 s64, s64, 2
	s_add_u32 s34, s34, 0x100
	s_addc_u32 s35, s35, 0
	s_add_u32 s31, s31, 0x100
	s_addc_u32 s63, s63, 0
	s_cmp_gt_u32 s64, 41
	s_cbranch_scc0 .LBB0_1324

.LBB0_1412:
	s_ashr_i32 s27, s26, 31
	s_lshl_b64 s[14:15], s[26:27], 19
	s_add_u32 s30, s82, s14
	s_addc_u32 s31, s83, s15
	s_and_b64 s[14:15], s[4:5], exec
	s_cselect_b32 s14, s31, s39
	s_cselect_b32 s15, s30, s38
	s_ashr_i32 s29, s28, 31
	s_lshl_b64 s[16:17], s[28:29], 19
	s_add_u32 s34, s6, s16
	s_addc_u32 s35, s7, s17
	s_and_b64 s[16:17], s[4:5], exec
	s_cselect_b32 s16, s35, s41
	s_cselect_b32 s17, s34, s40
	s_add_u32 s38, s38, 0x40080
	s_addc_u32 s39, s39, 0
	s_add_u32 s18, s40, 0x100
	s_addc_u32 s19, s41, 0
	s_mov_b32 s20, -2
	ds_read_b128 v[128:131], v171
	ds_read_b128 v[132:135], v171 offset:1024
	ds_read_b128 v[178:181], v171 offset:2048
	ds_read_b128 v[186:189], v171 offset:3072
	ds_read_b128 v[190:193], v173
	ds_read_b128 v[194:197], v173 offset:1024
	ds_read_b128 v[198:201], v173 offset:2048
	ds_read_b128 v[202:205], v173 offset:3072
	s_add_u32 s21, s38, 0xfffc0080
	s_addc_u32 s22, s39, -1
	s_cmp_eq_u32 s20, 12
	s_cselect_b32 s43, s14, s22
	s_cselect_b32 s42, s15, s21
	s_cselect_b32 s41, s16, s19
	s_cselect_b32 s40, s17, s18
	s_add_i32 m0, s37, 0xc000
	ds_read_b128 v[206:209], v175
	ds_read_b128 v[210:213], v175 offset:1024
	ds_read_b128 v[214:217], v175 offset:2048
	ds_read_b128 v[218:221], v175 offset:3072
	ds_read_b128 v[222:225], v175 offset:4096
	ds_read_b128 v[226:229], v175 offset:5120
	ds_read_b128 v[230:233], v175 offset:6144
	ds_read_b128 v[234:237], v175 offset:7168
	global_load_lds_dwordx4 v152, s[38:39]
	s_add_i32 m0, s37, 0xe000
	s_nop 0
	global_load_lds_dwordx4 v154, s[38:39]
	s_waitcnt vmcnt(8)
	s_waitcnt lgkmcnt(0)
	s_barrier
	s_waitcnt lgkmcnt(0)
	v_mfma_f32_16x16x32_bf16 v[124:127], v[128:131], v[206:209], 0
	v_mfma_f32_16x16x32_bf16 v[120:123], v[178:181], v[206:209], 0
	v_mfma_f32_16x16x32_bf16 v[100:103], v[178:181], v[214:217], 0
	v_mfma_f32_16x16x32_bf16 v[108:111], v[128:131], v[214:217], 0
	v_mfma_f32_16x16x32_bf16 v[92:95], v[128:131], v[222:225], 0
	v_mfma_f32_16x16x32_bf16 v[84:87], v[178:181], v[222:225], 0
	v_mfma_f32_16x16x32_bf16 v[68:71], v[178:181], v[230:233], 0
	v_mfma_f32_16x16x32_bf16 v[76:79], v[128:131], v[230:233], 0
	v_mfma_f32_16x16x32_bf16 v[124:127], v[132:135], v[210:213], v[124:127]
	v_mfma_f32_16x16x32_bf16 v[120:123], v[186:189], v[210:213], v[120:123]
	v_mfma_f32_16x16x32_bf16 v[100:103], v[186:189], v[218:221], v[100:103]
	v_mfma_f32_16x16x32_bf16 v[108:111], v[132:135], v[218:221], v[108:111]
	v_mfma_f32_16x16x32_bf16 v[92:95], v[132:135], v[226:229], v[92:95]
	v_mfma_f32_16x16x32_bf16 v[84:87], v[186:189], v[226:229], v[84:87]
	v_mfma_f32_16x16x32_bf16 v[68:71], v[186:189], v[234:237], v[68:71]
	v_mfma_f32_16x16x32_bf16 v[76:79], v[132:135], v[234:237], v[76:79]
	v_mfma_f32_16x16x32_bf16 v[116:119], v[190:193], v[206:209], 0
	v_mfma_f32_16x16x32_bf16 v[112:115], v[198:201], v[206:209], 0
	v_mfma_f32_16x16x32_bf16 v[96:99], v[198:201], v[214:217], 0
	v_mfma_f32_16x16x32_bf16 v[104:107], v[190:193], v[214:217], 0
	v_mfma_f32_16x16x32_bf16 v[88:91], v[190:193], v[222:225], 0
	v_mfma_f32_16x16x32_bf16 v[80:83], v[198:201], v[222:225], 0
	v_mfma_f32_16x16x32_bf16 v[64:67], v[198:201], v[230:233], 0
	v_mfma_f32_16x16x32_bf16 v[72:75], v[190:193], v[230:233], 0
	v_mfma_f32_16x16x32_bf16 v[116:119], v[194:197], v[210:213], v[116:119]
	v_mfma_f32_16x16x32_bf16 v[112:115], v[202:205], v[210:213], v[112:115]
	v_mfma_f32_16x16x32_bf16 v[96:99], v[202:205], v[218:221], v[96:99]
	v_mfma_f32_16x16x32_bf16 v[104:107], v[194:197], v[218:221], v[104:107]
	v_mfma_f32_16x16x32_bf16 v[88:91], v[194:197], v[226:229], v[88:91]
	v_mfma_f32_16x16x32_bf16 v[80:83], v[202:205], v[226:229], v[80:83]
	v_mfma_f32_16x16x32_bf16 v[64:67], v[202:205], v[234:237], v[64:67]
	v_mfma_f32_16x16x32_bf16 v[72:75], v[194:197], v[234:237], v[72:75]
	s_barrier
	s_add_i32 s21, s44, s60
	s_mov_b32 m0, s21
	ds_read_b128 v[206:209], v175 offset:16384
	ds_read_b128 v[210:213], v175 offset:17408
	ds_read_b128 v[214:217], v175 offset:18432
	ds_read_b128 v[218:221], v175 offset:19456
	ds_read_b128 v[222:225], v175 offset:20480
	ds_read_b128 v[226:229], v175 offset:21504
	ds_read_b128 v[230:233], v175 offset:22528
	ds_read_b128 v[234:237], v175 offset:23552
	global_load_lds_dwordx4 v140, s[40:41]
	s_add_i32 m0, s21, 0x2000
	s_add_u32 s22, s40, 0x40000
	s_addc_u32 s23, s41, 0
	s_add_i32 s21, s45, s60
	global_load_lds_dwordx4 v136, s[40:41]
	s_mov_b32 m0, s21
	global_load_lds_dwordx4 v140, s[22:23]
	s_add_i32 m0, s21, 0x2000
	s_nop 0
	global_load_lds_dwordx4 v136, s[22:23]
	s_mov_b32 m0, s37
	s_nop 0
	global_load_lds_dwordx4 v142, s[42:43]
	s_mov_b32 m0, s63
	s_nop 0
	global_load_lds_dwordx4 v138, s[42:43]
	s_add_u32 s98, s40, s12
	s_addc_u32 s99, s41, s13
	s_add_u32 s100, s42, s12
	s_addc_u32 s101, s43, s13
	s_waitcnt vmcnt(8)
	s_waitcnt lgkmcnt(0)
	s_barrier
	s_waitcnt lgkmcnt(0)
	v_mfma_f32_16x16x32_bf16 v[60:63], v[128:131], v[206:209], 0
	v_mfma_f32_16x16x32_bf16 v[52:55], v[178:181], v[206:209], 0
	v_mfma_f32_16x16x32_bf16 v[36:39], v[178:181], v[214:217], 0
	v_mfma_f32_16x16x32_bf16 v[44:47], v[128:131], v[214:217], 0
	v_mfma_f32_16x16x32_bf16 v[28:31], v[128:131], v[222:225], 0
	v_mfma_f32_16x16x32_bf16 v[20:23], v[178:181], v[222:225], 0
	v_mfma_f32_16x16x32_bf16 v[4:7], v[178:181], v[230:233], 0
	v_mfma_f32_16x16x32_bf16 v[12:15], v[128:131], v[230:233], 0
	v_mfma_f32_16x16x32_bf16 v[60:63], v[132:135], v[210:213], v[60:63]
	v_mfma_f32_16x16x32_bf16 v[52:55], v[186:189], v[210:213], v[52:55]
	v_mfma_f32_16x16x32_bf16 v[36:39], v[186:189], v[218:221], v[36:39]
	v_mfma_f32_16x16x32_bf16 v[44:47], v[132:135], v[218:221], v[44:47]
	v_mfma_f32_16x16x32_bf16 v[28:31], v[132:135], v[226:229], v[28:31]
	v_mfma_f32_16x16x32_bf16 v[20:23], v[186:189], v[226:229], v[20:23]
	v_mfma_f32_16x16x32_bf16 v[4:7], v[186:189], v[234:237], v[4:7]
	v_mfma_f32_16x16x32_bf16 v[12:15], v[132:135], v[234:237], v[12:15]
	v_mfma_f32_16x16x32_bf16 v[56:59], v[190:193], v[206:209], 0
	v_mfma_f32_16x16x32_bf16 v[48:51], v[198:201], v[206:209], 0
	v_mfma_f32_16x16x32_bf16 v[32:35], v[198:201], v[214:217], 0
	v_mfma_f32_16x16x32_bf16 v[40:43], v[190:193], v[214:217], 0
	v_mfma_f32_16x16x32_bf16 v[24:27], v[190:193], v[222:225], 0
	v_mfma_f32_16x16x32_bf16 v[16:19], v[198:201], v[222:225], 0
	v_mfma_f32_16x16x32_bf16 v[0:3], v[198:201], v[230:233], 0
	v_mfma_f32_16x16x32_bf16 v[8:11], v[190:193], v[230:233], 0
	v_mfma_f32_16x16x32_bf16 v[56:59], v[194:197], v[210:213], v[56:59]
	v_mfma_f32_16x16x32_bf16 v[48:51], v[202:205], v[210:213], v[48:51]
	v_mfma_f32_16x16x32_bf16 v[32:35], v[202:205], v[218:221], v[32:35]
	v_mfma_f32_16x16x32_bf16 v[40:43], v[194:197], v[218:221], v[40:43]
	v_mfma_f32_16x16x32_bf16 v[24:27], v[194:197], v[226:229], v[24:27]
	v_mfma_f32_16x16x32_bf16 v[16:19], v[202:205], v[226:229], v[16:19]
	v_mfma_f32_16x16x32_bf16 v[0:3], v[202:205], v[234:237], v[0:3]
	v_mfma_f32_16x16x32_bf16 v[8:11], v[194:197], v[234:237], v[8:11]
	s_barrier
	s_add_i32 s21, 0, 0x18000
	v_add_u32_e32 v144, s21, v165
	s_add_i32 s27, 0, 0x1c000
	ds_read_b128 v[128:131], v144
	ds_read_b128 v[132:135], v144 offset:1024
	ds_read_b128 v[178:181], v144 offset:2048
	ds_read_b128 v[186:189], v144 offset:3072
	v_add_u32_e32 v144, s27, v165
	ds_read_b128 v[190:193], v144
	ds_read_b128 v[194:197], v144 offset:1024
	ds_read_b128 v[198:201], v144 offset:2048
	ds_read_b128 v[202:205], v144 offset:3072
	s_add_u32 s22, s42, 0x40000
	s_addc_u32 s23, s43, 0
	s_mov_b32 m0, s64
	ds_read_b128 v[206:209], v175 offset:32768
	ds_read_b128 v[210:213], v175 offset:33792
	ds_read_b128 v[214:217], v175 offset:34816
	ds_read_b128 v[218:221], v175 offset:35840
	ds_read_b128 v[222:225], v175 offset:36864
	ds_read_b128 v[226:229], v175 offset:37888
	ds_read_b128 v[230:233], v175 offset:38912
	ds_read_b128 v[234:237], v175 offset:39936
	global_load_lds_dwordx4 v142, s[22:23]
	s_mov_b32 m0, s65
	s_nop 0
	global_load_lds_dwordx4 v138, s[22:23]
	s_waitcnt vmcnt(8)
	s_waitcnt lgkmcnt(0)
	s_barrier
	s_waitcnt lgkmcnt(0)
	v_mfma_f32_16x16x32_bf16 v[124:127], v[128:131], v[206:209], v[124:127]
	v_mfma_f32_16x16x32_bf16 v[120:123], v[178:181], v[206:209], v[120:123]
	v_mfma_f32_16x16x32_bf16 v[100:103], v[178:181], v[214:217], v[100:103]
	v_mfma_f32_16x16x32_bf16 v[108:111], v[128:131], v[214:217], v[108:111]
	v_mfma_f32_16x16x32_bf16 v[92:95], v[128:131], v[222:225], v[92:95]
	v_mfma_f32_16x16x32_bf16 v[84:87], v[178:181], v[222:225], v[84:87]
	v_mfma_f32_16x16x32_bf16 v[68:71], v[178:181], v[230:233], v[68:71]
	v_mfma_f32_16x16x32_bf16 v[76:79], v[128:131], v[230:233], v[76:79]
	v_mfma_f32_16x16x32_bf16 v[124:127], v[132:135], v[210:213], v[124:127]
	v_mfma_f32_16x16x32_bf16 v[120:123], v[186:189], v[210:213], v[120:123]
	v_mfma_f32_16x16x32_bf16 v[100:103], v[186:189], v[218:221], v[100:103]
	v_mfma_f32_16x16x32_bf16 v[108:111], v[132:135], v[218:221], v[108:111]
	v_mfma_f32_16x16x32_bf16 v[92:95], v[132:135], v[226:229], v[92:95]
	v_mfma_f32_16x16x32_bf16 v[84:87], v[186:189], v[226:229], v[84:87]
	v_mfma_f32_16x16x32_bf16 v[68:71], v[186:189], v[234:237], v[68:71]
	v_mfma_f32_16x16x32_bf16 v[76:79], v[132:135], v[234:237], v[76:79]
	v_mfma_f32_16x16x32_bf16 v[116:119], v[190:193], v[206:209], v[116:119]
	v_mfma_f32_16x16x32_bf16 v[112:115], v[198:201], v[206:209], v[112:115]
	v_mfma_f32_16x16x32_bf16 v[96:99], v[198:201], v[214:217], v[96:99]
	v_mfma_f32_16x16x32_bf16 v[104:107], v[190:193], v[214:217], v[104:107]
	v_mfma_f32_16x16x32_bf16 v[88:91], v[190:193], v[222:225], v[88:91]
	v_mfma_f32_16x16x32_bf16 v[80:83], v[198:201], v[222:225], v[80:83]
	v_mfma_f32_16x16x32_bf16 v[64:67], v[198:201], v[230:233], v[64:67]
	v_mfma_f32_16x16x32_bf16 v[72:75], v[190:193], v[230:233], v[72:75]
	v_mfma_f32_16x16x32_bf16 v[116:119], v[194:197], v[210:213], v[116:119]
	v_mfma_f32_16x16x32_bf16 v[112:115], v[202:205], v[210:213], v[112:115]
	v_mfma_f32_16x16x32_bf16 v[96:99], v[202:205], v[218:221], v[96:99]
	v_mfma_f32_16x16x32_bf16 v[104:107], v[194:197], v[218:221], v[104:107]
	v_mfma_f32_16x16x32_bf16 v[88:91], v[194:197], v[226:229], v[88:91]
	v_mfma_f32_16x16x32_bf16 v[80:83], v[202:205], v[226:229], v[80:83]
	v_mfma_f32_16x16x32_bf16 v[64:67], v[202:205], v[234:237], v[64:67]
	v_mfma_f32_16x16x32_bf16 v[72:75], v[194:197], v[234:237], v[72:75]
	s_barrier
	s_add_i32 s21, s21, s60
	s_mov_b32 m0, s21
	ds_read_b128 v[206:209], v175 offset:49152
	ds_read_b128 v[210:213], v175 offset:50176
	ds_read_b128 v[214:217], v175 offset:51200
	ds_read_b128 v[218:221], v175 offset:52224
	ds_read_b128 v[222:225], v175 offset:53248
	ds_read_b128 v[226:229], v175 offset:54272
	ds_read_b128 v[230:233], v175 offset:55296
	ds_read_b128 v[234:237], v175 offset:56320
	global_load_lds_dwordx4 v140, s[98:99]
	s_add_i32 m0, s21, 0x2000
	s_add_u32 s22, s40, 0x40080
	s_addc_u32 s23, s41, 0
	s_add_i32 s21, s27, s60
	global_load_lds_dwordx4 v136, s[98:99]
	s_mov_b32 m0, s21
	s_nop 0
	global_load_lds_dwordx4 v140, s[22:23]
	s_add_i32 m0, s21, 0x2000
	s_nop 0
	global_load_lds_dwordx4 v136, s[22:23]
	s_mov_b32 m0, s67
	s_nop 0
	global_load_lds_dwordx4 v142, s[100:101]
	s_mov_b32 m0, s70
	s_nop 0
	global_load_lds_dwordx4 v138, s[100:101]
	s_waitcnt vmcnt(8)
	s_waitcnt lgkmcnt(0)
	s_barrier
	s_waitcnt lgkmcnt(0)
	v_mfma_f32_16x16x32_bf16 v[60:63], v[128:131], v[206:209], v[60:63]
	v_mfma_f32_16x16x32_bf16 v[52:55], v[178:181], v[206:209], v[52:55]
	v_mfma_f32_16x16x32_bf16 v[36:39], v[178:181], v[214:217], v[36:39]
	v_mfma_f32_16x16x32_bf16 v[44:47], v[128:131], v[214:217], v[44:47]
	v_mfma_f32_16x16x32_bf16 v[28:31], v[128:131], v[222:225], v[28:31]
	v_mfma_f32_16x16x32_bf16 v[20:23], v[178:181], v[222:225], v[20:23]
	v_mfma_f32_16x16x32_bf16 v[4:7], v[178:181], v[230:233], v[4:7]
	v_mfma_f32_16x16x32_bf16 v[12:15], v[128:131], v[230:233], v[12:15]
	v_mfma_f32_16x16x32_bf16 v[60:63], v[132:135], v[210:213], v[60:63]
	v_mfma_f32_16x16x32_bf16 v[52:55], v[186:189], v[210:213], v[52:55]
	v_mfma_f32_16x16x32_bf16 v[36:39], v[186:189], v[218:221], v[36:39]
	v_mfma_f32_16x16x32_bf16 v[44:47], v[132:135], v[218:221], v[44:47]
	v_mfma_f32_16x16x32_bf16 v[28:31], v[132:135], v[226:229], v[28:31]
	v_mfma_f32_16x16x32_bf16 v[20:23], v[186:189], v[226:229], v[20:23]
	v_mfma_f32_16x16x32_bf16 v[4:7], v[186:189], v[234:237], v[4:7]
	v_mfma_f32_16x16x32_bf16 v[12:15], v[132:135], v[234:237], v[12:15]
	v_mfma_f32_16x16x32_bf16 v[56:59], v[190:193], v[206:209], v[56:59]
	v_mfma_f32_16x16x32_bf16 v[48:51], v[198:201], v[206:209], v[48:51]
	v_mfma_f32_16x16x32_bf16 v[32:35], v[198:201], v[214:217], v[32:35]
	v_mfma_f32_16x16x32_bf16 v[40:43], v[190:193], v[214:217], v[40:43]
	v_mfma_f32_16x16x32_bf16 v[24:27], v[190:193], v[222:225], v[24:27]
	v_mfma_f32_16x16x32_bf16 v[16:19], v[198:201], v[222:225], v[16:19]
	v_mfma_f32_16x16x32_bf16 v[0:3], v[198:201], v[230:233], v[0:3]
	v_mfma_f32_16x16x32_bf16 v[8:11], v[190:193], v[230:233], v[8:11]
	v_mfma_f32_16x16x32_bf16 v[56:59], v[194:197], v[210:213], v[56:59]
	v_mfma_f32_16x16x32_bf16 v[48:51], v[202:205], v[210:213], v[48:51]
	v_mfma_f32_16x16x32_bf16 v[32:35], v[202:205], v[218:221], v[32:35]
	v_mfma_f32_16x16x32_bf16 v[40:43], v[194:197], v[218:221], v[40:43]
	v_mfma_f32_16x16x32_bf16 v[24:27], v[194:197], v[226:229], v[24:27]
	v_mfma_f32_16x16x32_bf16 v[16:19], v[202:205], v[226:229], v[16:19]
	v_mfma_f32_16x16x32_bf16 v[0:3], v[202:205], v[234:237], v[0:3]
	v_mfma_f32_16x16x32_bf16 v[8:11], v[194:197], v[234:237], v[8:11]
	s_barrier
	s_add_i32 s20, s20, 2
	s_add_u32 s38, s38, 0x100
	s_addc_u32 s39, s39, 0
	s_add_u32 s18, s18, 0x100
	s_addc_u32 s19, s19, 0
	s_cmp_gt_u32 s20, 13
	s_cbranch_scc1 .Lpeel_exit_1413
.LBB0_1413:
	ds_read_b128 v[128:131], v171
	ds_read_b128 v[132:135], v171 offset:1024
	ds_read_b128 v[178:181], v171 offset:2048
	ds_read_b128 v[186:189], v171 offset:3072
	ds_read_b128 v[190:193], v173
	ds_read_b128 v[194:197], v173 offset:1024
	ds_read_b128 v[198:201], v173 offset:2048
	ds_read_b128 v[202:205], v173 offset:3072
	s_add_u32 s21, s38, 0xfffc0080
	s_addc_u32 s22, s39, -1
	s_cmp_eq_u32 s20, 12
	s_cselect_b32 s43, s14, s22
	s_cselect_b32 s42, s15, s21
	s_cselect_b32 s41, s16, s19
	s_cselect_b32 s40, s17, s18
	s_add_i32 m0, s37, 0xc000
	ds_read_b128 v[206:209], v175
	ds_read_b128 v[210:213], v175 offset:1024
	ds_read_b128 v[214:217], v175 offset:2048
	ds_read_b128 v[218:221], v175 offset:3072
	ds_read_b128 v[222:225], v175 offset:4096
	ds_read_b128 v[226:229], v175 offset:5120
	ds_read_b128 v[230:233], v175 offset:6144
	ds_read_b128 v[234:237], v175 offset:7168
	global_load_lds_dwordx4 v152, s[38:39]
	s_add_i32 m0, s37, 0xe000
	s_nop 0
	global_load_lds_dwordx4 v154, s[38:39]
	s_waitcnt vmcnt(8)
	s_waitcnt lgkmcnt(0)
	s_barrier
	s_waitcnt lgkmcnt(0)
	v_mfma_f32_16x16x32_bf16 v[124:127], v[128:131], v[206:209], v[124:127]
	v_mfma_f32_16x16x32_bf16 v[120:123], v[178:181], v[206:209], v[120:123]
	v_mfma_f32_16x16x32_bf16 v[100:103], v[178:181], v[214:217], v[100:103]
	v_mfma_f32_16x16x32_bf16 v[108:111], v[128:131], v[214:217], v[108:111]
	v_mfma_f32_16x16x32_bf16 v[92:95], v[128:131], v[222:225], v[92:95]
	v_mfma_f32_16x16x32_bf16 v[84:87], v[178:181], v[222:225], v[84:87]
	v_mfma_f32_16x16x32_bf16 v[68:71], v[178:181], v[230:233], v[68:71]
	v_mfma_f32_16x16x32_bf16 v[76:79], v[128:131], v[230:233], v[76:79]
	v_mfma_f32_16x16x32_bf16 v[124:127], v[132:135], v[210:213], v[124:127]
	v_mfma_f32_16x16x32_bf16 v[120:123], v[186:189], v[210:213], v[120:123]
	v_mfma_f32_16x16x32_bf16 v[100:103], v[186:189], v[218:221], v[100:103]
	v_mfma_f32_16x16x32_bf16 v[108:111], v[132:135], v[218:221], v[108:111]
	v_mfma_f32_16x16x32_bf16 v[92:95], v[132:135], v[226:229], v[92:95]
	v_mfma_f32_16x16x32_bf16 v[84:87], v[186:189], v[226:229], v[84:87]
	v_mfma_f32_16x16x32_bf16 v[68:71], v[186:189], v[234:237], v[68:71]
	v_mfma_f32_16x16x32_bf16 v[76:79], v[132:135], v[234:237], v[76:79]
	v_mfma_f32_16x16x32_bf16 v[116:119], v[190:193], v[206:209], v[116:119]
	v_mfma_f32_16x16x32_bf16 v[112:115], v[198:201], v[206:209], v[112:115]
	v_mfma_f32_16x16x32_bf16 v[96:99], v[198:201], v[214:217], v[96:99]
	v_mfma_f32_16x16x32_bf16 v[104:107], v[190:193], v[214:217], v[104:107]
	v_mfma_f32_16x16x32_bf16 v[88:91], v[190:193], v[222:225], v[88:91]
	v_mfma_f32_16x16x32_bf16 v[80:83], v[198:201], v[222:225], v[80:83]
	v_mfma_f32_16x16x32_bf16 v[64:67], v[198:201], v[230:233], v[64:67]
	v_mfma_f32_16x16x32_bf16 v[72:75], v[190:193], v[230:233], v[72:75]
	v_mfma_f32_16x16x32_bf16 v[116:119], v[194:197], v[210:213], v[116:119]
	v_mfma_f32_16x16x32_bf16 v[112:115], v[202:205], v[210:213], v[112:115]
	v_mfma_f32_16x16x32_bf16 v[96:99], v[202:205], v[218:221], v[96:99]
	v_mfma_f32_16x16x32_bf16 v[104:107], v[194:197], v[218:221], v[104:107]
	v_mfma_f32_16x16x32_bf16 v[88:91], v[194:197], v[226:229], v[88:91]
	v_mfma_f32_16x16x32_bf16 v[80:83], v[202:205], v[226:229], v[80:83]
	v_mfma_f32_16x16x32_bf16 v[64:67], v[202:205], v[234:237], v[64:67]
	v_mfma_f32_16x16x32_bf16 v[72:75], v[194:197], v[234:237], v[72:75]
	s_barrier
	s_add_i32 s21, s44, s60
	s_mov_b32 m0, s21
	ds_read_b128 v[206:209], v175 offset:16384
	ds_read_b128 v[210:213], v175 offset:17408
	ds_read_b128 v[214:217], v175 offset:18432
	ds_read_b128 v[218:221], v175 offset:19456
	ds_read_b128 v[222:225], v175 offset:20480
	ds_read_b128 v[226:229], v175 offset:21504
	ds_read_b128 v[230:233], v175 offset:22528
	ds_read_b128 v[234:237], v175 offset:23552
	global_load_lds_dwordx4 v140, s[40:41]
	s_add_i32 m0, s21, 0x2000
	s_add_u32 s22, s40, 0x40000
	s_addc_u32 s23, s41, 0
	s_add_i32 s21, s45, s60
	global_load_lds_dwordx4 v136, s[40:41]
	s_mov_b32 m0, s21
	global_load_lds_dwordx4 v140, s[22:23]
	s_add_i32 m0, s21, 0x2000
	s_nop 0
	global_load_lds_dwordx4 v136, s[22:23]
	s_mov_b32 m0, s37
	s_nop 0
	global_load_lds_dwordx4 v142, s[42:43]
	s_mov_b32 m0, s63
	s_nop 0
	global_load_lds_dwordx4 v138, s[42:43]
	s_add_u32 s98, s40, s12
	s_addc_u32 s99, s41, s13
	s_add_u32 s100, s42, s12
	s_addc_u32 s101, s43, s13
	s_waitcnt vmcnt(8)
	s_waitcnt lgkmcnt(0)
	s_barrier
	s_waitcnt lgkmcnt(0)
	v_mfma_f32_16x16x32_bf16 v[60:63], v[128:131], v[206:209], v[60:63]
	v_mfma_f32_16x16x32_bf16 v[52:55], v[178:181], v[206:209], v[52:55]
	v_mfma_f32_16x16x32_bf16 v[36:39], v[178:181], v[214:217], v[36:39]
	v_mfma_f32_16x16x32_bf16 v[44:47], v[128:131], v[214:217], v[44:47]
	v_mfma_f32_16x16x32_bf16 v[28:31], v[128:131], v[222:225], v[28:31]
	v_mfma_f32_16x16x32_bf16 v[20:23], v[178:181], v[222:225], v[20:23]
	v_mfma_f32_16x16x32_bf16 v[4:7], v[178:181], v[230:233], v[4:7]
	v_mfma_f32_16x16x32_bf16 v[12:15], v[128:131], v[230:233], v[12:15]
	v_mfma_f32_16x16x32_bf16 v[60:63], v[132:135], v[210:213], v[60:63]
	v_mfma_f32_16x16x32_bf16 v[52:55], v[186:189], v[210:213], v[52:55]
	v_mfma_f32_16x16x32_bf16 v[36:39], v[186:189], v[218:221], v[36:39]
	v_mfma_f32_16x16x32_bf16 v[44:47], v[132:135], v[218:221], v[44:47]
	v_mfma_f32_16x16x32_bf16 v[28:31], v[132:135], v[226:229], v[28:31]
	v_mfma_f32_16x16x32_bf16 v[20:23], v[186:189], v[226:229], v[20:23]
	v_mfma_f32_16x16x32_bf16 v[4:7], v[186:189], v[234:237], v[4:7]
	v_mfma_f32_16x16x32_bf16 v[12:15], v[132:135], v[234:237], v[12:15]
	v_mfma_f32_16x16x32_bf16 v[56:59], v[190:193], v[206:209], v[56:59]
	v_mfma_f32_16x16x32_bf16 v[48:51], v[198:201], v[206:209], v[48:51]
	v_mfma_f32_16x16x32_bf16 v[32:35], v[198:201], v[214:217], v[32:35]
	v_mfma_f32_16x16x32_bf16 v[40:43], v[190:193], v[214:217], v[40:43]
	v_mfma_f32_16x16x32_bf16 v[24:27], v[190:193], v[222:225], v[24:27]
	v_mfma_f32_16x16x32_bf16 v[16:19], v[198:201], v[222:225], v[16:19]
	v_mfma_f32_16x16x32_bf16 v[0:3], v[198:201], v[230:233], v[0:3]
	v_mfma_f32_16x16x32_bf16 v[8:11], v[190:193], v[230:233], v[8:11]
	v_mfma_f32_16x16x32_bf16 v[56:59], v[194:197], v[210:213], v[56:59]
	v_mfma_f32_16x16x32_bf16 v[48:51], v[202:205], v[210:213], v[48:51]
	v_mfma_f32_16x16x32_bf16 v[32:35], v[202:205], v[218:221], v[32:35]
	v_mfma_f32_16x16x32_bf16 v[40:43], v[194:197], v[218:221], v[40:43]
	v_mfma_f32_16x16x32_bf16 v[24:27], v[194:197], v[226:229], v[24:27]
	v_mfma_f32_16x16x32_bf16 v[16:19], v[202:205], v[226:229], v[16:19]
	v_mfma_f32_16x16x32_bf16 v[0:3], v[202:205], v[234:237], v[0:3]
	v_mfma_f32_16x16x32_bf16 v[8:11], v[194:197], v[234:237], v[8:11]
	s_barrier
	s_add_i32 s21, 0, 0x18000
	v_add_u32_e32 v144, s21, v165
	s_add_i32 s27, 0, 0x1c000
	ds_read_b128 v[128:131], v144
	ds_read_b128 v[132:135], v144 offset:1024
	ds_read_b128 v[178:181], v144 offset:2048
	ds_read_b128 v[186:189], v144 offset:3072
	v_add_u32_e32 v144, s27, v165
	ds_read_b128 v[190:193], v144
	ds_read_b128 v[194:197], v144 offset:1024
	ds_read_b128 v[198:201], v144 offset:2048
	ds_read_b128 v[202:205], v144 offset:3072
	s_add_u32 s22, s42, 0x40000
	s_addc_u32 s23, s43, 0
	s_mov_b32 m0, s64
	ds_read_b128 v[206:209], v175 offset:32768
	ds_read_b128 v[210:213], v175 offset:33792
	ds_read_b128 v[214:217], v175 offset:34816
	ds_read_b128 v[218:221], v175 offset:35840
	ds_read_b128 v[222:225], v175 offset:36864
	ds_read_b128 v[226:229], v175 offset:37888
	ds_read_b128 v[230:233], v175 offset:38912
	ds_read_b128 v[234:237], v175 offset:39936
	global_load_lds_dwordx4 v142, s[22:23]
	s_mov_b32 m0, s65
	s_nop 0
	global_load_lds_dwordx4 v138, s[22:23]
	s_waitcnt vmcnt(8)
	s_waitcnt lgkmcnt(0)
	s_barrier
	s_waitcnt lgkmcnt(0)
	v_mfma_f32_16x16x32_bf16 v[124:127], v[128:131], v[206:209], v[124:127]
	v_mfma_f32_16x16x32_bf16 v[120:123], v[178:181], v[206:209], v[120:123]
	v_mfma_f32_16x16x32_bf16 v[100:103], v[178:181], v[214:217], v[100:103]
	v_mfma_f32_16x16x32_bf16 v[108:111], v[128:131], v[214:217], v[108:111]
	v_mfma_f32_16x16x32_bf16 v[92:95], v[128:131], v[222:225], v[92:95]
	v_mfma_f32_16x16x32_bf16 v[84:87], v[178:181], v[222:225], v[84:87]
	v_mfma_f32_16x16x32_bf16 v[68:71], v[178:181], v[230:233], v[68:71]
	v_mfma_f32_16x16x32_bf16 v[76:79], v[128:131], v[230:233], v[76:79]
	v_mfma_f32_16x16x32_bf16 v[124:127], v[132:135], v[210:213], v[124:127]
	v_mfma_f32_16x16x32_bf16 v[120:123], v[186:189], v[210:213], v[120:123]
	v_mfma_f32_16x16x32_bf16 v[100:103], v[186:189], v[218:221], v[100:103]
	v_mfma_f32_16x16x32_bf16 v[108:111], v[132:135], v[218:221], v[108:111]
	v_mfma_f32_16x16x32_bf16 v[92:95], v[132:135], v[226:229], v[92:95]
	v_mfma_f32_16x16x32_bf16 v[84:87], v[186:189], v[226:229], v[84:87]
	v_mfma_f32_16x16x32_bf16 v[68:71], v[186:189], v[234:237], v[68:71]
	v_mfma_f32_16x16x32_bf16 v[76:79], v[132:135], v[234:237], v[76:79]
	v_mfma_f32_16x16x32_bf16 v[116:119], v[190:193], v[206:209], v[116:119]
	v_mfma_f32_16x16x32_bf16 v[112:115], v[198:201], v[206:209], v[112:115]
	v_mfma_f32_16x16x32_bf16 v[96:99], v[198:201], v[214:217], v[96:99]
	v_mfma_f32_16x16x32_bf16 v[104:107], v[190:193], v[214:217], v[104:107]
	v_mfma_f32_16x16x32_bf16 v[88:91], v[190:193], v[222:225], v[88:91]
	v_mfma_f32_16x16x32_bf16 v[80:83], v[198:201], v[222:225], v[80:83]
	v_mfma_f32_16x16x32_bf16 v[64:67], v[198:201], v[230:233], v[64:67]
	v_mfma_f32_16x16x32_bf16 v[72:75], v[190:193], v[230:233], v[72:75]
	v_mfma_f32_16x16x32_bf16 v[116:119], v[194:197], v[210:213], v[116:119]
	v_mfma_f32_16x16x32_bf16 v[112:115], v[202:205], v[210:213], v[112:115]
	v_mfma_f32_16x16x32_bf16 v[96:99], v[202:205], v[218:221], v[96:99]
	v_mfma_f32_16x16x32_bf16 v[104:107], v[194:197], v[218:221], v[104:107]
	v_mfma_f32_16x16x32_bf16 v[88:91], v[194:197], v[226:229], v[88:91]
	v_mfma_f32_16x16x32_bf16 v[80:83], v[202:205], v[226:229], v[80:83]
	v_mfma_f32_16x16x32_bf16 v[64:67], v[202:205], v[234:237], v[64:67]
	v_mfma_f32_16x16x32_bf16 v[72:75], v[194:197], v[234:237], v[72:75]
	s_barrier
	s_add_i32 s21, s21, s60
	s_mov_b32 m0, s21
	ds_read_b128 v[206:209], v175 offset:49152
	ds_read_b128 v[210:213], v175 offset:50176
	ds_read_b128 v[214:217], v175 offset:51200
	ds_read_b128 v[218:221], v175 offset:52224
	ds_read_b128 v[222:225], v175 offset:53248
	ds_read_b128 v[226:229], v175 offset:54272
	ds_read_b128 v[230:233], v175 offset:55296
	ds_read_b128 v[234:237], v175 offset:56320
	global_load_lds_dwordx4 v140, s[98:99]
	s_add_i32 m0, s21, 0x2000
	s_add_u32 s22, s40, 0x40080
	s_addc_u32 s23, s41, 0
	s_add_i32 s21, s27, s60
	global_load_lds_dwordx4 v136, s[98:99]
	s_mov_b32 m0, s21
	s_nop 0
	global_load_lds_dwordx4 v140, s[22:23]
	s_add_i32 m0, s21, 0x2000
	s_nop 0
	global_load_lds_dwordx4 v136, s[22:23]
	s_mov_b32 m0, s67
	s_nop 0
	global_load_lds_dwordx4 v142, s[100:101]
	s_mov_b32 m0, s70
	s_nop 0
	global_load_lds_dwordx4 v138, s[100:101]
	s_waitcnt vmcnt(8)
	s_waitcnt lgkmcnt(0)
	s_barrier
	s_waitcnt lgkmcnt(0)
	v_mfma_f32_16x16x32_bf16 v[60:63], v[128:131], v[206:209], v[60:63]
	v_mfma_f32_16x16x32_bf16 v[52:55], v[178:181], v[206:209], v[52:55]
	v_mfma_f32_16x16x32_bf16 v[36:39], v[178:181], v[214:217], v[36:39]
	v_mfma_f32_16x16x32_bf16 v[44:47], v[128:131], v[214:217], v[44:47]
	v_mfma_f32_16x16x32_bf16 v[28:31], v[128:131], v[222:225], v[28:31]
	v_mfma_f32_16x16x32_bf16 v[20:23], v[178:181], v[222:225], v[20:23]
	v_mfma_f32_16x16x32_bf16 v[4:7], v[178:181], v[230:233], v[4:7]
	v_mfma_f32_16x16x32_bf16 v[12:15], v[128:131], v[230:233], v[12:15]
	v_mfma_f32_16x16x32_bf16 v[60:63], v[132:135], v[210:213], v[60:63]
	v_mfma_f32_16x16x32_bf16 v[52:55], v[186:189], v[210:213], v[52:55]
	v_mfma_f32_16x16x32_bf16 v[36:39], v[186:189], v[218:221], v[36:39]
	v_mfma_f32_16x16x32_bf16 v[44:47], v[132:135], v[218:221], v[44:47]
	v_mfma_f32_16x16x32_bf16 v[28:31], v[132:135], v[226:229], v[28:31]
	v_mfma_f32_16x16x32_bf16 v[20:23], v[186:189], v[226:229], v[20:23]
	v_mfma_f32_16x16x32_bf16 v[4:7], v[186:189], v[234:237], v[4:7]
	v_mfma_f32_16x16x32_bf16 v[12:15], v[132:135], v[234:237], v[12:15]
	v_mfma_f32_16x16x32_bf16 v[56:59], v[190:193], v[206:209], v[56:59]
	v_mfma_f32_16x16x32_bf16 v[48:51], v[198:201], v[206:209], v[48:51]
	v_mfma_f32_16x16x32_bf16 v[32:35], v[198:201], v[214:217], v[32:35]
	v_mfma_f32_16x16x32_bf16 v[40:43], v[190:193], v[214:217], v[40:43]
	v_mfma_f32_16x16x32_bf16 v[24:27], v[190:193], v[222:225], v[24:27]
	v_mfma_f32_16x16x32_bf16 v[16:19], v[198:201], v[222:225], v[16:19]
	v_mfma_f32_16x16x32_bf16 v[0:3], v[198:201], v[230:233], v[0:3]
	v_mfma_f32_16x16x32_bf16 v[8:11], v[190:193], v[230:233], v[8:11]
	v_mfma_f32_16x16x32_bf16 v[56:59], v[194:197], v[210:213], v[56:59]
	v_mfma_f32_16x16x32_bf16 v[48:51], v[202:205], v[210:213], v[48:51]
	v_mfma_f32_16x16x32_bf16 v[32:35], v[202:205], v[218:221], v[32:35]
	v_mfma_f32_16x16x32_bf16 v[40:43], v[194:197], v[218:221], v[40:43]
	v_mfma_f32_16x16x32_bf16 v[24:27], v[194:197], v[226:229], v[24:27]
	v_mfma_f32_16x16x32_bf16 v[16:19], v[202:205], v[226:229], v[16:19]
	v_mfma_f32_16x16x32_bf16 v[0:3], v[202:205], v[234:237], v[0:3]
	v_mfma_f32_16x16x32_bf16 v[8:11], v[194:197], v[234:237], v[8:11]
	s_barrier
	s_add_i32 s20, s20, 2
	s_add_u32 s38, s38, 0x100
	s_addc_u32 s39, s39, 0
	s_add_u32 s18, s18, 0x100
	s_addc_u32 s19, s19, 0
	s_cmp_gt_u32 s20, 13
	s_cbranch_scc0 .LBB0_1413

.LBB0_1629:
	s_add_u32 s22, s22, 0xb0080
	s_addc_u32 s23, s23, 0
	s_add_u32 s21, s24, 0x100
	s_addc_u32 s47, s25, 0
	s_mov_b32 s50, -2
	s_waitcnt lgkmcnt(0)
	ds_read_b128 v[128:131], v189
	ds_read_b128 v[132:135], v189 offset:1024
	ds_read_b128 v[136:139], v189 offset:2048
	ds_read_b128 v[140:143], v189 offset:3072
	ds_read_b128 v[144:147], v190
	ds_read_b128 v[148:151], v190 offset:1024
	ds_read_b128 v[172:175], v190 offset:2048
	ds_read_b128 v[176:179], v190 offset:3072
	s_add_u32 s24, s22, 0xfff50080
	s_addc_u32 s25, s23, -1
	s_cmp_eq_u32 s50, 40
	s_cselect_b32 s27, s1, s25
	s_cselect_b32 s26, s0, s24
	s_cselect_b32 s25, s19, s47
	s_cselect_b32 s24, s18, s21
	s_add_i32 m0, s30, 0xc000
	ds_read_b128 v[180:183], v191
	ds_read_b128 v[194:197], v191 offset:1024
	ds_read_b128 v[198:201], v191 offset:2048
	ds_read_b128 v[202:205], v191 offset:3072
	ds_read_b128 v[206:209], v191 offset:4096
	ds_read_b128 v[210:213], v191 offset:5120
	ds_read_b128 v[214:217], v191 offset:6144
	ds_read_b128 v[218:221], v191 offset:7168
	global_load_lds_dwordx4 v164, s[22:23]
	s_add_i32 m0, s30, 0xe000
	s_nop 0
	global_load_lds_dwordx4 v166, s[22:23]
	s_waitcnt vmcnt(8)
	s_waitcnt lgkmcnt(0)
	s_barrier
	s_waitcnt lgkmcnt(0)
	v_mfma_f32_16x16x32_bf16 v[124:127], v[128:131], v[180:183], 0
	v_mfma_f32_16x16x32_bf16 v[120:123], v[136:139], v[180:183], 0
	v_mfma_f32_16x16x32_bf16 v[104:107], v[136:139], v[198:201], 0
	v_mfma_f32_16x16x32_bf16 v[108:111], v[128:131], v[198:201], 0
	v_mfma_f32_16x16x32_bf16 v[92:95], v[128:131], v[206:209], 0
	v_mfma_f32_16x16x32_bf16 v[88:91], v[136:139], v[206:209], 0
	v_mfma_f32_16x16x32_bf16 v[72:75], v[136:139], v[214:217], 0
	v_mfma_f32_16x16x32_bf16 v[76:79], v[128:131], v[214:217], 0
	v_mfma_f32_16x16x32_bf16 v[124:127], v[132:135], v[194:197], v[124:127]
	v_mfma_f32_16x16x32_bf16 v[120:123], v[140:143], v[194:197], v[120:123]
	v_mfma_f32_16x16x32_bf16 v[104:107], v[140:143], v[202:205], v[104:107]
	v_mfma_f32_16x16x32_bf16 v[108:111], v[132:135], v[202:205], v[108:111]
	v_mfma_f32_16x16x32_bf16 v[92:95], v[132:135], v[210:213], v[92:95]
	v_mfma_f32_16x16x32_bf16 v[88:91], v[140:143], v[210:213], v[88:91]
	v_mfma_f32_16x16x32_bf16 v[72:75], v[140:143], v[218:221], v[72:75]
	v_mfma_f32_16x16x32_bf16 v[76:79], v[132:135], v[218:221], v[76:79]
	v_mfma_f32_16x16x32_bf16 v[116:119], v[144:147], v[180:183], 0
	v_mfma_f32_16x16x32_bf16 v[112:115], v[172:175], v[180:183], 0
	v_mfma_f32_16x16x32_bf16 v[96:99], v[172:175], v[198:201], 0
	v_mfma_f32_16x16x32_bf16 v[100:103], v[144:147], v[198:201], 0
	v_mfma_f32_16x16x32_bf16 v[84:87], v[144:147], v[206:209], 0
	v_mfma_f32_16x16x32_bf16 v[80:83], v[172:175], v[206:209], 0
	v_mfma_f32_16x16x32_bf16 v[64:67], v[172:175], v[214:217], 0
	v_mfma_f32_16x16x32_bf16 v[68:71], v[144:147], v[214:217], 0
	v_mfma_f32_16x16x32_bf16 v[116:119], v[148:151], v[194:197], v[116:119]
	v_mfma_f32_16x16x32_bf16 v[112:115], v[176:179], v[194:197], v[112:115]
	v_mfma_f32_16x16x32_bf16 v[96:99], v[176:179], v[202:205], v[96:99]
	v_mfma_f32_16x16x32_bf16 v[100:103], v[148:151], v[202:205], v[100:103]
	v_mfma_f32_16x16x32_bf16 v[84:87], v[148:151], v[210:213], v[84:87]
	v_mfma_f32_16x16x32_bf16 v[80:83], v[176:179], v[210:213], v[80:83]
	v_mfma_f32_16x16x32_bf16 v[64:67], v[176:179], v[218:221], v[64:67]
	v_mfma_f32_16x16x32_bf16 v[68:71], v[148:151], v[218:221], v[68:71]
	s_barrier
	s_add_i32 s51, s42, s29
	s_mov_b32 m0, s51
	ds_read_b128 v[180:183], v191 offset:16384
	ds_read_b128 v[194:197], v191 offset:17408
	ds_read_b128 v[198:201], v191 offset:18432
	ds_read_b128 v[202:205], v191 offset:19456
	ds_read_b128 v[206:209], v191 offset:20480
	ds_read_b128 v[210:213], v191 offset:21504
	ds_read_b128 v[214:217], v191 offset:22528
	ds_read_b128 v[218:221], v191 offset:23552
	global_load_lds_dwordx4 v154, s[24:25]
	s_add_i32 m0, s51, 0x2000
	s_add_u32 s52, s24, 0xb0000
	s_addc_u32 s53, s25, 0
	s_add_i32 s51, s43, s29
	global_load_lds_dwordx4 v158, s[24:25]
	s_mov_b32 m0, s51
	global_load_lds_dwordx4 v154, s[52:53]
	s_add_i32 m0, s51, 0x2000
	s_nop 0
	global_load_lds_dwordx4 v158, s[52:53]
	s_mov_b32 m0, s30
	s_nop 0
	global_load_lds_dwordx4 v152, s[26:27]
	s_mov_b32 m0, s31
	s_nop 0
	global_load_lds_dwordx4 v156, s[26:27]
	s_add_u32 s98, s24, s14
	s_addc_u32 s99, s25, s15
	s_add_u32 s100, s26, s14
	s_addc_u32 s101, s27, s15
	s_waitcnt vmcnt(8)
	s_waitcnt lgkmcnt(0)
	s_barrier
	s_waitcnt lgkmcnt(0)
	v_mfma_f32_16x16x32_bf16 v[60:63], v[128:131], v[180:183], 0
	v_mfma_f32_16x16x32_bf16 v[56:59], v[136:139], v[180:183], 0
	v_mfma_f32_16x16x32_bf16 v[40:43], v[136:139], v[198:201], 0
	v_mfma_f32_16x16x32_bf16 v[44:47], v[128:131], v[198:201], 0
	v_mfma_f32_16x16x32_bf16 v[28:31], v[128:131], v[206:209], 0
	v_mfma_f32_16x16x32_bf16 v[24:27], v[136:139], v[206:209], 0
	v_mfma_f32_16x16x32_bf16 v[8:11], v[136:139], v[214:217], 0
	v_mfma_f32_16x16x32_bf16 v[12:15], v[128:131], v[214:217], 0
	v_mfma_f32_16x16x32_bf16 v[60:63], v[132:135], v[194:197], v[60:63]
	v_mfma_f32_16x16x32_bf16 v[56:59], v[140:143], v[194:197], v[56:59]
	v_mfma_f32_16x16x32_bf16 v[40:43], v[140:143], v[202:205], v[40:43]
	v_mfma_f32_16x16x32_bf16 v[44:47], v[132:135], v[202:205], v[44:47]
	v_mfma_f32_16x16x32_bf16 v[28:31], v[132:135], v[210:213], v[28:31]
	v_mfma_f32_16x16x32_bf16 v[24:27], v[140:143], v[210:213], v[24:27]
	v_mfma_f32_16x16x32_bf16 v[8:11], v[140:143], v[218:221], v[8:11]
	v_mfma_f32_16x16x32_bf16 v[12:15], v[132:135], v[218:221], v[12:15]
	v_mfma_f32_16x16x32_bf16 v[52:55], v[144:147], v[180:183], 0
	v_mfma_f32_16x16x32_bf16 v[48:51], v[172:175], v[180:183], 0
	v_mfma_f32_16x16x32_bf16 v[32:35], v[172:175], v[198:201], 0
	v_mfma_f32_16x16x32_bf16 v[36:39], v[144:147], v[198:201], 0
	v_mfma_f32_16x16x32_bf16 v[20:23], v[144:147], v[206:209], 0
	v_mfma_f32_16x16x32_bf16 v[16:19], v[172:175], v[206:209], 0
	v_mfma_f32_16x16x32_bf16 v[0:3], v[172:175], v[214:217], 0
	v_mfma_f32_16x16x32_bf16 v[4:7], v[144:147], v[214:217], 0
	v_mfma_f32_16x16x32_bf16 v[52:55], v[148:151], v[194:197], v[52:55]
	v_mfma_f32_16x16x32_bf16 v[48:51], v[176:179], v[194:197], v[48:51]
	v_mfma_f32_16x16x32_bf16 v[32:35], v[176:179], v[202:205], v[32:35]
	v_mfma_f32_16x16x32_bf16 v[36:39], v[148:151], v[202:205], v[36:39]
	v_mfma_f32_16x16x32_bf16 v[20:23], v[148:151], v[210:213], v[20:23]
	v_mfma_f32_16x16x32_bf16 v[16:19], v[176:179], v[210:213], v[16:19]
	v_mfma_f32_16x16x32_bf16 v[0:3], v[176:179], v[218:221], v[0:3]
	v_mfma_f32_16x16x32_bf16 v[4:7], v[148:151], v[218:221], v[4:7]
	s_barrier
	s_add_i32 s51, 0, 0x18000
	s_add_i32 s52, 0, 0x1c000
	v_add_u32_e32 v140, s51, v186
	v_add_u32_e32 v176, s52, v186
	ds_read_b128 v[128:131], v140
	ds_read_b128 v[132:135], v140 offset:1024
	ds_read_b128 v[136:139], v140 offset:2048
	ds_read_b128 v[140:143], v140 offset:3072
	ds_read_b128 v[144:147], v176
	ds_read_b128 v[148:151], v176 offset:1024
	ds_read_b128 v[172:175], v176 offset:2048
	ds_read_b128 v[176:179], v176 offset:3072
	s_add_u32 s26, s26, 0xb0000
	s_addc_u32 s27, s27, 0
	s_mov_b32 m0, s34
	ds_read_b128 v[180:183], v191 offset:32768
	ds_read_b128 v[194:197], v191 offset:33792
	ds_read_b128 v[198:201], v191 offset:34816
	ds_read_b128 v[202:205], v191 offset:35840
	ds_read_b128 v[206:209], v191 offset:36864
	ds_read_b128 v[210:213], v191 offset:37888
	ds_read_b128 v[214:217], v191 offset:38912
	ds_read_b128 v[218:221], v191 offset:39936
	global_load_lds_dwordx4 v152, s[26:27]
	s_mov_b32 m0, s35
	s_nop 0
	global_load_lds_dwordx4 v156, s[26:27]
	s_waitcnt vmcnt(8)
	s_waitcnt lgkmcnt(0)
	s_barrier
	s_waitcnt lgkmcnt(0)
	v_mfma_f32_16x16x32_bf16 v[124:127], v[128:131], v[180:183], v[124:127]
	v_mfma_f32_16x16x32_bf16 v[120:123], v[136:139], v[180:183], v[120:123]
	v_mfma_f32_16x16x32_bf16 v[104:107], v[136:139], v[198:201], v[104:107]
	v_mfma_f32_16x16x32_bf16 v[108:111], v[128:131], v[198:201], v[108:111]
	v_mfma_f32_16x16x32_bf16 v[92:95], v[128:131], v[206:209], v[92:95]
	v_mfma_f32_16x16x32_bf16 v[88:91], v[136:139], v[206:209], v[88:91]
	v_mfma_f32_16x16x32_bf16 v[72:75], v[136:139], v[214:217], v[72:75]
	v_mfma_f32_16x16x32_bf16 v[76:79], v[128:131], v[214:217], v[76:79]
	v_mfma_f32_16x16x32_bf16 v[124:127], v[132:135], v[194:197], v[124:127]
	v_mfma_f32_16x16x32_bf16 v[120:123], v[140:143], v[194:197], v[120:123]
	v_mfma_f32_16x16x32_bf16 v[104:107], v[140:143], v[202:205], v[104:107]
	v_mfma_f32_16x16x32_bf16 v[108:111], v[132:135], v[202:205], v[108:111]
	v_mfma_f32_16x16x32_bf16 v[92:95], v[132:135], v[210:213], v[92:95]
	v_mfma_f32_16x16x32_bf16 v[88:91], v[140:143], v[210:213], v[88:91]
	v_mfma_f32_16x16x32_bf16 v[72:75], v[140:143], v[218:221], v[72:75]
	v_mfma_f32_16x16x32_bf16 v[76:79], v[132:135], v[218:221], v[76:79]
	v_mfma_f32_16x16x32_bf16 v[116:119], v[144:147], v[180:183], v[116:119]
	v_mfma_f32_16x16x32_bf16 v[112:115], v[172:175], v[180:183], v[112:115]
	v_mfma_f32_16x16x32_bf16 v[96:99], v[172:175], v[198:201], v[96:99]
	v_mfma_f32_16x16x32_bf16 v[100:103], v[144:147], v[198:201], v[100:103]
	v_mfma_f32_16x16x32_bf16 v[84:87], v[144:147], v[206:209], v[84:87]
	v_mfma_f32_16x16x32_bf16 v[80:83], v[172:175], v[206:209], v[80:83]
	v_mfma_f32_16x16x32_bf16 v[64:67], v[172:175], v[214:217], v[64:67]
	v_mfma_f32_16x16x32_bf16 v[68:71], v[144:147], v[214:217], v[68:71]
	v_mfma_f32_16x16x32_bf16 v[116:119], v[148:151], v[194:197], v[116:119]
	v_mfma_f32_16x16x32_bf16 v[112:115], v[176:179], v[194:197], v[112:115]
	v_mfma_f32_16x16x32_bf16 v[96:99], v[176:179], v[202:205], v[96:99]
	v_mfma_f32_16x16x32_bf16 v[100:103], v[148:151], v[202:205], v[100:103]
	v_mfma_f32_16x16x32_bf16 v[84:87], v[148:151], v[210:213], v[84:87]
	v_mfma_f32_16x16x32_bf16 v[80:83], v[176:179], v[210:213], v[80:83]
	v_mfma_f32_16x16x32_bf16 v[64:67], v[176:179], v[218:221], v[64:67]
	v_mfma_f32_16x16x32_bf16 v[68:71], v[148:151], v[218:221], v[68:71]
	s_barrier
	s_add_i32 s26, s51, s29
	s_mov_b32 m0, s26
	ds_read_b128 v[180:183], v191 offset:49152
	ds_read_b128 v[194:197], v191 offset:50176
	ds_read_b128 v[198:201], v191 offset:51200
	ds_read_b128 v[202:205], v191 offset:52224
	ds_read_b128 v[206:209], v191 offset:53248
	ds_read_b128 v[210:213], v191 offset:54272
	ds_read_b128 v[214:217], v191 offset:55296
	ds_read_b128 v[218:221], v191 offset:56320
	global_load_lds_dwordx4 v154, s[98:99]
	s_add_i32 m0, s26, 0x2000
	s_add_u32 s24, s24, 0xb0080
	s_addc_u32 s25, s25, 0
	s_add_i32 s26, s52, s29
	global_load_lds_dwordx4 v158, s[98:99]
	s_mov_b32 m0, s26
	s_nop 0
	global_load_lds_dwordx4 v154, s[24:25]
	s_add_i32 m0, s26, 0x2000
	s_nop 0
	global_load_lds_dwordx4 v158, s[24:25]
	s_mov_b32 m0, s37
	s_nop 0
	global_load_lds_dwordx4 v152, s[100:101]
	s_mov_b32 m0, s38
	s_nop 0
	global_load_lds_dwordx4 v156, s[100:101]
	s_waitcnt vmcnt(8)
	s_waitcnt lgkmcnt(0)
	s_barrier
	s_waitcnt lgkmcnt(0)
	v_mfma_f32_16x16x32_bf16 v[60:63], v[128:131], v[180:183], v[60:63]
	v_mfma_f32_16x16x32_bf16 v[56:59], v[136:139], v[180:183], v[56:59]
	v_mfma_f32_16x16x32_bf16 v[40:43], v[136:139], v[198:201], v[40:43]
	v_mfma_f32_16x16x32_bf16 v[44:47], v[128:131], v[198:201], v[44:47]
	v_mfma_f32_16x16x32_bf16 v[28:31], v[128:131], v[206:209], v[28:31]
	v_mfma_f32_16x16x32_bf16 v[24:27], v[136:139], v[206:209], v[24:27]
	v_mfma_f32_16x16x32_bf16 v[8:11], v[136:139], v[214:217], v[8:11]
	v_mfma_f32_16x16x32_bf16 v[12:15], v[128:131], v[214:217], v[12:15]
	v_mfma_f32_16x16x32_bf16 v[60:63], v[132:135], v[194:197], v[60:63]
	v_mfma_f32_16x16x32_bf16 v[56:59], v[140:143], v[194:197], v[56:59]
	v_mfma_f32_16x16x32_bf16 v[40:43], v[140:143], v[202:205], v[40:43]
	v_mfma_f32_16x16x32_bf16 v[44:47], v[132:135], v[202:205], v[44:47]
	v_mfma_f32_16x16x32_bf16 v[28:31], v[132:135], v[210:213], v[28:31]
	v_mfma_f32_16x16x32_bf16 v[24:27], v[140:143], v[210:213], v[24:27]
	v_mfma_f32_16x16x32_bf16 v[8:11], v[140:143], v[218:221], v[8:11]
	v_mfma_f32_16x16x32_bf16 v[12:15], v[132:135], v[218:221], v[12:15]
	v_mfma_f32_16x16x32_bf16 v[52:55], v[144:147], v[180:183], v[52:55]
	v_mfma_f32_16x16x32_bf16 v[48:51], v[172:175], v[180:183], v[48:51]
	v_mfma_f32_16x16x32_bf16 v[32:35], v[172:175], v[198:201], v[32:35]
	v_mfma_f32_16x16x32_bf16 v[36:39], v[144:147], v[198:201], v[36:39]
	v_mfma_f32_16x16x32_bf16 v[20:23], v[144:147], v[206:209], v[20:23]
	v_mfma_f32_16x16x32_bf16 v[16:19], v[172:175], v[206:209], v[16:19]
	v_mfma_f32_16x16x32_bf16 v[0:3], v[172:175], v[214:217], v[0:3]
	v_mfma_f32_16x16x32_bf16 v[4:7], v[144:147], v[214:217], v[4:7]
	v_mfma_f32_16x16x32_bf16 v[52:55], v[148:151], v[194:197], v[52:55]
	v_mfma_f32_16x16x32_bf16 v[48:51], v[176:179], v[194:197], v[48:51]
	v_mfma_f32_16x16x32_bf16 v[32:35], v[176:179], v[202:205], v[32:35]
	v_mfma_f32_16x16x32_bf16 v[36:39], v[148:151], v[202:205], v[36:39]
	v_mfma_f32_16x16x32_bf16 v[20:23], v[148:151], v[210:213], v[20:23]
	v_mfma_f32_16x16x32_bf16 v[16:19], v[176:179], v[210:213], v[16:19]
	v_mfma_f32_16x16x32_bf16 v[0:3], v[176:179], v[218:221], v[0:3]
	v_mfma_f32_16x16x32_bf16 v[4:7], v[148:151], v[218:221], v[4:7]
	s_barrier
	s_add_i32 s50, s50, 2
	s_add_u32 s22, s22, 0x100
	s_addc_u32 s23, s23, 0
	s_add_u32 s21, s21, 0x100
	s_addc_u32 s47, s47, 0
	s_cmp_gt_u32 s50, 41
	s_cbranch_scc1 .Lpeel_exit_1630
.LBB0_1630:
	ds_read_b128 v[128:131], v189
	ds_read_b128 v[132:135], v189 offset:1024
	ds_read_b128 v[136:139], v189 offset:2048
	ds_read_b128 v[140:143], v189 offset:3072
	ds_read_b128 v[144:147], v190
	ds_read_b128 v[148:151], v190 offset:1024
	ds_read_b128 v[172:175], v190 offset:2048
	ds_read_b128 v[176:179], v190 offset:3072
	s_add_u32 s24, s22, 0xfff50080
	s_addc_u32 s25, s23, -1
	s_cmp_eq_u32 s50, 40
	s_cselect_b32 s27, s1, s25
	s_cselect_b32 s26, s0, s24
	s_cselect_b32 s25, s19, s47
	s_cselect_b32 s24, s18, s21
	s_add_i32 m0, s30, 0xc000
	ds_read_b128 v[180:183], v191
	ds_read_b128 v[194:197], v191 offset:1024
	ds_read_b128 v[198:201], v191 offset:2048
	ds_read_b128 v[202:205], v191 offset:3072
	ds_read_b128 v[206:209], v191 offset:4096
	ds_read_b128 v[210:213], v191 offset:5120
	ds_read_b128 v[214:217], v191 offset:6144
	ds_read_b128 v[218:221], v191 offset:7168
	global_load_lds_dwordx4 v164, s[22:23]
	s_add_i32 m0, s30, 0xe000
	s_nop 0
	global_load_lds_dwordx4 v166, s[22:23]
	s_waitcnt vmcnt(8)
	s_waitcnt lgkmcnt(0)
	s_barrier
	s_waitcnt lgkmcnt(0)
	v_mfma_f32_16x16x32_bf16 v[124:127], v[128:131], v[180:183], v[124:127]
	v_mfma_f32_16x16x32_bf16 v[120:123], v[136:139], v[180:183], v[120:123]
	v_mfma_f32_16x16x32_bf16 v[104:107], v[136:139], v[198:201], v[104:107]
	v_mfma_f32_16x16x32_bf16 v[108:111], v[128:131], v[198:201], v[108:111]
	v_mfma_f32_16x16x32_bf16 v[92:95], v[128:131], v[206:209], v[92:95]
	v_mfma_f32_16x16x32_bf16 v[88:91], v[136:139], v[206:209], v[88:91]
	v_mfma_f32_16x16x32_bf16 v[72:75], v[136:139], v[214:217], v[72:75]
	v_mfma_f32_16x16x32_bf16 v[76:79], v[128:131], v[214:217], v[76:79]
	v_mfma_f32_16x16x32_bf16 v[124:127], v[132:135], v[194:197], v[124:127]
	v_mfma_f32_16x16x32_bf16 v[120:123], v[140:143], v[194:197], v[120:123]
	v_mfma_f32_16x16x32_bf16 v[104:107], v[140:143], v[202:205], v[104:107]
	v_mfma_f32_16x16x32_bf16 v[108:111], v[132:135], v[202:205], v[108:111]
	v_mfma_f32_16x16x32_bf16 v[92:95], v[132:135], v[210:213], v[92:95]
	v_mfma_f32_16x16x32_bf16 v[88:91], v[140:143], v[210:213], v[88:91]
	v_mfma_f32_16x16x32_bf16 v[72:75], v[140:143], v[218:221], v[72:75]
	v_mfma_f32_16x16x32_bf16 v[76:79], v[132:135], v[218:221], v[76:79]
	v_mfma_f32_16x16x32_bf16 v[116:119], v[144:147], v[180:183], v[116:119]
	v_mfma_f32_16x16x32_bf16 v[112:115], v[172:175], v[180:183], v[112:115]
	v_mfma_f32_16x16x32_bf16 v[96:99], v[172:175], v[198:201], v[96:99]
	v_mfma_f32_16x16x32_bf16 v[100:103], v[144:147], v[198:201], v[100:103]
	v_mfma_f32_16x16x32_bf16 v[84:87], v[144:147], v[206:209], v[84:87]
	v_mfma_f32_16x16x32_bf16 v[80:83], v[172:175], v[206:209], v[80:83]
	v_mfma_f32_16x16x32_bf16 v[64:67], v[172:175], v[214:217], v[64:67]
	v_mfma_f32_16x16x32_bf16 v[68:71], v[144:147], v[214:217], v[68:71]
	v_mfma_f32_16x16x32_bf16 v[116:119], v[148:151], v[194:197], v[116:119]
	v_mfma_f32_16x16x32_bf16 v[112:115], v[176:179], v[194:197], v[112:115]
	v_mfma_f32_16x16x32_bf16 v[96:99], v[176:179], v[202:205], v[96:99]
	v_mfma_f32_16x16x32_bf16 v[100:103], v[148:151], v[202:205], v[100:103]
	v_mfma_f32_16x16x32_bf16 v[84:87], v[148:151], v[210:213], v[84:87]
	v_mfma_f32_16x16x32_bf16 v[80:83], v[176:179], v[210:213], v[80:83]
	v_mfma_f32_16x16x32_bf16 v[64:67], v[176:179], v[218:221], v[64:67]
	v_mfma_f32_16x16x32_bf16 v[68:71], v[148:151], v[218:221], v[68:71]
	s_barrier
	s_add_i32 s51, s42, s29
	s_mov_b32 m0, s51
	ds_read_b128 v[180:183], v191 offset:16384
	ds_read_b128 v[194:197], v191 offset:17408
	ds_read_b128 v[198:201], v191 offset:18432
	ds_read_b128 v[202:205], v191 offset:19456
	ds_read_b128 v[206:209], v191 offset:20480
	ds_read_b128 v[210:213], v191 offset:21504
	ds_read_b128 v[214:217], v191 offset:22528
	ds_read_b128 v[218:221], v191 offset:23552
	global_load_lds_dwordx4 v154, s[24:25]
	s_add_i32 m0, s51, 0x2000
	s_add_u32 s52, s24, 0xb0000
	s_addc_u32 s53, s25, 0
	s_add_i32 s51, s43, s29
	global_load_lds_dwordx4 v158, s[24:25]
	s_mov_b32 m0, s51
	global_load_lds_dwordx4 v154, s[52:53]
	s_add_i32 m0, s51, 0x2000
	s_nop 0
	global_load_lds_dwordx4 v158, s[52:53]
	s_mov_b32 m0, s30
	s_nop 0
	global_load_lds_dwordx4 v152, s[26:27]
	s_mov_b32 m0, s31
	s_nop 0
	global_load_lds_dwordx4 v156, s[26:27]
	s_add_u32 s98, s24, s14
	s_addc_u32 s99, s25, s15
	s_add_u32 s100, s26, s14
	s_addc_u32 s101, s27, s15
	s_waitcnt vmcnt(8)
	s_waitcnt lgkmcnt(0)
	s_barrier
	s_waitcnt lgkmcnt(0)
	v_mfma_f32_16x16x32_bf16 v[60:63], v[128:131], v[180:183], v[60:63]
	v_mfma_f32_16x16x32_bf16 v[56:59], v[136:139], v[180:183], v[56:59]
	v_mfma_f32_16x16x32_bf16 v[40:43], v[136:139], v[198:201], v[40:43]
	v_mfma_f32_16x16x32_bf16 v[44:47], v[128:131], v[198:201], v[44:47]
	v_mfma_f32_16x16x32_bf16 v[28:31], v[128:131], v[206:209], v[28:31]
	v_mfma_f32_16x16x32_bf16 v[24:27], v[136:139], v[206:209], v[24:27]
	v_mfma_f32_16x16x32_bf16 v[8:11], v[136:139], v[214:217], v[8:11]
	v_mfma_f32_16x16x32_bf16 v[12:15], v[128:131], v[214:217], v[12:15]
	v_mfma_f32_16x16x32_bf16 v[60:63], v[132:135], v[194:197], v[60:63]
	v_mfma_f32_16x16x32_bf16 v[56:59], v[140:143], v[194:197], v[56:59]
	v_mfma_f32_16x16x32_bf16 v[40:43], v[140:143], v[202:205], v[40:43]
	v_mfma_f32_16x16x32_bf16 v[44:47], v[132:135], v[202:205], v[44:47]
	v_mfma_f32_16x16x32_bf16 v[28:31], v[132:135], v[210:213], v[28:31]
	v_mfma_f32_16x16x32_bf16 v[24:27], v[140:143], v[210:213], v[24:27]
	v_mfma_f32_16x16x32_bf16 v[8:11], v[140:143], v[218:221], v[8:11]
	v_mfma_f32_16x16x32_bf16 v[12:15], v[132:135], v[218:221], v[12:15]
	v_mfma_f32_16x16x32_bf16 v[52:55], v[144:147], v[180:183], v[52:55]
	v_mfma_f32_16x16x32_bf16 v[48:51], v[172:175], v[180:183], v[48:51]
	v_mfma_f32_16x16x32_bf16 v[32:35], v[172:175], v[198:201], v[32:35]
	v_mfma_f32_16x16x32_bf16 v[36:39], v[144:147], v[198:201], v[36:39]
	v_mfma_f32_16x16x32_bf16 v[20:23], v[144:147], v[206:209], v[20:23]
	v_mfma_f32_16x16x32_bf16 v[16:19], v[172:175], v[206:209], v[16:19]
	v_mfma_f32_16x16x32_bf16 v[0:3], v[172:175], v[214:217], v[0:3]
	v_mfma_f32_16x16x32_bf16 v[4:7], v[144:147], v[214:217], v[4:7]
	v_mfma_f32_16x16x32_bf16 v[52:55], v[148:151], v[194:197], v[52:55]
	v_mfma_f32_16x16x32_bf16 v[48:51], v[176:179], v[194:197], v[48:51]
	v_mfma_f32_16x16x32_bf16 v[32:35], v[176:179], v[202:205], v[32:35]
	v_mfma_f32_16x16x32_bf16 v[36:39], v[148:151], v[202:205], v[36:39]
	v_mfma_f32_16x16x32_bf16 v[20:23], v[148:151], v[210:213], v[20:23]
	v_mfma_f32_16x16x32_bf16 v[16:19], v[176:179], v[210:213], v[16:19]
	v_mfma_f32_16x16x32_bf16 v[0:3], v[176:179], v[218:221], v[0:3]
	v_mfma_f32_16x16x32_bf16 v[4:7], v[148:151], v[218:221], v[4:7]
	s_barrier
	s_add_i32 s51, 0, 0x18000
	s_add_i32 s52, 0, 0x1c000
	v_add_u32_e32 v140, s51, v186
	v_add_u32_e32 v176, s52, v186
	ds_read_b128 v[128:131], v140
	ds_read_b128 v[132:135], v140 offset:1024
	ds_read_b128 v[136:139], v140 offset:2048
	ds_read_b128 v[140:143], v140 offset:3072
	ds_read_b128 v[144:147], v176
	ds_read_b128 v[148:151], v176 offset:1024
	ds_read_b128 v[172:175], v176 offset:2048
	ds_read_b128 v[176:179], v176 offset:3072
	s_add_u32 s26, s26, 0xb0000
	s_addc_u32 s27, s27, 0
	s_mov_b32 m0, s34
	ds_read_b128 v[180:183], v191 offset:32768
	ds_read_b128 v[194:197], v191 offset:33792
	ds_read_b128 v[198:201], v191 offset:34816
	ds_read_b128 v[202:205], v191 offset:35840
	ds_read_b128 v[206:209], v191 offset:36864
	ds_read_b128 v[210:213], v191 offset:37888
	ds_read_b128 v[214:217], v191 offset:38912
	ds_read_b128 v[218:221], v191 offset:39936
	global_load_lds_dwordx4 v152, s[26:27]
	s_mov_b32 m0, s35
	s_nop 0
	global_load_lds_dwordx4 v156, s[26:27]
	s_waitcnt vmcnt(8)
	s_waitcnt lgkmcnt(0)
	s_barrier
	s_waitcnt lgkmcnt(0)
	v_mfma_f32_16x16x32_bf16 v[124:127], v[128:131], v[180:183], v[124:127]
	v_mfma_f32_16x16x32_bf16 v[120:123], v[136:139], v[180:183], v[120:123]
	v_mfma_f32_16x16x32_bf16 v[104:107], v[136:139], v[198:201], v[104:107]
	v_mfma_f32_16x16x32_bf16 v[108:111], v[128:131], v[198:201], v[108:111]
	v_mfma_f32_16x16x32_bf16 v[92:95], v[128:131], v[206:209], v[92:95]
	v_mfma_f32_16x16x32_bf16 v[88:91], v[136:139], v[206:209], v[88:91]
	v_mfma_f32_16x16x32_bf16 v[72:75], v[136:139], v[214:217], v[72:75]
	v_mfma_f32_16x16x32_bf16 v[76:79], v[128:131], v[214:217], v[76:79]
	v_mfma_f32_16x16x32_bf16 v[124:127], v[132:135], v[194:197], v[124:127]
	v_mfma_f32_16x16x32_bf16 v[120:123], v[140:143], v[194:197], v[120:123]
	v_mfma_f32_16x16x32_bf16 v[104:107], v[140:143], v[202:205], v[104:107]
	v_mfma_f32_16x16x32_bf16 v[108:111], v[132:135], v[202:205], v[108:111]
	v_mfma_f32_16x16x32_bf16 v[92:95], v[132:135], v[210:213], v[92:95]
	v_mfma_f32_16x16x32_bf16 v[88:91], v[140:143], v[210:213], v[88:91]
	v_mfma_f32_16x16x32_bf16 v[72:75], v[140:143], v[218:221], v[72:75]
	v_mfma_f32_16x16x32_bf16 v[76:79], v[132:135], v[218:221], v[76:79]
	v_mfma_f32_16x16x32_bf16 v[116:119], v[144:147], v[180:183], v[116:119]
	v_mfma_f32_16x16x32_bf16 v[112:115], v[172:175], v[180:183], v[112:115]
	v_mfma_f32_16x16x32_bf16 v[96:99], v[172:175], v[198:201], v[96:99]
	v_mfma_f32_16x16x32_bf16 v[100:103], v[144:147], v[198:201], v[100:103]
	v_mfma_f32_16x16x32_bf16 v[84:87], v[144:147], v[206:209], v[84:87]
	v_mfma_f32_16x16x32_bf16 v[80:83], v[172:175], v[206:209], v[80:83]
	v_mfma_f32_16x16x32_bf16 v[64:67], v[172:175], v[214:217], v[64:67]
	v_mfma_f32_16x16x32_bf16 v[68:71], v[144:147], v[214:217], v[68:71]
	v_mfma_f32_16x16x32_bf16 v[116:119], v[148:151], v[194:197], v[116:119]
	v_mfma_f32_16x16x32_bf16 v[112:115], v[176:179], v[194:197], v[112:115]
	v_mfma_f32_16x16x32_bf16 v[96:99], v[176:179], v[202:205], v[96:99]
	v_mfma_f32_16x16x32_bf16 v[100:103], v[148:151], v[202:205], v[100:103]
	v_mfma_f32_16x16x32_bf16 v[84:87], v[148:151], v[210:213], v[84:87]
	v_mfma_f32_16x16x32_bf16 v[80:83], v[176:179], v[210:213], v[80:83]
	v_mfma_f32_16x16x32_bf16 v[64:67], v[176:179], v[218:221], v[64:67]
	v_mfma_f32_16x16x32_bf16 v[68:71], v[148:151], v[218:221], v[68:71]
	s_barrier
	s_add_i32 s26, s51, s29
	s_mov_b32 m0, s26
	ds_read_b128 v[180:183], v191 offset:49152
	ds_read_b128 v[194:197], v191 offset:50176
	ds_read_b128 v[198:201], v191 offset:51200
	ds_read_b128 v[202:205], v191 offset:52224
	ds_read_b128 v[206:209], v191 offset:53248
	ds_read_b128 v[210:213], v191 offset:54272
	ds_read_b128 v[214:217], v191 offset:55296
	ds_read_b128 v[218:221], v191 offset:56320
	global_load_lds_dwordx4 v154, s[98:99]
	s_add_i32 m0, s26, 0x2000
	s_add_u32 s24, s24, 0xb0080
	s_addc_u32 s25, s25, 0
	s_add_i32 s26, s52, s29
	global_load_lds_dwordx4 v158, s[98:99]
	s_mov_b32 m0, s26
	s_nop 0
	global_load_lds_dwordx4 v154, s[24:25]
	s_add_i32 m0, s26, 0x2000
	s_nop 0
	global_load_lds_dwordx4 v158, s[24:25]
	s_mov_b32 m0, s37
	s_nop 0
	global_load_lds_dwordx4 v152, s[100:101]
	s_mov_b32 m0, s38
	s_nop 0
	global_load_lds_dwordx4 v156, s[100:101]
	s_waitcnt vmcnt(8)
	s_waitcnt lgkmcnt(0)
	s_barrier
	s_waitcnt lgkmcnt(0)
	v_mfma_f32_16x16x32_bf16 v[60:63], v[128:131], v[180:183], v[60:63]
	v_mfma_f32_16x16x32_bf16 v[56:59], v[136:139], v[180:183], v[56:59]
	v_mfma_f32_16x16x32_bf16 v[40:43], v[136:139], v[198:201], v[40:43]
	v_mfma_f32_16x16x32_bf16 v[44:47], v[128:131], v[198:201], v[44:47]
	v_mfma_f32_16x16x32_bf16 v[28:31], v[128:131], v[206:209], v[28:31]
	v_mfma_f32_16x16x32_bf16 v[24:27], v[136:139], v[206:209], v[24:27]
	v_mfma_f32_16x16x32_bf16 v[8:11], v[136:139], v[214:217], v[8:11]
	v_mfma_f32_16x16x32_bf16 v[12:15], v[128:131], v[214:217], v[12:15]
	v_mfma_f32_16x16x32_bf16 v[60:63], v[132:135], v[194:197], v[60:63]
	v_mfma_f32_16x16x32_bf16 v[56:59], v[140:143], v[194:197], v[56:59]
	v_mfma_f32_16x16x32_bf16 v[40:43], v[140:143], v[202:205], v[40:43]
	v_mfma_f32_16x16x32_bf16 v[44:47], v[132:135], v[202:205], v[44:47]
	v_mfma_f32_16x16x32_bf16 v[28:31], v[132:135], v[210:213], v[28:31]
	v_mfma_f32_16x16x32_bf16 v[24:27], v[140:143], v[210:213], v[24:27]
	v_mfma_f32_16x16x32_bf16 v[8:11], v[140:143], v[218:221], v[8:11]
	v_mfma_f32_16x16x32_bf16 v[12:15], v[132:135], v[218:221], v[12:15]
	v_mfma_f32_16x16x32_bf16 v[52:55], v[144:147], v[180:183], v[52:55]
	v_mfma_f32_16x16x32_bf16 v[48:51], v[172:175], v[180:183], v[48:51]
	v_mfma_f32_16x16x32_bf16 v[32:35], v[172:175], v[198:201], v[32:35]
	v_mfma_f32_16x16x32_bf16 v[36:39], v[144:147], v[198:201], v[36:39]
	v_mfma_f32_16x16x32_bf16 v[20:23], v[144:147], v[206:209], v[20:23]
	v_mfma_f32_16x16x32_bf16 v[16:19], v[172:175], v[206:209], v[16:19]
	v_mfma_f32_16x16x32_bf16 v[0:3], v[172:175], v[214:217], v[0:3]
	v_mfma_f32_16x16x32_bf16 v[4:7], v[144:147], v[214:217], v[4:7]
	v_mfma_f32_16x16x32_bf16 v[52:55], v[148:151], v[194:197], v[52:55]
	v_mfma_f32_16x16x32_bf16 v[48:51], v[176:179], v[194:197], v[48:51]
	v_mfma_f32_16x16x32_bf16 v[32:35], v[176:179], v[202:205], v[32:35]
	v_mfma_f32_16x16x32_bf16 v[36:39], v[148:151], v[202:205], v[36:39]
	v_mfma_f32_16x16x32_bf16 v[20:23], v[148:151], v[210:213], v[20:23]
	v_mfma_f32_16x16x32_bf16 v[16:19], v[176:179], v[210:213], v[16:19]
	v_mfma_f32_16x16x32_bf16 v[0:3], v[176:179], v[218:221], v[0:3]
	v_mfma_f32_16x16x32_bf16 v[4:7], v[148:151], v[218:221], v[4:7]
	s_barrier
	s_add_i32 s50, s50, 2
	s_add_u32 s22, s22, 0x100
	s_addc_u32 s23, s23, 0
	s_add_u32 s21, s21, 0x100
	s_addc_u32 s47, s47, 0
	s_cmp_gt_u32 s50, 41
	s_cbranch_scc0 .LBB0_1630

.LBB0_1726:
	s_ashr_i32 s15, s14, 31
	s_lshl_b64 s[18:19], s[14:15], 19
	s_add_u32 s18, s82, s18
	s_addc_u32 s19, s83, s19
	s_and_b64 s[20:21], s[4:5], exec
	s_cselect_b32 s15, s19, s25
	s_cselect_b32 s47, s18, s24
	s_ashr_i32 s17, s16, 31
	s_lshl_b64 s[20:21], s[16:17], 19
	s_add_u32 s20, s30, s20
	s_addc_u32 s21, s31, s21
	s_and_b64 s[28:29], s[4:5], exec
	s_cselect_b32 s17, s21, s27
	s_cselect_b32 s48, s20, s26
	s_add_u32 s24, s24, 0x40080
	s_addc_u32 s25, s25, 0
	s_add_u32 s49, s26, 0x100
	s_addc_u32 s50, s27, 0
	s_mov_b32 s51, -2
	ds_read_b128 v[128:131], v163
	ds_read_b128 v[132:135], v163 offset:1024
	ds_read_b128 v[172:175], v163 offset:2048
	ds_read_b128 v[176:179], v163 offset:3072
	ds_read_b128 v[180:183], v165
	ds_read_b128 v[186:189], v165 offset:1024
	ds_read_b128 v[190:193], v165 offset:2048
	ds_read_b128 v[194:197], v165 offset:3072
	s_add_u32 s26, s24, 0xfffc0080
	s_addc_u32 s27, s25, -1
	s_cmp_eq_u32 s51, 12
	s_cselect_b32 s29, s15, s27
	s_cselect_b32 s28, s47, s26
	s_cselect_b32 s27, s17, s50
	s_cselect_b32 s26, s48, s49
	s_add_i32 m0, s23, 0xc000
	ds_read_b128 v[198:201], v167
	ds_read_b128 v[202:205], v167 offset:1024
	ds_read_b128 v[206:209], v167 offset:2048
	ds_read_b128 v[210:213], v167 offset:3072
	ds_read_b128 v[214:217], v167 offset:4096
	ds_read_b128 v[218:221], v167 offset:5120
	ds_read_b128 v[222:225], v167 offset:6144
	ds_read_b128 v[226:229], v167 offset:7168
	global_load_lds_dwordx4 v148, s[24:25]
	s_add_i32 m0, s23, 0xe000
	s_nop 0
	global_load_lds_dwordx4 v150, s[24:25]
	s_waitcnt vmcnt(8)
	s_waitcnt lgkmcnt(0)
	s_barrier
	s_waitcnt lgkmcnt(0)
	v_mfma_f32_16x16x32_bf16 v[124:127], v[128:131], v[198:201], 0
	v_mfma_f32_16x16x32_bf16 v[120:123], v[172:175], v[198:201], 0
	v_mfma_f32_16x16x32_bf16 v[112:115], v[172:175], v[206:209], 0
	v_mfma_f32_16x16x32_bf16 v[116:119], v[128:131], v[206:209], 0
	v_mfma_f32_16x16x32_bf16 v[108:111], v[128:131], v[214:217], 0
	v_mfma_f32_16x16x32_bf16 v[104:107], v[172:175], v[214:217], 0
	v_mfma_f32_16x16x32_bf16 v[96:99], v[172:175], v[222:225], 0
	v_mfma_f32_16x16x32_bf16 v[100:103], v[128:131], v[222:225], 0
	v_mfma_f32_16x16x32_bf16 v[124:127], v[132:135], v[202:205], v[124:127]
	v_mfma_f32_16x16x32_bf16 v[120:123], v[176:179], v[202:205], v[120:123]
	v_mfma_f32_16x16x32_bf16 v[112:115], v[176:179], v[210:213], v[112:115]
	v_mfma_f32_16x16x32_bf16 v[116:119], v[132:135], v[210:213], v[116:119]
	v_mfma_f32_16x16x32_bf16 v[108:111], v[132:135], v[218:221], v[108:111]
	v_mfma_f32_16x16x32_bf16 v[104:107], v[176:179], v[218:221], v[104:107]
	v_mfma_f32_16x16x32_bf16 v[96:99], v[176:179], v[226:229], v[96:99]
	v_mfma_f32_16x16x32_bf16 v[100:103], v[132:135], v[226:229], v[100:103]
	v_mfma_f32_16x16x32_bf16 v[72:75], v[180:183], v[198:201], 0
	v_mfma_f32_16x16x32_bf16 v[64:67], v[190:193], v[198:201], 0
	v_mfma_f32_16x16x32_bf16 v[48:51], v[190:193], v[206:209], 0
	v_mfma_f32_16x16x32_bf16 v[56:59], v[180:183], v[206:209], 0
	v_mfma_f32_16x16x32_bf16 v[44:47], v[180:183], v[214:217], 0
	v_mfma_f32_16x16x32_bf16 v[40:43], v[190:193], v[214:217], 0
	v_mfma_f32_16x16x32_bf16 v[32:35], v[190:193], v[222:225], 0
	v_mfma_f32_16x16x32_bf16 v[36:39], v[180:183], v[222:225], 0
	v_mfma_f32_16x16x32_bf16 v[72:75], v[186:189], v[202:205], v[72:75]
	v_mfma_f32_16x16x32_bf16 v[64:67], v[194:197], v[202:205], v[64:67]
	v_mfma_f32_16x16x32_bf16 v[48:51], v[194:197], v[210:213], v[48:51]
	v_mfma_f32_16x16x32_bf16 v[56:59], v[186:189], v[210:213], v[56:59]
	v_mfma_f32_16x16x32_bf16 v[44:47], v[186:189], v[218:221], v[44:47]
	v_mfma_f32_16x16x32_bf16 v[40:43], v[194:197], v[218:221], v[40:43]
	v_mfma_f32_16x16x32_bf16 v[32:35], v[194:197], v[226:229], v[32:35]
	v_mfma_f32_16x16x32_bf16 v[36:39], v[186:189], v[226:229], v[36:39]
	s_barrier
	s_add_i32 s52, s44, s34
	s_mov_b32 m0, s52
	ds_read_b128 v[198:201], v167 offset:16384
	ds_read_b128 v[202:205], v167 offset:17408
	ds_read_b128 v[206:209], v167 offset:18432
	ds_read_b128 v[210:213], v167 offset:19456
	ds_read_b128 v[214:217], v167 offset:20480
	ds_read_b128 v[218:221], v167 offset:21504
	ds_read_b128 v[222:225], v167 offset:22528
	ds_read_b128 v[226:229], v167 offset:23552
	global_load_lds_dwordx4 v138, s[26:27]
	s_add_i32 m0, s52, 0x2000
	s_add_u32 s52, s26, 0x40000
	s_addc_u32 s53, s27, 0
	s_add_i32 s54, s45, s34
	global_load_lds_dwordx4 v142, s[26:27]
	s_mov_b32 m0, s54
	global_load_lds_dwordx4 v138, s[52:53]
	s_add_i32 m0, s54, 0x2000
	s_nop 0
	global_load_lds_dwordx4 v142, s[52:53]
	s_mov_b32 m0, s23
	s_nop 0
	global_load_lds_dwordx4 v136, s[28:29]
	s_mov_b32 m0, s35
	s_nop 0
	global_load_lds_dwordx4 v140, s[28:29]
	s_add_u32 s98, s26, s10
	s_addc_u32 s99, s27, s11
	s_add_u32 s100, s28, s10
	s_addc_u32 s101, s29, s11
	s_waitcnt vmcnt(8)
	s_waitcnt lgkmcnt(0)
	s_barrier
	s_waitcnt lgkmcnt(0)
	v_mfma_f32_16x16x32_bf16 v[92:95], v[128:131], v[198:201], 0
	v_mfma_f32_16x16x32_bf16 v[88:91], v[172:175], v[198:201], 0
	v_mfma_f32_16x16x32_bf16 v[80:83], v[172:175], v[206:209], 0
	v_mfma_f32_16x16x32_bf16 v[84:87], v[128:131], v[206:209], 0
	v_mfma_f32_16x16x32_bf16 v[76:79], v[128:131], v[214:217], 0
	v_mfma_f32_16x16x32_bf16 v[68:71], v[172:175], v[214:217], 0
	v_mfma_f32_16x16x32_bf16 v[52:55], v[172:175], v[222:225], 0
	v_mfma_f32_16x16x32_bf16 v[60:63], v[128:131], v[222:225], 0
	v_mfma_f32_16x16x32_bf16 v[92:95], v[132:135], v[202:205], v[92:95]
	v_mfma_f32_16x16x32_bf16 v[88:91], v[176:179], v[202:205], v[88:91]
	v_mfma_f32_16x16x32_bf16 v[80:83], v[176:179], v[210:213], v[80:83]
	v_mfma_f32_16x16x32_bf16 v[84:87], v[132:135], v[210:213], v[84:87]
	v_mfma_f32_16x16x32_bf16 v[76:79], v[132:135], v[218:221], v[76:79]
	v_mfma_f32_16x16x32_bf16 v[68:71], v[176:179], v[218:221], v[68:71]
	v_mfma_f32_16x16x32_bf16 v[52:55], v[176:179], v[226:229], v[52:55]
	v_mfma_f32_16x16x32_bf16 v[60:63], v[132:135], v[226:229], v[60:63]
	v_mfma_f32_16x16x32_bf16 v[28:31], v[180:183], v[198:201], 0
	v_mfma_f32_16x16x32_bf16 v[24:27], v[190:193], v[198:201], 0
	v_mfma_f32_16x16x32_bf16 v[16:19], v[190:193], v[206:209], 0
	v_mfma_f32_16x16x32_bf16 v[20:23], v[180:183], v[206:209], 0
	v_mfma_f32_16x16x32_bf16 v[12:15], v[180:183], v[214:217], 0
	v_mfma_f32_16x16x32_bf16 v[8:11], v[190:193], v[214:217], 0
	v_mfma_f32_16x16x32_bf16 v[0:3], v[190:193], v[222:225], 0
	v_mfma_f32_16x16x32_bf16 v[4:7], v[180:183], v[222:225], 0
	v_mfma_f32_16x16x32_bf16 v[28:31], v[186:189], v[202:205], v[28:31]
	v_mfma_f32_16x16x32_bf16 v[24:27], v[194:197], v[202:205], v[24:27]
	v_mfma_f32_16x16x32_bf16 v[16:19], v[194:197], v[210:213], v[16:19]
	v_mfma_f32_16x16x32_bf16 v[20:23], v[186:189], v[210:213], v[20:23]
	v_mfma_f32_16x16x32_bf16 v[12:15], v[186:189], v[218:221], v[12:15]
	v_mfma_f32_16x16x32_bf16 v[8:11], v[194:197], v[218:221], v[8:11]
	v_mfma_f32_16x16x32_bf16 v[0:3], v[194:197], v[226:229], v[0:3]
	v_mfma_f32_16x16x32_bf16 v[4:7], v[186:189], v[226:229], v[4:7]
	s_barrier
	s_add_i32 s52, 0, 0x18000
	v_add_u32_e32 v158, s52, v161
	s_add_i32 s53, 0, 0x1c000
	ds_read_b128 v[128:131], v158
	ds_read_b128 v[132:135], v158 offset:1024
	ds_read_b128 v[172:175], v158 offset:2048
	ds_read_b128 v[176:179], v158 offset:3072
	v_add_u32_e32 v158, s53, v161
	ds_read_b128 v[180:183], v158
	ds_read_b128 v[186:189], v158 offset:1024
	ds_read_b128 v[190:193], v158 offset:2048
	ds_read_b128 v[194:197], v158 offset:3072
	s_add_u32 s28, s28, 0x40000
	s_addc_u32 s29, s29, 0
	s_mov_b32 m0, s36
	ds_read_b128 v[198:201], v167 offset:32768
	ds_read_b128 v[202:205], v167 offset:33792
	ds_read_b128 v[206:209], v167 offset:34816
	ds_read_b128 v[210:213], v167 offset:35840
	ds_read_b128 v[214:217], v167 offset:36864
	ds_read_b128 v[218:221], v167 offset:37888
	ds_read_b128 v[222:225], v167 offset:38912
	ds_read_b128 v[226:229], v167 offset:39936
	global_load_lds_dwordx4 v136, s[28:29]
	s_mov_b32 m0, s37
	s_nop 0
	global_load_lds_dwordx4 v140, s[28:29]
	s_waitcnt vmcnt(8)
	s_waitcnt lgkmcnt(0)
	s_barrier
	s_waitcnt lgkmcnt(0)
	v_mfma_f32_16x16x32_bf16 v[124:127], v[128:131], v[198:201], v[124:127]
	v_mfma_f32_16x16x32_bf16 v[120:123], v[172:175], v[198:201], v[120:123]
	v_mfma_f32_16x16x32_bf16 v[112:115], v[172:175], v[206:209], v[112:115]
	v_mfma_f32_16x16x32_bf16 v[116:119], v[128:131], v[206:209], v[116:119]
	v_mfma_f32_16x16x32_bf16 v[108:111], v[128:131], v[214:217], v[108:111]
	v_mfma_f32_16x16x32_bf16 v[104:107], v[172:175], v[214:217], v[104:107]
	v_mfma_f32_16x16x32_bf16 v[96:99], v[172:175], v[222:225], v[96:99]
	v_mfma_f32_16x16x32_bf16 v[100:103], v[128:131], v[222:225], v[100:103]
	v_mfma_f32_16x16x32_bf16 v[124:127], v[132:135], v[202:205], v[124:127]
	v_mfma_f32_16x16x32_bf16 v[120:123], v[176:179], v[202:205], v[120:123]
	v_mfma_f32_16x16x32_bf16 v[112:115], v[176:179], v[210:213], v[112:115]
	v_mfma_f32_16x16x32_bf16 v[116:119], v[132:135], v[210:213], v[116:119]
	v_mfma_f32_16x16x32_bf16 v[108:111], v[132:135], v[218:221], v[108:111]
	v_mfma_f32_16x16x32_bf16 v[104:107], v[176:179], v[218:221], v[104:107]
	v_mfma_f32_16x16x32_bf16 v[96:99], v[176:179], v[226:229], v[96:99]
	v_mfma_f32_16x16x32_bf16 v[100:103], v[132:135], v[226:229], v[100:103]
	v_mfma_f32_16x16x32_bf16 v[72:75], v[180:183], v[198:201], v[72:75]
	v_mfma_f32_16x16x32_bf16 v[64:67], v[190:193], v[198:201], v[64:67]
	v_mfma_f32_16x16x32_bf16 v[48:51], v[190:193], v[206:209], v[48:51]
	v_mfma_f32_16x16x32_bf16 v[56:59], v[180:183], v[206:209], v[56:59]
	v_mfma_f32_16x16x32_bf16 v[44:47], v[180:183], v[214:217], v[44:47]
	v_mfma_f32_16x16x32_bf16 v[40:43], v[190:193], v[214:217], v[40:43]
	v_mfma_f32_16x16x32_bf16 v[32:35], v[190:193], v[222:225], v[32:35]
	v_mfma_f32_16x16x32_bf16 v[36:39], v[180:183], v[222:225], v[36:39]
	v_mfma_f32_16x16x32_bf16 v[72:75], v[186:189], v[202:205], v[72:75]
	v_mfma_f32_16x16x32_bf16 v[64:67], v[194:197], v[202:205], v[64:67]
	v_mfma_f32_16x16x32_bf16 v[48:51], v[194:197], v[210:213], v[48:51]
	v_mfma_f32_16x16x32_bf16 v[56:59], v[186:189], v[210:213], v[56:59]
	v_mfma_f32_16x16x32_bf16 v[44:47], v[186:189], v[218:221], v[44:47]
	v_mfma_f32_16x16x32_bf16 v[40:43], v[194:197], v[218:221], v[40:43]
	v_mfma_f32_16x16x32_bf16 v[32:35], v[194:197], v[226:229], v[32:35]
	v_mfma_f32_16x16x32_bf16 v[36:39], v[186:189], v[226:229], v[36:39]
	s_barrier
	s_add_i32 s28, s52, s34
	s_mov_b32 m0, s28
	ds_read_b128 v[198:201], v167 offset:49152
	ds_read_b128 v[202:205], v167 offset:50176
	ds_read_b128 v[206:209], v167 offset:51200
	ds_read_b128 v[210:213], v167 offset:52224
	ds_read_b128 v[214:217], v167 offset:53248
	ds_read_b128 v[218:221], v167 offset:54272
	ds_read_b128 v[222:225], v167 offset:55296
	ds_read_b128 v[226:229], v167 offset:56320
	global_load_lds_dwordx4 v138, s[98:99]
	s_add_i32 m0, s28, 0x2000
	s_add_u32 s26, s26, 0x40080
	s_addc_u32 s27, s27, 0
	s_add_i32 s28, s53, s34
	global_load_lds_dwordx4 v142, s[98:99]
	s_mov_b32 m0, s28
	s_nop 0
	global_load_lds_dwordx4 v138, s[26:27]
	s_add_i32 m0, s28, 0x2000
	s_nop 0
	global_load_lds_dwordx4 v142, s[26:27]
	s_mov_b32 m0, s39
	s_nop 0
	global_load_lds_dwordx4 v136, s[100:101]
	s_mov_b32 m0, s40
	s_nop 0
	global_load_lds_dwordx4 v140, s[100:101]
	s_waitcnt vmcnt(8)
	s_waitcnt lgkmcnt(0)
	s_barrier
	s_waitcnt lgkmcnt(0)
	v_mfma_f32_16x16x32_bf16 v[92:95], v[128:131], v[198:201], v[92:95]
	v_mfma_f32_16x16x32_bf16 v[88:91], v[172:175], v[198:201], v[88:91]
	v_mfma_f32_16x16x32_bf16 v[80:83], v[172:175], v[206:209], v[80:83]
	v_mfma_f32_16x16x32_bf16 v[84:87], v[128:131], v[206:209], v[84:87]
	v_mfma_f32_16x16x32_bf16 v[76:79], v[128:131], v[214:217], v[76:79]
	v_mfma_f32_16x16x32_bf16 v[68:71], v[172:175], v[214:217], v[68:71]
	v_mfma_f32_16x16x32_bf16 v[52:55], v[172:175], v[222:225], v[52:55]
	v_mfma_f32_16x16x32_bf16 v[60:63], v[128:131], v[222:225], v[60:63]
	v_mfma_f32_16x16x32_bf16 v[92:95], v[132:135], v[202:205], v[92:95]
	v_mfma_f32_16x16x32_bf16 v[88:91], v[176:179], v[202:205], v[88:91]
	v_mfma_f32_16x16x32_bf16 v[80:83], v[176:179], v[210:213], v[80:83]
	v_mfma_f32_16x16x32_bf16 v[84:87], v[132:135], v[210:213], v[84:87]
	v_mfma_f32_16x16x32_bf16 v[76:79], v[132:135], v[218:221], v[76:79]
	v_mfma_f32_16x16x32_bf16 v[68:71], v[176:179], v[218:221], v[68:71]
	v_mfma_f32_16x16x32_bf16 v[52:55], v[176:179], v[226:229], v[52:55]
	v_mfma_f32_16x16x32_bf16 v[60:63], v[132:135], v[226:229], v[60:63]
	v_mfma_f32_16x16x32_bf16 v[28:31], v[180:183], v[198:201], v[28:31]
	v_mfma_f32_16x16x32_bf16 v[24:27], v[190:193], v[198:201], v[24:27]
	v_mfma_f32_16x16x32_bf16 v[16:19], v[190:193], v[206:209], v[16:19]
	v_mfma_f32_16x16x32_bf16 v[20:23], v[180:183], v[206:209], v[20:23]
	v_mfma_f32_16x16x32_bf16 v[12:15], v[180:183], v[214:217], v[12:15]
	v_mfma_f32_16x16x32_bf16 v[8:11], v[190:193], v[214:217], v[8:11]
	v_mfma_f32_16x16x32_bf16 v[0:3], v[190:193], v[222:225], v[0:3]
	v_mfma_f32_16x16x32_bf16 v[4:7], v[180:183], v[222:225], v[4:7]
	v_mfma_f32_16x16x32_bf16 v[28:31], v[186:189], v[202:205], v[28:31]
	v_mfma_f32_16x16x32_bf16 v[24:27], v[194:197], v[202:205], v[24:27]
	v_mfma_f32_16x16x32_bf16 v[16:19], v[194:197], v[210:213], v[16:19]
	v_mfma_f32_16x16x32_bf16 v[20:23], v[186:189], v[210:213], v[20:23]
	v_mfma_f32_16x16x32_bf16 v[12:15], v[186:189], v[218:221], v[12:15]
	v_mfma_f32_16x16x32_bf16 v[8:11], v[194:197], v[218:221], v[8:11]
	v_mfma_f32_16x16x32_bf16 v[0:3], v[194:197], v[226:229], v[0:3]
	v_mfma_f32_16x16x32_bf16 v[4:7], v[186:189], v[226:229], v[4:7]
	s_barrier
	s_add_i32 s51, s51, 2
	s_add_u32 s24, s24, 0x100
	s_addc_u32 s25, s25, 0
	s_add_u32 s49, s49, 0x100
	s_addc_u32 s50, s50, 0
	s_cmp_gt_u32 s51, 13
	s_cbranch_scc1 .Lpeel_exit_1727
.LBB0_1727:
	ds_read_b128 v[128:131], v163
	ds_read_b128 v[132:135], v163 offset:1024
	ds_read_b128 v[172:175], v163 offset:2048
	ds_read_b128 v[176:179], v163 offset:3072
	ds_read_b128 v[180:183], v165
	ds_read_b128 v[186:189], v165 offset:1024
	ds_read_b128 v[190:193], v165 offset:2048
	ds_read_b128 v[194:197], v165 offset:3072
	s_add_u32 s26, s24, 0xfffc0080
	s_addc_u32 s27, s25, -1
	s_cmp_eq_u32 s51, 12
	s_cselect_b32 s29, s15, s27
	s_cselect_b32 s28, s47, s26
	s_cselect_b32 s27, s17, s50
	s_cselect_b32 s26, s48, s49
	s_add_i32 m0, s23, 0xc000
	ds_read_b128 v[198:201], v167
	ds_read_b128 v[202:205], v167 offset:1024
	ds_read_b128 v[206:209], v167 offset:2048
	ds_read_b128 v[210:213], v167 offset:3072
	ds_read_b128 v[214:217], v167 offset:4096
	ds_read_b128 v[218:221], v167 offset:5120
	ds_read_b128 v[222:225], v167 offset:6144
	ds_read_b128 v[226:229], v167 offset:7168
	global_load_lds_dwordx4 v148, s[24:25]
	s_add_i32 m0, s23, 0xe000
	s_nop 0
	global_load_lds_dwordx4 v150, s[24:25]
	s_waitcnt vmcnt(8)
	s_waitcnt lgkmcnt(0)
	s_barrier
	s_waitcnt lgkmcnt(0)
	v_mfma_f32_16x16x32_bf16 v[124:127], v[128:131], v[198:201], v[124:127]
	v_mfma_f32_16x16x32_bf16 v[120:123], v[172:175], v[198:201], v[120:123]
	v_mfma_f32_16x16x32_bf16 v[112:115], v[172:175], v[206:209], v[112:115]
	v_mfma_f32_16x16x32_bf16 v[116:119], v[128:131], v[206:209], v[116:119]
	v_mfma_f32_16x16x32_bf16 v[108:111], v[128:131], v[214:217], v[108:111]
	v_mfma_f32_16x16x32_bf16 v[104:107], v[172:175], v[214:217], v[104:107]
	v_mfma_f32_16x16x32_bf16 v[96:99], v[172:175], v[222:225], v[96:99]
	v_mfma_f32_16x16x32_bf16 v[100:103], v[128:131], v[222:225], v[100:103]
	v_mfma_f32_16x16x32_bf16 v[124:127], v[132:135], v[202:205], v[124:127]
	v_mfma_f32_16x16x32_bf16 v[120:123], v[176:179], v[202:205], v[120:123]
	v_mfma_f32_16x16x32_bf16 v[112:115], v[176:179], v[210:213], v[112:115]
	v_mfma_f32_16x16x32_bf16 v[116:119], v[132:135], v[210:213], v[116:119]
	v_mfma_f32_16x16x32_bf16 v[108:111], v[132:135], v[218:221], v[108:111]
	v_mfma_f32_16x16x32_bf16 v[104:107], v[176:179], v[218:221], v[104:107]
	v_mfma_f32_16x16x32_bf16 v[96:99], v[176:179], v[226:229], v[96:99]
	v_mfma_f32_16x16x32_bf16 v[100:103], v[132:135], v[226:229], v[100:103]
	v_mfma_f32_16x16x32_bf16 v[72:75], v[180:183], v[198:201], v[72:75]
	v_mfma_f32_16x16x32_bf16 v[64:67], v[190:193], v[198:201], v[64:67]
	v_mfma_f32_16x16x32_bf16 v[48:51], v[190:193], v[206:209], v[48:51]
	v_mfma_f32_16x16x32_bf16 v[56:59], v[180:183], v[206:209], v[56:59]
	v_mfma_f32_16x16x32_bf16 v[44:47], v[180:183], v[214:217], v[44:47]
	v_mfma_f32_16x16x32_bf16 v[40:43], v[190:193], v[214:217], v[40:43]
	v_mfma_f32_16x16x32_bf16 v[32:35], v[190:193], v[222:225], v[32:35]
	v_mfma_f32_16x16x32_bf16 v[36:39], v[180:183], v[222:225], v[36:39]
	v_mfma_f32_16x16x32_bf16 v[72:75], v[186:189], v[202:205], v[72:75]
	v_mfma_f32_16x16x32_bf16 v[64:67], v[194:197], v[202:205], v[64:67]
	v_mfma_f32_16x16x32_bf16 v[48:51], v[194:197], v[210:213], v[48:51]
	v_mfma_f32_16x16x32_bf16 v[56:59], v[186:189], v[210:213], v[56:59]
	v_mfma_f32_16x16x32_bf16 v[44:47], v[186:189], v[218:221], v[44:47]
	v_mfma_f32_16x16x32_bf16 v[40:43], v[194:197], v[218:221], v[40:43]
	v_mfma_f32_16x16x32_bf16 v[32:35], v[194:197], v[226:229], v[32:35]
	v_mfma_f32_16x16x32_bf16 v[36:39], v[186:189], v[226:229], v[36:39]
	s_barrier
	s_add_i32 s52, s44, s34
	s_mov_b32 m0, s52
	ds_read_b128 v[198:201], v167 offset:16384
	ds_read_b128 v[202:205], v167 offset:17408
	ds_read_b128 v[206:209], v167 offset:18432
	ds_read_b128 v[210:213], v167 offset:19456
	ds_read_b128 v[214:217], v167 offset:20480
	ds_read_b128 v[218:221], v167 offset:21504
	ds_read_b128 v[222:225], v167 offset:22528
	ds_read_b128 v[226:229], v167 offset:23552
	global_load_lds_dwordx4 v138, s[26:27]
	s_add_i32 m0, s52, 0x2000
	s_add_u32 s52, s26, 0x40000
	s_addc_u32 s53, s27, 0
	s_add_i32 s54, s45, s34
	global_load_lds_dwordx4 v142, s[26:27]
	s_mov_b32 m0, s54
	global_load_lds_dwordx4 v138, s[52:53]
	s_add_i32 m0, s54, 0x2000
	s_nop 0
	global_load_lds_dwordx4 v142, s[52:53]
	s_mov_b32 m0, s23
	s_nop 0
	global_load_lds_dwordx4 v136, s[28:29]
	s_mov_b32 m0, s35
	s_nop 0
	global_load_lds_dwordx4 v140, s[28:29]
	s_add_u32 s98, s26, s10
	s_addc_u32 s99, s27, s11
	s_add_u32 s100, s28, s10
	s_addc_u32 s101, s29, s11
	s_waitcnt vmcnt(8)
	s_waitcnt lgkmcnt(0)
	s_barrier
	s_waitcnt lgkmcnt(0)
	v_mfma_f32_16x16x32_bf16 v[92:95], v[128:131], v[198:201], v[92:95]
	v_mfma_f32_16x16x32_bf16 v[88:91], v[172:175], v[198:201], v[88:91]
	v_mfma_f32_16x16x32_bf16 v[80:83], v[172:175], v[206:209], v[80:83]
	v_mfma_f32_16x16x32_bf16 v[84:87], v[128:131], v[206:209], v[84:87]
	v_mfma_f32_16x16x32_bf16 v[76:79], v[128:131], v[214:217], v[76:79]
	v_mfma_f32_16x16x32_bf16 v[68:71], v[172:175], v[214:217], v[68:71]
	v_mfma_f32_16x16x32_bf16 v[52:55], v[172:175], v[222:225], v[52:55]
	v_mfma_f32_16x16x32_bf16 v[60:63], v[128:131], v[222:225], v[60:63]
	v_mfma_f32_16x16x32_bf16 v[92:95], v[132:135], v[202:205], v[92:95]
	v_mfma_f32_16x16x32_bf16 v[88:91], v[176:179], v[202:205], v[88:91]
	v_mfma_f32_16x16x32_bf16 v[80:83], v[176:179], v[210:213], v[80:83]
	v_mfma_f32_16x16x32_bf16 v[84:87], v[132:135], v[210:213], v[84:87]
	v_mfma_f32_16x16x32_bf16 v[76:79], v[132:135], v[218:221], v[76:79]
	v_mfma_f32_16x16x32_bf16 v[68:71], v[176:179], v[218:221], v[68:71]
	v_mfma_f32_16x16x32_bf16 v[52:55], v[176:179], v[226:229], v[52:55]
	v_mfma_f32_16x16x32_bf16 v[60:63], v[132:135], v[226:229], v[60:63]
	v_mfma_f32_16x16x32_bf16 v[28:31], v[180:183], v[198:201], v[28:31]
	v_mfma_f32_16x16x32_bf16 v[24:27], v[190:193], v[198:201], v[24:27]
	v_mfma_f32_16x16x32_bf16 v[16:19], v[190:193], v[206:209], v[16:19]
	v_mfma_f32_16x16x32_bf16 v[20:23], v[180:183], v[206:209], v[20:23]
	v_mfma_f32_16x16x32_bf16 v[12:15], v[180:183], v[214:217], v[12:15]
	v_mfma_f32_16x16x32_bf16 v[8:11], v[190:193], v[214:217], v[8:11]
	v_mfma_f32_16x16x32_bf16 v[0:3], v[190:193], v[222:225], v[0:3]
	v_mfma_f32_16x16x32_bf16 v[4:7], v[180:183], v[222:225], v[4:7]
	v_mfma_f32_16x16x32_bf16 v[28:31], v[186:189], v[202:205], v[28:31]
	v_mfma_f32_16x16x32_bf16 v[24:27], v[194:197], v[202:205], v[24:27]
	v_mfma_f32_16x16x32_bf16 v[16:19], v[194:197], v[210:213], v[16:19]
	v_mfma_f32_16x16x32_bf16 v[20:23], v[186:189], v[210:213], v[20:23]
	v_mfma_f32_16x16x32_bf16 v[12:15], v[186:189], v[218:221], v[12:15]
	v_mfma_f32_16x16x32_bf16 v[8:11], v[194:197], v[218:221], v[8:11]
	v_mfma_f32_16x16x32_bf16 v[0:3], v[194:197], v[226:229], v[0:3]
	v_mfma_f32_16x16x32_bf16 v[4:7], v[186:189], v[226:229], v[4:7]
	s_barrier
	s_add_i32 s52, 0, 0x18000
	v_add_u32_e32 v158, s52, v161
	s_add_i32 s53, 0, 0x1c000
	ds_read_b128 v[128:131], v158
	ds_read_b128 v[132:135], v158 offset:1024
	ds_read_b128 v[172:175], v158 offset:2048
	ds_read_b128 v[176:179], v158 offset:3072
	v_add_u32_e32 v158, s53, v161
	ds_read_b128 v[180:183], v158
	ds_read_b128 v[186:189], v158 offset:1024
	ds_read_b128 v[190:193], v158 offset:2048
	ds_read_b128 v[194:197], v158 offset:3072
	s_add_u32 s28, s28, 0x40000
	s_addc_u32 s29, s29, 0
	s_mov_b32 m0, s36
	ds_read_b128 v[198:201], v167 offset:32768
	ds_read_b128 v[202:205], v167 offset:33792
	ds_read_b128 v[206:209], v167 offset:34816
	ds_read_b128 v[210:213], v167 offset:35840
	ds_read_b128 v[214:217], v167 offset:36864
	ds_read_b128 v[218:221], v167 offset:37888
	ds_read_b128 v[222:225], v167 offset:38912
	ds_read_b128 v[226:229], v167 offset:39936
	global_load_lds_dwordx4 v136, s[28:29]
	s_mov_b32 m0, s37
	s_nop 0
	global_load_lds_dwordx4 v140, s[28:29]
	s_waitcnt vmcnt(8)
	s_waitcnt lgkmcnt(0)
	s_barrier
	s_waitcnt lgkmcnt(0)
	v_mfma_f32_16x16x32_bf16 v[124:127], v[128:131], v[198:201], v[124:127]
	v_mfma_f32_16x16x32_bf16 v[120:123], v[172:175], v[198:201], v[120:123]
	v_mfma_f32_16x16x32_bf16 v[112:115], v[172:175], v[206:209], v[112:115]
	v_mfma_f32_16x16x32_bf16 v[116:119], v[128:131], v[206:209], v[116:119]
	v_mfma_f32_16x16x32_bf16 v[108:111], v[128:131], v[214:217], v[108:111]
	v_mfma_f32_16x16x32_bf16 v[104:107], v[172:175], v[214:217], v[104:107]
	v_mfma_f32_16x16x32_bf16 v[96:99], v[172:175], v[222:225], v[96:99]
	v_mfma_f32_16x16x32_bf16 v[100:103], v[128:131], v[222:225], v[100:103]
	v_mfma_f32_16x16x32_bf16 v[124:127], v[132:135], v[202:205], v[124:127]
	v_mfma_f32_16x16x32_bf16 v[120:123], v[176:179], v[202:205], v[120:123]
	v_mfma_f32_16x16x32_bf16 v[112:115], v[176:179], v[210:213], v[112:115]
	v_mfma_f32_16x16x32_bf16 v[116:119], v[132:135], v[210:213], v[116:119]
	v_mfma_f32_16x16x32_bf16 v[108:111], v[132:135], v[218:221], v[108:111]
	v_mfma_f32_16x16x32_bf16 v[104:107], v[176:179], v[218:221], v[104:107]
	v_mfma_f32_16x16x32_bf16 v[96:99], v[176:179], v[226:229], v[96:99]
	v_mfma_f32_16x16x32_bf16 v[100:103], v[132:135], v[226:229], v[100:103]
	v_mfma_f32_16x16x32_bf16 v[72:75], v[180:183], v[198:201], v[72:75]
	v_mfma_f32_16x16x32_bf16 v[64:67], v[190:193], v[198:201], v[64:67]
	v_mfma_f32_16x16x32_bf16 v[48:51], v[190:193], v[206:209], v[48:51]
	v_mfma_f32_16x16x32_bf16 v[56:59], v[180:183], v[206:209], v[56:59]
	v_mfma_f32_16x16x32_bf16 v[44:47], v[180:183], v[214:217], v[44:47]
	v_mfma_f32_16x16x32_bf16 v[40:43], v[190:193], v[214:217], v[40:43]
	v_mfma_f32_16x16x32_bf16 v[32:35], v[190:193], v[222:225], v[32:35]
	v_mfma_f32_16x16x32_bf16 v[36:39], v[180:183], v[222:225], v[36:39]
	v_mfma_f32_16x16x32_bf16 v[72:75], v[186:189], v[202:205], v[72:75]
	v_mfma_f32_16x16x32_bf16 v[64:67], v[194:197], v[202:205], v[64:67]
	v_mfma_f32_16x16x32_bf16 v[48:51], v[194:197], v[210:213], v[48:51]
	v_mfma_f32_16x16x32_bf16 v[56:59], v[186:189], v[210:213], v[56:59]
	v_mfma_f32_16x16x32_bf16 v[44:47], v[186:189], v[218:221], v[44:47]
	v_mfma_f32_16x16x32_bf16 v[40:43], v[194:197], v[218:221], v[40:43]
	v_mfma_f32_16x16x32_bf16 v[32:35], v[194:197], v[226:229], v[32:35]
	v_mfma_f32_16x16x32_bf16 v[36:39], v[186:189], v[226:229], v[36:39]
	s_barrier
	s_add_i32 s28, s52, s34
	s_mov_b32 m0, s28
	ds_read_b128 v[198:201], v167 offset:49152
	ds_read_b128 v[202:205], v167 offset:50176
	ds_read_b128 v[206:209], v167 offset:51200
	ds_read_b128 v[210:213], v167 offset:52224
	ds_read_b128 v[214:217], v167 offset:53248
	ds_read_b128 v[218:221], v167 offset:54272
	ds_read_b128 v[222:225], v167 offset:55296
	ds_read_b128 v[226:229], v167 offset:56320
	global_load_lds_dwordx4 v138, s[98:99]
	s_add_i32 m0, s28, 0x2000
	s_add_u32 s26, s26, 0x40080
	s_addc_u32 s27, s27, 0
	s_add_i32 s28, s53, s34
	global_load_lds_dwordx4 v142, s[98:99]
	s_mov_b32 m0, s28
	s_nop 0
	global_load_lds_dwordx4 v138, s[26:27]
	s_add_i32 m0, s28, 0x2000
	s_nop 0
	global_load_lds_dwordx4 v142, s[26:27]
	s_mov_b32 m0, s39
	s_nop 0
	global_load_lds_dwordx4 v136, s[100:101]
	s_mov_b32 m0, s40
	s_nop 0
	global_load_lds_dwordx4 v140, s[100:101]
	s_waitcnt vmcnt(8)
	s_waitcnt lgkmcnt(0)
	s_barrier
	s_waitcnt lgkmcnt(0)
	v_mfma_f32_16x16x32_bf16 v[92:95], v[128:131], v[198:201], v[92:95]
	v_mfma_f32_16x16x32_bf16 v[88:91], v[172:175], v[198:201], v[88:91]
	v_mfma_f32_16x16x32_bf16 v[80:83], v[172:175], v[206:209], v[80:83]
	v_mfma_f32_16x16x32_bf16 v[84:87], v[128:131], v[206:209], v[84:87]
	v_mfma_f32_16x16x32_bf16 v[76:79], v[128:131], v[214:217], v[76:79]
	v_mfma_f32_16x16x32_bf16 v[68:71], v[172:175], v[214:217], v[68:71]
	v_mfma_f32_16x16x32_bf16 v[52:55], v[172:175], v[222:225], v[52:55]
	v_mfma_f32_16x16x32_bf16 v[60:63], v[128:131], v[222:225], v[60:63]
	v_mfma_f32_16x16x32_bf16 v[92:95], v[132:135], v[202:205], v[92:95]
	v_mfma_f32_16x16x32_bf16 v[88:91], v[176:179], v[202:205], v[88:91]
	v_mfma_f32_16x16x32_bf16 v[80:83], v[176:179], v[210:213], v[80:83]
	v_mfma_f32_16x16x32_bf16 v[84:87], v[132:135], v[210:213], v[84:87]
	v_mfma_f32_16x16x32_bf16 v[76:79], v[132:135], v[218:221], v[76:79]
	v_mfma_f32_16x16x32_bf16 v[68:71], v[176:179], v[218:221], v[68:71]
	v_mfma_f32_16x16x32_bf16 v[52:55], v[176:179], v[226:229], v[52:55]
	v_mfma_f32_16x16x32_bf16 v[60:63], v[132:135], v[226:229], v[60:63]
	v_mfma_f32_16x16x32_bf16 v[28:31], v[180:183], v[198:201], v[28:31]
	v_mfma_f32_16x16x32_bf16 v[24:27], v[190:193], v[198:201], v[24:27]
	v_mfma_f32_16x16x32_bf16 v[16:19], v[190:193], v[206:209], v[16:19]
	v_mfma_f32_16x16x32_bf16 v[20:23], v[180:183], v[206:209], v[20:23]
	v_mfma_f32_16x16x32_bf16 v[12:15], v[180:183], v[214:217], v[12:15]
	v_mfma_f32_16x16x32_bf16 v[8:11], v[190:193], v[214:217], v[8:11]
	v_mfma_f32_16x16x32_bf16 v[0:3], v[190:193], v[222:225], v[0:3]
	v_mfma_f32_16x16x32_bf16 v[4:7], v[180:183], v[222:225], v[4:7]
	v_mfma_f32_16x16x32_bf16 v[28:31], v[186:189], v[202:205], v[28:31]
	v_mfma_f32_16x16x32_bf16 v[24:27], v[194:197], v[202:205], v[24:27]
	v_mfma_f32_16x16x32_bf16 v[16:19], v[194:197], v[210:213], v[16:19]
	v_mfma_f32_16x16x32_bf16 v[20:23], v[186:189], v[210:213], v[20:23]
	v_mfma_f32_16x16x32_bf16 v[12:15], v[186:189], v[218:221], v[12:15]
	v_mfma_f32_16x16x32_bf16 v[8:11], v[194:197], v[218:221], v[8:11]
	v_mfma_f32_16x16x32_bf16 v[0:3], v[194:197], v[226:229], v[0:3]
	v_mfma_f32_16x16x32_bf16 v[4:7], v[186:189], v[226:229], v[4:7]
	s_barrier
	s_add_i32 s51, s51, 2
	s_add_u32 s24, s24, 0x100
	s_addc_u32 s25, s25, 0
	s_add_u32 s49, s49, 0x100
	s_addc_u32 s50, s50, 0
	s_cmp_gt_u32 s51, 13
	s_cbranch_scc0 .LBB0_1727

.LBB0_1885:
	s_ashr_i32 s17, s16, 31
	s_lshl_b64 s[20:21], s[16:17], 19
	s_add_u32 s20, s3, s20
	s_addc_u32 s21, s33, s21
	s_and_b64 s[22:23], s[8:9], exec
	s_cselect_b32 s17, s21, s29
	s_cselect_b32 s25, s20, s28
	s_ashr_i32 s19, s18, 31
	s_lshl_b64 s[22:23], s[18:19], 19
	s_add_u32 s22, s36, s22
	s_addc_u32 s23, s37, s23
	s_and_b64 s[34:35], s[8:9], exec
	s_cselect_b32 s19, s23, s31
	s_cselect_b32 s27, s22, s30
	s_add_u32 s28, s28, 0x40080
	s_addc_u32 s29, s29, 0
	s_add_u32 s51, s30, 0x100
	s_addc_u32 s52, s31, 0
	s_mov_b32 s53, -2
	s_waitcnt lgkmcnt(0)
	ds_read_b128 v[128:131], v188
	ds_read_b128 v[132:135], v188 offset:1024
	ds_read_b128 v[136:139], v188 offset:2048
	ds_read_b128 v[140:143], v188 offset:3072
	ds_read_b128 v[144:147], v189
	ds_read_b128 v[148:151], v189 offset:1024
	ds_read_b128 v[172:175], v189 offset:2048
	ds_read_b128 v[176:179], v189 offset:3072
	s_add_u32 s30, s28, 0xfffc0080
	s_addc_u32 s31, s29, -1
	s_cmp_eq_u32 s53, 12
	s_cselect_b32 s35, s17, s31
	s_cselect_b32 s34, s25, s30
	s_cselect_b32 s31, s19, s52
	s_cselect_b32 s30, s27, s51
	s_add_i32 m0, s39, 0xc000
	ds_read_b128 v[180:183], v190
	ds_read_b128 v[192:195], v190 offset:1024
	ds_read_b128 v[196:199], v190 offset:2048
	ds_read_b128 v[200:203], v190 offset:3072
	ds_read_b128 v[204:207], v190 offset:4096
	ds_read_b128 v[208:211], v190 offset:5120
	ds_read_b128 v[212:215], v190 offset:6144
	ds_read_b128 v[216:219], v190 offset:7168
	global_load_lds_dwordx4 v164, s[28:29]
	s_add_i32 m0, s39, 0xe000
	s_nop 0
	global_load_lds_dwordx4 v166, s[28:29]
	s_waitcnt vmcnt(8)
	s_waitcnt lgkmcnt(0)
	s_barrier
	s_waitcnt lgkmcnt(0)
	v_mfma_f32_16x16x32_bf16 v[124:127], v[128:131], v[180:183], 0
	v_mfma_f32_16x16x32_bf16 v[120:123], v[136:139], v[180:183], 0
	v_mfma_f32_16x16x32_bf16 v[104:107], v[136:139], v[196:199], 0
	v_mfma_f32_16x16x32_bf16 v[108:111], v[128:131], v[196:199], 0
	v_mfma_f32_16x16x32_bf16 v[92:95], v[128:131], v[204:207], 0
	v_mfma_f32_16x16x32_bf16 v[88:91], v[136:139], v[204:207], 0
	v_mfma_f32_16x16x32_bf16 v[72:75], v[136:139], v[212:215], 0
	v_mfma_f32_16x16x32_bf16 v[76:79], v[128:131], v[212:215], 0
	v_mfma_f32_16x16x32_bf16 v[124:127], v[132:135], v[192:195], v[124:127]
	v_mfma_f32_16x16x32_bf16 v[120:123], v[140:143], v[192:195], v[120:123]
	v_mfma_f32_16x16x32_bf16 v[104:107], v[140:143], v[200:203], v[104:107]
	v_mfma_f32_16x16x32_bf16 v[108:111], v[132:135], v[200:203], v[108:111]
	v_mfma_f32_16x16x32_bf16 v[92:95], v[132:135], v[208:211], v[92:95]
	v_mfma_f32_16x16x32_bf16 v[88:91], v[140:143], v[208:211], v[88:91]
	v_mfma_f32_16x16x32_bf16 v[72:75], v[140:143], v[216:219], v[72:75]
	v_mfma_f32_16x16x32_bf16 v[76:79], v[132:135], v[216:219], v[76:79]
	v_mfma_f32_16x16x32_bf16 v[116:119], v[144:147], v[180:183], 0
	v_mfma_f32_16x16x32_bf16 v[112:115], v[172:175], v[180:183], 0
	v_mfma_f32_16x16x32_bf16 v[96:99], v[172:175], v[196:199], 0
	v_mfma_f32_16x16x32_bf16 v[100:103], v[144:147], v[196:199], 0
	v_mfma_f32_16x16x32_bf16 v[84:87], v[144:147], v[204:207], 0
	v_mfma_f32_16x16x32_bf16 v[80:83], v[172:175], v[204:207], 0
	v_mfma_f32_16x16x32_bf16 v[64:67], v[172:175], v[212:215], 0
	v_mfma_f32_16x16x32_bf16 v[68:71], v[144:147], v[212:215], 0
	v_mfma_f32_16x16x32_bf16 v[116:119], v[148:151], v[192:195], v[116:119]
	v_mfma_f32_16x16x32_bf16 v[112:115], v[176:179], v[192:195], v[112:115]
	v_mfma_f32_16x16x32_bf16 v[96:99], v[176:179], v[200:203], v[96:99]
	v_mfma_f32_16x16x32_bf16 v[100:103], v[148:151], v[200:203], v[100:103]
	v_mfma_f32_16x16x32_bf16 v[84:87], v[148:151], v[208:211], v[84:87]
	v_mfma_f32_16x16x32_bf16 v[80:83], v[176:179], v[208:211], v[80:83]
	v_mfma_f32_16x16x32_bf16 v[64:67], v[176:179], v[216:219], v[64:67]
	v_mfma_f32_16x16x32_bf16 v[68:71], v[148:151], v[216:219], v[68:71]
	s_barrier
	s_add_i32 s54, s49, s38
	s_mov_b32 m0, s54
	ds_read_b128 v[180:183], v190 offset:16384
	ds_read_b128 v[192:195], v190 offset:17408
	ds_read_b128 v[196:199], v190 offset:18432
	ds_read_b128 v[200:203], v190 offset:19456
	ds_read_b128 v[204:207], v190 offset:20480
	ds_read_b128 v[208:211], v190 offset:21504
	ds_read_b128 v[212:215], v190 offset:22528
	ds_read_b128 v[216:219], v190 offset:23552
	global_load_lds_dwordx4 v154, s[30:31]
	s_add_i32 m0, s54, 0x2000
	s_add_u32 s54, s30, 0x40000
	s_addc_u32 s55, s31, 0
	s_add_i32 s56, s50, s38
	global_load_lds_dwordx4 v158, s[30:31]
	s_mov_b32 m0, s56
	global_load_lds_dwordx4 v154, s[54:55]
	s_add_i32 m0, s56, 0x2000
	s_nop 0
	global_load_lds_dwordx4 v158, s[54:55]
	s_mov_b32 m0, s39
	s_nop 0
	global_load_lds_dwordx4 v152, s[34:35]
	s_mov_b32 m0, s40
	s_nop 0
	global_load_lds_dwordx4 v156, s[34:35]
	s_add_u32 s98, s30, s12
	s_addc_u32 s99, s31, s13
	s_add_u32 s100, s34, s12
	s_addc_u32 s101, s35, s13
	s_waitcnt vmcnt(8)
	s_waitcnt lgkmcnt(0)
	s_barrier
	s_waitcnt lgkmcnt(0)
	v_mfma_f32_16x16x32_bf16 v[60:63], v[128:131], v[180:183], 0
	v_mfma_f32_16x16x32_bf16 v[56:59], v[136:139], v[180:183], 0
	v_mfma_f32_16x16x32_bf16 v[40:43], v[136:139], v[196:199], 0
	v_mfma_f32_16x16x32_bf16 v[44:47], v[128:131], v[196:199], 0
	v_mfma_f32_16x16x32_bf16 v[28:31], v[128:131], v[204:207], 0
	v_mfma_f32_16x16x32_bf16 v[24:27], v[136:139], v[204:207], 0
	v_mfma_f32_16x16x32_bf16 v[8:11], v[136:139], v[212:215], 0
	v_mfma_f32_16x16x32_bf16 v[12:15], v[128:131], v[212:215], 0
	v_mfma_f32_16x16x32_bf16 v[60:63], v[132:135], v[192:195], v[60:63]
	v_mfma_f32_16x16x32_bf16 v[56:59], v[140:143], v[192:195], v[56:59]
	v_mfma_f32_16x16x32_bf16 v[40:43], v[140:143], v[200:203], v[40:43]
	v_mfma_f32_16x16x32_bf16 v[44:47], v[132:135], v[200:203], v[44:47]
	v_mfma_f32_16x16x32_bf16 v[28:31], v[132:135], v[208:211], v[28:31]
	v_mfma_f32_16x16x32_bf16 v[24:27], v[140:143], v[208:211], v[24:27]
	v_mfma_f32_16x16x32_bf16 v[8:11], v[140:143], v[216:219], v[8:11]
	v_mfma_f32_16x16x32_bf16 v[12:15], v[132:135], v[216:219], v[12:15]
	v_mfma_f32_16x16x32_bf16 v[52:55], v[144:147], v[180:183], 0
	v_mfma_f32_16x16x32_bf16 v[48:51], v[172:175], v[180:183], 0
	v_mfma_f32_16x16x32_bf16 v[32:35], v[172:175], v[196:199], 0
	v_mfma_f32_16x16x32_bf16 v[36:39], v[144:147], v[196:199], 0
	v_mfma_f32_16x16x32_bf16 v[20:23], v[144:147], v[204:207], 0
	v_mfma_f32_16x16x32_bf16 v[16:19], v[172:175], v[204:207], 0
	v_mfma_f32_16x16x32_bf16 v[0:3], v[172:175], v[212:215], 0
	v_mfma_f32_16x16x32_bf16 v[4:7], v[144:147], v[212:215], 0
	v_mfma_f32_16x16x32_bf16 v[52:55], v[148:151], v[192:195], v[52:55]
	v_mfma_f32_16x16x32_bf16 v[48:51], v[176:179], v[192:195], v[48:51]
	v_mfma_f32_16x16x32_bf16 v[32:35], v[176:179], v[200:203], v[32:35]
	v_mfma_f32_16x16x32_bf16 v[36:39], v[148:151], v[200:203], v[36:39]
	v_mfma_f32_16x16x32_bf16 v[20:23], v[148:151], v[208:211], v[20:23]
	v_mfma_f32_16x16x32_bf16 v[16:19], v[176:179], v[208:211], v[16:19]
	v_mfma_f32_16x16x32_bf16 v[0:3], v[176:179], v[216:219], v[0:3]
	v_mfma_f32_16x16x32_bf16 v[4:7], v[148:151], v[216:219], v[4:7]
	s_barrier
	s_add_i32 s54, 0, 0x18000
	s_add_i32 s55, 0, 0x1c000
	v_add_u32_e32 v140, s54, v184
	v_add_u32_e32 v176, s55, v184
	ds_read_b128 v[128:131], v140
	ds_read_b128 v[132:135], v140 offset:1024
	ds_read_b128 v[136:139], v140 offset:2048
	ds_read_b128 v[140:143], v140 offset:3072
	ds_read_b128 v[144:147], v176
	ds_read_b128 v[148:151], v176 offset:1024
	ds_read_b128 v[172:175], v176 offset:2048
	ds_read_b128 v[176:179], v176 offset:3072
	s_add_u32 s34, s34, 0x40000
	s_addc_u32 s35, s35, 0
	s_mov_b32 m0, s41
	ds_read_b128 v[180:183], v190 offset:32768
	ds_read_b128 v[192:195], v190 offset:33792
	ds_read_b128 v[196:199], v190 offset:34816
	ds_read_b128 v[200:203], v190 offset:35840
	ds_read_b128 v[204:207], v190 offset:36864
	ds_read_b128 v[208:211], v190 offset:37888
	ds_read_b128 v[212:215], v190 offset:38912
	ds_read_b128 v[216:219], v190 offset:39936
	global_load_lds_dwordx4 v152, s[34:35]
	s_mov_b32 m0, s42
	s_nop 0
	global_load_lds_dwordx4 v156, s[34:35]
	s_waitcnt vmcnt(8)
	s_waitcnt lgkmcnt(0)
	s_barrier
	s_waitcnt lgkmcnt(0)
	v_mfma_f32_16x16x32_bf16 v[124:127], v[128:131], v[180:183], v[124:127]
	v_mfma_f32_16x16x32_bf16 v[120:123], v[136:139], v[180:183], v[120:123]
	v_mfma_f32_16x16x32_bf16 v[104:107], v[136:139], v[196:199], v[104:107]
	v_mfma_f32_16x16x32_bf16 v[108:111], v[128:131], v[196:199], v[108:111]
	v_mfma_f32_16x16x32_bf16 v[92:95], v[128:131], v[204:207], v[92:95]
	v_mfma_f32_16x16x32_bf16 v[88:91], v[136:139], v[204:207], v[88:91]
	v_mfma_f32_16x16x32_bf16 v[72:75], v[136:139], v[212:215], v[72:75]
	v_mfma_f32_16x16x32_bf16 v[76:79], v[128:131], v[212:215], v[76:79]
	v_mfma_f32_16x16x32_bf16 v[124:127], v[132:135], v[192:195], v[124:127]
	v_mfma_f32_16x16x32_bf16 v[120:123], v[140:143], v[192:195], v[120:123]
	v_mfma_f32_16x16x32_bf16 v[104:107], v[140:143], v[200:203], v[104:107]
	v_mfma_f32_16x16x32_bf16 v[108:111], v[132:135], v[200:203], v[108:111]
	v_mfma_f32_16x16x32_bf16 v[92:95], v[132:135], v[208:211], v[92:95]
	v_mfma_f32_16x16x32_bf16 v[88:91], v[140:143], v[208:211], v[88:91]
	v_mfma_f32_16x16x32_bf16 v[72:75], v[140:143], v[216:219], v[72:75]
	v_mfma_f32_16x16x32_bf16 v[76:79], v[132:135], v[216:219], v[76:79]
	v_mfma_f32_16x16x32_bf16 v[116:119], v[144:147], v[180:183], v[116:119]
	v_mfma_f32_16x16x32_bf16 v[112:115], v[172:175], v[180:183], v[112:115]
	v_mfma_f32_16x16x32_bf16 v[96:99], v[172:175], v[196:199], v[96:99]
	v_mfma_f32_16x16x32_bf16 v[100:103], v[144:147], v[196:199], v[100:103]
	v_mfma_f32_16x16x32_bf16 v[84:87], v[144:147], v[204:207], v[84:87]
	v_mfma_f32_16x16x32_bf16 v[80:83], v[172:175], v[204:207], v[80:83]
	v_mfma_f32_16x16x32_bf16 v[64:67], v[172:175], v[212:215], v[64:67]
	v_mfma_f32_16x16x32_bf16 v[68:71], v[144:147], v[212:215], v[68:71]
	v_mfma_f32_16x16x32_bf16 v[116:119], v[148:151], v[192:195], v[116:119]
	v_mfma_f32_16x16x32_bf16 v[112:115], v[176:179], v[192:195], v[112:115]
	v_mfma_f32_16x16x32_bf16 v[96:99], v[176:179], v[200:203], v[96:99]
	v_mfma_f32_16x16x32_bf16 v[100:103], v[148:151], v[200:203], v[100:103]
	v_mfma_f32_16x16x32_bf16 v[84:87], v[148:151], v[208:211], v[84:87]
	v_mfma_f32_16x16x32_bf16 v[80:83], v[176:179], v[208:211], v[80:83]
	v_mfma_f32_16x16x32_bf16 v[64:67], v[176:179], v[216:219], v[64:67]
	v_mfma_f32_16x16x32_bf16 v[68:71], v[148:151], v[216:219], v[68:71]
	s_barrier
	s_add_i32 s34, s54, s38
	s_mov_b32 m0, s34
	ds_read_b128 v[180:183], v190 offset:49152
	ds_read_b128 v[192:195], v190 offset:50176
	ds_read_b128 v[196:199], v190 offset:51200
	ds_read_b128 v[200:203], v190 offset:52224
	ds_read_b128 v[204:207], v190 offset:53248
	ds_read_b128 v[208:211], v190 offset:54272
	ds_read_b128 v[212:215], v190 offset:55296
	ds_read_b128 v[216:219], v190 offset:56320
	global_load_lds_dwordx4 v154, s[98:99]
	s_add_i32 m0, s34, 0x2000
	s_add_u32 s30, s30, 0x40080
	s_addc_u32 s31, s31, 0
	s_add_i32 s34, s55, s38
	global_load_lds_dwordx4 v158, s[98:99]
	s_mov_b32 m0, s34
	s_nop 0
	global_load_lds_dwordx4 v154, s[30:31]
	s_add_i32 m0, s34, 0x2000
	s_nop 0
	global_load_lds_dwordx4 v158, s[30:31]
	s_mov_b32 m0, s44
	s_nop 0
	global_load_lds_dwordx4 v152, s[100:101]
	s_mov_b32 m0, s45
	s_nop 0
	global_load_lds_dwordx4 v156, s[100:101]
	s_waitcnt vmcnt(8)
	s_waitcnt lgkmcnt(0)
	s_barrier
	s_waitcnt lgkmcnt(0)
	v_mfma_f32_16x16x32_bf16 v[60:63], v[128:131], v[180:183], v[60:63]
	v_mfma_f32_16x16x32_bf16 v[56:59], v[136:139], v[180:183], v[56:59]
	v_mfma_f32_16x16x32_bf16 v[40:43], v[136:139], v[196:199], v[40:43]
	v_mfma_f32_16x16x32_bf16 v[44:47], v[128:131], v[196:199], v[44:47]
	v_mfma_f32_16x16x32_bf16 v[28:31], v[128:131], v[204:207], v[28:31]
	v_mfma_f32_16x16x32_bf16 v[24:27], v[136:139], v[204:207], v[24:27]
	v_mfma_f32_16x16x32_bf16 v[8:11], v[136:139], v[212:215], v[8:11]
	v_mfma_f32_16x16x32_bf16 v[12:15], v[128:131], v[212:215], v[12:15]
	v_mfma_f32_16x16x32_bf16 v[60:63], v[132:135], v[192:195], v[60:63]
	v_mfma_f32_16x16x32_bf16 v[56:59], v[140:143], v[192:195], v[56:59]
	v_mfma_f32_16x16x32_bf16 v[40:43], v[140:143], v[200:203], v[40:43]
	v_mfma_f32_16x16x32_bf16 v[44:47], v[132:135], v[200:203], v[44:47]
	v_mfma_f32_16x16x32_bf16 v[28:31], v[132:135], v[208:211], v[28:31]
	v_mfma_f32_16x16x32_bf16 v[24:27], v[140:143], v[208:211], v[24:27]
	v_mfma_f32_16x16x32_bf16 v[8:11], v[140:143], v[216:219], v[8:11]
	v_mfma_f32_16x16x32_bf16 v[12:15], v[132:135], v[216:219], v[12:15]
	v_mfma_f32_16x16x32_bf16 v[52:55], v[144:147], v[180:183], v[52:55]
	v_mfma_f32_16x16x32_bf16 v[48:51], v[172:175], v[180:183], v[48:51]
	v_mfma_f32_16x16x32_bf16 v[32:35], v[172:175], v[196:199], v[32:35]
	v_mfma_f32_16x16x32_bf16 v[36:39], v[144:147], v[196:199], v[36:39]
	v_mfma_f32_16x16x32_bf16 v[20:23], v[144:147], v[204:207], v[20:23]
	v_mfma_f32_16x16x32_bf16 v[16:19], v[172:175], v[204:207], v[16:19]
	v_mfma_f32_16x16x32_bf16 v[0:3], v[172:175], v[212:215], v[0:3]
	v_mfma_f32_16x16x32_bf16 v[4:7], v[144:147], v[212:215], v[4:7]
	v_mfma_f32_16x16x32_bf16 v[52:55], v[148:151], v[192:195], v[52:55]
	v_mfma_f32_16x16x32_bf16 v[48:51], v[176:179], v[192:195], v[48:51]
	v_mfma_f32_16x16x32_bf16 v[32:35], v[176:179], v[200:203], v[32:35]
	v_mfma_f32_16x16x32_bf16 v[36:39], v[148:151], v[200:203], v[36:39]
	v_mfma_f32_16x16x32_bf16 v[20:23], v[148:151], v[208:211], v[20:23]
	v_mfma_f32_16x16x32_bf16 v[16:19], v[176:179], v[208:211], v[16:19]
	v_mfma_f32_16x16x32_bf16 v[0:3], v[176:179], v[216:219], v[0:3]
	v_mfma_f32_16x16x32_bf16 v[4:7], v[148:151], v[216:219], v[4:7]
	s_barrier
	s_add_i32 s53, s53, 2
	s_add_u32 s28, s28, 0x100
	s_addc_u32 s29, s29, 0
	s_add_u32 s51, s51, 0x100
	s_addc_u32 s52, s52, 0
	s_cmp_gt_u32 s53, 13
	s_cbranch_scc1 .Lpeel_exit_1886
.LBB0_1886:
	ds_read_b128 v[128:131], v188
	ds_read_b128 v[132:135], v188 offset:1024
	ds_read_b128 v[136:139], v188 offset:2048
	ds_read_b128 v[140:143], v188 offset:3072
	ds_read_b128 v[144:147], v189
	ds_read_b128 v[148:151], v189 offset:1024
	ds_read_b128 v[172:175], v189 offset:2048
	ds_read_b128 v[176:179], v189 offset:3072
	s_add_u32 s30, s28, 0xfffc0080
	s_addc_u32 s31, s29, -1
	s_cmp_eq_u32 s53, 12
	s_cselect_b32 s35, s17, s31
	s_cselect_b32 s34, s25, s30
	s_cselect_b32 s31, s19, s52
	s_cselect_b32 s30, s27, s51
	s_add_i32 m0, s39, 0xc000
	ds_read_b128 v[180:183], v190
	ds_read_b128 v[192:195], v190 offset:1024
	ds_read_b128 v[196:199], v190 offset:2048
	ds_read_b128 v[200:203], v190 offset:3072
	ds_read_b128 v[204:207], v190 offset:4096
	ds_read_b128 v[208:211], v190 offset:5120
	ds_read_b128 v[212:215], v190 offset:6144
	ds_read_b128 v[216:219], v190 offset:7168
	global_load_lds_dwordx4 v164, s[28:29]
	s_add_i32 m0, s39, 0xe000
	s_nop 0
	global_load_lds_dwordx4 v166, s[28:29]
	s_waitcnt vmcnt(8)
	s_waitcnt lgkmcnt(0)
	s_barrier
	s_waitcnt lgkmcnt(0)
	v_mfma_f32_16x16x32_bf16 v[124:127], v[128:131], v[180:183], v[124:127]
	v_mfma_f32_16x16x32_bf16 v[120:123], v[136:139], v[180:183], v[120:123]
	v_mfma_f32_16x16x32_bf16 v[104:107], v[136:139], v[196:199], v[104:107]
	v_mfma_f32_16x16x32_bf16 v[108:111], v[128:131], v[196:199], v[108:111]
	v_mfma_f32_16x16x32_bf16 v[92:95], v[128:131], v[204:207], v[92:95]
	v_mfma_f32_16x16x32_bf16 v[88:91], v[136:139], v[204:207], v[88:91]
	v_mfma_f32_16x16x32_bf16 v[72:75], v[136:139], v[212:215], v[72:75]
	v_mfma_f32_16x16x32_bf16 v[76:79], v[128:131], v[212:215], v[76:79]
	v_mfma_f32_16x16x32_bf16 v[124:127], v[132:135], v[192:195], v[124:127]
	v_mfma_f32_16x16x32_bf16 v[120:123], v[140:143], v[192:195], v[120:123]
	v_mfma_f32_16x16x32_bf16 v[104:107], v[140:143], v[200:203], v[104:107]
	v_mfma_f32_16x16x32_bf16 v[108:111], v[132:135], v[200:203], v[108:111]
	v_mfma_f32_16x16x32_bf16 v[92:95], v[132:135], v[208:211], v[92:95]
	v_mfma_f32_16x16x32_bf16 v[88:91], v[140:143], v[208:211], v[88:91]
	v_mfma_f32_16x16x32_bf16 v[72:75], v[140:143], v[216:219], v[72:75]
	v_mfma_f32_16x16x32_bf16 v[76:79], v[132:135], v[216:219], v[76:79]
	v_mfma_f32_16x16x32_bf16 v[116:119], v[144:147], v[180:183], v[116:119]
	v_mfma_f32_16x16x32_bf16 v[112:115], v[172:175], v[180:183], v[112:115]
	v_mfma_f32_16x16x32_bf16 v[96:99], v[172:175], v[196:199], v[96:99]
	v_mfma_f32_16x16x32_bf16 v[100:103], v[144:147], v[196:199], v[100:103]
	v_mfma_f32_16x16x32_bf16 v[84:87], v[144:147], v[204:207], v[84:87]
	v_mfma_f32_16x16x32_bf16 v[80:83], v[172:175], v[204:207], v[80:83]
	v_mfma_f32_16x16x32_bf16 v[64:67], v[172:175], v[212:215], v[64:67]
	v_mfma_f32_16x16x32_bf16 v[68:71], v[144:147], v[212:215], v[68:71]
	v_mfma_f32_16x16x32_bf16 v[116:119], v[148:151], v[192:195], v[116:119]
	v_mfma_f32_16x16x32_bf16 v[112:115], v[176:179], v[192:195], v[112:115]
	v_mfma_f32_16x16x32_bf16 v[96:99], v[176:179], v[200:203], v[96:99]
	v_mfma_f32_16x16x32_bf16 v[100:103], v[148:151], v[200:203], v[100:103]
	v_mfma_f32_16x16x32_bf16 v[84:87], v[148:151], v[208:211], v[84:87]
	v_mfma_f32_16x16x32_bf16 v[80:83], v[176:179], v[208:211], v[80:83]
	v_mfma_f32_16x16x32_bf16 v[64:67], v[176:179], v[216:219], v[64:67]
	v_mfma_f32_16x16x32_bf16 v[68:71], v[148:151], v[216:219], v[68:71]
	s_barrier
	s_add_i32 s54, s49, s38
	s_mov_b32 m0, s54
	ds_read_b128 v[180:183], v190 offset:16384
	ds_read_b128 v[192:195], v190 offset:17408
	ds_read_b128 v[196:199], v190 offset:18432
	ds_read_b128 v[200:203], v190 offset:19456
	ds_read_b128 v[204:207], v190 offset:20480
	ds_read_b128 v[208:211], v190 offset:21504
	ds_read_b128 v[212:215], v190 offset:22528
	ds_read_b128 v[216:219], v190 offset:23552
	global_load_lds_dwordx4 v154, s[30:31]
	s_add_i32 m0, s54, 0x2000
	s_add_u32 s54, s30, 0x40000
	s_addc_u32 s55, s31, 0
	s_add_i32 s56, s50, s38
	global_load_lds_dwordx4 v158, s[30:31]
	s_mov_b32 m0, s56
	global_load_lds_dwordx4 v154, s[54:55]
	s_add_i32 m0, s56, 0x2000
	s_nop 0
	global_load_lds_dwordx4 v158, s[54:55]
	s_mov_b32 m0, s39
	s_nop 0
	global_load_lds_dwordx4 v152, s[34:35]
	s_mov_b32 m0, s40
	s_nop 0
	global_load_lds_dwordx4 v156, s[34:35]
	s_add_u32 s98, s30, s12
	s_addc_u32 s99, s31, s13
	s_add_u32 s100, s34, s12
	s_addc_u32 s101, s35, s13
	s_waitcnt vmcnt(8)
	s_waitcnt lgkmcnt(0)
	s_barrier
	s_waitcnt lgkmcnt(0)
	v_mfma_f32_16x16x32_bf16 v[60:63], v[128:131], v[180:183], v[60:63]
	v_mfma_f32_16x16x32_bf16 v[56:59], v[136:139], v[180:183], v[56:59]
	v_mfma_f32_16x16x32_bf16 v[40:43], v[136:139], v[196:199], v[40:43]
	v_mfma_f32_16x16x32_bf16 v[44:47], v[128:131], v[196:199], v[44:47]
	v_mfma_f32_16x16x32_bf16 v[28:31], v[128:131], v[204:207], v[28:31]
	v_mfma_f32_16x16x32_bf16 v[24:27], v[136:139], v[204:207], v[24:27]
	v_mfma_f32_16x16x32_bf16 v[8:11], v[136:139], v[212:215], v[8:11]
	v_mfma_f32_16x16x32_bf16 v[12:15], v[128:131], v[212:215], v[12:15]
	v_mfma_f32_16x16x32_bf16 v[60:63], v[132:135], v[192:195], v[60:63]
	v_mfma_f32_16x16x32_bf16 v[56:59], v[140:143], v[192:195], v[56:59]
	v_mfma_f32_16x16x32_bf16 v[40:43], v[140:143], v[200:203], v[40:43]
	v_mfma_f32_16x16x32_bf16 v[44:47], v[132:135], v[200:203], v[44:47]
	v_mfma_f32_16x16x32_bf16 v[28:31], v[132:135], v[208:211], v[28:31]
	v_mfma_f32_16x16x32_bf16 v[24:27], v[140:143], v[208:211], v[24:27]
	v_mfma_f32_16x16x32_bf16 v[8:11], v[140:143], v[216:219], v[8:11]
	v_mfma_f32_16x16x32_bf16 v[12:15], v[132:135], v[216:219], v[12:15]
	v_mfma_f32_16x16x32_bf16 v[52:55], v[144:147], v[180:183], v[52:55]
	v_mfma_f32_16x16x32_bf16 v[48:51], v[172:175], v[180:183], v[48:51]
	v_mfma_f32_16x16x32_bf16 v[32:35], v[172:175], v[196:199], v[32:35]
	v_mfma_f32_16x16x32_bf16 v[36:39], v[144:147], v[196:199], v[36:39]
	v_mfma_f32_16x16x32_bf16 v[20:23], v[144:147], v[204:207], v[20:23]
	v_mfma_f32_16x16x32_bf16 v[16:19], v[172:175], v[204:207], v[16:19]
	v_mfma_f32_16x16x32_bf16 v[0:3], v[172:175], v[212:215], v[0:3]
	v_mfma_f32_16x16x32_bf16 v[4:7], v[144:147], v[212:215], v[4:7]
	v_mfma_f32_16x16x32_bf16 v[52:55], v[148:151], v[192:195], v[52:55]
	v_mfma_f32_16x16x32_bf16 v[48:51], v[176:179], v[192:195], v[48:51]
	v_mfma_f32_16x16x32_bf16 v[32:35], v[176:179], v[200:203], v[32:35]
	v_mfma_f32_16x16x32_bf16 v[36:39], v[148:151], v[200:203], v[36:39]
	v_mfma_f32_16x16x32_bf16 v[20:23], v[148:151], v[208:211], v[20:23]
	v_mfma_f32_16x16x32_bf16 v[16:19], v[176:179], v[208:211], v[16:19]
	v_mfma_f32_16x16x32_bf16 v[0:3], v[176:179], v[216:219], v[0:3]
	v_mfma_f32_16x16x32_bf16 v[4:7], v[148:151], v[216:219], v[4:7]
	s_barrier
	s_add_i32 s54, 0, 0x18000
	s_add_i32 s55, 0, 0x1c000
	v_add_u32_e32 v140, s54, v184
	v_add_u32_e32 v176, s55, v184
	ds_read_b128 v[128:131], v140
	ds_read_b128 v[132:135], v140 offset:1024
	ds_read_b128 v[136:139], v140 offset:2048
	ds_read_b128 v[140:143], v140 offset:3072
	ds_read_b128 v[144:147], v176
	ds_read_b128 v[148:151], v176 offset:1024
	ds_read_b128 v[172:175], v176 offset:2048
	ds_read_b128 v[176:179], v176 offset:3072
	s_add_u32 s34, s34, 0x40000
	s_addc_u32 s35, s35, 0
	s_mov_b32 m0, s41
	ds_read_b128 v[180:183], v190 offset:32768
	ds_read_b128 v[192:195], v190 offset:33792
	ds_read_b128 v[196:199], v190 offset:34816
	ds_read_b128 v[200:203], v190 offset:35840
	ds_read_b128 v[204:207], v190 offset:36864
	ds_read_b128 v[208:211], v190 offset:37888
	ds_read_b128 v[212:215], v190 offset:38912
	ds_read_b128 v[216:219], v190 offset:39936
	global_load_lds_dwordx4 v152, s[34:35]
	s_mov_b32 m0, s42
	s_nop 0
	global_load_lds_dwordx4 v156, s[34:35]
	s_waitcnt vmcnt(8)
	s_waitcnt lgkmcnt(0)
	s_barrier
	s_waitcnt lgkmcnt(0)
	v_mfma_f32_16x16x32_bf16 v[124:127], v[128:131], v[180:183], v[124:127]
	v_mfma_f32_16x16x32_bf16 v[120:123], v[136:139], v[180:183], v[120:123]
	v_mfma_f32_16x16x32_bf16 v[104:107], v[136:139], v[196:199], v[104:107]
	v_mfma_f32_16x16x32_bf16 v[108:111], v[128:131], v[196:199], v[108:111]
	v_mfma_f32_16x16x32_bf16 v[92:95], v[128:131], v[204:207], v[92:95]
	v_mfma_f32_16x16x32_bf16 v[88:91], v[136:139], v[204:207], v[88:91]
	v_mfma_f32_16x16x32_bf16 v[72:75], v[136:139], v[212:215], v[72:75]
	v_mfma_f32_16x16x32_bf16 v[76:79], v[128:131], v[212:215], v[76:79]
	v_mfma_f32_16x16x32_bf16 v[124:127], v[132:135], v[192:195], v[124:127]
	v_mfma_f32_16x16x32_bf16 v[120:123], v[140:143], v[192:195], v[120:123]
	v_mfma_f32_16x16x32_bf16 v[104:107], v[140:143], v[200:203], v[104:107]
	v_mfma_f32_16x16x32_bf16 v[108:111], v[132:135], v[200:203], v[108:111]
	v_mfma_f32_16x16x32_bf16 v[92:95], v[132:135], v[208:211], v[92:95]
	v_mfma_f32_16x16x32_bf16 v[88:91], v[140:143], v[208:211], v[88:91]
	v_mfma_f32_16x16x32_bf16 v[72:75], v[140:143], v[216:219], v[72:75]
	v_mfma_f32_16x16x32_bf16 v[76:79], v[132:135], v[216:219], v[76:79]
	v_mfma_f32_16x16x32_bf16 v[116:119], v[144:147], v[180:183], v[116:119]
	v_mfma_f32_16x16x32_bf16 v[112:115], v[172:175], v[180:183], v[112:115]
	v_mfma_f32_16x16x32_bf16 v[96:99], v[172:175], v[196:199], v[96:99]
	v_mfma_f32_16x16x32_bf16 v[100:103], v[144:147], v[196:199], v[100:103]
	v_mfma_f32_16x16x32_bf16 v[84:87], v[144:147], v[204:207], v[84:87]
	v_mfma_f32_16x16x32_bf16 v[80:83], v[172:175], v[204:207], v[80:83]
	v_mfma_f32_16x16x32_bf16 v[64:67], v[172:175], v[212:215], v[64:67]
	v_mfma_f32_16x16x32_bf16 v[68:71], v[144:147], v[212:215], v[68:71]
	v_mfma_f32_16x16x32_bf16 v[116:119], v[148:151], v[192:195], v[116:119]
	v_mfma_f32_16x16x32_bf16 v[112:115], v[176:179], v[192:195], v[112:115]
	v_mfma_f32_16x16x32_bf16 v[96:99], v[176:179], v[200:203], v[96:99]
	v_mfma_f32_16x16x32_bf16 v[100:103], v[148:151], v[200:203], v[100:103]
	v_mfma_f32_16x16x32_bf16 v[84:87], v[148:151], v[208:211], v[84:87]
	v_mfma_f32_16x16x32_bf16 v[80:83], v[176:179], v[208:211], v[80:83]
	v_mfma_f32_16x16x32_bf16 v[64:67], v[176:179], v[216:219], v[64:67]
	v_mfma_f32_16x16x32_bf16 v[68:71], v[148:151], v[216:219], v[68:71]
	s_barrier
	s_add_i32 s34, s54, s38
	s_mov_b32 m0, s34
	ds_read_b128 v[180:183], v190 offset:49152
	ds_read_b128 v[192:195], v190 offset:50176
	ds_read_b128 v[196:199], v190 offset:51200
	ds_read_b128 v[200:203], v190 offset:52224
	ds_read_b128 v[204:207], v190 offset:53248
	ds_read_b128 v[208:211], v190 offset:54272
	ds_read_b128 v[212:215], v190 offset:55296
	ds_read_b128 v[216:219], v190 offset:56320
	global_load_lds_dwordx4 v154, s[98:99]
	s_add_i32 m0, s34, 0x2000
	s_add_u32 s30, s30, 0x40080
	s_addc_u32 s31, s31, 0
	s_add_i32 s34, s55, s38
	global_load_lds_dwordx4 v158, s[98:99]
	s_mov_b32 m0, s34
	s_nop 0
	global_load_lds_dwordx4 v154, s[30:31]
	s_add_i32 m0, s34, 0x2000
	s_nop 0
	global_load_lds_dwordx4 v158, s[30:31]
	s_mov_b32 m0, s44
	s_nop 0
	global_load_lds_dwordx4 v152, s[100:101]
	s_mov_b32 m0, s45
	s_nop 0
	global_load_lds_dwordx4 v156, s[100:101]
	s_waitcnt vmcnt(8)
	s_waitcnt lgkmcnt(0)
	s_barrier
	s_waitcnt lgkmcnt(0)
	v_mfma_f32_16x16x32_bf16 v[60:63], v[128:131], v[180:183], v[60:63]
	v_mfma_f32_16x16x32_bf16 v[56:59], v[136:139], v[180:183], v[56:59]
	v_mfma_f32_16x16x32_bf16 v[40:43], v[136:139], v[196:199], v[40:43]
	v_mfma_f32_16x16x32_bf16 v[44:47], v[128:131], v[196:199], v[44:47]
	v_mfma_f32_16x16x32_bf16 v[28:31], v[128:131], v[204:207], v[28:31]
	v_mfma_f32_16x16x32_bf16 v[24:27], v[136:139], v[204:207], v[24:27]
	v_mfma_f32_16x16x32_bf16 v[8:11], v[136:139], v[212:215], v[8:11]
	v_mfma_f32_16x16x32_bf16 v[12:15], v[128:131], v[212:215], v[12:15]
	v_mfma_f32_16x16x32_bf16 v[60:63], v[132:135], v[192:195], v[60:63]
	v_mfma_f32_16x16x32_bf16 v[56:59], v[140:143], v[192:195], v[56:59]
	v_mfma_f32_16x16x32_bf16 v[40:43], v[140:143], v[200:203], v[40:43]
	v_mfma_f32_16x16x32_bf16 v[44:47], v[132:135], v[200:203], v[44:47]
	v_mfma_f32_16x16x32_bf16 v[28:31], v[132:135], v[208:211], v[28:31]
	v_mfma_f32_16x16x32_bf16 v[24:27], v[140:143], v[208:211], v[24:27]
	v_mfma_f32_16x16x32_bf16 v[8:11], v[140:143], v[216:219], v[8:11]
	v_mfma_f32_16x16x32_bf16 v[12:15], v[132:135], v[216:219], v[12:15]
	v_mfma_f32_16x16x32_bf16 v[52:55], v[144:147], v[180:183], v[52:55]
	v_mfma_f32_16x16x32_bf16 v[48:51], v[172:175], v[180:183], v[48:51]
	v_mfma_f32_16x16x32_bf16 v[32:35], v[172:175], v[196:199], v[32:35]
	v_mfma_f32_16x16x32_bf16 v[36:39], v[144:147], v[196:199], v[36:39]
	v_mfma_f32_16x16x32_bf16 v[20:23], v[144:147], v[204:207], v[20:23]
	v_mfma_f32_16x16x32_bf16 v[16:19], v[172:175], v[204:207], v[16:19]
	v_mfma_f32_16x16x32_bf16 v[0:3], v[172:175], v[212:215], v[0:3]
	v_mfma_f32_16x16x32_bf16 v[4:7], v[144:147], v[212:215], v[4:7]
	v_mfma_f32_16x16x32_bf16 v[52:55], v[148:151], v[192:195], v[52:55]
	v_mfma_f32_16x16x32_bf16 v[48:51], v[176:179], v[192:195], v[48:51]
	v_mfma_f32_16x16x32_bf16 v[32:35], v[176:179], v[200:203], v[32:35]
	v_mfma_f32_16x16x32_bf16 v[36:39], v[148:151], v[200:203], v[36:39]
	v_mfma_f32_16x16x32_bf16 v[20:23], v[148:151], v[208:211], v[20:23]
	v_mfma_f32_16x16x32_bf16 v[16:19], v[176:179], v[208:211], v[16:19]
	v_mfma_f32_16x16x32_bf16 v[0:3], v[176:179], v[216:219], v[0:3]
	v_mfma_f32_16x16x32_bf16 v[4:7], v[148:151], v[216:219], v[4:7]
	s_barrier
	s_add_i32 s53, s53, 2
	s_add_u32 s28, s28, 0x100
	s_addc_u32 s29, s29, 0
	s_add_u32 s51, s51, 0x100
	s_addc_u32 s52, s52, 0
	s_cmp_gt_u32 s53, 13
	s_cbranch_scc0 .LBB0_1886

.LBB0_1974:
	s_ashr_i32 s15, s14, 31
	s_lshl_b64 s[18:19], s[14:15], 19
	s_add_u32 s18, s82, s18
	s_addc_u32 s19, s83, s19
	s_and_b64 s[20:21], s[4:5], exec
	s_cselect_b32 s15, s19, s25
	s_cselect_b32 s47, s18, s24
	s_ashr_i32 s17, s16, 31
	s_lshl_b64 s[20:21], s[16:17], 19
	s_add_u32 s20, s3, s20
	s_addc_u32 s21, s30, s21
	s_and_b64 s[28:29], s[4:5], exec
	s_cselect_b32 s17, s21, s27
	s_cselect_b32 s48, s20, s26
	s_add_u32 s24, s24, 0x40080
	s_addc_u32 s25, s25, 0
	s_add_u32 s49, s26, 0x100
	s_addc_u32 s50, s27, 0
	s_mov_b32 s51, -2
	ds_read_b128 v[144:147], v155
	ds_read_b128 v[160:163], v155 offset:1024
	ds_read_b128 v[164:167], v155 offset:2048
	ds_read_b128 v[168:171], v155 offset:3072
	ds_read_b128 v[172:175], v157
	ds_read_b128 v[176:179], v157 offset:1024
	ds_read_b128 v[180:183], v157 offset:2048
	ds_read_b128 v[186:189], v157 offset:3072
	s_add_u32 s26, s24, 0xfffc0080
	s_addc_u32 s27, s25, -1
	s_cmp_eq_u32 s51, 12
	s_cselect_b32 s29, s15, s27
	s_cselect_b32 s28, s47, s26
	s_cselect_b32 s27, s17, s50
	s_cselect_b32 s26, s48, s49
	s_add_i32 m0, s23, 0xc000
	ds_read_b128 v[190:193], v158
	ds_read_b128 v[194:197], v158 offset:1024
	ds_read_b128 v[198:201], v158 offset:2048
	ds_read_b128 v[202:205], v158 offset:3072
	ds_read_b128 v[206:209], v158 offset:4096
	ds_read_b128 v[210:213], v158 offset:5120
	ds_read_b128 v[214:217], v158 offset:6144
	ds_read_b128 v[218:221], v158 offset:7168
	global_load_lds_dwordx4 v136, s[24:25]
	s_add_i32 m0, s23, 0xe000
	s_nop 0
	global_load_lds_dwordx4 v138, s[24:25]
	s_waitcnt vmcnt(8)
	s_waitcnt lgkmcnt(0)
	s_barrier
	s_waitcnt lgkmcnt(0)
	v_mfma_f32_16x16x32_bf16 v[124:127], v[144:147], v[190:193], 0
	v_mfma_f32_16x16x32_bf16 v[120:123], v[164:167], v[190:193], 0
	v_mfma_f32_16x16x32_bf16 v[104:107], v[164:167], v[198:201], 0
	v_mfma_f32_16x16x32_bf16 v[116:119], v[144:147], v[198:201], 0
	v_mfma_f32_16x16x32_bf16 v[92:95], v[144:147], v[206:209], 0
	v_mfma_f32_16x16x32_bf16 v[88:91], v[164:167], v[206:209], 0
	v_mfma_f32_16x16x32_bf16 v[72:75], v[164:167], v[214:217], 0
	v_mfma_f32_16x16x32_bf16 v[76:79], v[144:147], v[214:217], 0
	v_mfma_f32_16x16x32_bf16 v[124:127], v[160:163], v[194:197], v[124:127]
	v_mfma_f32_16x16x32_bf16 v[120:123], v[168:171], v[194:197], v[120:123]
	v_mfma_f32_16x16x32_bf16 v[104:107], v[168:171], v[202:205], v[104:107]
	v_mfma_f32_16x16x32_bf16 v[116:119], v[160:163], v[202:205], v[116:119]
	v_mfma_f32_16x16x32_bf16 v[92:95], v[160:163], v[210:213], v[92:95]
	v_mfma_f32_16x16x32_bf16 v[88:91], v[168:171], v[210:213], v[88:91]
	v_mfma_f32_16x16x32_bf16 v[72:75], v[168:171], v[218:221], v[72:75]
	v_mfma_f32_16x16x32_bf16 v[76:79], v[160:163], v[218:221], v[76:79]
	v_mfma_f32_16x16x32_bf16 v[112:115], v[172:175], v[190:193], 0
	v_mfma_f32_16x16x32_bf16 v[108:111], v[180:183], v[190:193], 0
	v_mfma_f32_16x16x32_bf16 v[96:99], v[180:183], v[198:201], 0
	v_mfma_f32_16x16x32_bf16 v[100:103], v[172:175], v[198:201], 0
	v_mfma_f32_16x16x32_bf16 v[84:87], v[172:175], v[206:209], 0
	v_mfma_f32_16x16x32_bf16 v[80:83], v[180:183], v[206:209], 0
	v_mfma_f32_16x16x32_bf16 v[64:67], v[180:183], v[214:217], 0
	v_mfma_f32_16x16x32_bf16 v[68:71], v[172:175], v[214:217], 0
	v_mfma_f32_16x16x32_bf16 v[112:115], v[176:179], v[194:197], v[112:115]
	v_mfma_f32_16x16x32_bf16 v[108:111], v[186:189], v[194:197], v[108:111]
	v_mfma_f32_16x16x32_bf16 v[96:99], v[186:189], v[202:205], v[96:99]
	v_mfma_f32_16x16x32_bf16 v[100:103], v[176:179], v[202:205], v[100:103]
	v_mfma_f32_16x16x32_bf16 v[84:87], v[176:179], v[210:213], v[84:87]
	v_mfma_f32_16x16x32_bf16 v[80:83], v[186:189], v[210:213], v[80:83]
	v_mfma_f32_16x16x32_bf16 v[64:67], v[186:189], v[218:221], v[64:67]
	v_mfma_f32_16x16x32_bf16 v[68:71], v[176:179], v[218:221], v[68:71]
	s_barrier
	s_add_i32 s52, s43, s31
	s_mov_b32 m0, s52
	ds_read_b128 v[190:193], v158 offset:16384
	ds_read_b128 v[194:197], v158 offset:17408
	ds_read_b128 v[198:201], v158 offset:18432
	ds_read_b128 v[202:205], v158 offset:19456
	ds_read_b128 v[206:209], v158 offset:20480
	ds_read_b128 v[210:213], v158 offset:21504
	ds_read_b128 v[214:217], v158 offset:22528
	ds_read_b128 v[218:221], v158 offset:23552
	global_load_lds_dwordx4 v132, s[26:27]
	s_add_i32 m0, s52, 0x2000
	s_add_u32 s52, s26, 0x40000
	s_addc_u32 s53, s27, 0
	s_add_i32 s54, s44, s31
	global_load_lds_dwordx4 v128, s[26:27]
	s_mov_b32 m0, s54
	global_load_lds_dwordx4 v132, s[52:53]
	s_add_i32 m0, s54, 0x2000
	s_nop 0
	global_load_lds_dwordx4 v128, s[52:53]
	s_mov_b32 m0, s23
	s_nop 0
	global_load_lds_dwordx4 v134, s[28:29]
	s_mov_b32 m0, s35
	s_nop 0
	global_load_lds_dwordx4 v130, s[28:29]
	s_add_u32 s98, s26, s10
	s_addc_u32 s99, s27, s11
	s_add_u32 s100, s28, s10
	s_addc_u32 s101, s29, s11
	s_waitcnt vmcnt(8)
	s_waitcnt lgkmcnt(0)
	s_barrier
	s_waitcnt lgkmcnt(0)
	v_mfma_f32_16x16x32_bf16 v[60:63], v[144:147], v[190:193], 0
	v_mfma_f32_16x16x32_bf16 v[56:59], v[164:167], v[190:193], 0
	v_mfma_f32_16x16x32_bf16 v[40:43], v[164:167], v[198:201], 0
	v_mfma_f32_16x16x32_bf16 v[44:47], v[144:147], v[198:201], 0
	v_mfma_f32_16x16x32_bf16 v[28:31], v[144:147], v[206:209], 0
	v_mfma_f32_16x16x32_bf16 v[24:27], v[164:167], v[206:209], 0
	v_mfma_f32_16x16x32_bf16 v[8:11], v[164:167], v[214:217], 0
	v_mfma_f32_16x16x32_bf16 v[12:15], v[144:147], v[214:217], 0
	v_mfma_f32_16x16x32_bf16 v[60:63], v[160:163], v[194:197], v[60:63]
	v_mfma_f32_16x16x32_bf16 v[56:59], v[168:171], v[194:197], v[56:59]
	v_mfma_f32_16x16x32_bf16 v[40:43], v[168:171], v[202:205], v[40:43]
	v_mfma_f32_16x16x32_bf16 v[44:47], v[160:163], v[202:205], v[44:47]
	v_mfma_f32_16x16x32_bf16 v[28:31], v[160:163], v[210:213], v[28:31]
	v_mfma_f32_16x16x32_bf16 v[24:27], v[168:171], v[210:213], v[24:27]
	v_mfma_f32_16x16x32_bf16 v[8:11], v[168:171], v[218:221], v[8:11]
	v_mfma_f32_16x16x32_bf16 v[12:15], v[160:163], v[218:221], v[12:15]
	v_mfma_f32_16x16x32_bf16 v[52:55], v[172:175], v[190:193], 0
	v_mfma_f32_16x16x32_bf16 v[48:51], v[180:183], v[190:193], 0
	v_mfma_f32_16x16x32_bf16 v[32:35], v[180:183], v[198:201], 0
	v_mfma_f32_16x16x32_bf16 v[36:39], v[172:175], v[198:201], 0
	v_mfma_f32_16x16x32_bf16 v[20:23], v[172:175], v[206:209], 0
	v_mfma_f32_16x16x32_bf16 v[16:19], v[180:183], v[206:209], 0
	v_mfma_f32_16x16x32_bf16 v[0:3], v[180:183], v[214:217], 0
	v_mfma_f32_16x16x32_bf16 v[4:7], v[172:175], v[214:217], 0
	v_mfma_f32_16x16x32_bf16 v[52:55], v[176:179], v[194:197], v[52:55]
	v_mfma_f32_16x16x32_bf16 v[48:51], v[186:189], v[194:197], v[48:51]
	v_mfma_f32_16x16x32_bf16 v[32:35], v[186:189], v[202:205], v[32:35]
	v_mfma_f32_16x16x32_bf16 v[36:39], v[176:179], v[202:205], v[36:39]
	v_mfma_f32_16x16x32_bf16 v[20:23], v[176:179], v[210:213], v[20:23]
	v_mfma_f32_16x16x32_bf16 v[16:19], v[186:189], v[210:213], v[16:19]
	v_mfma_f32_16x16x32_bf16 v[0:3], v[186:189], v[218:221], v[0:3]
	v_mfma_f32_16x16x32_bf16 v[4:7], v[176:179], v[218:221], v[4:7]
	s_barrier
	s_add_i32 s52, 0, 0x18000
	v_add_u32_e32 v148, s52, v151
	s_add_i32 s53, 0, 0x1c000
	ds_read_b128 v[144:147], v148
	ds_read_b128 v[160:163], v148 offset:1024
	ds_read_b128 v[164:167], v148 offset:2048
	ds_read_b128 v[168:171], v148 offset:3072
	v_add_u32_e32 v148, s53, v151
	ds_read_b128 v[172:175], v148
	ds_read_b128 v[176:179], v148 offset:1024
	ds_read_b128 v[180:183], v148 offset:2048
	ds_read_b128 v[186:189], v148 offset:3072
	s_add_u32 s28, s28, 0x40000
	s_addc_u32 s29, s29, 0
	s_mov_b32 m0, s36
	ds_read_b128 v[190:193], v158 offset:32768
	ds_read_b128 v[194:197], v158 offset:33792
	ds_read_b128 v[198:201], v158 offset:34816
	ds_read_b128 v[202:205], v158 offset:35840
	ds_read_b128 v[206:209], v158 offset:36864
	ds_read_b128 v[210:213], v158 offset:37888
	ds_read_b128 v[214:217], v158 offset:38912
	ds_read_b128 v[218:221], v158 offset:39936
	global_load_lds_dwordx4 v134, s[28:29]
	s_mov_b32 m0, s37
	s_nop 0
	global_load_lds_dwordx4 v130, s[28:29]
	s_waitcnt vmcnt(8)
	s_waitcnt lgkmcnt(0)
	s_barrier
	s_waitcnt lgkmcnt(0)
	v_mfma_f32_16x16x32_bf16 v[124:127], v[144:147], v[190:193], v[124:127]
	v_mfma_f32_16x16x32_bf16 v[120:123], v[164:167], v[190:193], v[120:123]
	v_mfma_f32_16x16x32_bf16 v[104:107], v[164:167], v[198:201], v[104:107]
	v_mfma_f32_16x16x32_bf16 v[116:119], v[144:147], v[198:201], v[116:119]
	v_mfma_f32_16x16x32_bf16 v[92:95], v[144:147], v[206:209], v[92:95]
	v_mfma_f32_16x16x32_bf16 v[88:91], v[164:167], v[206:209], v[88:91]
	v_mfma_f32_16x16x32_bf16 v[72:75], v[164:167], v[214:217], v[72:75]
	v_mfma_f32_16x16x32_bf16 v[76:79], v[144:147], v[214:217], v[76:79]
	v_mfma_f32_16x16x32_bf16 v[124:127], v[160:163], v[194:197], v[124:127]
	v_mfma_f32_16x16x32_bf16 v[120:123], v[168:171], v[194:197], v[120:123]
	v_mfma_f32_16x16x32_bf16 v[104:107], v[168:171], v[202:205], v[104:107]
	v_mfma_f32_16x16x32_bf16 v[116:119], v[160:163], v[202:205], v[116:119]
	v_mfma_f32_16x16x32_bf16 v[92:95], v[160:163], v[210:213], v[92:95]
	v_mfma_f32_16x16x32_bf16 v[88:91], v[168:171], v[210:213], v[88:91]
	v_mfma_f32_16x16x32_bf16 v[72:75], v[168:171], v[218:221], v[72:75]
	v_mfma_f32_16x16x32_bf16 v[76:79], v[160:163], v[218:221], v[76:79]
	v_mfma_f32_16x16x32_bf16 v[112:115], v[172:175], v[190:193], v[112:115]
	v_mfma_f32_16x16x32_bf16 v[108:111], v[180:183], v[190:193], v[108:111]
	v_mfma_f32_16x16x32_bf16 v[96:99], v[180:183], v[198:201], v[96:99]
	v_mfma_f32_16x16x32_bf16 v[100:103], v[172:175], v[198:201], v[100:103]
	v_mfma_f32_16x16x32_bf16 v[84:87], v[172:175], v[206:209], v[84:87]
	v_mfma_f32_16x16x32_bf16 v[80:83], v[180:183], v[206:209], v[80:83]
	v_mfma_f32_16x16x32_bf16 v[64:67], v[180:183], v[214:217], v[64:67]
	v_mfma_f32_16x16x32_bf16 v[68:71], v[172:175], v[214:217], v[68:71]
	v_mfma_f32_16x16x32_bf16 v[112:115], v[176:179], v[194:197], v[112:115]
	v_mfma_f32_16x16x32_bf16 v[108:111], v[186:189], v[194:197], v[108:111]
	v_mfma_f32_16x16x32_bf16 v[96:99], v[186:189], v[202:205], v[96:99]
	v_mfma_f32_16x16x32_bf16 v[100:103], v[176:179], v[202:205], v[100:103]
	v_mfma_f32_16x16x32_bf16 v[84:87], v[176:179], v[210:213], v[84:87]
	v_mfma_f32_16x16x32_bf16 v[80:83], v[186:189], v[210:213], v[80:83]
	v_mfma_f32_16x16x32_bf16 v[64:67], v[186:189], v[218:221], v[64:67]
	v_mfma_f32_16x16x32_bf16 v[68:71], v[176:179], v[218:221], v[68:71]
	s_barrier
	s_add_i32 s28, s52, s31
	s_mov_b32 m0, s28
	ds_read_b128 v[190:193], v158 offset:49152
	ds_read_b128 v[194:197], v158 offset:50176
	ds_read_b128 v[198:201], v158 offset:51200
	ds_read_b128 v[202:205], v158 offset:52224
	ds_read_b128 v[206:209], v158 offset:53248
	ds_read_b128 v[210:213], v158 offset:54272
	ds_read_b128 v[214:217], v158 offset:55296
	ds_read_b128 v[218:221], v158 offset:56320
	global_load_lds_dwordx4 v132, s[98:99]
	s_add_i32 m0, s28, 0x2000
	s_add_u32 s26, s26, 0x40080
	s_addc_u32 s27, s27, 0
	s_add_i32 s28, s53, s31
	global_load_lds_dwordx4 v128, s[98:99]
	s_mov_b32 m0, s28
	s_nop 0
	global_load_lds_dwordx4 v132, s[26:27]
	s_add_i32 m0, s28, 0x2000
	s_nop 0
	global_load_lds_dwordx4 v128, s[26:27]
	s_mov_b32 m0, s39
	s_nop 0
	global_load_lds_dwordx4 v134, s[100:101]
	s_mov_b32 m0, s40
	s_nop 0
	global_load_lds_dwordx4 v130, s[100:101]
	s_waitcnt vmcnt(8)
	s_waitcnt lgkmcnt(0)
	s_barrier
	s_waitcnt lgkmcnt(0)
	v_mfma_f32_16x16x32_bf16 v[60:63], v[144:147], v[190:193], v[60:63]
	v_mfma_f32_16x16x32_bf16 v[56:59], v[164:167], v[190:193], v[56:59]
	v_mfma_f32_16x16x32_bf16 v[40:43], v[164:167], v[198:201], v[40:43]
	v_mfma_f32_16x16x32_bf16 v[44:47], v[144:147], v[198:201], v[44:47]
	v_mfma_f32_16x16x32_bf16 v[28:31], v[144:147], v[206:209], v[28:31]
	v_mfma_f32_16x16x32_bf16 v[24:27], v[164:167], v[206:209], v[24:27]
	v_mfma_f32_16x16x32_bf16 v[8:11], v[164:167], v[214:217], v[8:11]
	v_mfma_f32_16x16x32_bf16 v[12:15], v[144:147], v[214:217], v[12:15]
	v_mfma_f32_16x16x32_bf16 v[60:63], v[160:163], v[194:197], v[60:63]
	v_mfma_f32_16x16x32_bf16 v[56:59], v[168:171], v[194:197], v[56:59]
	v_mfma_f32_16x16x32_bf16 v[40:43], v[168:171], v[202:205], v[40:43]
	v_mfma_f32_16x16x32_bf16 v[44:47], v[160:163], v[202:205], v[44:47]
	v_mfma_f32_16x16x32_bf16 v[28:31], v[160:163], v[210:213], v[28:31]
	v_mfma_f32_16x16x32_bf16 v[24:27], v[168:171], v[210:213], v[24:27]
	v_mfma_f32_16x16x32_bf16 v[8:11], v[168:171], v[218:221], v[8:11]
	v_mfma_f32_16x16x32_bf16 v[12:15], v[160:163], v[218:221], v[12:15]
	v_mfma_f32_16x16x32_bf16 v[52:55], v[172:175], v[190:193], v[52:55]
	v_mfma_f32_16x16x32_bf16 v[48:51], v[180:183], v[190:193], v[48:51]
	v_mfma_f32_16x16x32_bf16 v[32:35], v[180:183], v[198:201], v[32:35]
	v_mfma_f32_16x16x32_bf16 v[36:39], v[172:175], v[198:201], v[36:39]
	v_mfma_f32_16x16x32_bf16 v[20:23], v[172:175], v[206:209], v[20:23]
	v_mfma_f32_16x16x32_bf16 v[16:19], v[180:183], v[206:209], v[16:19]
	v_mfma_f32_16x16x32_bf16 v[0:3], v[180:183], v[214:217], v[0:3]
	v_mfma_f32_16x16x32_bf16 v[4:7], v[172:175], v[214:217], v[4:7]
	v_mfma_f32_16x16x32_bf16 v[52:55], v[176:179], v[194:197], v[52:55]
	v_mfma_f32_16x16x32_bf16 v[48:51], v[186:189], v[194:197], v[48:51]
	v_mfma_f32_16x16x32_bf16 v[32:35], v[186:189], v[202:205], v[32:35]
	v_mfma_f32_16x16x32_bf16 v[36:39], v[176:179], v[202:205], v[36:39]
	v_mfma_f32_16x16x32_bf16 v[20:23], v[176:179], v[210:213], v[20:23]
	v_mfma_f32_16x16x32_bf16 v[16:19], v[186:189], v[210:213], v[16:19]
	v_mfma_f32_16x16x32_bf16 v[0:3], v[186:189], v[218:221], v[0:3]
	v_mfma_f32_16x16x32_bf16 v[4:7], v[176:179], v[218:221], v[4:7]
	s_barrier
	s_add_i32 s51, s51, 2
	s_add_u32 s24, s24, 0x100
	s_addc_u32 s25, s25, 0
	s_add_u32 s49, s49, 0x100
	s_addc_u32 s50, s50, 0
	s_cmp_gt_u32 s51, 13
	s_cbranch_scc1 .Lpeel_exit_1975
.LBB0_1975:
	ds_read_b128 v[144:147], v155
	ds_read_b128 v[160:163], v155 offset:1024
	ds_read_b128 v[164:167], v155 offset:2048
	ds_read_b128 v[168:171], v155 offset:3072
	ds_read_b128 v[172:175], v157
	ds_read_b128 v[176:179], v157 offset:1024
	ds_read_b128 v[180:183], v157 offset:2048
	ds_read_b128 v[186:189], v157 offset:3072
	s_add_u32 s26, s24, 0xfffc0080
	s_addc_u32 s27, s25, -1
	s_cmp_eq_u32 s51, 12
	s_cselect_b32 s29, s15, s27
	s_cselect_b32 s28, s47, s26
	s_cselect_b32 s27, s17, s50
	s_cselect_b32 s26, s48, s49
	s_add_i32 m0, s23, 0xc000
	ds_read_b128 v[190:193], v158
	ds_read_b128 v[194:197], v158 offset:1024
	ds_read_b128 v[198:201], v158 offset:2048
	ds_read_b128 v[202:205], v158 offset:3072
	ds_read_b128 v[206:209], v158 offset:4096
	ds_read_b128 v[210:213], v158 offset:5120
	ds_read_b128 v[214:217], v158 offset:6144
	ds_read_b128 v[218:221], v158 offset:7168
	global_load_lds_dwordx4 v136, s[24:25]
	s_add_i32 m0, s23, 0xe000
	s_nop 0
	global_load_lds_dwordx4 v138, s[24:25]
	s_waitcnt vmcnt(8)
	s_waitcnt lgkmcnt(0)
	s_barrier
	s_waitcnt lgkmcnt(0)
	v_mfma_f32_16x16x32_bf16 v[124:127], v[144:147], v[190:193], v[124:127]
	v_mfma_f32_16x16x32_bf16 v[120:123], v[164:167], v[190:193], v[120:123]
	v_mfma_f32_16x16x32_bf16 v[104:107], v[164:167], v[198:201], v[104:107]
	v_mfma_f32_16x16x32_bf16 v[116:119], v[144:147], v[198:201], v[116:119]
	v_mfma_f32_16x16x32_bf16 v[92:95], v[144:147], v[206:209], v[92:95]
	v_mfma_f32_16x16x32_bf16 v[88:91], v[164:167], v[206:209], v[88:91]
	v_mfma_f32_16x16x32_bf16 v[72:75], v[164:167], v[214:217], v[72:75]
	v_mfma_f32_16x16x32_bf16 v[76:79], v[144:147], v[214:217], v[76:79]
	v_mfma_f32_16x16x32_bf16 v[124:127], v[160:163], v[194:197], v[124:127]
	v_mfma_f32_16x16x32_bf16 v[120:123], v[168:171], v[194:197], v[120:123]
	v_mfma_f32_16x16x32_bf16 v[104:107], v[168:171], v[202:205], v[104:107]
	v_mfma_f32_16x16x32_bf16 v[116:119], v[160:163], v[202:205], v[116:119]
	v_mfma_f32_16x16x32_bf16 v[92:95], v[160:163], v[210:213], v[92:95]
	v_mfma_f32_16x16x32_bf16 v[88:91], v[168:171], v[210:213], v[88:91]
	v_mfma_f32_16x16x32_bf16 v[72:75], v[168:171], v[218:221], v[72:75]
	v_mfma_f32_16x16x32_bf16 v[76:79], v[160:163], v[218:221], v[76:79]
	v_mfma_f32_16x16x32_bf16 v[112:115], v[172:175], v[190:193], v[112:115]
	v_mfma_f32_16x16x32_bf16 v[108:111], v[180:183], v[190:193], v[108:111]
	v_mfma_f32_16x16x32_bf16 v[96:99], v[180:183], v[198:201], v[96:99]
	v_mfma_f32_16x16x32_bf16 v[100:103], v[172:175], v[198:201], v[100:103]
	v_mfma_f32_16x16x32_bf16 v[84:87], v[172:175], v[206:209], v[84:87]
	v_mfma_f32_16x16x32_bf16 v[80:83], v[180:183], v[206:209], v[80:83]
	v_mfma_f32_16x16x32_bf16 v[64:67], v[180:183], v[214:217], v[64:67]
	v_mfma_f32_16x16x32_bf16 v[68:71], v[172:175], v[214:217], v[68:71]
	v_mfma_f32_16x16x32_bf16 v[112:115], v[176:179], v[194:197], v[112:115]
	v_mfma_f32_16x16x32_bf16 v[108:111], v[186:189], v[194:197], v[108:111]
	v_mfma_f32_16x16x32_bf16 v[96:99], v[186:189], v[202:205], v[96:99]
	v_mfma_f32_16x16x32_bf16 v[100:103], v[176:179], v[202:205], v[100:103]
	v_mfma_f32_16x16x32_bf16 v[84:87], v[176:179], v[210:213], v[84:87]
	v_mfma_f32_16x16x32_bf16 v[80:83], v[186:189], v[210:213], v[80:83]
	v_mfma_f32_16x16x32_bf16 v[64:67], v[186:189], v[218:221], v[64:67]
	v_mfma_f32_16x16x32_bf16 v[68:71], v[176:179], v[218:221], v[68:71]
	s_barrier
	s_add_i32 s52, s43, s31
	s_mov_b32 m0, s52
	ds_read_b128 v[190:193], v158 offset:16384
	ds_read_b128 v[194:197], v158 offset:17408
	ds_read_b128 v[198:201], v158 offset:18432
	ds_read_b128 v[202:205], v158 offset:19456
	ds_read_b128 v[206:209], v158 offset:20480
	ds_read_b128 v[210:213], v158 offset:21504
	ds_read_b128 v[214:217], v158 offset:22528
	ds_read_b128 v[218:221], v158 offset:23552
	global_load_lds_dwordx4 v132, s[26:27]
	s_add_i32 m0, s52, 0x2000
	s_add_u32 s52, s26, 0x40000
	s_addc_u32 s53, s27, 0
	s_add_i32 s54, s44, s31
	global_load_lds_dwordx4 v128, s[26:27]
	s_mov_b32 m0, s54
	global_load_lds_dwordx4 v132, s[52:53]
	s_add_i32 m0, s54, 0x2000
	s_nop 0
	global_load_lds_dwordx4 v128, s[52:53]
	s_mov_b32 m0, s23
	s_nop 0
	global_load_lds_dwordx4 v134, s[28:29]
	s_mov_b32 m0, s35
	s_nop 0
	global_load_lds_dwordx4 v130, s[28:29]
	s_add_u32 s98, s26, s10
	s_addc_u32 s99, s27, s11
	s_add_u32 s100, s28, s10
	s_addc_u32 s101, s29, s11
	s_waitcnt vmcnt(8)
	s_waitcnt lgkmcnt(0)
	s_barrier
	s_waitcnt lgkmcnt(0)
	v_mfma_f32_16x16x32_bf16 v[60:63], v[144:147], v[190:193], v[60:63]
	v_mfma_f32_16x16x32_bf16 v[56:59], v[164:167], v[190:193], v[56:59]
	v_mfma_f32_16x16x32_bf16 v[40:43], v[164:167], v[198:201], v[40:43]
	v_mfma_f32_16x16x32_bf16 v[44:47], v[144:147], v[198:201], v[44:47]
	v_mfma_f32_16x16x32_bf16 v[28:31], v[144:147], v[206:209], v[28:31]
	v_mfma_f32_16x16x32_bf16 v[24:27], v[164:167], v[206:209], v[24:27]
	v_mfma_f32_16x16x32_bf16 v[8:11], v[164:167], v[214:217], v[8:11]
	v_mfma_f32_16x16x32_bf16 v[12:15], v[144:147], v[214:217], v[12:15]
	v_mfma_f32_16x16x32_bf16 v[60:63], v[160:163], v[194:197], v[60:63]
	v_mfma_f32_16x16x32_bf16 v[56:59], v[168:171], v[194:197], v[56:59]
	v_mfma_f32_16x16x32_bf16 v[40:43], v[168:171], v[202:205], v[40:43]
	v_mfma_f32_16x16x32_bf16 v[44:47], v[160:163], v[202:205], v[44:47]
	v_mfma_f32_16x16x32_bf16 v[28:31], v[160:163], v[210:213], v[28:31]
	v_mfma_f32_16x16x32_bf16 v[24:27], v[168:171], v[210:213], v[24:27]
	v_mfma_f32_16x16x32_bf16 v[8:11], v[168:171], v[218:221], v[8:11]
	v_mfma_f32_16x16x32_bf16 v[12:15], v[160:163], v[218:221], v[12:15]
	v_mfma_f32_16x16x32_bf16 v[52:55], v[172:175], v[190:193], v[52:55]
	v_mfma_f32_16x16x32_bf16 v[48:51], v[180:183], v[190:193], v[48:51]
	v_mfma_f32_16x16x32_bf16 v[32:35], v[180:183], v[198:201], v[32:35]
	v_mfma_f32_16x16x32_bf16 v[36:39], v[172:175], v[198:201], v[36:39]
	v_mfma_f32_16x16x32_bf16 v[20:23], v[172:175], v[206:209], v[20:23]
	v_mfma_f32_16x16x32_bf16 v[16:19], v[180:183], v[206:209], v[16:19]
	v_mfma_f32_16x16x32_bf16 v[0:3], v[180:183], v[214:217], v[0:3]
	v_mfma_f32_16x16x32_bf16 v[4:7], v[172:175], v[214:217], v[4:7]
	v_mfma_f32_16x16x32_bf16 v[52:55], v[176:179], v[194:197], v[52:55]
	v_mfma_f32_16x16x32_bf16 v[48:51], v[186:189], v[194:197], v[48:51]
	v_mfma_f32_16x16x32_bf16 v[32:35], v[186:189], v[202:205], v[32:35]
	v_mfma_f32_16x16x32_bf16 v[36:39], v[176:179], v[202:205], v[36:39]
	v_mfma_f32_16x16x32_bf16 v[20:23], v[176:179], v[210:213], v[20:23]
	v_mfma_f32_16x16x32_bf16 v[16:19], v[186:189], v[210:213], v[16:19]
	v_mfma_f32_16x16x32_bf16 v[0:3], v[186:189], v[218:221], v[0:3]
	v_mfma_f32_16x16x32_bf16 v[4:7], v[176:179], v[218:221], v[4:7]
	s_barrier
	s_add_i32 s52, 0, 0x18000
	v_add_u32_e32 v148, s52, v151
	s_add_i32 s53, 0, 0x1c000
	ds_read_b128 v[144:147], v148
	ds_read_b128 v[160:163], v148 offset:1024
	ds_read_b128 v[164:167], v148 offset:2048
	ds_read_b128 v[168:171], v148 offset:3072
	v_add_u32_e32 v148, s53, v151
	ds_read_b128 v[172:175], v148
	ds_read_b128 v[176:179], v148 offset:1024
	ds_read_b128 v[180:183], v148 offset:2048
	ds_read_b128 v[186:189], v148 offset:3072
	s_add_u32 s28, s28, 0x40000
	s_addc_u32 s29, s29, 0
	s_mov_b32 m0, s36
	ds_read_b128 v[190:193], v158 offset:32768
	ds_read_b128 v[194:197], v158 offset:33792
	ds_read_b128 v[198:201], v158 offset:34816
	ds_read_b128 v[202:205], v158 offset:35840
	ds_read_b128 v[206:209], v158 offset:36864
	ds_read_b128 v[210:213], v158 offset:37888
	ds_read_b128 v[214:217], v158 offset:38912
	ds_read_b128 v[218:221], v158 offset:39936
	global_load_lds_dwordx4 v134, s[28:29]
	s_mov_b32 m0, s37
	s_nop 0
	global_load_lds_dwordx4 v130, s[28:29]
	s_waitcnt vmcnt(8)
	s_waitcnt lgkmcnt(0)
	s_barrier
	s_waitcnt lgkmcnt(0)
	v_mfma_f32_16x16x32_bf16 v[124:127], v[144:147], v[190:193], v[124:127]
	v_mfma_f32_16x16x32_bf16 v[120:123], v[164:167], v[190:193], v[120:123]
	v_mfma_f32_16x16x32_bf16 v[104:107], v[164:167], v[198:201], v[104:107]
	v_mfma_f32_16x16x32_bf16 v[116:119], v[144:147], v[198:201], v[116:119]
	v_mfma_f32_16x16x32_bf16 v[92:95], v[144:147], v[206:209], v[92:95]
	v_mfma_f32_16x16x32_bf16 v[88:91], v[164:167], v[206:209], v[88:91]
	v_mfma_f32_16x16x32_bf16 v[72:75], v[164:167], v[214:217], v[72:75]
	v_mfma_f32_16x16x32_bf16 v[76:79], v[144:147], v[214:217], v[76:79]
	v_mfma_f32_16x16x32_bf16 v[124:127], v[160:163], v[194:197], v[124:127]
	v_mfma_f32_16x16x32_bf16 v[120:123], v[168:171], v[194:197], v[120:123]
	v_mfma_f32_16x16x32_bf16 v[104:107], v[168:171], v[202:205], v[104:107]
	v_mfma_f32_16x16x32_bf16 v[116:119], v[160:163], v[202:205], v[116:119]
	v_mfma_f32_16x16x32_bf16 v[92:95], v[160:163], v[210:213], v[92:95]
	v_mfma_f32_16x16x32_bf16 v[88:91], v[168:171], v[210:213], v[88:91]
	v_mfma_f32_16x16x32_bf16 v[72:75], v[168:171], v[218:221], v[72:75]
	v_mfma_f32_16x16x32_bf16 v[76:79], v[160:163], v[218:221], v[76:79]
	v_mfma_f32_16x16x32_bf16 v[112:115], v[172:175], v[190:193], v[112:115]
	v_mfma_f32_16x16x32_bf16 v[108:111], v[180:183], v[190:193], v[108:111]
	v_mfma_f32_16x16x32_bf16 v[96:99], v[180:183], v[198:201], v[96:99]
	v_mfma_f32_16x16x32_bf16 v[100:103], v[172:175], v[198:201], v[100:103]
	v_mfma_f32_16x16x32_bf16 v[84:87], v[172:175], v[206:209], v[84:87]
	v_mfma_f32_16x16x32_bf16 v[80:83], v[180:183], v[206:209], v[80:83]
	v_mfma_f32_16x16x32_bf16 v[64:67], v[180:183], v[214:217], v[64:67]
	v_mfma_f32_16x16x32_bf16 v[68:71], v[172:175], v[214:217], v[68:71]
	v_mfma_f32_16x16x32_bf16 v[112:115], v[176:179], v[194:197], v[112:115]
	v_mfma_f32_16x16x32_bf16 v[108:111], v[186:189], v[194:197], v[108:111]
	v_mfma_f32_16x16x32_bf16 v[96:99], v[186:189], v[202:205], v[96:99]
	v_mfma_f32_16x16x32_bf16 v[100:103], v[176:179], v[202:205], v[100:103]
	v_mfma_f32_16x16x32_bf16 v[84:87], v[176:179], v[210:213], v[84:87]
	v_mfma_f32_16x16x32_bf16 v[80:83], v[186:189], v[210:213], v[80:83]
	v_mfma_f32_16x16x32_bf16 v[64:67], v[186:189], v[218:221], v[64:67]
	v_mfma_f32_16x16x32_bf16 v[68:71], v[176:179], v[218:221], v[68:71]
	s_barrier
	s_add_i32 s28, s52, s31
	s_mov_b32 m0, s28
	ds_read_b128 v[190:193], v158 offset:49152
	ds_read_b128 v[194:197], v158 offset:50176
	ds_read_b128 v[198:201], v158 offset:51200
	ds_read_b128 v[202:205], v158 offset:52224
	ds_read_b128 v[206:209], v158 offset:53248
	ds_read_b128 v[210:213], v158 offset:54272
	ds_read_b128 v[214:217], v158 offset:55296
	ds_read_b128 v[218:221], v158 offset:56320
	global_load_lds_dwordx4 v132, s[98:99]
	s_add_i32 m0, s28, 0x2000
	s_add_u32 s26, s26, 0x40080
	s_addc_u32 s27, s27, 0
	s_add_i32 s28, s53, s31
	global_load_lds_dwordx4 v128, s[98:99]
	s_mov_b32 m0, s28
	s_nop 0
	global_load_lds_dwordx4 v132, s[26:27]
	s_add_i32 m0, s28, 0x2000
	s_nop 0
	global_load_lds_dwordx4 v128, s[26:27]
	s_mov_b32 m0, s39
	s_nop 0
	global_load_lds_dwordx4 v134, s[100:101]
	s_mov_b32 m0, s40
	s_nop 0
	global_load_lds_dwordx4 v130, s[100:101]
	s_waitcnt vmcnt(8)
	s_waitcnt lgkmcnt(0)
	s_barrier
	s_waitcnt lgkmcnt(0)
	v_mfma_f32_16x16x32_bf16 v[60:63], v[144:147], v[190:193], v[60:63]
	v_mfma_f32_16x16x32_bf16 v[56:59], v[164:167], v[190:193], v[56:59]
	v_mfma_f32_16x16x32_bf16 v[40:43], v[164:167], v[198:201], v[40:43]
	v_mfma_f32_16x16x32_bf16 v[44:47], v[144:147], v[198:201], v[44:47]
	v_mfma_f32_16x16x32_bf16 v[28:31], v[144:147], v[206:209], v[28:31]
	v_mfma_f32_16x16x32_bf16 v[24:27], v[164:167], v[206:209], v[24:27]
	v_mfma_f32_16x16x32_bf16 v[8:11], v[164:167], v[214:217], v[8:11]
	v_mfma_f32_16x16x32_bf16 v[12:15], v[144:147], v[214:217], v[12:15]
	v_mfma_f32_16x16x32_bf16 v[60:63], v[160:163], v[194:197], v[60:63]
	v_mfma_f32_16x16x32_bf16 v[56:59], v[168:171], v[194:197], v[56:59]
	v_mfma_f32_16x16x32_bf16 v[40:43], v[168:171], v[202:205], v[40:43]
	v_mfma_f32_16x16x32_bf16 v[44:47], v[160:163], v[202:205], v[44:47]
	v_mfma_f32_16x16x32_bf16 v[28:31], v[160:163], v[210:213], v[28:31]
	v_mfma_f32_16x16x32_bf16 v[24:27], v[168:171], v[210:213], v[24:27]
	v_mfma_f32_16x16x32_bf16 v[8:11], v[168:171], v[218:221], v[8:11]
	v_mfma_f32_16x16x32_bf16 v[12:15], v[160:163], v[218:221], v[12:15]
	v_mfma_f32_16x16x32_bf16 v[52:55], v[172:175], v[190:193], v[52:55]
	v_mfma_f32_16x16x32_bf16 v[48:51], v[180:183], v[190:193], v[48:51]
	v_mfma_f32_16x16x32_bf16 v[32:35], v[180:183], v[198:201], v[32:35]
	v_mfma_f32_16x16x32_bf16 v[36:39], v[172:175], v[198:201], v[36:39]
	v_mfma_f32_16x16x32_bf16 v[20:23], v[172:175], v[206:209], v[20:23]
	v_mfma_f32_16x16x32_bf16 v[16:19], v[180:183], v[206:209], v[16:19]
	v_mfma_f32_16x16x32_bf16 v[0:3], v[180:183], v[214:217], v[0:3]
	v_mfma_f32_16x16x32_bf16 v[4:7], v[172:175], v[214:217], v[4:7]
	v_mfma_f32_16x16x32_bf16 v[52:55], v[176:179], v[194:197], v[52:55]
	v_mfma_f32_16x16x32_bf16 v[48:51], v[186:189], v[194:197], v[48:51]
	v_mfma_f32_16x16x32_bf16 v[32:35], v[186:189], v[202:205], v[32:35]
	v_mfma_f32_16x16x32_bf16 v[36:39], v[176:179], v[202:205], v[36:39]
	v_mfma_f32_16x16x32_bf16 v[20:23], v[176:179], v[210:213], v[20:23]
	v_mfma_f32_16x16x32_bf16 v[16:19], v[186:189], v[210:213], v[16:19]
	v_mfma_f32_16x16x32_bf16 v[0:3], v[186:189], v[218:221], v[0:3]
	v_mfma_f32_16x16x32_bf16 v[4:7], v[176:179], v[218:221], v[4:7]
	s_barrier
	s_add_i32 s51, s51, 2
	s_add_u32 s24, s24, 0x100
	s_addc_u32 s25, s25, 0
	s_add_u32 s49, s49, 0x100
	s_addc_u32 s50, s50, 0
	s_cmp_gt_u32 s51, 13
	s_cbranch_scc0 .LBB0_1975

.LBB0_2057:
	s_add_u32 s18, s18, 0xb0080
	s_addc_u32 s19, s19, 0
	s_add_u32 s17, s20, 0x100
	s_addc_u32 s42, s21, 0
	s_mov_b32 s43, -2
	ds_read_b128 v[146:149], v155
	ds_read_b128 v[150:153], v155 offset:1024
	ds_read_b128 v[158:161], v155 offset:2048
	ds_read_b128 v[162:165], v155 offset:3072
	ds_read_b128 v[166:169], v156
	ds_read_b128 v[170:173], v156 offset:1024
	ds_read_b128 v[174:177], v156 offset:2048
	ds_read_b128 v[178:181], v156 offset:3072
	s_add_u32 s20, s18, 0xfff50080
	s_addc_u32 s21, s19, -1
	s_cmp_eq_u32 s43, 40
	s_cselect_b32 s23, s5, s21
	s_cselect_b32 s22, s4, s20
	s_cselect_b32 s21, s15, s42
	s_cselect_b32 s20, s14, s17
	s_add_i32 m0, s27, 0xc000
	ds_read_b128 v[182:185], v157
	ds_read_b128 v[186:189], v157 offset:1024
	ds_read_b128 v[190:193], v157 offset:2048
	ds_read_b128 v[194:197], v157 offset:3072
	ds_read_b128 v[198:201], v157 offset:4096
	ds_read_b128 v[202:205], v157 offset:5120
	ds_read_b128 v[206:209], v157 offset:6144
	ds_read_b128 v[210:213], v157 offset:7168
	global_load_lds_dwordx4 v138, s[18:19]
	s_add_i32 m0, s27, 0xe000
	s_nop 0
	global_load_lds_dwordx4 v140, s[18:19]
	s_waitcnt vmcnt(8)
	s_waitcnt lgkmcnt(0)
	s_barrier
	s_waitcnt lgkmcnt(0)
	v_mfma_f32_16x16x32_bf16 v[124:127], v[146:149], v[182:185], 0
	v_mfma_f32_16x16x32_bf16 v[120:123], v[158:161], v[182:185], 0
	v_mfma_f32_16x16x32_bf16 v[112:115], v[158:161], v[190:193], 0
	v_mfma_f32_16x16x32_bf16 v[116:119], v[146:149], v[190:193], 0
	v_mfma_f32_16x16x32_bf16 v[96:99], v[146:149], v[198:201], 0
	v_mfma_f32_16x16x32_bf16 v[88:91], v[158:161], v[198:201], 0
	v_mfma_f32_16x16x32_bf16 v[72:75], v[158:161], v[206:209], 0
	v_mfma_f32_16x16x32_bf16 v[80:83], v[146:149], v[206:209], 0
	v_mfma_f32_16x16x32_bf16 v[124:127], v[150:153], v[186:189], v[124:127]
	v_mfma_f32_16x16x32_bf16 v[120:123], v[162:165], v[186:189], v[120:123]
	v_mfma_f32_16x16x32_bf16 v[112:115], v[162:165], v[194:197], v[112:115]
	v_mfma_f32_16x16x32_bf16 v[116:119], v[150:153], v[194:197], v[116:119]
	v_mfma_f32_16x16x32_bf16 v[96:99], v[150:153], v[202:205], v[96:99]
	v_mfma_f32_16x16x32_bf16 v[88:91], v[162:165], v[202:205], v[88:91]
	v_mfma_f32_16x16x32_bf16 v[72:75], v[162:165], v[210:213], v[72:75]
	v_mfma_f32_16x16x32_bf16 v[80:83], v[150:153], v[210:213], v[80:83]
	v_mfma_f32_16x16x32_bf16 v[108:111], v[166:169], v[182:185], 0
	v_mfma_f32_16x16x32_bf16 v[104:107], v[174:177], v[182:185], 0
	v_mfma_f32_16x16x32_bf16 v[92:95], v[174:177], v[190:193], 0
	v_mfma_f32_16x16x32_bf16 v[100:103], v[166:169], v[190:193], 0
	v_mfma_f32_16x16x32_bf16 v[84:87], v[166:169], v[198:201], 0
	v_mfma_f32_16x16x32_bf16 v[76:79], v[174:177], v[198:201], 0
	v_mfma_f32_16x16x32_bf16 v[64:67], v[174:177], v[206:209], 0
	v_mfma_f32_16x16x32_bf16 v[68:71], v[166:169], v[206:209], 0
	v_mfma_f32_16x16x32_bf16 v[108:111], v[170:173], v[186:189], v[108:111]
	v_mfma_f32_16x16x32_bf16 v[104:107], v[178:181], v[186:189], v[104:107]
	v_mfma_f32_16x16x32_bf16 v[92:95], v[178:181], v[194:197], v[92:95]
	v_mfma_f32_16x16x32_bf16 v[100:103], v[170:173], v[194:197], v[100:103]
	v_mfma_f32_16x16x32_bf16 v[84:87], v[170:173], v[202:205], v[84:87]
	v_mfma_f32_16x16x32_bf16 v[76:79], v[178:181], v[202:205], v[76:79]
	v_mfma_f32_16x16x32_bf16 v[64:67], v[178:181], v[210:213], v[64:67]
	v_mfma_f32_16x16x32_bf16 v[68:71], v[170:173], v[210:213], v[68:71]
	s_barrier
	s_add_i32 s44, s37, s26
	s_mov_b32 m0, s44
	ds_read_b128 v[182:185], v157 offset:16384
	ds_read_b128 v[186:189], v157 offset:17408
	ds_read_b128 v[190:193], v157 offset:18432
	ds_read_b128 v[194:197], v157 offset:19456
	ds_read_b128 v[198:201], v157 offset:20480
	ds_read_b128 v[202:205], v157 offset:21504
	ds_read_b128 v[206:209], v157 offset:22528
	ds_read_b128 v[210:213], v157 offset:23552
	global_load_lds_dwordx4 v130, s[20:21]
	s_add_i32 m0, s44, 0x2000
	s_add_u32 s44, s20, 0xb0000
	s_addc_u32 s45, s21, 0
	s_add_i32 s46, s38, s26
	global_load_lds_dwordx4 v134, s[20:21]
	s_mov_b32 m0, s46
	global_load_lds_dwordx4 v130, s[44:45]
	s_add_i32 m0, s46, 0x2000
	s_nop 0
	global_load_lds_dwordx4 v134, s[44:45]
	s_mov_b32 m0, s27
	s_nop 0
	global_load_lds_dwordx4 v128, s[22:23]
	s_mov_b32 m0, s28
	s_nop 0
	global_load_lds_dwordx4 v132, s[22:23]
	s_add_u32 s98, s20, s10
	s_addc_u32 s99, s21, s11
	s_add_u32 s100, s22, s10
	s_addc_u32 s101, s23, s11
	s_waitcnt vmcnt(8)
	s_waitcnt lgkmcnt(0)
	s_barrier
	s_waitcnt lgkmcnt(0)
	v_mfma_f32_16x16x32_bf16 v[60:63], v[146:149], v[182:185], 0
	v_mfma_f32_16x16x32_bf16 v[56:59], v[158:161], v[182:185], 0
	v_mfma_f32_16x16x32_bf16 v[40:43], v[158:161], v[190:193], 0
	v_mfma_f32_16x16x32_bf16 v[48:51], v[146:149], v[190:193], 0
	v_mfma_f32_16x16x32_bf16 v[32:35], v[146:149], v[198:201], 0
	v_mfma_f32_16x16x32_bf16 v[24:27], v[158:161], v[198:201], 0
	v_mfma_f32_16x16x32_bf16 v[8:11], v[158:161], v[206:209], 0
	v_mfma_f32_16x16x32_bf16 v[16:19], v[146:149], v[206:209], 0
	v_mfma_f32_16x16x32_bf16 v[60:63], v[150:153], v[186:189], v[60:63]
	v_mfma_f32_16x16x32_bf16 v[56:59], v[162:165], v[186:189], v[56:59]
	v_mfma_f32_16x16x32_bf16 v[40:43], v[162:165], v[194:197], v[40:43]
	v_mfma_f32_16x16x32_bf16 v[48:51], v[150:153], v[194:197], v[48:51]
	v_mfma_f32_16x16x32_bf16 v[32:35], v[150:153], v[202:205], v[32:35]
	v_mfma_f32_16x16x32_bf16 v[24:27], v[162:165], v[202:205], v[24:27]
	v_mfma_f32_16x16x32_bf16 v[8:11], v[162:165], v[210:213], v[8:11]
	v_mfma_f32_16x16x32_bf16 v[16:19], v[150:153], v[210:213], v[16:19]
	v_mfma_f32_16x16x32_bf16 v[52:55], v[166:169], v[182:185], 0
	v_mfma_f32_16x16x32_bf16 v[44:47], v[174:177], v[182:185], 0
	v_mfma_f32_16x16x32_bf16 v[28:31], v[174:177], v[190:193], 0
	v_mfma_f32_16x16x32_bf16 v[36:39], v[166:169], v[190:193], 0
	v_mfma_f32_16x16x32_bf16 v[20:23], v[166:169], v[198:201], 0
	v_mfma_f32_16x16x32_bf16 v[12:15], v[174:177], v[198:201], 0
	v_mfma_f32_16x16x32_bf16 v[0:3], v[174:177], v[206:209], 0
	v_mfma_f32_16x16x32_bf16 v[4:7], v[166:169], v[206:209], 0
	v_mfma_f32_16x16x32_bf16 v[52:55], v[170:173], v[186:189], v[52:55]
	v_mfma_f32_16x16x32_bf16 v[44:47], v[178:181], v[186:189], v[44:47]
	v_mfma_f32_16x16x32_bf16 v[28:31], v[178:181], v[194:197], v[28:31]
	v_mfma_f32_16x16x32_bf16 v[36:39], v[170:173], v[194:197], v[36:39]
	v_mfma_f32_16x16x32_bf16 v[20:23], v[170:173], v[202:205], v[20:23]
	v_mfma_f32_16x16x32_bf16 v[12:15], v[178:181], v[202:205], v[12:15]
	v_mfma_f32_16x16x32_bf16 v[0:3], v[178:181], v[210:213], v[0:3]
	v_mfma_f32_16x16x32_bf16 v[4:7], v[170:173], v[210:213], v[4:7]
	s_barrier
	s_add_i32 s44, 0, 0x18000
	s_add_i32 s45, 0, 0x1c000
	v_add_u32_e32 v162, s44, v154
	v_add_u32_e32 v178, s45, v154
	ds_read_b128 v[146:149], v162
	ds_read_b128 v[150:153], v162 offset:1024
	ds_read_b128 v[158:161], v162 offset:2048
	ds_read_b128 v[162:165], v162 offset:3072
	ds_read_b128 v[166:169], v178
	ds_read_b128 v[170:173], v178 offset:1024
	ds_read_b128 v[174:177], v178 offset:2048
	ds_read_b128 v[178:181], v178 offset:3072
	s_add_u32 s22, s22, 0xb0000
	s_addc_u32 s23, s23, 0
	s_mov_b32 m0, s29
	ds_read_b128 v[182:185], v157 offset:32768
	ds_read_b128 v[186:189], v157 offset:33792
	ds_read_b128 v[190:193], v157 offset:34816
	ds_read_b128 v[194:197], v157 offset:35840
	ds_read_b128 v[198:201], v157 offset:36864
	ds_read_b128 v[202:205], v157 offset:37888
	ds_read_b128 v[206:209], v157 offset:38912
	ds_read_b128 v[210:213], v157 offset:39936
	global_load_lds_dwordx4 v128, s[22:23]
	s_mov_b32 m0, s30
	s_nop 0
	global_load_lds_dwordx4 v132, s[22:23]
	s_waitcnt vmcnt(8)
	s_waitcnt lgkmcnt(0)
	s_barrier
	s_waitcnt lgkmcnt(0)
	v_mfma_f32_16x16x32_bf16 v[124:127], v[146:149], v[182:185], v[124:127]
	v_mfma_f32_16x16x32_bf16 v[120:123], v[158:161], v[182:185], v[120:123]
	v_mfma_f32_16x16x32_bf16 v[112:115], v[158:161], v[190:193], v[112:115]
	v_mfma_f32_16x16x32_bf16 v[116:119], v[146:149], v[190:193], v[116:119]
	v_mfma_f32_16x16x32_bf16 v[96:99], v[146:149], v[198:201], v[96:99]
	v_mfma_f32_16x16x32_bf16 v[88:91], v[158:161], v[198:201], v[88:91]
	v_mfma_f32_16x16x32_bf16 v[72:75], v[158:161], v[206:209], v[72:75]
	v_mfma_f32_16x16x32_bf16 v[80:83], v[146:149], v[206:209], v[80:83]
	v_mfma_f32_16x16x32_bf16 v[124:127], v[150:153], v[186:189], v[124:127]
	v_mfma_f32_16x16x32_bf16 v[120:123], v[162:165], v[186:189], v[120:123]
	v_mfma_f32_16x16x32_bf16 v[112:115], v[162:165], v[194:197], v[112:115]
	v_mfma_f32_16x16x32_bf16 v[116:119], v[150:153], v[194:197], v[116:119]
	v_mfma_f32_16x16x32_bf16 v[96:99], v[150:153], v[202:205], v[96:99]
	v_mfma_f32_16x16x32_bf16 v[88:91], v[162:165], v[202:205], v[88:91]
	v_mfma_f32_16x16x32_bf16 v[72:75], v[162:165], v[210:213], v[72:75]
	v_mfma_f32_16x16x32_bf16 v[80:83], v[150:153], v[210:213], v[80:83]
	v_mfma_f32_16x16x32_bf16 v[108:111], v[166:169], v[182:185], v[108:111]
	v_mfma_f32_16x16x32_bf16 v[104:107], v[174:177], v[182:185], v[104:107]
	v_mfma_f32_16x16x32_bf16 v[92:95], v[174:177], v[190:193], v[92:95]
	v_mfma_f32_16x16x32_bf16 v[100:103], v[166:169], v[190:193], v[100:103]
	v_mfma_f32_16x16x32_bf16 v[84:87], v[166:169], v[198:201], v[84:87]
	v_mfma_f32_16x16x32_bf16 v[76:79], v[174:177], v[198:201], v[76:79]
	v_mfma_f32_16x16x32_bf16 v[64:67], v[174:177], v[206:209], v[64:67]
	v_mfma_f32_16x16x32_bf16 v[68:71], v[166:169], v[206:209], v[68:71]
	v_mfma_f32_16x16x32_bf16 v[108:111], v[170:173], v[186:189], v[108:111]
	v_mfma_f32_16x16x32_bf16 v[104:107], v[178:181], v[186:189], v[104:107]
	v_mfma_f32_16x16x32_bf16 v[92:95], v[178:181], v[194:197], v[92:95]
	v_mfma_f32_16x16x32_bf16 v[100:103], v[170:173], v[194:197], v[100:103]
	v_mfma_f32_16x16x32_bf16 v[84:87], v[170:173], v[202:205], v[84:87]
	v_mfma_f32_16x16x32_bf16 v[76:79], v[178:181], v[202:205], v[76:79]
	v_mfma_f32_16x16x32_bf16 v[64:67], v[178:181], v[210:213], v[64:67]
	v_mfma_f32_16x16x32_bf16 v[68:71], v[170:173], v[210:213], v[68:71]
	s_barrier
	s_add_i32 s22, s44, s26
	s_mov_b32 m0, s22
	ds_read_b128 v[182:185], v157 offset:49152
	ds_read_b128 v[186:189], v157 offset:50176
	ds_read_b128 v[190:193], v157 offset:51200
	ds_read_b128 v[194:197], v157 offset:52224
	ds_read_b128 v[198:201], v157 offset:53248
	ds_read_b128 v[202:205], v157 offset:54272
	ds_read_b128 v[206:209], v157 offset:55296
	ds_read_b128 v[210:213], v157 offset:56320
	global_load_lds_dwordx4 v130, s[98:99]
	s_add_i32 m0, s22, 0x2000
	s_add_u32 s20, s20, 0xb0080
	s_addc_u32 s21, s21, 0
	s_add_i32 s22, s45, s26
	global_load_lds_dwordx4 v134, s[98:99]
	s_mov_b32 m0, s22
	s_nop 0
	global_load_lds_dwordx4 v130, s[20:21]
	s_add_i32 m0, s22, 0x2000
	s_nop 0
	global_load_lds_dwordx4 v134, s[20:21]
	s_mov_b32 m0, s33
	s_nop 0
	global_load_lds_dwordx4 v128, s[100:101]
	s_mov_b32 m0, s34
	s_nop 0
	global_load_lds_dwordx4 v132, s[100:101]
	s_waitcnt vmcnt(8)
	s_waitcnt lgkmcnt(0)
	s_barrier
	s_waitcnt lgkmcnt(0)
	v_mfma_f32_16x16x32_bf16 v[60:63], v[146:149], v[182:185], v[60:63]
	v_mfma_f32_16x16x32_bf16 v[56:59], v[158:161], v[182:185], v[56:59]
	v_mfma_f32_16x16x32_bf16 v[40:43], v[158:161], v[190:193], v[40:43]
	v_mfma_f32_16x16x32_bf16 v[48:51], v[146:149], v[190:193], v[48:51]
	v_mfma_f32_16x16x32_bf16 v[32:35], v[146:149], v[198:201], v[32:35]
	v_mfma_f32_16x16x32_bf16 v[24:27], v[158:161], v[198:201], v[24:27]
	v_mfma_f32_16x16x32_bf16 v[8:11], v[158:161], v[206:209], v[8:11]
	v_mfma_f32_16x16x32_bf16 v[16:19], v[146:149], v[206:209], v[16:19]
	v_mfma_f32_16x16x32_bf16 v[60:63], v[150:153], v[186:189], v[60:63]
	v_mfma_f32_16x16x32_bf16 v[56:59], v[162:165], v[186:189], v[56:59]
	v_mfma_f32_16x16x32_bf16 v[40:43], v[162:165], v[194:197], v[40:43]
	v_mfma_f32_16x16x32_bf16 v[48:51], v[150:153], v[194:197], v[48:51]
	v_mfma_f32_16x16x32_bf16 v[32:35], v[150:153], v[202:205], v[32:35]
	v_mfma_f32_16x16x32_bf16 v[24:27], v[162:165], v[202:205], v[24:27]
	v_mfma_f32_16x16x32_bf16 v[8:11], v[162:165], v[210:213], v[8:11]
	v_mfma_f32_16x16x32_bf16 v[16:19], v[150:153], v[210:213], v[16:19]
	v_mfma_f32_16x16x32_bf16 v[52:55], v[166:169], v[182:185], v[52:55]
	v_mfma_f32_16x16x32_bf16 v[44:47], v[174:177], v[182:185], v[44:47]
	v_mfma_f32_16x16x32_bf16 v[28:31], v[174:177], v[190:193], v[28:31]
	v_mfma_f32_16x16x32_bf16 v[36:39], v[166:169], v[190:193], v[36:39]
	v_mfma_f32_16x16x32_bf16 v[20:23], v[166:169], v[198:201], v[20:23]
	v_mfma_f32_16x16x32_bf16 v[12:15], v[174:177], v[198:201], v[12:15]
	v_mfma_f32_16x16x32_bf16 v[0:3], v[174:177], v[206:209], v[0:3]
	v_mfma_f32_16x16x32_bf16 v[4:7], v[166:169], v[206:209], v[4:7]
	v_mfma_f32_16x16x32_bf16 v[52:55], v[170:173], v[186:189], v[52:55]
	v_mfma_f32_16x16x32_bf16 v[44:47], v[178:181], v[186:189], v[44:47]
	v_mfma_f32_16x16x32_bf16 v[28:31], v[178:181], v[194:197], v[28:31]
	v_mfma_f32_16x16x32_bf16 v[36:39], v[170:173], v[194:197], v[36:39]
	v_mfma_f32_16x16x32_bf16 v[20:23], v[170:173], v[202:205], v[20:23]
	v_mfma_f32_16x16x32_bf16 v[12:15], v[178:181], v[202:205], v[12:15]
	v_mfma_f32_16x16x32_bf16 v[0:3], v[178:181], v[210:213], v[0:3]
	v_mfma_f32_16x16x32_bf16 v[4:7], v[170:173], v[210:213], v[4:7]
	s_barrier
	s_add_i32 s43, s43, 2
	s_add_u32 s18, s18, 0x100
	s_addc_u32 s19, s19, 0
	s_add_u32 s17, s17, 0x100
	s_addc_u32 s42, s42, 0
	s_cmp_gt_u32 s43, 41
	s_cbranch_scc1 .Lpeel_exit_2058
.LBB0_2058:
	ds_read_b128 v[146:149], v155
	ds_read_b128 v[150:153], v155 offset:1024
	ds_read_b128 v[158:161], v155 offset:2048
	ds_read_b128 v[162:165], v155 offset:3072
	ds_read_b128 v[166:169], v156
	ds_read_b128 v[170:173], v156 offset:1024
	ds_read_b128 v[174:177], v156 offset:2048
	ds_read_b128 v[178:181], v156 offset:3072
	s_add_u32 s20, s18, 0xfff50080
	s_addc_u32 s21, s19, -1
	s_cmp_eq_u32 s43, 40
	s_cselect_b32 s23, s5, s21
	s_cselect_b32 s22, s4, s20
	s_cselect_b32 s21, s15, s42
	s_cselect_b32 s20, s14, s17
	s_add_i32 m0, s27, 0xc000
	ds_read_b128 v[182:185], v157
	ds_read_b128 v[186:189], v157 offset:1024
	ds_read_b128 v[190:193], v157 offset:2048
	ds_read_b128 v[194:197], v157 offset:3072
	ds_read_b128 v[198:201], v157 offset:4096
	ds_read_b128 v[202:205], v157 offset:5120
	ds_read_b128 v[206:209], v157 offset:6144
	ds_read_b128 v[210:213], v157 offset:7168
	global_load_lds_dwordx4 v138, s[18:19]
	s_add_i32 m0, s27, 0xe000
	s_nop 0
	global_load_lds_dwordx4 v140, s[18:19]
	s_waitcnt vmcnt(8)
	s_waitcnt lgkmcnt(0)
	s_barrier
	s_waitcnt lgkmcnt(0)
	v_mfma_f32_16x16x32_bf16 v[124:127], v[146:149], v[182:185], v[124:127]
	v_mfma_f32_16x16x32_bf16 v[120:123], v[158:161], v[182:185], v[120:123]
	v_mfma_f32_16x16x32_bf16 v[112:115], v[158:161], v[190:193], v[112:115]
	v_mfma_f32_16x16x32_bf16 v[116:119], v[146:149], v[190:193], v[116:119]
	v_mfma_f32_16x16x32_bf16 v[96:99], v[146:149], v[198:201], v[96:99]
	v_mfma_f32_16x16x32_bf16 v[88:91], v[158:161], v[198:201], v[88:91]
	v_mfma_f32_16x16x32_bf16 v[72:75], v[158:161], v[206:209], v[72:75]
	v_mfma_f32_16x16x32_bf16 v[80:83], v[146:149], v[206:209], v[80:83]
	v_mfma_f32_16x16x32_bf16 v[124:127], v[150:153], v[186:189], v[124:127]
	v_mfma_f32_16x16x32_bf16 v[120:123], v[162:165], v[186:189], v[120:123]
	v_mfma_f32_16x16x32_bf16 v[112:115], v[162:165], v[194:197], v[112:115]
	v_mfma_f32_16x16x32_bf16 v[116:119], v[150:153], v[194:197], v[116:119]
	v_mfma_f32_16x16x32_bf16 v[96:99], v[150:153], v[202:205], v[96:99]
	v_mfma_f32_16x16x32_bf16 v[88:91], v[162:165], v[202:205], v[88:91]
	v_mfma_f32_16x16x32_bf16 v[72:75], v[162:165], v[210:213], v[72:75]
	v_mfma_f32_16x16x32_bf16 v[80:83], v[150:153], v[210:213], v[80:83]
	v_mfma_f32_16x16x32_bf16 v[108:111], v[166:169], v[182:185], v[108:111]
	v_mfma_f32_16x16x32_bf16 v[104:107], v[174:177], v[182:185], v[104:107]
	v_mfma_f32_16x16x32_bf16 v[92:95], v[174:177], v[190:193], v[92:95]
	v_mfma_f32_16x16x32_bf16 v[100:103], v[166:169], v[190:193], v[100:103]
	v_mfma_f32_16x16x32_bf16 v[84:87], v[166:169], v[198:201], v[84:87]
	v_mfma_f32_16x16x32_bf16 v[76:79], v[174:177], v[198:201], v[76:79]
	v_mfma_f32_16x16x32_bf16 v[64:67], v[174:177], v[206:209], v[64:67]
	v_mfma_f32_16x16x32_bf16 v[68:71], v[166:169], v[206:209], v[68:71]
	v_mfma_f32_16x16x32_bf16 v[108:111], v[170:173], v[186:189], v[108:111]
	v_mfma_f32_16x16x32_bf16 v[104:107], v[178:181], v[186:189], v[104:107]
	v_mfma_f32_16x16x32_bf16 v[92:95], v[178:181], v[194:197], v[92:95]
	v_mfma_f32_16x16x32_bf16 v[100:103], v[170:173], v[194:197], v[100:103]
	v_mfma_f32_16x16x32_bf16 v[84:87], v[170:173], v[202:205], v[84:87]
	v_mfma_f32_16x16x32_bf16 v[76:79], v[178:181], v[202:205], v[76:79]
	v_mfma_f32_16x16x32_bf16 v[64:67], v[178:181], v[210:213], v[64:67]
	v_mfma_f32_16x16x32_bf16 v[68:71], v[170:173], v[210:213], v[68:71]
	s_barrier
	s_add_i32 s44, s37, s26
	s_mov_b32 m0, s44
	ds_read_b128 v[182:185], v157 offset:16384
	ds_read_b128 v[186:189], v157 offset:17408
	ds_read_b128 v[190:193], v157 offset:18432
	ds_read_b128 v[194:197], v157 offset:19456
	ds_read_b128 v[198:201], v157 offset:20480
	ds_read_b128 v[202:205], v157 offset:21504
	ds_read_b128 v[206:209], v157 offset:22528
	ds_read_b128 v[210:213], v157 offset:23552
	global_load_lds_dwordx4 v130, s[20:21]
	s_add_i32 m0, s44, 0x2000
	s_add_u32 s44, s20, 0xb0000
	s_addc_u32 s45, s21, 0
	s_add_i32 s46, s38, s26
	global_load_lds_dwordx4 v134, s[20:21]
	s_mov_b32 m0, s46
	global_load_lds_dwordx4 v130, s[44:45]
	s_add_i32 m0, s46, 0x2000
	s_nop 0
	global_load_lds_dwordx4 v134, s[44:45]
	s_mov_b32 m0, s27
	s_nop 0
	global_load_lds_dwordx4 v128, s[22:23]
	s_mov_b32 m0, s28
	s_nop 0
	global_load_lds_dwordx4 v132, s[22:23]
	s_add_u32 s98, s20, s10
	s_addc_u32 s99, s21, s11
	s_add_u32 s100, s22, s10
	s_addc_u32 s101, s23, s11
	s_waitcnt vmcnt(8)
	s_waitcnt lgkmcnt(0)
	s_barrier
	s_waitcnt lgkmcnt(0)
	v_mfma_f32_16x16x32_bf16 v[60:63], v[146:149], v[182:185], v[60:63]
	v_mfma_f32_16x16x32_bf16 v[56:59], v[158:161], v[182:185], v[56:59]
	v_mfma_f32_16x16x32_bf16 v[40:43], v[158:161], v[190:193], v[40:43]
	v_mfma_f32_16x16x32_bf16 v[48:51], v[146:149], v[190:193], v[48:51]
	v_mfma_f32_16x16x32_bf16 v[32:35], v[146:149], v[198:201], v[32:35]
	v_mfma_f32_16x16x32_bf16 v[24:27], v[158:161], v[198:201], v[24:27]
	v_mfma_f32_16x16x32_bf16 v[8:11], v[158:161], v[206:209], v[8:11]
	v_mfma_f32_16x16x32_bf16 v[16:19], v[146:149], v[206:209], v[16:19]
	v_mfma_f32_16x16x32_bf16 v[60:63], v[150:153], v[186:189], v[60:63]
	v_mfma_f32_16x16x32_bf16 v[56:59], v[162:165], v[186:189], v[56:59]
	v_mfma_f32_16x16x32_bf16 v[40:43], v[162:165], v[194:197], v[40:43]
	v_mfma_f32_16x16x32_bf16 v[48:51], v[150:153], v[194:197], v[48:51]
	v_mfma_f32_16x16x32_bf16 v[32:35], v[150:153], v[202:205], v[32:35]
	v_mfma_f32_16x16x32_bf16 v[24:27], v[162:165], v[202:205], v[24:27]
	v_mfma_f32_16x16x32_bf16 v[8:11], v[162:165], v[210:213], v[8:11]
	v_mfma_f32_16x16x32_bf16 v[16:19], v[150:153], v[210:213], v[16:19]
	v_mfma_f32_16x16x32_bf16 v[52:55], v[166:169], v[182:185], v[52:55]
	v_mfma_f32_16x16x32_bf16 v[44:47], v[174:177], v[182:185], v[44:47]
	v_mfma_f32_16x16x32_bf16 v[28:31], v[174:177], v[190:193], v[28:31]
	v_mfma_f32_16x16x32_bf16 v[36:39], v[166:169], v[190:193], v[36:39]
	v_mfma_f32_16x16x32_bf16 v[20:23], v[166:169], v[198:201], v[20:23]
	v_mfma_f32_16x16x32_bf16 v[12:15], v[174:177], v[198:201], v[12:15]
	v_mfma_f32_16x16x32_bf16 v[0:3], v[174:177], v[206:209], v[0:3]
	v_mfma_f32_16x16x32_bf16 v[4:7], v[166:169], v[206:209], v[4:7]
	v_mfma_f32_16x16x32_bf16 v[52:55], v[170:173], v[186:189], v[52:55]
	v_mfma_f32_16x16x32_bf16 v[44:47], v[178:181], v[186:189], v[44:47]
	v_mfma_f32_16x16x32_bf16 v[28:31], v[178:181], v[194:197], v[28:31]
	v_mfma_f32_16x16x32_bf16 v[36:39], v[170:173], v[194:197], v[36:39]
	v_mfma_f32_16x16x32_bf16 v[20:23], v[170:173], v[202:205], v[20:23]
	v_mfma_f32_16x16x32_bf16 v[12:15], v[178:181], v[202:205], v[12:15]
	v_mfma_f32_16x16x32_bf16 v[0:3], v[178:181], v[210:213], v[0:3]
	v_mfma_f32_16x16x32_bf16 v[4:7], v[170:173], v[210:213], v[4:7]
	s_barrier
	s_add_i32 s44, 0, 0x18000
	s_add_i32 s45, 0, 0x1c000
	v_add_u32_e32 v162, s44, v154
	v_add_u32_e32 v178, s45, v154
	ds_read_b128 v[146:149], v162
	ds_read_b128 v[150:153], v162 offset:1024
	ds_read_b128 v[158:161], v162 offset:2048
	ds_read_b128 v[162:165], v162 offset:3072
	ds_read_b128 v[166:169], v178
	ds_read_b128 v[170:173], v178 offset:1024
	ds_read_b128 v[174:177], v178 offset:2048
	ds_read_b128 v[178:181], v178 offset:3072
	s_add_u32 s22, s22, 0xb0000
	s_addc_u32 s23, s23, 0
	s_mov_b32 m0, s29
	ds_read_b128 v[182:185], v157 offset:32768
	ds_read_b128 v[186:189], v157 offset:33792
	ds_read_b128 v[190:193], v157 offset:34816
	ds_read_b128 v[194:197], v157 offset:35840
	ds_read_b128 v[198:201], v157 offset:36864
	ds_read_b128 v[202:205], v157 offset:37888
	ds_read_b128 v[206:209], v157 offset:38912
	ds_read_b128 v[210:213], v157 offset:39936
	global_load_lds_dwordx4 v128, s[22:23]
	s_mov_b32 m0, s30
	s_nop 0
	global_load_lds_dwordx4 v132, s[22:23]
	s_waitcnt vmcnt(8)
	s_waitcnt lgkmcnt(0)
	s_barrier
	s_waitcnt lgkmcnt(0)
	v_mfma_f32_16x16x32_bf16 v[124:127], v[146:149], v[182:185], v[124:127]
	v_mfma_f32_16x16x32_bf16 v[120:123], v[158:161], v[182:185], v[120:123]
	v_mfma_f32_16x16x32_bf16 v[112:115], v[158:161], v[190:193], v[112:115]
	v_mfma_f32_16x16x32_bf16 v[116:119], v[146:149], v[190:193], v[116:119]
	v_mfma_f32_16x16x32_bf16 v[96:99], v[146:149], v[198:201], v[96:99]
	v_mfma_f32_16x16x32_bf16 v[88:91], v[158:161], v[198:201], v[88:91]
	v_mfma_f32_16x16x32_bf16 v[72:75], v[158:161], v[206:209], v[72:75]
	v_mfma_f32_16x16x32_bf16 v[80:83], v[146:149], v[206:209], v[80:83]
	v_mfma_f32_16x16x32_bf16 v[124:127], v[150:153], v[186:189], v[124:127]
	v_mfma_f32_16x16x32_bf16 v[120:123], v[162:165], v[186:189], v[120:123]
	v_mfma_f32_16x16x32_bf16 v[112:115], v[162:165], v[194:197], v[112:115]
	v_mfma_f32_16x16x32_bf16 v[116:119], v[150:153], v[194:197], v[116:119]
	v_mfma_f32_16x16x32_bf16 v[96:99], v[150:153], v[202:205], v[96:99]
	v_mfma_f32_16x16x32_bf16 v[88:91], v[162:165], v[202:205], v[88:91]
	v_mfma_f32_16x16x32_bf16 v[72:75], v[162:165], v[210:213], v[72:75]
	v_mfma_f32_16x16x32_bf16 v[80:83], v[150:153], v[210:213], v[80:83]
	v_mfma_f32_16x16x32_bf16 v[108:111], v[166:169], v[182:185], v[108:111]
	v_mfma_f32_16x16x32_bf16 v[104:107], v[174:177], v[182:185], v[104:107]
	v_mfma_f32_16x16x32_bf16 v[92:95], v[174:177], v[190:193], v[92:95]
	v_mfma_f32_16x16x32_bf16 v[100:103], v[166:169], v[190:193], v[100:103]
	v_mfma_f32_16x16x32_bf16 v[84:87], v[166:169], v[198:201], v[84:87]
	v_mfma_f32_16x16x32_bf16 v[76:79], v[174:177], v[198:201], v[76:79]
	v_mfma_f32_16x16x32_bf16 v[64:67], v[174:177], v[206:209], v[64:67]
	v_mfma_f32_16x16x32_bf16 v[68:71], v[166:169], v[206:209], v[68:71]
	v_mfma_f32_16x16x32_bf16 v[108:111], v[170:173], v[186:189], v[108:111]
	v_mfma_f32_16x16x32_bf16 v[104:107], v[178:181], v[186:189], v[104:107]
	v_mfma_f32_16x16x32_bf16 v[92:95], v[178:181], v[194:197], v[92:95]
	v_mfma_f32_16x16x32_bf16 v[100:103], v[170:173], v[194:197], v[100:103]
	v_mfma_f32_16x16x32_bf16 v[84:87], v[170:173], v[202:205], v[84:87]
	v_mfma_f32_16x16x32_bf16 v[76:79], v[178:181], v[202:205], v[76:79]
	v_mfma_f32_16x16x32_bf16 v[64:67], v[178:181], v[210:213], v[64:67]
	v_mfma_f32_16x16x32_bf16 v[68:71], v[170:173], v[210:213], v[68:71]
	s_barrier
	s_add_i32 s22, s44, s26
	s_mov_b32 m0, s22
	ds_read_b128 v[182:185], v157 offset:49152
	ds_read_b128 v[186:189], v157 offset:50176
	ds_read_b128 v[190:193], v157 offset:51200
	ds_read_b128 v[194:197], v157 offset:52224
	ds_read_b128 v[198:201], v157 offset:53248
	ds_read_b128 v[202:205], v157 offset:54272
	ds_read_b128 v[206:209], v157 offset:55296
	ds_read_b128 v[210:213], v157 offset:56320
	global_load_lds_dwordx4 v130, s[98:99]
	s_add_i32 m0, s22, 0x2000
	s_add_u32 s20, s20, 0xb0080
	s_addc_u32 s21, s21, 0
	s_add_i32 s22, s45, s26
	global_load_lds_dwordx4 v134, s[98:99]
	s_mov_b32 m0, s22
	s_nop 0
	global_load_lds_dwordx4 v130, s[20:21]
	s_add_i32 m0, s22, 0x2000
	s_nop 0
	global_load_lds_dwordx4 v134, s[20:21]
	s_mov_b32 m0, s33
	s_nop 0
	global_load_lds_dwordx4 v128, s[100:101]
	s_mov_b32 m0, s34
	s_nop 0
	global_load_lds_dwordx4 v132, s[100:101]
	s_waitcnt vmcnt(8)
	s_waitcnt lgkmcnt(0)
	s_barrier
	s_waitcnt lgkmcnt(0)
	v_mfma_f32_16x16x32_bf16 v[60:63], v[146:149], v[182:185], v[60:63]
	v_mfma_f32_16x16x32_bf16 v[56:59], v[158:161], v[182:185], v[56:59]
	v_mfma_f32_16x16x32_bf16 v[40:43], v[158:161], v[190:193], v[40:43]
	v_mfma_f32_16x16x32_bf16 v[48:51], v[146:149], v[190:193], v[48:51]
	v_mfma_f32_16x16x32_bf16 v[32:35], v[146:149], v[198:201], v[32:35]
	v_mfma_f32_16x16x32_bf16 v[24:27], v[158:161], v[198:201], v[24:27]
	v_mfma_f32_16x16x32_bf16 v[8:11], v[158:161], v[206:209], v[8:11]
	v_mfma_f32_16x16x32_bf16 v[16:19], v[146:149], v[206:209], v[16:19]
	v_mfma_f32_16x16x32_bf16 v[60:63], v[150:153], v[186:189], v[60:63]
	v_mfma_f32_16x16x32_bf16 v[56:59], v[162:165], v[186:189], v[56:59]
	v_mfma_f32_16x16x32_bf16 v[40:43], v[162:165], v[194:197], v[40:43]
	v_mfma_f32_16x16x32_bf16 v[48:51], v[150:153], v[194:197], v[48:51]
	v_mfma_f32_16x16x32_bf16 v[32:35], v[150:153], v[202:205], v[32:35]
	v_mfma_f32_16x16x32_bf16 v[24:27], v[162:165], v[202:205], v[24:27]
	v_mfma_f32_16x16x32_bf16 v[8:11], v[162:165], v[210:213], v[8:11]
	v_mfma_f32_16x16x32_bf16 v[16:19], v[150:153], v[210:213], v[16:19]
	v_mfma_f32_16x16x32_bf16 v[52:55], v[166:169], v[182:185], v[52:55]
	v_mfma_f32_16x16x32_bf16 v[44:47], v[174:177], v[182:185], v[44:47]
	v_mfma_f32_16x16x32_bf16 v[28:31], v[174:177], v[190:193], v[28:31]
	v_mfma_f32_16x16x32_bf16 v[36:39], v[166:169], v[190:193], v[36:39]
	v_mfma_f32_16x16x32_bf16 v[20:23], v[166:169], v[198:201], v[20:23]
	v_mfma_f32_16x16x32_bf16 v[12:15], v[174:177], v[198:201], v[12:15]
	v_mfma_f32_16x16x32_bf16 v[0:3], v[174:177], v[206:209], v[0:3]
	v_mfma_f32_16x16x32_bf16 v[4:7], v[166:169], v[206:209], v[4:7]
	v_mfma_f32_16x16x32_bf16 v[52:55], v[170:173], v[186:189], v[52:55]
	v_mfma_f32_16x16x32_bf16 v[44:47], v[178:181], v[186:189], v[44:47]
	v_mfma_f32_16x16x32_bf16 v[28:31], v[178:181], v[194:197], v[28:31]
	v_mfma_f32_16x16x32_bf16 v[36:39], v[170:173], v[194:197], v[36:39]
	v_mfma_f32_16x16x32_bf16 v[20:23], v[170:173], v[202:205], v[20:23]
	v_mfma_f32_16x16x32_bf16 v[12:15], v[178:181], v[202:205], v[12:15]
	v_mfma_f32_16x16x32_bf16 v[0:3], v[178:181], v[210:213], v[0:3]
	v_mfma_f32_16x16x32_bf16 v[4:7], v[170:173], v[210:213], v[4:7]
	s_barrier
	s_add_i32 s43, s43, 2
	s_add_u32 s18, s18, 0x100
	s_addc_u32 s19, s19, 0
	s_add_u32 s17, s17, 0x100
	s_addc_u32 s42, s42, 0
	s_cmp_gt_u32 s43, 41
	s_cbranch_scc0 .LBB0_2058
